# v87 + nt (streaming) hint added to prep_weights' write-through bf16 weight stores (read only in the next layer)
# baseline (speedup 1.0000x reference)
; #define LAS __attribute__((address_space(3)))
; __device__ __forceinline__ void transpose_item(const float* W, int K, int N, bf16_t* WT, int kb, int nb, int drow0, const float* kscale, LAS float* scr, int lane) {
;     const int k0 = 64 * kb, n0 = 32 * nb, c = lane & 7;
;     f32x4 s0 = {1.f, 1.f, 1.f, 1.f}, s1 = {1.f, 1.f, 1.f, 1.f};
;     if (kscale) { s0 = *(const f32x4*)(kscale + k0 + 8 * c); s1 = *(const f32x4*)(kscale + k0 + 8 * c + 4); }
;     const float* src = W + (size_t)(k0 + (lane >> 5)) * N + n0 + (lane & 31);
;     float w[32];
; #pragma unroll
;     for (int i = 0; i < 32; ++i) w[i] = __builtin_nontemporal_load(src + (size_t)(2 * i) * N);
; __device__ __forceinline__ void prep_weights(Frame& F, const Args& a, int l, int it_lo, int it_hi, int gw, int ngw) {
;     ...
;         if (r < I0) { const int kb = r / 184, nb = r % 184, n0 = 32 * nb; int d0 = n0;
;             if (n0 >= C_CC && n0 < C_CX) { const int c = n0 - C_CC; d0 = 256 * (5 + c / 128) + (c % 128); }
;             else if (n0 >= C_CX && n0 < C_U) { const int c = n0 - C_CX; d0 = 256 * (5 + c / 128) + 128 + (c % 128); }
;             else if (n0 >= C_G && n0 < C_G + 1024) { const int c = n0 - C_G; d0 = 256 * (11 + c / 128) + (c % 128); }
;             else if (n0 >= C_G + 1024 && n0 < C_G + 2048) { const int c = n0 - C_G - 1024; d0 = 256 * (11 + c / 128) + 128 + (c % 128); }
;             transpose_item(w_in, DM, INCOLS, W + WO_IN, kb, nb, d0, nmix, scr, F.lane); continue; } r -= I0;
.LBB0_57:
	v_or_b32_e32 v46, s10, v30
	v_mov_b64_e32 v[44:45], s[84:85]
	s_movk_i32 s13, 0x5c00
	v_mad_i64_i32 v[44:45], s[62:63], v46, s13, v[44:45]
	s_ashr_i32 s13, s12, 31
	v_lshl_add_u64 v[44:45], s[12:13], 2, v[44:45]
	v_lshl_add_u64 v[44:45], v[44:45], 0, v[8:9]
	v_add_co_u32_e32 v46, vcc, s58, v44
	s_mov_b32 s12, 0x17000
	s_nop 0
	v_addc_co_u32_e32 v47, vcc, 0, v45, vcc
	v_add_co_u32_e32 v48, vcc, s12, v44
	s_mov_b32 s12, 0x39000
	s_nop 0
	v_addc_co_u32_e32 v49, vcc, 0, v45, vcc
	v_add_co_u32_e32 v50, vcc, s41, v44
	s_nop 1
	v_addc_co_u32_e32 v51, vcc, 0, v45, vcc
	v_add_co_u32_e32 v52, vcc, s47, v44
	s_nop 1
	v_addc_co_u32_e32 v53, vcc, 0, v45, vcc
	v_add_co_u32_e32 v54, vcc, s12, v44
	s_mov_b32 s12, 0x45000
	s_nop 0
	v_addc_co_u32_e32 v55, vcc, 0, v45, vcc
	v_add_co_u32_e32 v56, vcc, s12, v44
	s_mov_b32 s12, 0x50000
	s_nop 0
	v_addc_co_u32_e32 v57, vcc, 0, v45, vcc
	v_add_co_u32_e32 v58, vcc, s12, v44
	s_mov_b32 s12, 0x5c000
	s_nop 0
	v_addc_co_u32_e32 v59, vcc, 0, v45, vcc
	global_load_dword v62, v[44:45], off nt
	global_load_dword v63, v[46:47], off offset:2048 nt
	global_load_dword v64, v[48:49], off nt
	global_load_dword v65, v[50:51], off offset:2048 nt
	global_load_dword v66, v[52:53], off nt
	global_load_dword v67, v[54:55], off offset:2048 nt
	global_load_dword v68, v[56:57], off nt
	global_load_dword v69, v[58:59], off offset:2048 nt
	v_add_co_u32_e32 v46, vcc, s12, v44
	s_mov_b32 s12, 0x67000
	s_nop 0
	v_addc_co_u32_e32 v47, vcc, 0, v45, vcc
	v_add_co_u32_e32 v48, vcc, s12, v44
	s_mov_b32 s12, 0x73000
	s_nop 0
	v_addc_co_u32_e32 v49, vcc, 0, v45, vcc
	v_add_co_u32_e32 v50, vcc, s12, v44
	s_mov_b32 s12, 0x7e000
	s_nop 0
	v_addc_co_u32_e32 v51, vcc, 0, v45, vcc
	v_add_co_u32_e32 v52, vcc, s12, v44
	s_mov_b32 s12, 0x8a000
	s_nop 0
	v_addc_co_u32_e32 v53, vcc, 0, v45, vcc
	v_add_co_u32_e32 v54, vcc, s12, v44
	s_mov_b32 s12, 0x95000
	s_nop 0
	v_addc_co_u32_e32 v55, vcc, 0, v45, vcc
	v_add_co_u32_e32 v56, vcc, s12, v44
	s_mov_b32 s12, 0xa1000
	s_nop 0
	v_addc_co_u32_e32 v57, vcc, 0, v45, vcc
	v_add_co_u32_e32 v58, vcc, s12, v44
	s_mov_b32 s12, 0xac000
	s_nop 0
	v_addc_co_u32_e32 v59, vcc, 0, v45, vcc
	v_add_co_u32_e32 v60, vcc, s12, v44
	s_mov_b32 s12, 0xb8000
	s_nop 0
	v_addc_co_u32_e32 v61, vcc, 0, v45, vcc
	global_load_dword v70, v[46:47], off nt
	global_load_dword v71, v[48:49], off offset:2048 nt
	global_load_dword v72, v[50:51], off nt
	global_load_dword v73, v[52:53], off offset:2048 nt
	global_load_dword v74, v[54:55], off nt
	global_load_dword v75, v[56:57], off offset:2048 nt
	global_load_dword v76, v[58:59], off nt
	global_load_dword v77, v[60:61], off offset:2048 nt
	v_add_co_u32_e32 v46, vcc, s12, v44
	s_mov_b32 s12, 0xc3000
	s_nop 0
	v_addc_co_u32_e32 v47, vcc, 0, v45, vcc
	v_add_co_u32_e32 v48, vcc, s12, v44
	s_mov_b32 s12, 0xcf000
	s_nop 0
	v_addc_co_u32_e32 v49, vcc, 0, v45, vcc
	v_add_co_u32_e32 v50, vcc, s12, v44
	s_mov_b32 s12, 0xda000
	s_nop 0
	v_addc_co_u32_e32 v51, vcc, 0, v45, vcc
	v_add_co_u32_e32 v52, vcc, s12, v44
	s_mov_b32 s12, 0xe6000
	s_nop 0
	v_addc_co_u32_e32 v53, vcc, 0, v45, vcc
	v_add_co_u32_e32 v54, vcc, s12, v44
	s_mov_b32 s12, 0xf1000
	s_nop 0
	v_addc_co_u32_e32 v55, vcc, 0, v45, vcc
	v_add_co_u32_e32 v56, vcc, s12, v44
	s_mov_b32 s12, 0x114000
	s_nop 0
	v_addc_co_u32_e32 v57, vcc, 0, v45, vcc
	v_add_co_u32_e32 v58, vcc, s59, v44
	s_nop 1
	v_addc_co_u32_e32 v59, vcc, 0, v45, vcc
	v_add_co_u32_e32 v60, vcc, s60, v44
	s_nop 1
	v_addc_co_u32_e32 v61, vcc, 0, v45, vcc
	global_load_dword v78, v[46:47], off nt
	global_load_dword v79, v[48:49], off offset:2048 nt
	global_load_dword v80, v[50:51], off nt
	global_load_dword v81, v[52:53], off offset:2048 nt
	global_load_dword v82, v[54:55], off nt
	global_load_dword v83, v[56:57], off offset:2048 nt
	global_load_dword v84, v[58:59], off nt
	s_nop 0
	global_load_dword v60, v[60:61], off offset:2048 nt
	v_add_co_u32_e32 v46, vcc, s12, v44
	s_mov_b32 s12, 0x11f000
	s_nop 0
	v_addc_co_u32_e32 v47, vcc, 0, v45, vcc
	v_add_co_u32_e32 v48, vcc, s12, v44
	s_mov_b32 s12, 0x12b000
	s_nop 0
	v_addc_co_u32_e32 v49, vcc, 0, v45, vcc
	v_add_co_u32_e32 v50, vcc, s12, v44
	s_mov_b32 s12, 0x136000
	s_nop 0
	v_addc_co_u32_e32 v51, vcc, 0, v45, vcc
	v_add_co_u32_e32 v52, vcc, s12, v44
	s_mov_b32 s12, 0x142000
	s_nop 0
	v_addc_co_u32_e32 v53, vcc, 0, v45, vcc
	v_add_co_u32_e32 v54, vcc, s12, v44
	s_mov_b32 s12, 0x14d000
	s_nop 0
	v_addc_co_u32_e32 v55, vcc, 0, v45, vcc
	v_add_co_u32_e32 v56, vcc, s12, v44
	s_mov_b32 s12, 0x159000
	s_nop 0
	v_addc_co_u32_e32 v57, vcc, 0, v45, vcc
	v_add_co_u32_e32 v58, vcc, s12, v44
	s_mov_b32 s12, 0x164000
	s_nop 0
	v_addc_co_u32_e32 v59, vcc, 0, v45, vcc
	v_add_co_u32_e32 v44, vcc, s12, v44
	s_nop 1
	v_addc_co_u32_e32 v45, vcc, 0, v45, vcc
	global_load_dword v46, v[46:47], off nt
	s_nop 0
	global_load_dword v47, v[48:49], off offset:2048 nt
	s_nop 0
	global_load_dword v48, v[50:51], off nt
	global_load_dword v49, v[52:53], off offset:2048 nt
	s_nop 0
	global_load_dword v50, v[54:55], off nt
	global_load_dword v51, v[56:57], off offset:2048 nt
	global_load_dword v52, v[58:59], off nt
	s_nop 0
	global_load_dword v44, v[44:45], off offset:2048 nt
	s_waitcnt vmcnt(30)
; #define LAS __attribute__((address_space(3)))
; __device__ __forceinline__ unsigned pk2(float lo, float hi) { const f32x2 v = {lo, hi}; const bf16x2_hw b = __builtin_convertvector(v, bf16x2_hw); return __builtin_bit_cast(unsigned, b); }
; __device__ __forceinline__ void gst_wt16(void* p, const u32x4 v) { asm volatile("global_store_dwordx4 %0, %1, off sc1\n\ts_nop 1" :: "v"(p), "v"(v) : "memory"); }
; __device__ __forceinline__ void transpose_item(const float* W, int K, int N, bf16_t* WT, int kb, int nb, int drow0, const float* kscale, LAS float* scr, int lane) {
;     ...
; #pragma unroll
;     for (int i = 0; i < 32; ++i) scr[(2 * i + (lane >> 5)) * 33 + (lane & 31)] = w[i];
;     asm volatile("s_waitcnt lgkmcnt(0)" ::: "memory");
; #pragma unroll
;     for (int j = 0; j < 4; ++j) { const int n = (lane >> 3) + 8 * j; const LAS float* s = scr + (8 * c) * 33 + n;
;         u32x4 o; o.x = pk2(s[0 * 33] * s0[0], s[1 * 33] * s0[1]); o.y = pk2(s[2 * 33] * s0[2], s[3 * 33] * s0[3]); o.z = pk2(s[4 * 33] * s1[0], s[5 * 33] * s1[1]); o.w = pk2(s[6 * 33] * s1[2], s[7 * 33] * s1[3]);
;         gst_wt16(WT + (size_t)(drow0 + n) * K + k0 + 8 * c, o); }
;     asm volatile("s_waitcnt lgkmcnt(0)" ::: "memory");
	ds_write2_b32 v31, v62, v63 offset1:66
	s_waitcnt vmcnt(28)
	ds_write2_b32 v31, v64, v65 offset0:132 offset1:198
	s_waitcnt vmcnt(26)
	ds_write2_b32 v37, v66, v67 offset0:8 offset1:74
	s_waitcnt vmcnt(24)
	ds_write2_b32 v37, v68, v69 offset0:140 offset1:206
	s_waitcnt vmcnt(22)
	ds_write2_b32 v38, v70, v71 offset0:16 offset1:82
	s_waitcnt vmcnt(20)
	ds_write2_b32 v38, v72, v73 offset0:148 offset1:214
	s_waitcnt vmcnt(18)
	ds_write2_b32 v39, v74, v75 offset0:24 offset1:90
	s_waitcnt vmcnt(16)
	ds_write2_b32 v39, v76, v77 offset0:156 offset1:222
	s_waitcnt vmcnt(14)
	ds_write2_b32 v40, v78, v79 offset0:32 offset1:98
	s_waitcnt vmcnt(12)
	ds_write2_b32 v40, v80, v81 offset0:164 offset1:230
	s_waitcnt vmcnt(10)
	ds_write2_b32 v41, v82, v83 offset0:40 offset1:106
	s_waitcnt vmcnt(8)
	ds_write2_b32 v41, v84, v60 offset0:172 offset1:238
	s_waitcnt vmcnt(6)
	ds_write2_b32 v42, v46, v47 offset0:48 offset1:114
	s_waitcnt vmcnt(4)
	ds_write2_b32 v42, v48, v49 offset0:180 offset1:246
	s_waitcnt vmcnt(2)
	ds_write2_b32 v43, v50, v51 offset0:56 offset1:122
	s_waitcnt vmcnt(0)
	ds_write2_b32 v43, v52, v44 offset0:188 offset1:254
	s_waitcnt lgkmcnt(0)
	ds_read2_b32 v[44:45], v33 offset1:33
	ds_read2_b32 v[46:47], v33 offset0:66 offset1:99
	ds_read2_b32 v[50:51], v33 offset0:132 offset1:165
	ds_read2_b32 v[52:53], v33 offset0:198 offset1:231
	v_lshl_add_u64 v[48:49], s[10:11], 1, v[28:29]
	s_waitcnt lgkmcnt(3)
	v_pk_mul_f32 v[44:45], v[4:5], v[44:45]
	s_waitcnt lgkmcnt(2)
	v_pk_mul_f32 v[46:47], v[6:7], v[46:47]
	v_cvt_pk_bf16_f32 v44, v44, v45
	v_cvt_pk_bf16_f32 v45, v46, v47
	s_waitcnt lgkmcnt(1)
	v_pk_mul_f32 v[46:47], v[0:1], v[50:51]
	s_waitcnt lgkmcnt(0)
	v_pk_mul_f32 v[50:51], v[2:3], v[52:53]
	v_cvt_pk_bf16_f32 v46, v46, v47
	v_cvt_pk_bf16_f32 v47, v50, v51
	v_add_u32_e32 v50, s8, v32
	v_ashrrev_i32_e32 v51, 31, v50
	v_lshlrev_b64 v[50:51], 11, v[50:51]
	v_lshl_add_u64 v[50:51], v[48:49], 0, v[50:51]
	global_store_dwordx4 v[50:51], v[44:47], off sc1 nt
	s_nop 1
	ds_read2_b32 v[44:45], v33 offset0:8 offset1:41
	ds_read2_b32 v[46:47], v33 offset0:74 offset1:107
	ds_read2_b32 v[50:51], v33 offset0:140 offset1:173
	ds_read2_b32 v[52:53], v33 offset0:206 offset1:239
	s_waitcnt lgkmcnt(3)
	v_pk_mul_f32 v[44:45], v[4:5], v[44:45]
	s_waitcnt lgkmcnt(2)
	v_pk_mul_f32 v[46:47], v[6:7], v[46:47]
	v_cvt_pk_bf16_f32 v44, v44, v45
	v_cvt_pk_bf16_f32 v45, v46, v47
	s_waitcnt lgkmcnt(1)
	v_pk_mul_f32 v[46:47], v[0:1], v[50:51]
	s_waitcnt lgkmcnt(0)
	v_pk_mul_f32 v[50:51], v[2:3], v[52:53]
	v_cvt_pk_bf16_f32 v46, v46, v47
	v_cvt_pk_bf16_f32 v47, v50, v51
	v_add_u32_e32 v50, s8, v34
	v_ashrrev_i32_e32 v51, 31, v50
	v_lshlrev_b64 v[50:51], 11, v[50:51]
	v_lshl_add_u64 v[50:51], v[48:49], 0, v[50:51]
	global_store_dwordx4 v[50:51], v[44:47], off sc1 nt
	s_nop 1
	ds_read2_b32 v[44:45], v33 offset0:16 offset1:49
	ds_read2_b32 v[46:47], v33 offset0:82 offset1:115
	ds_read2_b32 v[50:51], v33 offset0:148 offset1:181
	ds_read2_b32 v[52:53], v33 offset0:214 offset1:247
	s_waitcnt lgkmcnt(3)
	v_pk_mul_f32 v[44:45], v[4:5], v[44:45]
	s_waitcnt lgkmcnt(2)
	v_pk_mul_f32 v[46:47], v[6:7], v[46:47]
	v_cvt_pk_bf16_f32 v44, v44, v45
	v_cvt_pk_bf16_f32 v45, v46, v47
	s_waitcnt lgkmcnt(1)
	v_pk_mul_f32 v[46:47], v[0:1], v[50:51]
	s_waitcnt lgkmcnt(0)
	v_pk_mul_f32 v[50:51], v[2:3], v[52:53]
	v_cvt_pk_bf16_f32 v46, v46, v47
	v_cvt_pk_bf16_f32 v47, v50, v51
	v_add_u32_e32 v50, s8, v35
	v_ashrrev_i32_e32 v51, 31, v50
	v_lshlrev_b64 v[50:51], 11, v[50:51]
	v_lshl_add_u64 v[50:51], v[48:49], 0, v[50:51]
	global_store_dwordx4 v[50:51], v[44:47], off sc1 nt
	s_nop 1
	ds_read2_b32 v[44:45], v33 offset0:24 offset1:57
	ds_read2_b32 v[46:47], v33 offset0:90 offset1:123
	ds_read2_b32 v[50:51], v33 offset0:222 offset1:255
	s_waitcnt lgkmcnt(2)
	v_pk_mul_f32 v[4:5], v[4:5], v[44:45]
	ds_read2_b32 v[44:45], v33 offset0:156 offset1:189
	s_waitcnt lgkmcnt(2)
	v_pk_mul_f32 v[6:7], v[6:7], v[46:47]
	v_cvt_pk_bf16_f32 v4, v4, v5
	v_cvt_pk_bf16_f32 v5, v6, v7
	s_waitcnt lgkmcnt(0)
	v_pk_mul_f32 v[0:1], v[0:1], v[44:45]
	s_nop 0
	v_cvt_pk_bf16_f32 v6, v0, v1
	v_pk_mul_f32 v[0:1], v[2:3], v[50:51]
	s_nop 0
	v_cvt_pk_bf16_f32 v7, v0, v1
	v_add_u32_e32 v0, s8, v36
	v_ashrrev_i32_e32 v1, 31, v0
	v_lshlrev_b64 v[0:1], 11, v[0:1]
	v_lshl_add_u64 v[0:1], v[48:49], 0, v[0:1]
	global_store_dwordx4 v[0:1], v[4:7], off sc1 nt
	s_nop 1
	s_waitcnt lgkmcnt(0)

; __device__ __forceinline__ void transpose_item(const float* W, int K, int N, bf16_t* WT, int kb, int nb, int drow0, const float* kscale, LAS float* scr, int lane) {
;     const int k0 = 64 * kb, n0 = 32 * nb, c = lane & 7;
;     f32x4 s0 = {1.f, 1.f, 1.f, 1.f}, s1 = {1.f, 1.f, 1.f, 1.f};
;     if (kscale) { s0 = *(const f32x4*)(kscale + k0 + 8 * c); s1 = *(const f32x4*)(kscale + k0 + 8 * c + 4); }
;     const float* src = W + (size_t)(k0 + (lane >> 5)) * N + n0 + (lane & 31);
;     float w[32];
; #pragma unroll
;     for (int i = 0; i < 32; ++i) w[i] = __builtin_nontemporal_load(src + (size_t)(2 * i) * N);
; __device__ __forceinline__ void prep_weights(Frame& F, const Args& a, int l, int it_lo, int it_hi, int gw, int ngw) {
;     ...
;         if (r < I1) { const int kb = r / 32, nb = r % 32; transpose_item(w_ao, 512, DM, W + WO_AO, kb, nb, 32 * nb, nullptr, scr, F.lane); continue; } r -= I1;
;         if (r < I2) { const int kb = r / 32, nb = r % 32; transpose_item(w_co, 512, DM, W + WO_CO, kb, nb, 32 * nb, nullptr, scr, F.lane); continue; } r -= I2;
;         if (r < I3) { const int kb = r / 16, nb = r % 16; transpose_item(w_gl, 512, 512, W + WO_GLU, kb, nb, 32 * nb, nullptr, scr, F.lane); continue; } r -= I3;
;         if (r < I4) { const int kb = r / 32, nb = r % 32; transpose_item(w_so, 512, DM, W + WO_SO, kb, nb, 32 * nb, nullptr, scr, F.lane); continue; } r -= I4;
;         if (r < I5) { const int kb = r / 32, nb = r % 32; transpose_item(w_mx, DM, DM, W + WO_MIX, kb, nb, 32 * nb, nullptr, scr, F.lane); continue; } r -= I5;
;         if (r < I6) { const int kb = r / 176, nb = r % 176; const int n0 = 32 * nb; const int j0 = n0 < FFN ? n0 : n0 - FFN; const int drow0 = 256 * (j0 / 128) + (n0 < FFN ? 0 : 128) + (j0 % 128);
;             transpose_item(w_fi, DM, FFN2, W + WO_FI, kb, nb, drow0, nffn, scr, F.lane); continue; } r -= I6;
;         { const int kb = r / 32, nb = r % 32; transpose_item(w_fo, FFN, DM, W + WO_FO, kb, nb, 32 * nb, nullptr, scr, F.lane); }
.LBB0_59:
	s_cmpk_gt_i32 s17, 0xb7f
	s_mov_b64 s[10:11], -1
	s_cbranch_scc0 .LBB0_89
	s_cmpk_gt_u32 s17, 0xc7f
	s_cbranch_scc0 .LBB0_86
	s_cmpk_gt_u32 s17, 0xd7f
	s_cbranch_scc0 .LBB0_83
	s_cmpk_gt_u32 s17, 0xdff
	s_cbranch_scc0 .LBB0_80
	s_cmpk_gt_u32 s17, 0xeff
	s_cbranch_scc0 .LBB0_77
	s_cmpk_gt_u32 s17, 0x10ff
	s_cbranch_scc0 .LBB0_74
	s_cmpk_gt_u32 s17, 0x1bff
	s_cbranch_scc0 .LBB0_67
	s_and_b32 s8, s20, 0x7fffffc0
	s_addk_i32 s8, 0xc800
	v_or_b32_e32 v0, s8, v30
	v_mov_b32_e32 v1, v9
	v_readlane_b32 s80, v249, 3
	s_and_b32 s10, s14, 0x3e0
	v_lshlrev_b64 v[0:1], 12, v[0:1]
	v_readlane_b32 s90, v249, 13
	v_readlane_b32 s91, v249, 14
	s_lshl_b32 s12, s10, 2
	s_mov_b32 s13, s9
	v_lshl_add_u64 v[0:1], s[90:91], 0, v[0:1]
	v_lshl_add_u64 v[0:1], v[0:1], 0, s[12:13]
	v_lshl_add_u64 v[0:1], v[0:1], 0, v[8:9]
	v_add_co_u32_e32 v2, vcc, s24, v0
	v_readlane_b32 s81, v249, 4
	s_nop 0
	v_addc_co_u32_e32 v3, vcc, 0, v1, vcc
	v_add_co_u32_e32 v4, vcc, s25, v0
	v_readlane_b32 s82, v249, 5
	s_nop 0
	v_addc_co_u32_e32 v5, vcc, 0, v1, vcc
	v_add_co_u32_e32 v6, vcc, s26, v0
	v_readlane_b32 s83, v249, 6
	s_nop 0
	v_addc_co_u32_e32 v7, vcc, 0, v1, vcc
	v_add_co_u32_e32 v44, vcc, s27, v0
	v_readlane_b32 s84, v249, 7
	s_nop 0
	v_addc_co_u32_e32 v45, vcc, 0, v1, vcc
	v_add_co_u32_e32 v46, vcc, s28, v0
	v_readlane_b32 s85, v249, 8
	s_nop 0
	v_addc_co_u32_e32 v47, vcc, 0, v1, vcc
	v_add_co_u32_e32 v48, vcc, s29, v0
	v_readlane_b32 s86, v249, 9
	s_nop 0
	v_addc_co_u32_e32 v49, vcc, 0, v1, vcc
	v_add_co_u32_e32 v50, vcc, s30, v0
	v_readlane_b32 s87, v249, 10
	s_nop 0
	v_addc_co_u32_e32 v51, vcc, 0, v1, vcc
	global_load_dword v54, v[0:1], off nt
	global_load_dword v55, v[2:3], off nt
	global_load_dword v56, v[4:5], off nt
	global_load_dword v57, v[6:7], off nt
	global_load_dword v58, v[44:45], off nt
	global_load_dword v59, v[46:47], off nt
	global_load_dword v60, v[48:49], off nt
	global_load_dword v61, v[50:51], off nt
	v_add_co_u32_e32 v2, vcc, s31, v0
	v_readlane_b32 s88, v249, 11
	s_nop 0
	v_addc_co_u32_e32 v3, vcc, 0, v1, vcc
	v_add_co_u32_e32 v4, vcc, s33, v0
	v_readlane_b32 s89, v249, 12
	s_nop 0
	v_addc_co_u32_e32 v5, vcc, 0, v1, vcc
	v_add_co_u32_e32 v6, vcc, s34, v0
	v_readlane_b32 s92, v249, 15
	s_nop 0
	v_addc_co_u32_e32 v7, vcc, 0, v1, vcc
	v_add_co_u32_e32 v44, vcc, s35, v0
	v_readlane_b32 s93, v249, 16
	s_nop 0
	v_addc_co_u32_e32 v45, vcc, 0, v1, vcc
	v_add_co_u32_e32 v46, vcc, s36, v0
	v_readlane_b32 s94, v249, 17
	s_nop 0
	v_addc_co_u32_e32 v47, vcc, 0, v1, vcc
	v_add_co_u32_e32 v48, vcc, s37, v0
	v_readlane_b32 s95, v249, 18
	s_nop 0
	v_addc_co_u32_e32 v49, vcc, 0, v1, vcc
	v_add_co_u32_e32 v50, vcc, s38, v0
	v_readlane_b32 s80, v249, 36
	s_nop 0
	v_addc_co_u32_e32 v51, vcc, 0, v1, vcc
	v_add_co_u32_e32 v52, vcc, s39, v0
	v_readlane_b32 s81, v249, 37
	s_nop 0
	v_addc_co_u32_e32 v53, vcc, 0, v1, vcc
	global_load_dword v62, v[2:3], off nt
	global_load_dword v63, v[4:5], off nt
	global_load_dword v64, v[6:7], off nt
	global_load_dword v65, v[44:45], off nt
	global_load_dword v66, v[46:47], off nt
	global_load_dword v67, v[48:49], off nt
	global_load_dword v68, v[50:51], off nt
	global_load_dword v69, v[52:53], off nt
	v_add_co_u32_e32 v2, vcc, s40, v0
	v_readlane_b32 s82, v249, 38
	s_nop 0
	v_addc_co_u32_e32 v3, vcc, 0, v1, vcc
	v_add_co_u32_e32 v4, vcc, s41, v0
	v_readlane_b32 s83, v249, 39
	s_nop 0
	v_addc_co_u32_e32 v5, vcc, 0, v1, vcc
	v_add_co_u32_e32 v6, vcc, s42, v0
	v_readlane_b32 s84, v249, 40
	s_nop 0
	v_addc_co_u32_e32 v7, vcc, 0, v1, vcc
	v_add_co_u32_e32 v44, vcc, s43, v0
	v_readlane_b32 s85, v249, 41
	s_nop 0
	v_addc_co_u32_e32 v45, vcc, 0, v1, vcc
	v_add_co_u32_e32 v46, vcc, s44, v0
	v_readlane_b32 s86, v249, 42
	s_nop 0
	v_addc_co_u32_e32 v47, vcc, 0, v1, vcc
	v_add_co_u32_e32 v48, vcc, s45, v0
	v_readlane_b32 s87, v249, 43
	s_nop 0
	v_addc_co_u32_e32 v49, vcc, 0, v1, vcc
	v_add_co_u32_e32 v50, vcc, s46, v0
	v_readlane_b32 s88, v249, 44
	s_nop 0
	v_addc_co_u32_e32 v51, vcc, 0, v1, vcc
	v_add_co_u32_e32 v52, vcc, s47, v0
	v_readlane_b32 s89, v249, 45
	s_nop 0
	v_addc_co_u32_e32 v53, vcc, 0, v1, vcc
	global_load_dword v70, v[2:3], off nt
	global_load_dword v71, v[4:5], off nt
	global_load_dword v72, v[6:7], off nt
	global_load_dword v73, v[44:45], off nt
	global_load_dword v74, v[46:47], off nt
	global_load_dword v75, v[48:49], off nt
	global_load_dword v76, v[50:51], off nt
	s_nop 0
	global_load_dword v52, v[52:53], off nt
	v_add_co_u32_e32 v2, vcc, s48, v0
	v_readlane_b32 s90, v249, 46
	s_nop 0
	v_addc_co_u32_e32 v3, vcc, 0, v1, vcc
	v_add_co_u32_e32 v4, vcc, s49, v0
	v_readlane_b32 s91, v249, 47
	s_nop 0
	v_addc_co_u32_e32 v5, vcc, 0, v1, vcc
	v_add_co_u32_e32 v6, vcc, s52, v0
	v_readlane_b32 s92, v249, 48
	s_nop 0
	v_addc_co_u32_e32 v7, vcc, 0, v1, vcc
	v_add_co_u32_e32 v44, vcc, s53, v0
	v_readlane_b32 s93, v249, 49
	s_nop 0
	v_addc_co_u32_e32 v45, vcc, 0, v1, vcc
	v_add_co_u32_e32 v46, vcc, s54, v0
	v_readlane_b32 s94, v249, 50
	s_nop 0
	v_addc_co_u32_e32 v47, vcc, 0, v1, vcc
	v_add_co_u32_e32 v48, vcc, s55, v0
	v_readlane_b32 s95, v249, 51
	s_nop 0
	v_addc_co_u32_e32 v49, vcc, 0, v1, vcc
	v_add_co_u32_e32 v50, vcc, s56, v0
	s_nop 1
	v_addc_co_u32_e32 v51, vcc, 0, v1, vcc
	v_add_co_u32_e32 v0, vcc, s57, v0
	s_nop 1
	v_addc_co_u32_e32 v1, vcc, 0, v1, vcc
	global_load_dword v2, v[2:3], off nt
	s_nop 0
	global_load_dword v3, v[4:5], off nt
	s_nop 0
	global_load_dword v4, v[6:7], off nt
	global_load_dword v5, v[44:45], off nt
	s_nop 0
	global_load_dword v6, v[46:47], off nt
	global_load_dword v7, v[48:49], off nt
	global_load_dword v44, v[50:51], off nt
	s_nop 0
	global_load_dword v0, v[0:1], off nt
	s_waitcnt vmcnt(30)
; #define LAS __attribute__((address_space(3)))
; __device__ __forceinline__ unsigned pk2(float lo, float hi) { const f32x2 v = {lo, hi}; const bf16x2_hw b = __builtin_convertvector(v, bf16x2_hw); return __builtin_bit_cast(unsigned, b); }
; __device__ __forceinline__ void gst_wt16(void* p, const u32x4 v) { asm volatile("global_store_dwordx4 %0, %1, off sc1\n\ts_nop 1" :: "v"(p), "v"(v) : "memory"); }
; __device__ __forceinline__ void transpose_item(const float* W, int K, int N, bf16_t* WT, int kb, int nb, int drow0, const float* kscale, LAS float* scr, int lane) {
;     ...
;     for (int i = 0; i < 32; ++i) scr[(2 * i + (lane >> 5)) * 33 + (lane & 31)] = w[i];
;     asm volatile("s_waitcnt lgkmcnt(0)" ::: "memory");
; #pragma unroll
;     for (int j = 0; j < 4; ++j) { const int n = (lane >> 3) + 8 * j; const LAS float* s = scr + (8 * c) * 33 + n;
;         u32x4 o; o.x = pk2(s[0 * 33] * s0[0], s[1 * 33] * s0[1]); o.y = pk2(s[2 * 33] * s0[2], s[3 * 33] * s0[3]); o.z = pk2(s[4 * 33] * s1[0], s[5 * 33] * s1[1]); o.w = pk2(s[6 * 33] * s1[2], s[7 * 33] * s1[3]);
;         gst_wt16(WT + (size_t)(drow0 + n) * K + k0 + 8 * c, o); }
;     asm volatile("s_waitcnt lgkmcnt(0)" ::: "memory");
	ds_write2_b32 v31, v54, v55 offset1:66
	s_waitcnt vmcnt(28)
	ds_write2_b32 v31, v56, v57 offset0:132 offset1:198
	s_waitcnt vmcnt(26)
	ds_write2_b32 v37, v58, v59 offset0:8 offset1:74
	s_waitcnt vmcnt(24)
	ds_write2_b32 v37, v60, v61 offset0:140 offset1:206
	s_waitcnt vmcnt(22)
	ds_write2_b32 v38, v62, v63 offset0:16 offset1:82
	s_waitcnt vmcnt(20)
	ds_write2_b32 v38, v64, v65 offset0:148 offset1:214
	s_waitcnt vmcnt(18)
	ds_write2_b32 v39, v66, v67 offset0:24 offset1:90
	s_waitcnt vmcnt(16)
	ds_write2_b32 v39, v68, v69 offset0:156 offset1:222
	s_waitcnt vmcnt(14)
	ds_write2_b32 v40, v70, v71 offset0:32 offset1:98
	s_waitcnt vmcnt(12)
	ds_write2_b32 v40, v72, v73 offset0:164 offset1:230
	s_waitcnt vmcnt(10)
	ds_write2_b32 v41, v74, v75 offset0:40 offset1:106
	s_waitcnt vmcnt(8)
	ds_write2_b32 v41, v76, v52 offset0:172 offset1:238
	s_waitcnt vmcnt(6)
	ds_write2_b32 v42, v2, v3 offset0:48 offset1:114
	s_waitcnt vmcnt(4)
	ds_write2_b32 v42, v4, v5 offset0:180 offset1:246
	s_waitcnt vmcnt(2)
	ds_write2_b32 v43, v6, v7 offset0:56 offset1:122
	s_waitcnt vmcnt(0)
	ds_write2_b32 v43, v44, v0 offset0:188 offset1:254
	s_waitcnt lgkmcnt(0)
	ds_read2_b32 v[0:1], v33 offset1:33
	ds_read2_b32 v[2:3], v33 offset0:66 offset1:99
	ds_read2_b32 v[4:5], v33 offset0:132 offset1:165
	ds_read2_b32 v[6:7], v33 offset0:198 offset1:231
	v_lshl_add_u64 v[44:45], s[8:9], 1, v[10:11]
	s_waitcnt lgkmcnt(3)
	v_cvt_pk_bf16_f32 v0, v0, v1
	s_waitcnt lgkmcnt(2)
	v_cvt_pk_bf16_f32 v1, v2, v3
	s_waitcnt lgkmcnt(1)
	v_cvt_pk_bf16_f32 v2, v4, v5
	v_or_b32_e32 v4, s10, v32
	v_mul_u32_u24_e32 v4, 0x1600, v4
	v_mov_b32_e32 v5, v9
	s_waitcnt lgkmcnt(0)
	v_cvt_pk_bf16_f32 v3, v6, v7
	v_lshl_add_u64 v[4:5], v[44:45], 0, v[4:5]
	global_store_dwordx4 v[4:5], v[0:3], off sc1 nt
	s_nop 1
	ds_read2_b32 v[0:1], v33 offset0:8 offset1:41
	ds_read2_b32 v[2:3], v33 offset0:74 offset1:107
	ds_read2_b32 v[4:5], v33 offset0:140 offset1:173
	ds_read2_b32 v[6:7], v33 offset0:206 offset1:239
	s_waitcnt lgkmcnt(3)
	v_cvt_pk_bf16_f32 v0, v0, v1
	s_waitcnt lgkmcnt(2)
	v_cvt_pk_bf16_f32 v1, v2, v3
	s_waitcnt lgkmcnt(1)
	v_cvt_pk_bf16_f32 v2, v4, v5
	v_or_b32_e32 v4, s10, v34
	v_mul_u32_u24_e32 v4, 0x1600, v4
	v_mov_b32_e32 v5, v9
	s_waitcnt lgkmcnt(0)
	v_cvt_pk_bf16_f32 v3, v6, v7
	v_lshl_add_u64 v[4:5], v[44:45], 0, v[4:5]
	global_store_dwordx4 v[4:5], v[0:3], off sc1 nt
	s_nop 1
	ds_read2_b32 v[0:1], v33 offset0:16 offset1:49
	ds_read2_b32 v[2:3], v33 offset0:82 offset1:115
	ds_read2_b32 v[4:5], v33 offset0:148 offset1:181
	ds_read2_b32 v[6:7], v33 offset0:214 offset1:247
	s_waitcnt lgkmcnt(3)
	v_cvt_pk_bf16_f32 v0, v0, v1
	s_waitcnt lgkmcnt(2)
	v_cvt_pk_bf16_f32 v1, v2, v3
	s_waitcnt lgkmcnt(1)
	v_cvt_pk_bf16_f32 v2, v4, v5
	v_or_b32_e32 v4, s10, v35
	v_mul_u32_u24_e32 v4, 0x1600, v4
	v_mov_b32_e32 v5, v9
	s_waitcnt lgkmcnt(0)
	v_cvt_pk_bf16_f32 v3, v6, v7
	v_lshl_add_u64 v[4:5], v[44:45], 0, v[4:5]
	global_store_dwordx4 v[4:5], v[0:3], off sc1 nt
	s_nop 1
	ds_read2_b32 v[0:1], v33 offset0:24 offset1:57
	ds_read2_b32 v[2:3], v33 offset0:90 offset1:123
	ds_read2_b32 v[4:5], v33 offset0:156 offset1:189
	ds_read2_b32 v[6:7], v33 offset0:222 offset1:255
	s_waitcnt lgkmcnt(3)
	v_cvt_pk_bf16_f32 v0, v0, v1
	s_waitcnt lgkmcnt(2)
	v_cvt_pk_bf16_f32 v1, v2, v3
	s_waitcnt lgkmcnt(1)
	v_cvt_pk_bf16_f32 v2, v4, v5
	v_or_b32_e32 v4, s10, v36
	v_mul_u32_u24_e32 v4, 0x1600, v4
	v_mov_b32_e32 v5, v9
	s_waitcnt lgkmcnt(0)
	v_cvt_pk_bf16_f32 v3, v6, v7
	v_lshl_add_u64 v[4:5], v[44:45], 0, v[4:5]
	global_store_dwordx4 v[4:5], v[0:3], off sc1 nt
	s_nop 1
	s_waitcnt lgkmcnt(0)
	s_mov_b64 s[10:11], 0

; __device__ __forceinline__ void transpose_item(const float* W, int K, int N, bf16_t* WT, int kb, int nb, int drow0, const float* kscale, LAS float* scr, int lane) {
;     const int k0 = 64 * kb, n0 = 32 * nb, c = lane & 7;
;     f32x4 s0 = {1.f, 1.f, 1.f, 1.f}, s1 = {1.f, 1.f, 1.f, 1.f};
;     if (kscale) { s0 = *(const f32x4*)(kscale + k0 + 8 * c); s1 = *(const f32x4*)(kscale + k0 + 8 * c + 4); }
;     const float* src = W + (size_t)(k0 + (lane >> 5)) * N + n0 + (lane & 31);
;     float w[32];
; #pragma unroll
;     for (int i = 0; i < 32; ++i) w[i] = __builtin_nontemporal_load(src + (size_t)(2 * i) * N);
; __device__ __forceinline__ void prep_weights(Frame& F, const Args& a, int l, int it_lo, int it_hi, int gw, int ngw) {
;     ...
;         if (r < I6) { const int kb = r / 176, nb = r % 176; const int n0 = 32 * nb; const int j0 = n0 < FFN ? n0 : n0 - FFN; const int drow0 = 256 * (j0 / 128) + (n0 < FFN ? 0 : 128) + (j0 % 128);
;             transpose_item(w_fi, DM, FFN2, W + WO_FI, kb, nb, drow0, nffn, scr, F.lane); continue; } r -= I6;
.LBB0_72:
	s_mulk_i32 s12, 0xb0
	s_sub_i32 s8, s11, s12
	s_lshl_b32 s11, s8, 5
	s_and_b32 s12, s8, 0xffff
	s_add_i32 s13, s11, 0xf500
	s_cmpk_lt_u32 s12, 0x58
	s_cselect_b32 s11, s11, s13
	s_cselect_b32 s12, 0, 0x80
	s_and_b32 s13, 0xffff, s10
	v_or_b32_e32 v44, s13, v30
	v_readlane_b32 s80, v249, 3
	v_mul_u32_u24_e32 v44, 0x5800, v44
	v_mov_b32_e32 v45, v9
	v_readlane_b32 s88, v249, 11
	v_readlane_b32 s89, v249, 12
	s_lshl_b32 s8, s8, 7
	s_and_b32 s8, s8, 0x3ff80
	v_lshl_add_u64 v[44:45], s[88:89], 0, v[44:45]
	v_lshl_add_u64 v[44:45], v[44:45], 0, s[8:9]
	v_lshl_add_u64 v[44:45], v[44:45], 0, v[8:9]
	v_add_co_u32_e32 v46, vcc, s58, v44
	s_mov_b32 s8, 0x21000
	s_nop 0
	v_addc_co_u32_e32 v47, vcc, 0, v45, vcc
	v_add_co_u32_e32 v48, vcc, s35, v44
	v_readlane_b32 s81, v249, 4
	s_nop 0
	v_addc_co_u32_e32 v49, vcc, 0, v45, vcc
	v_add_co_u32_e32 v50, vcc, s8, v44
	s_mov_b32 s8, 0x37000
	s_nop 0
	v_addc_co_u32_e32 v51, vcc, 0, v45, vcc
	v_add_co_u32_e32 v52, vcc, s46, v44
	v_readlane_b32 s82, v249, 5
	s_nop 0
	v_addc_co_u32_e32 v53, vcc, 0, v45, vcc
	v_add_co_u32_e32 v54, vcc, s8, v44
	s_mov_b32 s8, 0x42000
	s_nop 0
	v_addc_co_u32_e32 v55, vcc, 0, v45, vcc
	v_add_co_u32_e32 v56, vcc, s8, v44
	s_mov_b32 s8, 0x4d000
	s_nop 0
	v_addc_co_u32_e32 v57, vcc, 0, v45, vcc
	v_add_co_u32_e32 v58, vcc, s8, v44
	s_mov_b32 s8, 0x58000
	s_nop 0
	v_addc_co_u32_e32 v59, vcc, 0, v45, vcc
	global_load_dword v62, v[44:45], off nt
	global_load_dword v63, v[46:47], off nt
	global_load_dword v64, v[48:49], off nt
	global_load_dword v65, v[50:51], off nt
	global_load_dword v66, v[52:53], off nt
	global_load_dword v67, v[54:55], off nt
	global_load_dword v68, v[56:57], off nt
	global_load_dword v69, v[58:59], off nt
	v_add_co_u32_e32 v46, vcc, s8, v44
	s_mov_b32 s8, 0x63000
	s_nop 0
	v_addc_co_u32_e32 v47, vcc, 0, v45, vcc
	v_add_co_u32_e32 v48, vcc, s8, v44
	s_mov_b32 s8, 0x6e000
	s_nop 0
	v_addc_co_u32_e32 v49, vcc, 0, v45, vcc
	v_add_co_u32_e32 v50, vcc, s8, v44
	s_mov_b32 s8, 0x79000
	s_nop 0
	v_addc_co_u32_e32 v51, vcc, 0, v45, vcc
	v_add_co_u32_e32 v52, vcc, s8, v44
	s_mov_b32 s8, 0x84000
	s_nop 0
	v_addc_co_u32_e32 v53, vcc, 0, v45, vcc
	v_add_co_u32_e32 v54, vcc, s8, v44
	s_mov_b32 s8, 0x8f000
	s_nop 0
	v_addc_co_u32_e32 v55, vcc, 0, v45, vcc
	v_add_co_u32_e32 v56, vcc, s8, v44
	s_mov_b32 s8, 0x9a000
	s_nop 0
	v_addc_co_u32_e32 v57, vcc, 0, v45, vcc
	v_add_co_u32_e32 v58, vcc, s8, v44
	s_mov_b32 s8, 0xa5000
	s_nop 0
	v_addc_co_u32_e32 v59, vcc, 0, v45, vcc
	v_add_co_u32_e32 v60, vcc, s8, v44
	s_mov_b32 s8, 0xb0000
	s_nop 0
	v_addc_co_u32_e32 v61, vcc, 0, v45, vcc
	global_load_dword v70, v[46:47], off nt
	global_load_dword v71, v[48:49], off nt
	global_load_dword v72, v[50:51], off nt
	global_load_dword v73, v[52:53], off nt
	global_load_dword v74, v[54:55], off nt
	global_load_dword v75, v[56:57], off nt
	global_load_dword v76, v[58:59], off nt
	global_load_dword v77, v[60:61], off nt
	v_add_co_u32_e32 v46, vcc, s8, v44
	s_mov_b32 s8, 0xbb000
	s_nop 0
	v_addc_co_u32_e32 v47, vcc, 0, v45, vcc
	v_add_co_u32_e32 v48, vcc, s8, v44
	s_mov_b32 s8, 0xc6000
	s_nop 0
	v_addc_co_u32_e32 v49, vcc, 0, v45, vcc
	v_add_co_u32_e32 v50, vcc, s8, v44
	s_mov_b32 s8, 0xd1000
	s_nop 0
	v_addc_co_u32_e32 v51, vcc, 0, v45, vcc
	v_add_co_u32_e32 v52, vcc, s8, v44
	s_mov_b32 s8, 0xdc000
	s_nop 0
	v_addc_co_u32_e32 v53, vcc, 0, v45, vcc
	v_add_co_u32_e32 v54, vcc, s8, v44
	s_mov_b32 s8, 0xe7000
	s_nop 0
	v_addc_co_u32_e32 v55, vcc, 0, v45, vcc
	v_add_co_u32_e32 v56, vcc, s8, v44
	s_mov_b32 s8, 0xf2000
	s_nop 0
	v_addc_co_u32_e32 v57, vcc, 0, v45, vcc
	v_add_co_u32_e32 v58, vcc, s8, v44
	s_mov_b32 s8, 0x113000
	s_nop 0
	v_addc_co_u32_e32 v59, vcc, 0, v45, vcc
	v_add_co_u32_e32 v60, vcc, s59, v44
	v_readlane_b32 s83, v249, 6
	s_nop 0
	v_addc_co_u32_e32 v61, vcc, 0, v45, vcc
	global_load_dword v78, v[46:47], off nt
	global_load_dword v79, v[48:49], off nt
	global_load_dword v80, v[50:51], off nt
	global_load_dword v81, v[52:53], off nt
	global_load_dword v82, v[54:55], off nt
	global_load_dword v83, v[56:57], off nt
	global_load_dword v84, v[58:59], off nt
	s_nop 0
	global_load_dword v60, v[60:61], off nt
	v_add_co_u32_e32 v46, vcc, s60, v44
	v_readlane_b32 s84, v249, 7
	s_nop 0
	v_addc_co_u32_e32 v47, vcc, 0, v45, vcc
	v_add_co_u32_e32 v48, vcc, s8, v44
	s_mov_b32 s8, 0x11e000
	s_nop 0
	v_addc_co_u32_e32 v49, vcc, 0, v45, vcc
	v_add_co_u32_e32 v50, vcc, s8, v44
	s_mov_b32 s8, 0x129000
	s_nop 0
	v_addc_co_u32_e32 v51, vcc, 0, v45, vcc
	v_add_co_u32_e32 v52, vcc, s8, v44
	s_mov_b32 s8, 0x134000
	s_nop 0
	v_addc_co_u32_e32 v53, vcc, 0, v45, vcc
	v_add_co_u32_e32 v54, vcc, s8, v44
	s_mov_b32 s8, 0x13f000
	s_nop 0
	v_addc_co_u32_e32 v55, vcc, 0, v45, vcc
	v_add_co_u32_e32 v56, vcc, s8, v44
	s_mov_b32 s8, 0x14a000
	s_nop 0
	v_addc_co_u32_e32 v57, vcc, 0, v45, vcc
	v_add_co_u32_e32 v58, vcc, s8, v44
	s_mov_b32 s8, 0x155000
	s_nop 0
	v_addc_co_u32_e32 v59, vcc, 0, v45, vcc
	v_add_co_u32_e32 v44, vcc, s8, v44
	s_sext_i32_i16 s8, s11
	s_nop 0
	v_addc_co_u32_e32 v45, vcc, 0, v45, vcc
	global_load_dword v46, v[46:47], off nt
	s_nop 0
	global_load_dword v47, v[48:49], off nt
	s_nop 0
	global_load_dword v48, v[50:51], off nt
	global_load_dword v49, v[52:53], off nt
	s_nop 0
	global_load_dword v50, v[54:55], off nt
	global_load_dword v51, v[56:57], off nt
	global_load_dword v52, v[58:59], off nt
	s_nop 0
	global_load_dword v44, v[44:45], off nt
	s_waitcnt vmcnt(30)
; #define LAS __attribute__((address_space(3)))
; __device__ __forceinline__ unsigned pk2(float lo, float hi) { const f32x2 v = {lo, hi}; const bf16x2_hw b = __builtin_convertvector(v, bf16x2_hw); return __builtin_bit_cast(unsigned, b); }
; __device__ __forceinline__ void gst_wt16(void* p, const u32x4 v) { asm volatile("global_store_dwordx4 %0, %1, off sc1\n\ts_nop 1" :: "v"(p), "v"(v) : "memory"); }
; __device__ __forceinline__ void transpose_item(const float* W, int K, int N, bf16_t* WT, int kb, int nb, int drow0, const float* kscale, LAS float* scr, int lane) {
;     ...
;     for (int i = 0; i < 32; ++i) scr[(2 * i + (lane >> 5)) * 33 + (lane & 31)] = w[i];
;     asm volatile("s_waitcnt lgkmcnt(0)" ::: "memory");
; #pragma unroll
;     for (int j = 0; j < 4; ++j) { const int n = (lane >> 3) + 8 * j; const LAS float* s = scr + (8 * c) * 33 + n;
;         u32x4 o; o.x = pk2(s[0 * 33] * s0[0], s[1 * 33] * s0[1]); o.y = pk2(s[2 * 33] * s0[2], s[3 * 33] * s0[3]); o.z = pk2(s[4 * 33] * s1[0], s[5 * 33] * s1[1]); o.w = pk2(s[6 * 33] * s1[2], s[7 * 33] * s1[3]);
;         gst_wt16(WT + (size_t)(drow0 + n) * K + k0 + 8 * c, o); }
;     asm volatile("s_waitcnt lgkmcnt(0)" ::: "memory");
; __device__ __forceinline__ void prep_weights(Frame& F, const Args& a, int l, int it_lo, int it_hi, int gw, int ngw) {
;     ...
;         if (r < I6) { const int kb = r / 176, nb = r % 176; const int n0 = 32 * nb; const int j0 = n0 < FFN ? n0 : n0 - FFN; const int drow0 = 256 * (j0 / 128) + (n0 < FFN ? 0 : 128) + (j0 % 128);
;             transpose_item(w_fi, DM, FFN2, W + WO_FI, kb, nb, drow0, nffn, scr, F.lane); continue; } r -= I6;
	ds_write2_b32 v31, v62, v63 offset1:66
	s_waitcnt vmcnt(28)
	ds_write2_b32 v31, v64, v65 offset0:132 offset1:198
	s_waitcnt vmcnt(26)
	ds_write2_b32 v37, v66, v67 offset0:8 offset1:74
	s_waitcnt vmcnt(24)
	ds_write2_b32 v37, v68, v69 offset0:140 offset1:206
	s_waitcnt vmcnt(22)
	ds_write2_b32 v38, v70, v71 offset0:16 offset1:82
	s_waitcnt vmcnt(20)
	ds_write2_b32 v38, v72, v73 offset0:148 offset1:214
	s_waitcnt vmcnt(18)
	ds_write2_b32 v39, v74, v75 offset0:24 offset1:90
	s_waitcnt vmcnt(16)
	ds_write2_b32 v39, v76, v77 offset0:156 offset1:222
	s_waitcnt vmcnt(14)
	ds_write2_b32 v40, v78, v79 offset0:32 offset1:98
	s_waitcnt vmcnt(12)
	ds_write2_b32 v40, v80, v81 offset0:164 offset1:230
	s_waitcnt vmcnt(10)
	ds_write2_b32 v41, v82, v83 offset0:40 offset1:106
	s_waitcnt vmcnt(8)
	ds_write2_b32 v41, v84, v60 offset0:172 offset1:238
	s_waitcnt vmcnt(6)
	ds_write2_b32 v42, v46, v47 offset0:48 offset1:114
	s_waitcnt vmcnt(4)
	ds_write2_b32 v42, v48, v49 offset0:180 offset1:246
	s_waitcnt vmcnt(2)
	ds_write2_b32 v43, v50, v51 offset0:56 offset1:122
	s_waitcnt vmcnt(0)
	ds_write2_b32 v43, v52, v44 offset0:188 offset1:254
	s_waitcnt lgkmcnt(0)
	s_bfe_u32 s8, s8, 0x70018
	ds_read2_b32 v[44:45], v33 offset1:33
	ds_read2_b32 v[46:47], v33 offset0:66 offset1:99
	s_add_i32 s8, s11, s8
	ds_read2_b32 v[50:51], v33 offset0:132 offset1:165
	ds_read2_b32 v[52:53], v33 offset0:198 offset1:231
	s_sext_i32_i16 s13, s8
	s_and_b32 s8, s8, 0xff80
	s_sub_i32 s8, s11, s8
	s_lshl_b32 s13, s13, 1
	s_sext_i32_i16 s8, s8
	s_and_b32 s13, s13, 0xffffff00
	s_add_i32 s8, s12, s8
	s_waitcnt lgkmcnt(3)
	v_pk_mul_f32 v[44:45], v[4:5], v[44:45]
	s_waitcnt lgkmcnt(2)
	v_pk_mul_f32 v[46:47], v[6:7], v[46:47]
	s_add_i32 s11, s8, s13
	v_cvt_pk_bf16_f32 v44, v44, v45
	v_cvt_pk_bf16_f32 v45, v46, v47
	s_waitcnt lgkmcnt(1)
	v_pk_mul_f32 v[46:47], v[0:1], v[50:51]
	s_waitcnt lgkmcnt(0)
	v_pk_mul_f32 v[50:51], v[2:3], v[52:53]
	v_cvt_pk_bf16_f32 v46, v46, v47
	v_cvt_pk_bf16_f32 v47, v50, v51
	v_add_u32_e32 v50, s11, v32
	s_lshl_b32 s8, s10, 1
	v_ashrrev_i32_e32 v51, 31, v50
	v_lshl_add_u64 v[48:49], v[26:27], 0, s[8:9]
	v_lshlrev_b64 v[50:51], 11, v[50:51]
	v_lshl_add_u64 v[50:51], v[48:49], 0, v[50:51]
	global_store_dwordx4 v[50:51], v[44:47], off sc1 nt
	s_nop 1
	ds_read2_b32 v[44:45], v33 offset0:8 offset1:41
	ds_read2_b32 v[46:47], v33 offset0:74 offset1:107
	ds_read2_b32 v[50:51], v33 offset0:140 offset1:173
	ds_read2_b32 v[52:53], v33 offset0:206 offset1:239
	v_readlane_b32 s85, v249, 8
	s_waitcnt lgkmcnt(3)
	v_pk_mul_f32 v[44:45], v[4:5], v[44:45]
	s_waitcnt lgkmcnt(2)
	v_pk_mul_f32 v[46:47], v[6:7], v[46:47]
	v_cvt_pk_bf16_f32 v44, v44, v45
	v_cvt_pk_bf16_f32 v45, v46, v47
	s_waitcnt lgkmcnt(1)
	v_pk_mul_f32 v[46:47], v[0:1], v[50:51]
	s_waitcnt lgkmcnt(0)
	v_pk_mul_f32 v[50:51], v[2:3], v[52:53]
	v_cvt_pk_bf16_f32 v46, v46, v47
	v_cvt_pk_bf16_f32 v47, v50, v51
	v_add_u32_e32 v50, s11, v34
	v_ashrrev_i32_e32 v51, 31, v50
	v_lshlrev_b64 v[50:51], 11, v[50:51]
	v_lshl_add_u64 v[50:51], v[48:49], 0, v[50:51]
	global_store_dwordx4 v[50:51], v[44:47], off sc1 nt
	s_nop 1
	ds_read2_b32 v[44:45], v33 offset0:16 offset1:49
	ds_read2_b32 v[46:47], v33 offset0:82 offset1:115
	ds_read2_b32 v[50:51], v33 offset0:148 offset1:181
	ds_read2_b32 v[52:53], v33 offset0:214 offset1:247
	v_readlane_b32 s86, v249, 9
	s_waitcnt lgkmcnt(3)
	v_pk_mul_f32 v[44:45], v[4:5], v[44:45]
	s_waitcnt lgkmcnt(2)
	v_pk_mul_f32 v[46:47], v[6:7], v[46:47]
	v_cvt_pk_bf16_f32 v44, v44, v45
	v_cvt_pk_bf16_f32 v45, v46, v47
	s_waitcnt lgkmcnt(1)
	v_pk_mul_f32 v[46:47], v[0:1], v[50:51]
	s_waitcnt lgkmcnt(0)
	v_pk_mul_f32 v[50:51], v[2:3], v[52:53]
	v_cvt_pk_bf16_f32 v46, v46, v47
	v_cvt_pk_bf16_f32 v47, v50, v51
	v_add_u32_e32 v50, s11, v35
	v_ashrrev_i32_e32 v51, 31, v50
	v_lshlrev_b64 v[50:51], 11, v[50:51]
	v_lshl_add_u64 v[50:51], v[48:49], 0, v[50:51]
	global_store_dwordx4 v[50:51], v[44:47], off sc1 nt
	s_nop 1
	ds_read2_b32 v[44:45], v33 offset0:24 offset1:57
	ds_read2_b32 v[46:47], v33 offset0:90 offset1:123
	ds_read2_b32 v[50:51], v33 offset0:222 offset1:255
	v_readlane_b32 s87, v249, 10
	v_readlane_b32 s90, v249, 13
	s_waitcnt lgkmcnt(2)
	v_pk_mul_f32 v[4:5], v[4:5], v[44:45]
	ds_read2_b32 v[44:45], v33 offset0:156 offset1:189
	s_waitcnt lgkmcnt(2)
	v_pk_mul_f32 v[6:7], v[6:7], v[46:47]
	v_cvt_pk_bf16_f32 v4, v4, v5
	v_cvt_pk_bf16_f32 v5, v6, v7
	v_readlane_b32 s91, v249, 14
	s_waitcnt lgkmcnt(0)
	v_pk_mul_f32 v[0:1], v[0:1], v[44:45]
	v_readlane_b32 s92, v249, 15
	v_cvt_pk_bf16_f32 v6, v0, v1
	v_pk_mul_f32 v[0:1], v[2:3], v[50:51]
	v_readlane_b32 s93, v249, 16
	v_cvt_pk_bf16_f32 v7, v0, v1
	v_add_u32_e32 v0, s11, v36
	v_ashrrev_i32_e32 v1, 31, v0
	v_lshlrev_b64 v[0:1], 11, v[0:1]
	v_lshl_add_u64 v[0:1], v[48:49], 0, v[0:1]
	global_store_dwordx4 v[0:1], v[4:7], off sc1 nt
	s_nop 1
	v_readlane_b32 s94, v249, 17
	v_readlane_b32 s95, v249, 18
	s_waitcnt lgkmcnt(0)
	v_readlane_b32 s80, v249, 36
	v_readlane_b32 s84, v249, 40
	v_readlane_b32 s85, v249, 41
	v_readlane_b32 s90, v249, 46
	v_readlane_b32 s91, v249, 47
	v_readlane_b32 s94, v249, 50
	v_readlane_b32 s95, v249, 51
	v_readlane_b32 s81, v249, 37
	v_readlane_b32 s82, v249, 38
	v_readlane_b32 s83, v249, 39
	v_readlane_b32 s86, v249, 42
	v_readlane_b32 s87, v249, 43
	v_readlane_b32 s88, v249, 44
	v_readlane_b32 s89, v249, 45
	v_readlane_b32 s92, v249, 48
	v_readlane_b32 s93, v249, 49

; __device__ __forceinline__ void transpose_item(const float* W, int K, int N, bf16_t* WT, int kb, int nb, int drow0, const float* kscale, LAS float* scr, int lane) {
;     const int k0 = 64 * kb, n0 = 32 * nb, c = lane & 7;
;     f32x4 s0 = {1.f, 1.f, 1.f, 1.f}, s1 = {1.f, 1.f, 1.f, 1.f};
;     if (kscale) { s0 = *(const f32x4*)(kscale + k0 + 8 * c); s1 = *(const f32x4*)(kscale + k0 + 8 * c + 4); }
;     const float* src = W + (size_t)(k0 + (lane >> 5)) * N + n0 + (lane & 31);
;     float w[32];
; #pragma unroll
;     for (int i = 0; i < 32; ++i) w[i] = __builtin_nontemporal_load(src + (size_t)(2 * i) * N);
; __device__ __forceinline__ void prep_weights(Frame& F, const Args& a, int l, int it_lo, int it_hi, int gw, int ngw) {
;     ...
;         if (r < I5) { const int kb = r / 32, nb = r % 32; transpose_item(w_mx, DM, DM, W + WO_MIX, kb, nb, 32 * nb, nullptr, scr, F.lane); continue; } r -= I5;
.LBB0_74:
	s_andn2_b64 vcc, exec, s[10:11]
	s_cbranch_vccnz .LBB0_76
	s_and_b32 s8, s20, 0x3fc0
	s_addk_i32 s8, 0xe200
	v_or_b32_e32 v0, s8, v30
	v_mov_b32_e32 v1, v9
	v_readlane_b32 s80, v249, 3
	s_and_b32 s10, s14, 0x3e0
	v_lshlrev_b64 v[0:1], 12, v[0:1]
	v_readlane_b32 s84, v249, 7
	v_readlane_b32 s85, v249, 8
	s_lshl_b32 s12, s10, 2
	s_mov_b32 s13, s9
	v_lshl_add_u64 v[0:1], s[84:85], 0, v[0:1]
	v_lshl_add_u64 v[0:1], v[0:1], 0, s[12:13]
	v_lshl_add_u64 v[0:1], v[0:1], 0, v[8:9]
	v_add_co_u32_e32 v2, vcc, s24, v0
	v_readlane_b32 s81, v249, 4
	s_nop 0
	v_addc_co_u32_e32 v3, vcc, 0, v1, vcc
	v_add_co_u32_e32 v4, vcc, s25, v0
	v_readlane_b32 s82, v249, 5
	s_nop 0
	v_addc_co_u32_e32 v5, vcc, 0, v1, vcc
	v_add_co_u32_e32 v6, vcc, s26, v0
	v_readlane_b32 s83, v249, 6
	s_nop 0
	v_addc_co_u32_e32 v7, vcc, 0, v1, vcc
	v_add_co_u32_e32 v44, vcc, s27, v0
	v_readlane_b32 s86, v249, 9
	s_nop 0
	v_addc_co_u32_e32 v45, vcc, 0, v1, vcc
	v_add_co_u32_e32 v46, vcc, s28, v0
	v_readlane_b32 s87, v249, 10
	s_nop 0
	v_addc_co_u32_e32 v47, vcc, 0, v1, vcc
	v_add_co_u32_e32 v48, vcc, s29, v0
	v_readlane_b32 s88, v249, 11
	s_nop 0
	v_addc_co_u32_e32 v49, vcc, 0, v1, vcc
	v_add_co_u32_e32 v50, vcc, s30, v0
	v_readlane_b32 s89, v249, 12
	s_nop 0
	v_addc_co_u32_e32 v51, vcc, 0, v1, vcc
	global_load_dword v54, v[0:1], off nt
	global_load_dword v55, v[2:3], off nt
	global_load_dword v56, v[4:5], off nt
	global_load_dword v57, v[6:7], off nt
	global_load_dword v58, v[44:45], off nt
	global_load_dword v59, v[46:47], off nt
	global_load_dword v60, v[48:49], off nt
	global_load_dword v61, v[50:51], off nt
	v_add_co_u32_e32 v2, vcc, s31, v0
	v_readlane_b32 s90, v249, 13
	s_nop 0
	v_addc_co_u32_e32 v3, vcc, 0, v1, vcc
	v_add_co_u32_e32 v4, vcc, s33, v0
	v_readlane_b32 s91, v249, 14
	s_nop 0
	v_addc_co_u32_e32 v5, vcc, 0, v1, vcc
	v_add_co_u32_e32 v6, vcc, s34, v0
	v_readlane_b32 s92, v249, 15
	s_nop 0
	v_addc_co_u32_e32 v7, vcc, 0, v1, vcc
	v_add_co_u32_e32 v44, vcc, s35, v0
	v_readlane_b32 s93, v249, 16
	s_nop 0
	v_addc_co_u32_e32 v45, vcc, 0, v1, vcc
	v_add_co_u32_e32 v46, vcc, s36, v0
	v_readlane_b32 s94, v249, 17
	s_nop 0
	v_addc_co_u32_e32 v47, vcc, 0, v1, vcc
	v_add_co_u32_e32 v48, vcc, s37, v0
	v_readlane_b32 s95, v249, 18
	s_nop 0
	v_addc_co_u32_e32 v49, vcc, 0, v1, vcc
	v_add_co_u32_e32 v50, vcc, s38, v0
	v_readlane_b32 s80, v249, 36
	s_nop 0
	v_addc_co_u32_e32 v51, vcc, 0, v1, vcc
	v_add_co_u32_e32 v52, vcc, s39, v0
	v_readlane_b32 s84, v249, 40
	s_nop 0
	v_addc_co_u32_e32 v53, vcc, 0, v1, vcc
	global_load_dword v62, v[2:3], off nt
	global_load_dword v63, v[4:5], off nt
	global_load_dword v64, v[6:7], off nt
	global_load_dword v65, v[44:45], off nt
	global_load_dword v66, v[46:47], off nt
	global_load_dword v67, v[48:49], off nt
	global_load_dword v68, v[50:51], off nt
	global_load_dword v69, v[52:53], off nt
	v_add_co_u32_e32 v2, vcc, s40, v0
	v_readlane_b32 s85, v249, 41
	s_nop 0
	v_addc_co_u32_e32 v3, vcc, 0, v1, vcc
	v_add_co_u32_e32 v4, vcc, s41, v0
	v_readlane_b32 s90, v249, 46
	s_nop 0
	v_addc_co_u32_e32 v5, vcc, 0, v1, vcc
	v_add_co_u32_e32 v6, vcc, s42, v0
	v_readlane_b32 s91, v249, 47
	s_nop 0
	v_addc_co_u32_e32 v7, vcc, 0, v1, vcc
	v_add_co_u32_e32 v44, vcc, s43, v0
	v_readlane_b32 s94, v249, 50
	s_nop 0
	v_addc_co_u32_e32 v45, vcc, 0, v1, vcc
	v_add_co_u32_e32 v46, vcc, s44, v0
	v_readlane_b32 s95, v249, 51
	s_nop 0
	v_addc_co_u32_e32 v47, vcc, 0, v1, vcc
	v_add_co_u32_e32 v48, vcc, s45, v0
	v_readlane_b32 s81, v249, 37
	s_nop 0
	v_addc_co_u32_e32 v49, vcc, 0, v1, vcc
	v_add_co_u32_e32 v50, vcc, s46, v0
	v_readlane_b32 s82, v249, 38
	s_nop 0
	v_addc_co_u32_e32 v51, vcc, 0, v1, vcc
	v_add_co_u32_e32 v52, vcc, s47, v0
	v_readlane_b32 s83, v249, 39
	s_nop 0
	v_addc_co_u32_e32 v53, vcc, 0, v1, vcc
	global_load_dword v70, v[2:3], off nt
	global_load_dword v71, v[4:5], off nt
	global_load_dword v72, v[6:7], off nt
	global_load_dword v73, v[44:45], off nt
	global_load_dword v74, v[46:47], off nt
	global_load_dword v75, v[48:49], off nt
	global_load_dword v76, v[50:51], off nt
	s_nop 0
	global_load_dword v52, v[52:53], off nt
	v_add_co_u32_e32 v2, vcc, s48, v0
	v_readlane_b32 s86, v249, 42
	s_nop 0
	v_addc_co_u32_e32 v3, vcc, 0, v1, vcc
	v_add_co_u32_e32 v4, vcc, s49, v0
	v_readlane_b32 s87, v249, 43
	s_nop 0
	v_addc_co_u32_e32 v5, vcc, 0, v1, vcc
	v_add_co_u32_e32 v6, vcc, s52, v0
	v_readlane_b32 s88, v249, 44
	s_nop 0
	v_addc_co_u32_e32 v7, vcc, 0, v1, vcc
	v_add_co_u32_e32 v44, vcc, s53, v0
	v_readlane_b32 s89, v249, 45
	s_nop 0
	v_addc_co_u32_e32 v45, vcc, 0, v1, vcc
	v_add_co_u32_e32 v46, vcc, s54, v0
	v_readlane_b32 s92, v249, 48
	s_nop 0
	v_addc_co_u32_e32 v47, vcc, 0, v1, vcc
	v_add_co_u32_e32 v48, vcc, s55, v0
	v_readlane_b32 s93, v249, 49
	s_nop 0
	v_addc_co_u32_e32 v49, vcc, 0, v1, vcc
	v_add_co_u32_e32 v50, vcc, s56, v0
	s_nop 1
	v_addc_co_u32_e32 v51, vcc, 0, v1, vcc
	v_add_co_u32_e32 v0, vcc, s57, v0
	s_nop 1
	v_addc_co_u32_e32 v1, vcc, 0, v1, vcc
	global_load_dword v2, v[2:3], off nt
	s_nop 0
	global_load_dword v3, v[4:5], off nt
	s_nop 0
	global_load_dword v4, v[6:7], off nt
	global_load_dword v5, v[44:45], off nt
	s_nop 0
	global_load_dword v6, v[46:47], off nt
	global_load_dword v7, v[48:49], off nt
	global_load_dword v44, v[50:51], off nt
	s_nop 0
	global_load_dword v0, v[0:1], off nt
	s_waitcnt vmcnt(30)
; #define LAS __attribute__((address_space(3)))
; __device__ __forceinline__ unsigned pk2(float lo, float hi) { const f32x2 v = {lo, hi}; const bf16x2_hw b = __builtin_convertvector(v, bf16x2_hw); return __builtin_bit_cast(unsigned, b); }
; __device__ __forceinline__ void gst_wt16(void* p, const u32x4 v) { asm volatile("global_store_dwordx4 %0, %1, off sc1\n\ts_nop 1" :: "v"(p), "v"(v) : "memory"); }
; __device__ __forceinline__ void transpose_item(const float* W, int K, int N, bf16_t* WT, int kb, int nb, int drow0, const float* kscale, LAS float* scr, int lane) {
;     ...
;     for (int i = 0; i < 32; ++i) scr[(2 * i + (lane >> 5)) * 33 + (lane & 31)] = w[i];
;     asm volatile("s_waitcnt lgkmcnt(0)" ::: "memory");
; #pragma unroll
;     for (int j = 0; j < 4; ++j) { const int n = (lane >> 3) + 8 * j; const LAS float* s = scr + (8 * c) * 33 + n;
;         u32x4 o; o.x = pk2(s[0 * 33] * s0[0], s[1 * 33] * s0[1]); o.y = pk2(s[2 * 33] * s0[2], s[3 * 33] * s0[3]); o.z = pk2(s[4 * 33] * s1[0], s[5 * 33] * s1[1]); o.w = pk2(s[6 * 33] * s1[2], s[7 * 33] * s1[3]);
;         gst_wt16(WT + (size_t)(drow0 + n) * K + k0 + 8 * c, o); }
;     asm volatile("s_waitcnt lgkmcnt(0)" ::: "memory");
	ds_write2_b32 v31, v54, v55 offset1:66
	s_waitcnt vmcnt(28)
	ds_write2_b32 v31, v56, v57 offset0:132 offset1:198
	s_waitcnt vmcnt(26)
	ds_write2_b32 v37, v58, v59 offset0:8 offset1:74
	s_waitcnt vmcnt(24)
	ds_write2_b32 v37, v60, v61 offset0:140 offset1:206
	s_waitcnt vmcnt(22)
	ds_write2_b32 v38, v62, v63 offset0:16 offset1:82
	s_waitcnt vmcnt(20)
	ds_write2_b32 v38, v64, v65 offset0:148 offset1:214
	s_waitcnt vmcnt(18)
	ds_write2_b32 v39, v66, v67 offset0:24 offset1:90
	s_waitcnt vmcnt(16)
	ds_write2_b32 v39, v68, v69 offset0:156 offset1:222
	s_waitcnt vmcnt(14)
	ds_write2_b32 v40, v70, v71 offset0:32 offset1:98
	s_waitcnt vmcnt(12)
	ds_write2_b32 v40, v72, v73 offset0:164 offset1:230
	s_waitcnt vmcnt(10)
	ds_write2_b32 v41, v74, v75 offset0:40 offset1:106
	s_waitcnt vmcnt(8)
	ds_write2_b32 v41, v76, v52 offset0:172 offset1:238
	s_waitcnt vmcnt(6)
	ds_write2_b32 v42, v2, v3 offset0:48 offset1:114
	s_waitcnt vmcnt(4)
	ds_write2_b32 v42, v4, v5 offset0:180 offset1:246
	s_waitcnt vmcnt(2)
	ds_write2_b32 v43, v6, v7 offset0:56 offset1:122
	s_waitcnt vmcnt(0)
	ds_write2_b32 v43, v44, v0 offset0:188 offset1:254
	s_waitcnt lgkmcnt(0)
	ds_read2_b32 v[0:1], v33 offset1:33
	ds_read2_b32 v[2:3], v33 offset0:66 offset1:99
	ds_read2_b32 v[4:5], v33 offset0:132 offset1:165
	ds_read2_b32 v[6:7], v33 offset0:198 offset1:231
	v_lshl_add_u64 v[44:45], s[8:9], 1, v[14:15]
	s_waitcnt lgkmcnt(3)
	v_cvt_pk_bf16_f32 v0, v0, v1
	s_waitcnt lgkmcnt(2)
	v_cvt_pk_bf16_f32 v1, v2, v3
	s_waitcnt lgkmcnt(1)
	v_cvt_pk_bf16_f32 v2, v4, v5
	v_or_b32_e32 v4, s10, v32
	v_lshlrev_b32_e32 v4, 11, v4
	v_mov_b32_e32 v5, v9
	s_waitcnt lgkmcnt(0)
	v_cvt_pk_bf16_f32 v3, v6, v7
	v_lshl_add_u64 v[4:5], v[44:45], 0, v[4:5]
	global_store_dwordx4 v[4:5], v[0:3], off sc1 nt
	s_nop 1
	ds_read2_b32 v[0:1], v33 offset0:8 offset1:41
	ds_read2_b32 v[2:3], v33 offset0:74 offset1:107
	ds_read2_b32 v[4:5], v33 offset0:140 offset1:173
	ds_read2_b32 v[6:7], v33 offset0:206 offset1:239
	s_waitcnt lgkmcnt(3)
	v_cvt_pk_bf16_f32 v0, v0, v1
	s_waitcnt lgkmcnt(2)
	v_cvt_pk_bf16_f32 v1, v2, v3
	s_waitcnt lgkmcnt(1)
	v_cvt_pk_bf16_f32 v2, v4, v5
	v_or_b32_e32 v4, s10, v34
	v_lshlrev_b32_e32 v4, 11, v4
	v_mov_b32_e32 v5, v9
	s_waitcnt lgkmcnt(0)
	v_cvt_pk_bf16_f32 v3, v6, v7
	v_lshl_add_u64 v[4:5], v[44:45], 0, v[4:5]
	global_store_dwordx4 v[4:5], v[0:3], off sc1 nt
	s_nop 1
	ds_read2_b32 v[0:1], v33 offset0:16 offset1:49
	ds_read2_b32 v[2:3], v33 offset0:82 offset1:115
	ds_read2_b32 v[4:5], v33 offset0:148 offset1:181
	ds_read2_b32 v[6:7], v33 offset0:214 offset1:247
	s_waitcnt lgkmcnt(3)
	v_cvt_pk_bf16_f32 v0, v0, v1
	s_waitcnt lgkmcnt(2)
	v_cvt_pk_bf16_f32 v1, v2, v3
	s_waitcnt lgkmcnt(1)
	v_cvt_pk_bf16_f32 v2, v4, v5
	v_or_b32_e32 v4, s10, v35
	v_lshlrev_b32_e32 v4, 11, v4
	v_mov_b32_e32 v5, v9
	s_waitcnt lgkmcnt(0)
	v_cvt_pk_bf16_f32 v3, v6, v7
	v_lshl_add_u64 v[4:5], v[44:45], 0, v[4:5]
	global_store_dwordx4 v[4:5], v[0:3], off sc1 nt
	s_nop 1
	ds_read2_b32 v[0:1], v33 offset0:24 offset1:57
	ds_read2_b32 v[2:3], v33 offset0:90 offset1:123
	ds_read2_b32 v[4:5], v33 offset0:156 offset1:189
	ds_read2_b32 v[6:7], v33 offset0:222 offset1:255
	s_waitcnt lgkmcnt(3)
	v_cvt_pk_bf16_f32 v0, v0, v1
	s_waitcnt lgkmcnt(2)
	v_cvt_pk_bf16_f32 v1, v2, v3
	s_waitcnt lgkmcnt(1)
	v_cvt_pk_bf16_f32 v2, v4, v5
	v_or_b32_e32 v4, s10, v36
	v_lshlrev_b32_e32 v4, 11, v4
	v_mov_b32_e32 v5, v9
	s_waitcnt lgkmcnt(0)
	v_cvt_pk_bf16_f32 v3, v6, v7
	v_lshl_add_u64 v[4:5], v[44:45], 0, v[4:5]
	global_store_dwordx4 v[4:5], v[0:3], off sc1 nt
	s_nop 1
	s_waitcnt lgkmcnt(0)

; __device__ __forceinline__ void transpose_item(const float* W, int K, int N, bf16_t* WT, int kb, int nb, int drow0, const float* kscale, LAS float* scr, int lane) {
;     const int k0 = 64 * kb, n0 = 32 * nb, c = lane & 7;
;     f32x4 s0 = {1.f, 1.f, 1.f, 1.f}, s1 = {1.f, 1.f, 1.f, 1.f};
;     if (kscale) { s0 = *(const f32x4*)(kscale + k0 + 8 * c); s1 = *(const f32x4*)(kscale + k0 + 8 * c + 4); }
;     const float* src = W + (size_t)(k0 + (lane >> 5)) * N + n0 + (lane & 31);
;     float w[32];
; #pragma unroll
;     for (int i = 0; i < 32; ++i) w[i] = __builtin_nontemporal_load(src + (size_t)(2 * i) * N);
; __device__ __forceinline__ void prep_weights(Frame& F, const Args& a, int l, int it_lo, int it_hi, int gw, int ngw) {
;     ...
;         if (r < I4) { const int kb = r / 32, nb = r % 32; transpose_item(w_so, 512, DM, W + WO_SO, kb, nb, 32 * nb, nullptr, scr, F.lane); continue; } r -= I4;
.LBB0_77:
	s_andn2_b64 vcc, exec, s[10:11]
	s_cbranch_vccnz .LBB0_79
	s_and_b32 s8, s20, 0x1fc0
	s_addk_i32 s8, 0xe400
	v_or_b32_e32 v0, s8, v30
	v_mov_b32_e32 v1, v9
	v_readlane_b32 s80, v249, 3
	s_and_b32 s10, s14, 0x3e0
	v_lshlrev_b64 v[0:1], 12, v[0:1]
	v_readlane_b32 s82, v249, 5
	v_readlane_b32 s83, v249, 6
	s_lshl_b32 s12, s10, 2
	s_mov_b32 s13, s9
	v_lshl_add_u64 v[0:1], s[82:83], 0, v[0:1]
	v_lshl_add_u64 v[0:1], v[0:1], 0, s[12:13]
	v_lshl_add_u64 v[0:1], v[0:1], 0, v[8:9]
	v_add_co_u32_e32 v2, vcc, s24, v0
	v_readlane_b32 s81, v249, 4
	s_nop 0
	v_addc_co_u32_e32 v3, vcc, 0, v1, vcc
	v_add_co_u32_e32 v4, vcc, s25, v0
	v_readlane_b32 s84, v249, 7
	s_nop 0
	v_addc_co_u32_e32 v5, vcc, 0, v1, vcc
	v_add_co_u32_e32 v6, vcc, s26, v0
	v_readlane_b32 s85, v249, 8
	s_nop 0
	v_addc_co_u32_e32 v7, vcc, 0, v1, vcc
	v_add_co_u32_e32 v44, vcc, s27, v0
	v_readlane_b32 s86, v249, 9
	s_nop 0
	v_addc_co_u32_e32 v45, vcc, 0, v1, vcc
	v_add_co_u32_e32 v46, vcc, s28, v0
	v_readlane_b32 s87, v249, 10
	s_nop 0
	v_addc_co_u32_e32 v47, vcc, 0, v1, vcc
	v_add_co_u32_e32 v48, vcc, s29, v0
	v_readlane_b32 s88, v249, 11
	s_nop 0
	v_addc_co_u32_e32 v49, vcc, 0, v1, vcc
	v_add_co_u32_e32 v50, vcc, s30, v0
	v_readlane_b32 s89, v249, 12
	s_nop 0
	v_addc_co_u32_e32 v51, vcc, 0, v1, vcc
	global_load_dword v54, v[0:1], off nt
	global_load_dword v55, v[2:3], off nt
	global_load_dword v56, v[4:5], off nt
	global_load_dword v57, v[6:7], off nt
	global_load_dword v58, v[44:45], off nt
	global_load_dword v59, v[46:47], off nt
	global_load_dword v60, v[48:49], off nt
	global_load_dword v61, v[50:51], off nt
	v_add_co_u32_e32 v2, vcc, s31, v0
	v_readlane_b32 s90, v249, 13
	s_nop 0
	v_addc_co_u32_e32 v3, vcc, 0, v1, vcc
	v_add_co_u32_e32 v4, vcc, s33, v0
	v_readlane_b32 s91, v249, 14
	s_nop 0
	v_addc_co_u32_e32 v5, vcc, 0, v1, vcc
	v_add_co_u32_e32 v6, vcc, s34, v0
	v_readlane_b32 s92, v249, 15
	s_nop 0
	v_addc_co_u32_e32 v7, vcc, 0, v1, vcc
	v_add_co_u32_e32 v44, vcc, s35, v0
	v_readlane_b32 s93, v249, 16
	s_nop 0
	v_addc_co_u32_e32 v45, vcc, 0, v1, vcc
	v_add_co_u32_e32 v46, vcc, s36, v0
	v_readlane_b32 s94, v249, 17
	s_nop 0
	v_addc_co_u32_e32 v47, vcc, 0, v1, vcc
	v_add_co_u32_e32 v48, vcc, s37, v0
	v_readlane_b32 s95, v249, 18
	s_nop 0
	v_addc_co_u32_e32 v49, vcc, 0, v1, vcc
	v_add_co_u32_e32 v50, vcc, s38, v0
	v_readlane_b32 s80, v249, 36
	s_nop 0
	v_addc_co_u32_e32 v51, vcc, 0, v1, vcc
	v_add_co_u32_e32 v52, vcc, s39, v0
	v_readlane_b32 s84, v249, 40
	s_nop 0
	v_addc_co_u32_e32 v53, vcc, 0, v1, vcc
	global_load_dword v62, v[2:3], off nt
	global_load_dword v63, v[4:5], off nt
	global_load_dword v64, v[6:7], off nt
	global_load_dword v65, v[44:45], off nt
	global_load_dword v66, v[46:47], off nt
	global_load_dword v67, v[48:49], off nt
	global_load_dword v68, v[50:51], off nt
	global_load_dword v69, v[52:53], off nt
	v_add_co_u32_e32 v2, vcc, s40, v0
	v_readlane_b32 s85, v249, 41
	s_nop 0
	v_addc_co_u32_e32 v3, vcc, 0, v1, vcc
	v_add_co_u32_e32 v4, vcc, s41, v0
	v_readlane_b32 s90, v249, 46
	s_nop 0
	v_addc_co_u32_e32 v5, vcc, 0, v1, vcc
	v_add_co_u32_e32 v6, vcc, s42, v0
	v_readlane_b32 s91, v249, 47
	s_nop 0
	v_addc_co_u32_e32 v7, vcc, 0, v1, vcc
	v_add_co_u32_e32 v44, vcc, s43, v0
	v_readlane_b32 s94, v249, 50
	s_nop 0
	v_addc_co_u32_e32 v45, vcc, 0, v1, vcc
	v_add_co_u32_e32 v46, vcc, s44, v0
	v_readlane_b32 s95, v249, 51
	s_nop 0
	v_addc_co_u32_e32 v47, vcc, 0, v1, vcc
	v_add_co_u32_e32 v48, vcc, s45, v0
	v_readlane_b32 s81, v249, 37
	s_nop 0
	v_addc_co_u32_e32 v49, vcc, 0, v1, vcc
	v_add_co_u32_e32 v50, vcc, s46, v0
	v_readlane_b32 s82, v249, 38
	s_nop 0
	v_addc_co_u32_e32 v51, vcc, 0, v1, vcc
	v_add_co_u32_e32 v52, vcc, s47, v0
	v_readlane_b32 s83, v249, 39
	s_nop 0
	v_addc_co_u32_e32 v53, vcc, 0, v1, vcc
	global_load_dword v70, v[2:3], off nt
	global_load_dword v71, v[4:5], off nt
	global_load_dword v72, v[6:7], off nt
	global_load_dword v73, v[44:45], off nt
	global_load_dword v74, v[46:47], off nt
	global_load_dword v75, v[48:49], off nt
	global_load_dword v76, v[50:51], off nt
	s_nop 0
	global_load_dword v52, v[52:53], off nt
	v_add_co_u32_e32 v2, vcc, s48, v0
	v_readlane_b32 s86, v249, 42
	s_nop 0
	v_addc_co_u32_e32 v3, vcc, 0, v1, vcc
	v_add_co_u32_e32 v4, vcc, s49, v0
	v_readlane_b32 s87, v249, 43
	s_nop 0
	v_addc_co_u32_e32 v5, vcc, 0, v1, vcc
	v_add_co_u32_e32 v6, vcc, s52, v0
	v_readlane_b32 s88, v249, 44
	s_nop 0
	v_addc_co_u32_e32 v7, vcc, 0, v1, vcc
	v_add_co_u32_e32 v44, vcc, s53, v0
	v_readlane_b32 s89, v249, 45
	s_nop 0
	v_addc_co_u32_e32 v45, vcc, 0, v1, vcc
	v_add_co_u32_e32 v46, vcc, s54, v0
	v_readlane_b32 s92, v249, 48
	s_nop 0
	v_addc_co_u32_e32 v47, vcc, 0, v1, vcc
	v_add_co_u32_e32 v48, vcc, s55, v0
	v_readlane_b32 s93, v249, 49
	s_nop 0
	v_addc_co_u32_e32 v49, vcc, 0, v1, vcc
	v_add_co_u32_e32 v50, vcc, s56, v0
	s_nop 1
	v_addc_co_u32_e32 v51, vcc, 0, v1, vcc
	v_add_co_u32_e32 v0, vcc, s57, v0
	s_nop 1
	v_addc_co_u32_e32 v1, vcc, 0, v1, vcc
	global_load_dword v2, v[2:3], off nt
	s_nop 0
	global_load_dword v3, v[4:5], off nt
	s_nop 0
	global_load_dword v4, v[6:7], off nt
	global_load_dword v5, v[44:45], off nt
	s_nop 0
	global_load_dword v6, v[46:47], off nt
	global_load_dword v7, v[48:49], off nt
	global_load_dword v44, v[50:51], off nt
	s_nop 0
	global_load_dword v0, v[0:1], off nt
	s_waitcnt vmcnt(30)
; #define LAS __attribute__((address_space(3)))
; __device__ __forceinline__ unsigned pk2(float lo, float hi) { const f32x2 v = {lo, hi}; const bf16x2_hw b = __builtin_convertvector(v, bf16x2_hw); return __builtin_bit_cast(unsigned, b); }
; __device__ __forceinline__ void gst_wt16(void* p, const u32x4 v) { asm volatile("global_store_dwordx4 %0, %1, off sc1\n\ts_nop 1" :: "v"(p), "v"(v) : "memory"); }
; __device__ __forceinline__ void transpose_item(const float* W, int K, int N, bf16_t* WT, int kb, int nb, int drow0, const float* kscale, LAS float* scr, int lane) {
;     ...
;     for (int i = 0; i < 32; ++i) scr[(2 * i + (lane >> 5)) * 33 + (lane & 31)] = w[i];
;     asm volatile("s_waitcnt lgkmcnt(0)" ::: "memory");
; #pragma unroll
;     for (int j = 0; j < 4; ++j) { const int n = (lane >> 3) + 8 * j; const LAS float* s = scr + (8 * c) * 33 + n;
;         u32x4 o; o.x = pk2(s[0 * 33] * s0[0], s[1 * 33] * s0[1]); o.y = pk2(s[2 * 33] * s0[2], s[3 * 33] * s0[3]); o.z = pk2(s[4 * 33] * s1[0], s[5 * 33] * s1[1]); o.w = pk2(s[6 * 33] * s1[2], s[7 * 33] * s1[3]);
;         gst_wt16(WT + (size_t)(drow0 + n) * K + k0 + 8 * c, o); }
;     asm volatile("s_waitcnt lgkmcnt(0)" ::: "memory");
	ds_write2_b32 v31, v54, v55 offset1:66
	s_waitcnt vmcnt(28)
	ds_write2_b32 v31, v56, v57 offset0:132 offset1:198
	s_waitcnt vmcnt(26)
	ds_write2_b32 v37, v58, v59 offset0:8 offset1:74
	s_waitcnt vmcnt(24)
	ds_write2_b32 v37, v60, v61 offset0:140 offset1:206
	s_waitcnt vmcnt(22)
	ds_write2_b32 v38, v62, v63 offset0:16 offset1:82
	s_waitcnt vmcnt(20)
	ds_write2_b32 v38, v64, v65 offset0:148 offset1:214
	s_waitcnt vmcnt(18)
	ds_write2_b32 v39, v66, v67 offset0:24 offset1:90
	s_waitcnt vmcnt(16)
	ds_write2_b32 v39, v68, v69 offset0:156 offset1:222
	s_waitcnt vmcnt(14)
	ds_write2_b32 v40, v70, v71 offset0:32 offset1:98
	s_waitcnt vmcnt(12)
	ds_write2_b32 v40, v72, v73 offset0:164 offset1:230
	s_waitcnt vmcnt(10)
	ds_write2_b32 v41, v74, v75 offset0:40 offset1:106
	s_waitcnt vmcnt(8)
	ds_write2_b32 v41, v76, v52 offset0:172 offset1:238
	s_waitcnt vmcnt(6)
	ds_write2_b32 v42, v2, v3 offset0:48 offset1:114
	s_waitcnt vmcnt(4)
	ds_write2_b32 v42, v4, v5 offset0:180 offset1:246
	s_waitcnt vmcnt(2)
	ds_write2_b32 v43, v6, v7 offset0:56 offset1:122
	s_waitcnt vmcnt(0)
	ds_write2_b32 v43, v44, v0 offset0:188 offset1:254
	s_waitcnt lgkmcnt(0)
	ds_read2_b32 v[0:1], v33 offset1:33
	ds_read2_b32 v[2:3], v33 offset0:66 offset1:99
	ds_read2_b32 v[4:5], v33 offset0:132 offset1:165
	ds_read2_b32 v[6:7], v33 offset0:198 offset1:231
	v_lshl_add_u64 v[44:45], s[8:9], 1, v[16:17]
	s_waitcnt lgkmcnt(3)
	v_cvt_pk_bf16_f32 v0, v0, v1
	s_waitcnt lgkmcnt(2)
	v_cvt_pk_bf16_f32 v1, v2, v3
	s_waitcnt lgkmcnt(1)
	v_cvt_pk_bf16_f32 v2, v4, v5
	v_or_b32_e32 v4, s10, v32
	v_lshlrev_b32_e32 v4, 10, v4
	v_mov_b32_e32 v5, v9
	s_waitcnt lgkmcnt(0)
	v_cvt_pk_bf16_f32 v3, v6, v7
	v_lshl_add_u64 v[4:5], v[44:45], 0, v[4:5]
	global_store_dwordx4 v[4:5], v[0:3], off sc1 nt
	s_nop 1
	ds_read2_b32 v[0:1], v33 offset0:8 offset1:41
	ds_read2_b32 v[2:3], v33 offset0:74 offset1:107
	ds_read2_b32 v[4:5], v33 offset0:140 offset1:173
	ds_read2_b32 v[6:7], v33 offset0:206 offset1:239
	s_waitcnt lgkmcnt(3)
	v_cvt_pk_bf16_f32 v0, v0, v1
	s_waitcnt lgkmcnt(2)
	v_cvt_pk_bf16_f32 v1, v2, v3
	s_waitcnt lgkmcnt(1)
	v_cvt_pk_bf16_f32 v2, v4, v5
	v_or_b32_e32 v4, s10, v34
	v_lshlrev_b32_e32 v4, 10, v4
	v_mov_b32_e32 v5, v9
	s_waitcnt lgkmcnt(0)
	v_cvt_pk_bf16_f32 v3, v6, v7
	v_lshl_add_u64 v[4:5], v[44:45], 0, v[4:5]
	global_store_dwordx4 v[4:5], v[0:3], off sc1 nt
	s_nop 1
	ds_read2_b32 v[0:1], v33 offset0:16 offset1:49
	ds_read2_b32 v[2:3], v33 offset0:82 offset1:115
	ds_read2_b32 v[4:5], v33 offset0:148 offset1:181
	ds_read2_b32 v[6:7], v33 offset0:214 offset1:247
	s_waitcnt lgkmcnt(3)
	v_cvt_pk_bf16_f32 v0, v0, v1
	s_waitcnt lgkmcnt(2)
	v_cvt_pk_bf16_f32 v1, v2, v3
	s_waitcnt lgkmcnt(1)
	v_cvt_pk_bf16_f32 v2, v4, v5
	v_or_b32_e32 v4, s10, v35
	v_lshlrev_b32_e32 v4, 10, v4
	v_mov_b32_e32 v5, v9
	s_waitcnt lgkmcnt(0)
	v_cvt_pk_bf16_f32 v3, v6, v7
	v_lshl_add_u64 v[4:5], v[44:45], 0, v[4:5]
	global_store_dwordx4 v[4:5], v[0:3], off sc1 nt
	s_nop 1
	ds_read2_b32 v[0:1], v33 offset0:24 offset1:57
	ds_read2_b32 v[2:3], v33 offset0:90 offset1:123
	ds_read2_b32 v[4:5], v33 offset0:156 offset1:189
	ds_read2_b32 v[6:7], v33 offset0:222 offset1:255
	s_waitcnt lgkmcnt(3)
	v_cvt_pk_bf16_f32 v0, v0, v1
	s_waitcnt lgkmcnt(2)
	v_cvt_pk_bf16_f32 v1, v2, v3
	s_waitcnt lgkmcnt(1)
	v_cvt_pk_bf16_f32 v2, v4, v5
	v_or_b32_e32 v4, s10, v36
	v_lshlrev_b32_e32 v4, 10, v4
	v_mov_b32_e32 v5, v9
	s_waitcnt lgkmcnt(0)
	v_cvt_pk_bf16_f32 v3, v6, v7
	v_lshl_add_u64 v[4:5], v[44:45], 0, v[4:5]
	global_store_dwordx4 v[4:5], v[0:3], off sc1 nt
	s_nop 1
	s_waitcnt lgkmcnt(0)

; __device__ __forceinline__ void transpose_item(const float* W, int K, int N, bf16_t* WT, int kb, int nb, int drow0, const float* kscale, LAS float* scr, int lane) {
;     const int k0 = 64 * kb, n0 = 32 * nb, c = lane & 7;
;     f32x4 s0 = {1.f, 1.f, 1.f, 1.f}, s1 = {1.f, 1.f, 1.f, 1.f};
;     if (kscale) { s0 = *(const f32x4*)(kscale + k0 + 8 * c); s1 = *(const f32x4*)(kscale + k0 + 8 * c + 4); }
;     const float* src = W + (size_t)(k0 + (lane >> 5)) * N + n0 + (lane & 31);
;     float w[32];
; #pragma unroll
;     for (int i = 0; i < 32; ++i) w[i] = __builtin_nontemporal_load(src + (size_t)(2 * i) * N);
; __device__ __forceinline__ void prep_weights(Frame& F, const Args& a, int l, int it_lo, int it_hi, int gw, int ngw) {
;     ...
;         if (r < I3) { const int kb = r / 16, nb = r % 16; transpose_item(w_gl, 512, 512, W + WO_GLU, kb, nb, 32 * nb, nullptr, scr, F.lane); continue; } r -= I3;
.LBB0_80:
	s_andn2_b64 vcc, exec, s[10:11]
	s_cbranch_vccnz .LBB0_82
	s_and_b32 s8, s22, 0x3fc0
	s_addk_i32 s8, 0xca00
	v_or_b32_e32 v0, s8, v30
	v_mov_b32_e32 v1, v9
	v_readlane_b32 s80, v249, 3
	s_and_b32 s10, s14, 0x1e0
	v_lshlrev_b64 v[0:1], 11, v[0:1]
	v_readlane_b32 s81, v249, 4
	s_lshl_b32 s12, s10, 2
	s_mov_b32 s13, s9
	v_lshl_add_u64 v[0:1], s[80:81], 0, v[0:1]
	v_lshl_add_u64 v[0:1], v[0:1], 0, s[12:13]
	v_lshl_add_u64 v[0:1], v[0:1], 0, v[8:9]
	v_add_co_u32_e32 v2, vcc, s24, v0
	s_mov_b32 s11, 0x1f000
	s_nop 0
	v_addc_co_u32_e32 v3, vcc, 0, v1, vcc
	v_add_co_u32_e32 v4, vcc, s25, v0
	v_readlane_b32 s82, v249, 5
	s_nop 0
	v_addc_co_u32_e32 v5, vcc, 0, v1, vcc
	v_add_co_u32_e32 v6, vcc, s26, v0
	v_readlane_b32 s83, v249, 6
	s_nop 0
	v_addc_co_u32_e32 v7, vcc, 0, v1, vcc
	global_load_dword v46, v[0:1], off nt
	global_load_dword v47, v[2:3], off offset:-4096 nt
	global_load_dword v48, v[2:3], off nt
	global_load_dword v49, v[4:5], off offset:-4096 nt
	global_load_dword v50, v[4:5], off nt
	global_load_dword v51, v[6:7], off offset:-4096 nt
	global_load_dword v52, v[6:7], off nt
	v_add_co_u32_e32 v2, vcc, s27, v0
	v_readlane_b32 s84, v249, 7
	s_nop 0
	v_addc_co_u32_e32 v3, vcc, 0, v1, vcc
	v_add_co_u32_e32 v4, vcc, s28, v0
	v_readlane_b32 s85, v249, 8
	s_nop 0
	v_addc_co_u32_e32 v5, vcc, 0, v1, vcc
	v_add_co_u32_e32 v6, vcc, s29, v0
	v_readlane_b32 s86, v249, 9
	s_nop 0
	v_addc_co_u32_e32 v7, vcc, 0, v1, vcc
	v_add_co_u32_e32 v44, vcc, s30, v0
	v_readlane_b32 s87, v249, 10
	s_nop 0
	v_addc_co_u32_e32 v45, vcc, 0, v1, vcc
	global_load_dword v53, v[2:3], off offset:-4096 nt
	global_load_dword v54, v[2:3], off nt
	global_load_dword v55, v[4:5], off offset:-4096 nt
	global_load_dword v56, v[4:5], off nt
	global_load_dword v57, v[6:7], off offset:-4096 nt
	global_load_dword v58, v[6:7], off nt
	global_load_dword v59, v[44:45], off offset:-4096 nt
	global_load_dword v60, v[44:45], off nt
	v_add_co_u32_e32 v2, vcc, s31, v0
	v_readlane_b32 s88, v249, 11
	s_nop 0
	v_addc_co_u32_e32 v3, vcc, 0, v1, vcc
	v_add_co_u32_e32 v4, vcc, s33, v0
	v_readlane_b32 s89, v249, 12
	s_nop 0
	v_addc_co_u32_e32 v5, vcc, 0, v1, vcc
	v_add_co_u32_e32 v6, vcc, s34, v0
	v_readlane_b32 s90, v249, 13
	s_nop 0
	v_addc_co_u32_e32 v7, vcc, 0, v1, vcc
	v_add_co_u32_e32 v44, vcc, s35, v0
	v_readlane_b32 s91, v249, 14
	s_nop 0
	v_addc_co_u32_e32 v45, vcc, 0, v1, vcc
	global_load_dword v61, v[2:3], off offset:-4096 nt
	global_load_dword v62, v[2:3], off nt
	global_load_dword v63, v[4:5], off offset:-4096 nt
	global_load_dword v64, v[4:5], off nt
	global_load_dword v65, v[6:7], off offset:-4096 nt
	global_load_dword v66, v[6:7], off nt
	global_load_dword v67, v[44:45], off offset:-4096 nt
	global_load_dword v68, v[44:45], off nt
	v_add_co_u32_e32 v2, vcc, s36, v0
	v_readlane_b32 s92, v249, 15
	s_nop 0
	v_addc_co_u32_e32 v3, vcc, 0, v1, vcc
	v_add_co_u32_e32 v4, vcc, s37, v0
	v_readlane_b32 s93, v249, 16
	s_nop 0
	v_addc_co_u32_e32 v5, vcc, 0, v1, vcc
	v_add_co_u32_e32 v6, vcc, s38, v0
	v_readlane_b32 s94, v249, 17
	s_nop 0
	v_addc_co_u32_e32 v7, vcc, 0, v1, vcc
	v_add_co_u32_e32 v44, vcc, s39, v0
	v_readlane_b32 s95, v249, 18
	s_nop 0
	v_addc_co_u32_e32 v45, vcc, 0, v1, vcc
	global_load_dword v69, v[2:3], off offset:-4096 nt
	s_nop 0
	global_load_dword v2, v[2:3], off nt
	s_nop 0
	global_load_dword v3, v[4:5], off offset:-4096 nt
	s_nop 0
	global_load_dword v4, v[4:5], off nt
	s_nop 0
	global_load_dword v5, v[6:7], off offset:-4096 nt
	s_nop 0
	global_load_dword v6, v[6:7], off nt
	s_nop 0
	global_load_dword v7, v[44:45], off offset:-4096 nt
	s_nop 0
	global_load_dword v44, v[44:45], off nt
	v_add_co_u32_e32 v0, vcc, s11, v0
	v_readlane_b32 s80, v249, 36
	s_nop 0
	v_addc_co_u32_e32 v1, vcc, 0, v1, vcc
	global_load_dword v0, v[0:1], off nt
	v_readlane_b32 s84, v249, 40
	v_readlane_b32 s85, v249, 41
	v_readlane_b32 s90, v249, 46
	v_readlane_b32 s91, v249, 47
	v_readlane_b32 s94, v249, 50
	v_readlane_b32 s95, v249, 51
	v_readlane_b32 s81, v249, 37
	v_readlane_b32 s82, v249, 38
	v_readlane_b32 s83, v249, 39
	v_readlane_b32 s86, v249, 42
	v_readlane_b32 s87, v249, 43
	v_readlane_b32 s88, v249, 44
	v_readlane_b32 s89, v249, 45
	v_readlane_b32 s92, v249, 48
	v_readlane_b32 s93, v249, 49
	s_waitcnt vmcnt(30)
; #define LAS __attribute__((address_space(3)))
; __device__ __forceinline__ unsigned pk2(float lo, float hi) { const f32x2 v = {lo, hi}; const bf16x2_hw b = __builtin_convertvector(v, bf16x2_hw); return __builtin_bit_cast(unsigned, b); }
; __device__ __forceinline__ void gst_wt16(void* p, const u32x4 v) { asm volatile("global_store_dwordx4 %0, %1, off sc1\n\ts_nop 1" :: "v"(p), "v"(v) : "memory"); }
; __device__ __forceinline__ void transpose_item(const float* W, int K, int N, bf16_t* WT, int kb, int nb, int drow0, const float* kscale, LAS float* scr, int lane) {
;     ...
;     for (int i = 0; i < 32; ++i) scr[(2 * i + (lane >> 5)) * 33 + (lane & 31)] = w[i];
;     asm volatile("s_waitcnt lgkmcnt(0)" ::: "memory");
; #pragma unroll
;     for (int j = 0; j < 4; ++j) { const int n = (lane >> 3) + 8 * j; const LAS float* s = scr + (8 * c) * 33 + n;
;         u32x4 o; o.x = pk2(s[0 * 33] * s0[0], s[1 * 33] * s0[1]); o.y = pk2(s[2 * 33] * s0[2], s[3 * 33] * s0[3]); o.z = pk2(s[4 * 33] * s1[0], s[5 * 33] * s1[1]); o.w = pk2(s[6 * 33] * s1[2], s[7 * 33] * s1[3]);
;         gst_wt16(WT + (size_t)(drow0 + n) * K + k0 + 8 * c, o); }
;     asm volatile("s_waitcnt lgkmcnt(0)" ::: "memory");
	ds_write2_b32 v31, v46, v47 offset1:66
	s_waitcnt vmcnt(28)
	ds_write2_b32 v31, v48, v49 offset0:132 offset1:198
	s_waitcnt vmcnt(26)
	ds_write2_b32 v37, v50, v51 offset0:8 offset1:74
	s_waitcnt vmcnt(24)
	ds_write2_b32 v37, v52, v53 offset0:140 offset1:206
	s_waitcnt vmcnt(22)
	ds_write2_b32 v38, v54, v55 offset0:16 offset1:82
	s_waitcnt vmcnt(20)
	ds_write2_b32 v38, v56, v57 offset0:148 offset1:214
	s_waitcnt vmcnt(18)
	ds_write2_b32 v39, v58, v59 offset0:24 offset1:90
	s_waitcnt vmcnt(16)
	ds_write2_b32 v39, v60, v61 offset0:156 offset1:222
	s_waitcnt vmcnt(14)
	ds_write2_b32 v40, v62, v63 offset0:32 offset1:98
	s_waitcnt vmcnt(12)
	ds_write2_b32 v40, v64, v65 offset0:164 offset1:230
	s_waitcnt vmcnt(10)
	ds_write2_b32 v41, v66, v67 offset0:40 offset1:106
	s_waitcnt vmcnt(8)
	ds_write2_b32 v41, v68, v69 offset0:172 offset1:238
	s_waitcnt vmcnt(6)
	ds_write2_b32 v42, v2, v3 offset0:48 offset1:114
	s_waitcnt vmcnt(4)
	ds_write2_b32 v42, v4, v5 offset0:180 offset1:246
	s_waitcnt vmcnt(2)
	ds_write2_b32 v43, v6, v7 offset0:56 offset1:122
	s_waitcnt vmcnt(0)
	ds_write2_b32 v43, v44, v0 offset0:188 offset1:254
	s_waitcnt lgkmcnt(0)
	ds_read2_b32 v[0:1], v33 offset1:33
	ds_read2_b32 v[2:3], v33 offset0:66 offset1:99
	ds_read2_b32 v[4:5], v33 offset0:132 offset1:165
	ds_read2_b32 v[6:7], v33 offset0:198 offset1:231
	v_lshl_add_u64 v[44:45], s[8:9], 1, v[18:19]
	s_waitcnt lgkmcnt(3)
	v_cvt_pk_bf16_f32 v0, v0, v1
	s_waitcnt lgkmcnt(2)
	v_cvt_pk_bf16_f32 v1, v2, v3
	s_waitcnt lgkmcnt(1)
	v_cvt_pk_bf16_f32 v2, v4, v5
	v_or_b32_e32 v4, s10, v32
	v_lshlrev_b32_e32 v4, 10, v4
	v_mov_b32_e32 v5, v9
	s_waitcnt lgkmcnt(0)
	v_cvt_pk_bf16_f32 v3, v6, v7
	v_lshl_add_u64 v[4:5], v[44:45], 0, v[4:5]
	global_store_dwordx4 v[4:5], v[0:3], off sc1 nt
	s_nop 1
	ds_read2_b32 v[0:1], v33 offset0:8 offset1:41
	ds_read2_b32 v[2:3], v33 offset0:74 offset1:107
	ds_read2_b32 v[4:5], v33 offset0:140 offset1:173
	ds_read2_b32 v[6:7], v33 offset0:206 offset1:239
	s_waitcnt lgkmcnt(3)
	v_cvt_pk_bf16_f32 v0, v0, v1
	s_waitcnt lgkmcnt(2)
	v_cvt_pk_bf16_f32 v1, v2, v3
	s_waitcnt lgkmcnt(1)
	v_cvt_pk_bf16_f32 v2, v4, v5
	v_or_b32_e32 v4, s10, v34
	v_lshlrev_b32_e32 v4, 10, v4
	v_mov_b32_e32 v5, v9
	s_waitcnt lgkmcnt(0)
	v_cvt_pk_bf16_f32 v3, v6, v7
	v_lshl_add_u64 v[4:5], v[44:45], 0, v[4:5]
	global_store_dwordx4 v[4:5], v[0:3], off sc1 nt
	s_nop 1
	ds_read2_b32 v[0:1], v33 offset0:16 offset1:49
	ds_read2_b32 v[2:3], v33 offset0:82 offset1:115
	ds_read2_b32 v[4:5], v33 offset0:148 offset1:181
	ds_read2_b32 v[6:7], v33 offset0:214 offset1:247
	s_waitcnt lgkmcnt(3)
	v_cvt_pk_bf16_f32 v0, v0, v1
	s_waitcnt lgkmcnt(2)
	v_cvt_pk_bf16_f32 v1, v2, v3
	s_waitcnt lgkmcnt(1)
	v_cvt_pk_bf16_f32 v2, v4, v5
	v_or_b32_e32 v4, s10, v35
	v_lshlrev_b32_e32 v4, 10, v4
	v_mov_b32_e32 v5, v9
	s_waitcnt lgkmcnt(0)
	v_cvt_pk_bf16_f32 v3, v6, v7
	v_lshl_add_u64 v[4:5], v[44:45], 0, v[4:5]
	global_store_dwordx4 v[4:5], v[0:3], off sc1 nt
	s_nop 1
	ds_read2_b32 v[0:1], v33 offset0:24 offset1:57
	ds_read2_b32 v[2:3], v33 offset0:90 offset1:123
	ds_read2_b32 v[4:5], v33 offset0:156 offset1:189
	ds_read2_b32 v[6:7], v33 offset0:222 offset1:255
	s_waitcnt lgkmcnt(3)
	v_cvt_pk_bf16_f32 v0, v0, v1
	s_waitcnt lgkmcnt(2)
	v_cvt_pk_bf16_f32 v1, v2, v3
	s_waitcnt lgkmcnt(1)
	v_cvt_pk_bf16_f32 v2, v4, v5
	v_or_b32_e32 v4, s10, v36
	v_lshlrev_b32_e32 v4, 10, v4
	v_mov_b32_e32 v5, v9
	s_waitcnt lgkmcnt(0)
	v_cvt_pk_bf16_f32 v3, v6, v7
	v_lshl_add_u64 v[4:5], v[44:45], 0, v[4:5]
	global_store_dwordx4 v[4:5], v[0:3], off sc1 nt
	s_nop 1
	s_waitcnt lgkmcnt(0)

; __device__ __forceinline__ void transpose_item(const float* W, int K, int N, bf16_t* WT, int kb, int nb, int drow0, const float* kscale, LAS float* scr, int lane) {
;     const int k0 = 64 * kb, n0 = 32 * nb, c = lane & 7;
;     f32x4 s0 = {1.f, 1.f, 1.f, 1.f}, s1 = {1.f, 1.f, 1.f, 1.f};
;     if (kscale) { s0 = *(const f32x4*)(kscale + k0 + 8 * c); s1 = *(const f32x4*)(kscale + k0 + 8 * c + 4); }
;     const float* src = W + (size_t)(k0 + (lane >> 5)) * N + n0 + (lane & 31);
;     float w[32];
; #pragma unroll
;     for (int i = 0; i < 32; ++i) w[i] = __builtin_nontemporal_load(src + (size_t)(2 * i) * N);
; __device__ __forceinline__ void prep_weights(Frame& F, const Args& a, int l, int it_lo, int it_hi, int gw, int ngw) {
;     ...
;         if (r < I2) { const int kb = r / 32, nb = r % 32; transpose_item(w_co, 512, DM, W + WO_CO, kb, nb, 32 * nb, nullptr, scr, F.lane); continue; } r -= I2;
.LBB0_83:
	s_andn2_b64 vcc, exec, s[10:11]
	s_cbranch_vccnz .LBB0_85
	s_and_b32 s8, s20, 0x1fc0
	s_addk_i32 s8, 0xe700
	v_or_b32_e32 v0, s8, v30
	v_mov_b32_e32 v1, v9
	s_and_b32 s10, s14, 0x3e0
	v_lshlrev_b64 v[0:1], 12, v[0:1]
	v_lshl_add_u64 v[0:1], s[94:95], 0, v[0:1]
	s_lshl_b32 s12, s10, 2
	s_mov_b32 s13, s9
	v_lshl_add_u64 v[0:1], v[0:1], 0, s[12:13]
	v_lshl_add_u64 v[0:1], v[0:1], 0, v[8:9]
	v_add_co_u32_e32 v2, vcc, s24, v0
	s_nop 1
	v_addc_co_u32_e32 v3, vcc, 0, v1, vcc
	v_add_co_u32_e32 v4, vcc, s25, v0
	s_nop 1
	v_addc_co_u32_e32 v5, vcc, 0, v1, vcc
	v_add_co_u32_e32 v6, vcc, s26, v0
	s_nop 1
	v_addc_co_u32_e32 v7, vcc, 0, v1, vcc
	v_add_co_u32_e32 v44, vcc, s27, v0
	s_nop 1
	v_addc_co_u32_e32 v45, vcc, 0, v1, vcc
	v_add_co_u32_e32 v46, vcc, s28, v0
	s_nop 1
	v_addc_co_u32_e32 v47, vcc, 0, v1, vcc
	v_add_co_u32_e32 v48, vcc, s29, v0
	s_nop 1
	v_addc_co_u32_e32 v49, vcc, 0, v1, vcc
	v_add_co_u32_e32 v50, vcc, s30, v0
	s_nop 1
	v_addc_co_u32_e32 v51, vcc, 0, v1, vcc
	global_load_dword v54, v[0:1], off nt
	global_load_dword v55, v[2:3], off nt
	global_load_dword v56, v[4:5], off nt
	global_load_dword v57, v[6:7], off nt
	global_load_dword v58, v[44:45], off nt
	global_load_dword v59, v[46:47], off nt
	global_load_dword v60, v[48:49], off nt
	global_load_dword v61, v[50:51], off nt
	v_add_co_u32_e32 v2, vcc, s31, v0
	s_nop 1
	v_addc_co_u32_e32 v3, vcc, 0, v1, vcc
	v_add_co_u32_e32 v4, vcc, s33, v0
	s_nop 1
	v_addc_co_u32_e32 v5, vcc, 0, v1, vcc
	v_add_co_u32_e32 v6, vcc, s34, v0
	s_nop 1
	v_addc_co_u32_e32 v7, vcc, 0, v1, vcc
	v_add_co_u32_e32 v44, vcc, s35, v0
	s_nop 1
	v_addc_co_u32_e32 v45, vcc, 0, v1, vcc
	v_add_co_u32_e32 v46, vcc, s36, v0
	s_nop 1
	v_addc_co_u32_e32 v47, vcc, 0, v1, vcc
	v_add_co_u32_e32 v48, vcc, s37, v0
	s_nop 1
	v_addc_co_u32_e32 v49, vcc, 0, v1, vcc
	v_add_co_u32_e32 v50, vcc, s38, v0
	s_nop 1
	v_addc_co_u32_e32 v51, vcc, 0, v1, vcc
	v_add_co_u32_e32 v52, vcc, s39, v0
	s_nop 1
	v_addc_co_u32_e32 v53, vcc, 0, v1, vcc
	global_load_dword v62, v[2:3], off nt
	global_load_dword v63, v[4:5], off nt
	global_load_dword v64, v[6:7], off nt
	global_load_dword v65, v[44:45], off nt
	global_load_dword v66, v[46:47], off nt
	global_load_dword v67, v[48:49], off nt
	global_load_dword v68, v[50:51], off nt
	global_load_dword v69, v[52:53], off nt
	v_add_co_u32_e32 v2, vcc, s40, v0
	s_nop 1
	v_addc_co_u32_e32 v3, vcc, 0, v1, vcc
	v_add_co_u32_e32 v4, vcc, s41, v0
	s_nop 1
	v_addc_co_u32_e32 v5, vcc, 0, v1, vcc
	v_add_co_u32_e32 v6, vcc, s42, v0
	s_nop 1
	v_addc_co_u32_e32 v7, vcc, 0, v1, vcc
	v_add_co_u32_e32 v44, vcc, s43, v0
	s_nop 1
	v_addc_co_u32_e32 v45, vcc, 0, v1, vcc
	v_add_co_u32_e32 v46, vcc, s44, v0
	s_nop 1
	v_addc_co_u32_e32 v47, vcc, 0, v1, vcc
	v_add_co_u32_e32 v48, vcc, s45, v0
	s_nop 1
	v_addc_co_u32_e32 v49, vcc, 0, v1, vcc
	v_add_co_u32_e32 v50, vcc, s46, v0
	s_nop 1
	v_addc_co_u32_e32 v51, vcc, 0, v1, vcc
	v_add_co_u32_e32 v52, vcc, s47, v0
	s_nop 1
	v_addc_co_u32_e32 v53, vcc, 0, v1, vcc
	global_load_dword v70, v[2:3], off nt
	global_load_dword v71, v[4:5], off nt
	global_load_dword v72, v[6:7], off nt
	global_load_dword v73, v[44:45], off nt
	global_load_dword v74, v[46:47], off nt
	global_load_dword v75, v[48:49], off nt
	global_load_dword v76, v[50:51], off nt
	s_nop 0
	global_load_dword v52, v[52:53], off nt
	v_add_co_u32_e32 v2, vcc, s48, v0
	s_nop 1
	v_addc_co_u32_e32 v3, vcc, 0, v1, vcc
	v_add_co_u32_e32 v4, vcc, s49, v0
	s_nop 1
	v_addc_co_u32_e32 v5, vcc, 0, v1, vcc
	v_add_co_u32_e32 v6, vcc, s52, v0
	s_nop 1
	v_addc_co_u32_e32 v7, vcc, 0, v1, vcc
	v_add_co_u32_e32 v44, vcc, s53, v0
	s_nop 1
	v_addc_co_u32_e32 v45, vcc, 0, v1, vcc
	v_add_co_u32_e32 v46, vcc, s54, v0
	s_nop 1
	v_addc_co_u32_e32 v47, vcc, 0, v1, vcc
	v_add_co_u32_e32 v48, vcc, s55, v0
	s_nop 1
	v_addc_co_u32_e32 v49, vcc, 0, v1, vcc
	v_add_co_u32_e32 v50, vcc, s56, v0
	s_nop 1
	v_addc_co_u32_e32 v51, vcc, 0, v1, vcc
	v_add_co_u32_e32 v0, vcc, s57, v0
	s_nop 1
	v_addc_co_u32_e32 v1, vcc, 0, v1, vcc
	global_load_dword v2, v[2:3], off nt
	s_nop 0
	global_load_dword v3, v[4:5], off nt
	s_nop 0
	global_load_dword v4, v[6:7], off nt
	global_load_dword v5, v[44:45], off nt
	s_nop 0
	global_load_dword v6, v[46:47], off nt
	global_load_dword v7, v[48:49], off nt
	global_load_dword v44, v[50:51], off nt
	s_nop 0
	global_load_dword v0, v[0:1], off nt
	s_waitcnt vmcnt(30)
; #define LAS __attribute__((address_space(3)))
; __device__ __forceinline__ unsigned pk2(float lo, float hi) { const f32x2 v = {lo, hi}; const bf16x2_hw b = __builtin_convertvector(v, bf16x2_hw); return __builtin_bit_cast(unsigned, b); }
; __device__ __forceinline__ void gst_wt16(void* p, const u32x4 v) { asm volatile("global_store_dwordx4 %0, %1, off sc1\n\ts_nop 1" :: "v"(p), "v"(v) : "memory"); }
; __device__ __forceinline__ void transpose_item(const float* W, int K, int N, bf16_t* WT, int kb, int nb, int drow0, const float* kscale, LAS float* scr, int lane) {
;     ...
;     for (int i = 0; i < 32; ++i) scr[(2 * i + (lane >> 5)) * 33 + (lane & 31)] = w[i];
;     asm volatile("s_waitcnt lgkmcnt(0)" ::: "memory");
; #pragma unroll
;     for (int j = 0; j < 4; ++j) { const int n = (lane >> 3) + 8 * j; const LAS float* s = scr + (8 * c) * 33 + n;
;         u32x4 o; o.x = pk2(s[0 * 33] * s0[0], s[1 * 33] * s0[1]); o.y = pk2(s[2 * 33] * s0[2], s[3 * 33] * s0[3]); o.z = pk2(s[4 * 33] * s1[0], s[5 * 33] * s1[1]); o.w = pk2(s[6 * 33] * s1[2], s[7 * 33] * s1[3]);
;         gst_wt16(WT + (size_t)(drow0 + n) * K + k0 + 8 * c, o); }
;     asm volatile("s_waitcnt lgkmcnt(0)" ::: "memory");
	ds_write2_b32 v31, v54, v55 offset1:66
	s_waitcnt vmcnt(28)
	ds_write2_b32 v31, v56, v57 offset0:132 offset1:198
	s_waitcnt vmcnt(26)
	ds_write2_b32 v37, v58, v59 offset0:8 offset1:74
	s_waitcnt vmcnt(24)
	ds_write2_b32 v37, v60, v61 offset0:140 offset1:206
	s_waitcnt vmcnt(22)
	ds_write2_b32 v38, v62, v63 offset0:16 offset1:82
	s_waitcnt vmcnt(20)
	ds_write2_b32 v38, v64, v65 offset0:148 offset1:214
	s_waitcnt vmcnt(18)
	ds_write2_b32 v39, v66, v67 offset0:24 offset1:90
	s_waitcnt vmcnt(16)
	ds_write2_b32 v39, v68, v69 offset0:156 offset1:222
	s_waitcnt vmcnt(14)
	ds_write2_b32 v40, v70, v71 offset0:32 offset1:98
	s_waitcnt vmcnt(12)
	ds_write2_b32 v40, v72, v73 offset0:164 offset1:230
	s_waitcnt vmcnt(10)
	ds_write2_b32 v41, v74, v75 offset0:40 offset1:106
	s_waitcnt vmcnt(8)
	ds_write2_b32 v41, v76, v52 offset0:172 offset1:238
	s_waitcnt vmcnt(6)
	ds_write2_b32 v42, v2, v3 offset0:48 offset1:114
	s_waitcnt vmcnt(4)
	ds_write2_b32 v42, v4, v5 offset0:180 offset1:246
	s_waitcnt vmcnt(2)
	ds_write2_b32 v43, v6, v7 offset0:56 offset1:122
	s_waitcnt vmcnt(0)
	ds_write2_b32 v43, v44, v0 offset0:188 offset1:254
	s_waitcnt lgkmcnt(0)
	ds_read2_b32 v[0:1], v33 offset1:33
	ds_read2_b32 v[2:3], v33 offset0:66 offset1:99
	ds_read2_b32 v[4:5], v33 offset0:132 offset1:165
	ds_read2_b32 v[6:7], v33 offset0:198 offset1:231
	v_lshl_add_u64 v[44:45], s[8:9], 1, v[20:21]
	s_waitcnt lgkmcnt(3)
	v_cvt_pk_bf16_f32 v0, v0, v1
	s_waitcnt lgkmcnt(2)
	v_cvt_pk_bf16_f32 v1, v2, v3
	s_waitcnt lgkmcnt(1)
	v_cvt_pk_bf16_f32 v2, v4, v5
	v_or_b32_e32 v4, s10, v32
	v_lshlrev_b32_e32 v4, 10, v4
	v_mov_b32_e32 v5, v9
	s_waitcnt lgkmcnt(0)
	v_cvt_pk_bf16_f32 v3, v6, v7
	v_lshl_add_u64 v[4:5], v[44:45], 0, v[4:5]
	global_store_dwordx4 v[4:5], v[0:3], off sc1 nt
	s_nop 1
	ds_read2_b32 v[0:1], v33 offset0:8 offset1:41
	ds_read2_b32 v[2:3], v33 offset0:74 offset1:107
	ds_read2_b32 v[4:5], v33 offset0:140 offset1:173
	ds_read2_b32 v[6:7], v33 offset0:206 offset1:239
	s_waitcnt lgkmcnt(3)
	v_cvt_pk_bf16_f32 v0, v0, v1
	s_waitcnt lgkmcnt(2)
	v_cvt_pk_bf16_f32 v1, v2, v3
	s_waitcnt lgkmcnt(1)
	v_cvt_pk_bf16_f32 v2, v4, v5
	v_or_b32_e32 v4, s10, v34
	v_lshlrev_b32_e32 v4, 10, v4
	v_mov_b32_e32 v5, v9
	s_waitcnt lgkmcnt(0)
	v_cvt_pk_bf16_f32 v3, v6, v7
	v_lshl_add_u64 v[4:5], v[44:45], 0, v[4:5]
	global_store_dwordx4 v[4:5], v[0:3], off sc1 nt
	s_nop 1
	ds_read2_b32 v[0:1], v33 offset0:16 offset1:49
	ds_read2_b32 v[2:3], v33 offset0:82 offset1:115
	ds_read2_b32 v[4:5], v33 offset0:148 offset1:181
	ds_read2_b32 v[6:7], v33 offset0:214 offset1:247
	s_waitcnt lgkmcnt(3)
	v_cvt_pk_bf16_f32 v0, v0, v1
	s_waitcnt lgkmcnt(2)
	v_cvt_pk_bf16_f32 v1, v2, v3
	s_waitcnt lgkmcnt(1)
	v_cvt_pk_bf16_f32 v2, v4, v5
	v_or_b32_e32 v4, s10, v35
	v_lshlrev_b32_e32 v4, 10, v4
	v_mov_b32_e32 v5, v9
	s_waitcnt lgkmcnt(0)
	v_cvt_pk_bf16_f32 v3, v6, v7
	v_lshl_add_u64 v[4:5], v[44:45], 0, v[4:5]
	global_store_dwordx4 v[4:5], v[0:3], off sc1 nt
	s_nop 1
	ds_read2_b32 v[0:1], v33 offset0:24 offset1:57
	ds_read2_b32 v[2:3], v33 offset0:90 offset1:123
	ds_read2_b32 v[4:5], v33 offset0:156 offset1:189
	ds_read2_b32 v[6:7], v33 offset0:222 offset1:255
	s_waitcnt lgkmcnt(3)
	v_cvt_pk_bf16_f32 v0, v0, v1
	s_waitcnt lgkmcnt(2)
	v_cvt_pk_bf16_f32 v1, v2, v3
	s_waitcnt lgkmcnt(1)
	v_cvt_pk_bf16_f32 v2, v4, v5
	v_or_b32_e32 v4, s10, v36
	v_lshlrev_b32_e32 v4, 10, v4
	v_mov_b32_e32 v5, v9
	s_waitcnt lgkmcnt(0)
	v_cvt_pk_bf16_f32 v3, v6, v7
	v_lshl_add_u64 v[4:5], v[44:45], 0, v[4:5]
	global_store_dwordx4 v[4:5], v[0:3], off sc1 nt
	s_nop 1
	s_waitcnt lgkmcnt(0)

; __device__ __forceinline__ void transpose_item(const float* W, int K, int N, bf16_t* WT, int kb, int nb, int drow0, const float* kscale, LAS float* scr, int lane) {
;     const int k0 = 64 * kb, n0 = 32 * nb, c = lane & 7;
;     f32x4 s0 = {1.f, 1.f, 1.f, 1.f}, s1 = {1.f, 1.f, 1.f, 1.f};
;     if (kscale) { s0 = *(const f32x4*)(kscale + k0 + 8 * c); s1 = *(const f32x4*)(kscale + k0 + 8 * c + 4); }
;     const float* src = W + (size_t)(k0 + (lane >> 5)) * N + n0 + (lane & 31);
;     float w[32];
; #pragma unroll
;     for (int i = 0; i < 32; ++i) w[i] = __builtin_nontemporal_load(src + (size_t)(2 * i) * N);
; __device__ __forceinline__ void prep_weights(Frame& F, const Args& a, int l, int it_lo, int it_hi, int gw, int ngw) {
;     ...
;         if (r < I1) { const int kb = r / 32, nb = r % 32; transpose_item(w_ao, 512, DM, W + WO_AO, kb, nb, 32 * nb, nullptr, scr, F.lane); continue; } r -= I1;
.LBB0_86:
	s_andn2_b64 vcc, exec, s[10:11]
	s_cbranch_vccnz .LBB0_88
	s_and_b32 s8, s20, 0x1fc0
	s_addk_i32 s8, 0xe900
	v_or_b32_e32 v0, s8, v30
	v_mov_b32_e32 v1, v9
	s_and_b32 s10, s14, 0x3e0
	v_lshlrev_b64 v[0:1], 12, v[0:1]
	v_lshl_add_u64 v[0:1], s[90:91], 0, v[0:1]
	s_lshl_b32 s12, s10, 2
	s_mov_b32 s13, s9
	v_lshl_add_u64 v[0:1], v[0:1], 0, s[12:13]
	v_lshl_add_u64 v[0:1], v[0:1], 0, v[8:9]
	v_add_co_u32_e32 v2, vcc, s24, v0
	s_nop 1
	v_addc_co_u32_e32 v3, vcc, 0, v1, vcc
	v_add_co_u32_e32 v4, vcc, s25, v0
	s_nop 1
	v_addc_co_u32_e32 v5, vcc, 0, v1, vcc
	v_add_co_u32_e32 v6, vcc, s26, v0
	s_nop 1
	v_addc_co_u32_e32 v7, vcc, 0, v1, vcc
	v_add_co_u32_e32 v44, vcc, s27, v0
	s_nop 1
	v_addc_co_u32_e32 v45, vcc, 0, v1, vcc
	v_add_co_u32_e32 v46, vcc, s28, v0
	s_nop 1
	v_addc_co_u32_e32 v47, vcc, 0, v1, vcc
	v_add_co_u32_e32 v48, vcc, s29, v0
	s_nop 1
	v_addc_co_u32_e32 v49, vcc, 0, v1, vcc
	v_add_co_u32_e32 v50, vcc, s30, v0
	s_nop 1
	v_addc_co_u32_e32 v51, vcc, 0, v1, vcc
	global_load_dword v54, v[0:1], off nt
	global_load_dword v55, v[2:3], off nt
	global_load_dword v56, v[4:5], off nt
	global_load_dword v57, v[6:7], off nt
	global_load_dword v58, v[44:45], off nt
	global_load_dword v59, v[46:47], off nt
	global_load_dword v60, v[48:49], off nt
	global_load_dword v61, v[50:51], off nt
	v_add_co_u32_e32 v2, vcc, s31, v0
	s_nop 1
	v_addc_co_u32_e32 v3, vcc, 0, v1, vcc
	v_add_co_u32_e32 v4, vcc, s33, v0
	s_nop 1
	v_addc_co_u32_e32 v5, vcc, 0, v1, vcc
	v_add_co_u32_e32 v6, vcc, s34, v0
	s_nop 1
	v_addc_co_u32_e32 v7, vcc, 0, v1, vcc
	v_add_co_u32_e32 v44, vcc, s35, v0
	s_nop 1
	v_addc_co_u32_e32 v45, vcc, 0, v1, vcc
	v_add_co_u32_e32 v46, vcc, s36, v0
	s_nop 1
	v_addc_co_u32_e32 v47, vcc, 0, v1, vcc
	v_add_co_u32_e32 v48, vcc, s37, v0
	s_nop 1
	v_addc_co_u32_e32 v49, vcc, 0, v1, vcc
	v_add_co_u32_e32 v50, vcc, s38, v0
	s_nop 1
	v_addc_co_u32_e32 v51, vcc, 0, v1, vcc
	v_add_co_u32_e32 v52, vcc, s39, v0
	s_nop 1
	v_addc_co_u32_e32 v53, vcc, 0, v1, vcc
	global_load_dword v62, v[2:3], off nt
	global_load_dword v63, v[4:5], off nt
	global_load_dword v64, v[6:7], off nt
	global_load_dword v65, v[44:45], off nt
	global_load_dword v66, v[46:47], off nt
	global_load_dword v67, v[48:49], off nt
	global_load_dword v68, v[50:51], off nt
	global_load_dword v69, v[52:53], off nt
	v_add_co_u32_e32 v2, vcc, s40, v0
	s_nop 1
	v_addc_co_u32_e32 v3, vcc, 0, v1, vcc
	v_add_co_u32_e32 v4, vcc, s41, v0
	s_nop 1
	v_addc_co_u32_e32 v5, vcc, 0, v1, vcc
	v_add_co_u32_e32 v6, vcc, s42, v0
	s_nop 1
	v_addc_co_u32_e32 v7, vcc, 0, v1, vcc
	v_add_co_u32_e32 v44, vcc, s43, v0
	s_nop 1
	v_addc_co_u32_e32 v45, vcc, 0, v1, vcc
	v_add_co_u32_e32 v46, vcc, s44, v0
	s_nop 1
	v_addc_co_u32_e32 v47, vcc, 0, v1, vcc
	v_add_co_u32_e32 v48, vcc, s45, v0
	s_nop 1
	v_addc_co_u32_e32 v49, vcc, 0, v1, vcc
	v_add_co_u32_e32 v50, vcc, s46, v0
	s_nop 1
	v_addc_co_u32_e32 v51, vcc, 0, v1, vcc
	v_add_co_u32_e32 v52, vcc, s47, v0
	s_nop 1
	v_addc_co_u32_e32 v53, vcc, 0, v1, vcc
	global_load_dword v70, v[2:3], off nt
	global_load_dword v71, v[4:5], off nt
	global_load_dword v72, v[6:7], off nt
	global_load_dword v73, v[44:45], off nt
	global_load_dword v74, v[46:47], off nt
	global_load_dword v75, v[48:49], off nt
	global_load_dword v76, v[50:51], off nt
	s_nop 0
	global_load_dword v52, v[52:53], off nt
	v_add_co_u32_e32 v2, vcc, s48, v0
	s_nop 1
	v_addc_co_u32_e32 v3, vcc, 0, v1, vcc
	v_add_co_u32_e32 v4, vcc, s49, v0
	s_nop 1
	v_addc_co_u32_e32 v5, vcc, 0, v1, vcc
	v_add_co_u32_e32 v6, vcc, s52, v0
	s_nop 1
	v_addc_co_u32_e32 v7, vcc, 0, v1, vcc
	v_add_co_u32_e32 v44, vcc, s53, v0
	s_nop 1
	v_addc_co_u32_e32 v45, vcc, 0, v1, vcc
	v_add_co_u32_e32 v46, vcc, s54, v0
	s_nop 1
	v_addc_co_u32_e32 v47, vcc, 0, v1, vcc
	v_add_co_u32_e32 v48, vcc, s55, v0
	s_nop 1
	v_addc_co_u32_e32 v49, vcc, 0, v1, vcc
	v_add_co_u32_e32 v50, vcc, s56, v0
	s_nop 1
	v_addc_co_u32_e32 v51, vcc, 0, v1, vcc
	v_add_co_u32_e32 v0, vcc, s57, v0
	s_nop 1
	v_addc_co_u32_e32 v1, vcc, 0, v1, vcc
	global_load_dword v2, v[2:3], off nt
	s_nop 0
	global_load_dword v3, v[4:5], off nt
	s_nop 0
	global_load_dword v4, v[6:7], off nt
	global_load_dword v5, v[44:45], off nt
	s_nop 0
	global_load_dword v6, v[46:47], off nt
	global_load_dword v7, v[48:49], off nt
	global_load_dword v44, v[50:51], off nt
	s_nop 0
	global_load_dword v0, v[0:1], off nt
	s_waitcnt vmcnt(30)
; #define LAS __attribute__((address_space(3)))
; __device__ __forceinline__ unsigned pk2(float lo, float hi) { const f32x2 v = {lo, hi}; const bf16x2_hw b = __builtin_convertvector(v, bf16x2_hw); return __builtin_bit_cast(unsigned, b); }
; __device__ __forceinline__ void gst_wt16(void* p, const u32x4 v) { asm volatile("global_store_dwordx4 %0, %1, off sc1\n\ts_nop 1" :: "v"(p), "v"(v) : "memory"); }
; __device__ __forceinline__ void transpose_item(const float* W, int K, int N, bf16_t* WT, int kb, int nb, int drow0, const float* kscale, LAS float* scr, int lane) {
;     ...
;     for (int i = 0; i < 32; ++i) scr[(2 * i + (lane >> 5)) * 33 + (lane & 31)] = w[i];
;     asm volatile("s_waitcnt lgkmcnt(0)" ::: "memory");
; #pragma unroll
;     for (int j = 0; j < 4; ++j) { const int n = (lane >> 3) + 8 * j; const LAS float* s = scr + (8 * c) * 33 + n;
;         u32x4 o; o.x = pk2(s[0 * 33] * s0[0], s[1 * 33] * s0[1]); o.y = pk2(s[2 * 33] * s0[2], s[3 * 33] * s0[3]); o.z = pk2(s[4 * 33] * s1[0], s[5 * 33] * s1[1]); o.w = pk2(s[6 * 33] * s1[2], s[7 * 33] * s1[3]);
;         gst_wt16(WT + (size_t)(drow0 + n) * K + k0 + 8 * c, o); }
;     asm volatile("s_waitcnt lgkmcnt(0)" ::: "memory");
	ds_write2_b32 v31, v54, v55 offset1:66
	s_waitcnt vmcnt(28)
	ds_write2_b32 v31, v56, v57 offset0:132 offset1:198
	s_waitcnt vmcnt(26)
	ds_write2_b32 v37, v58, v59 offset0:8 offset1:74
	s_waitcnt vmcnt(24)
	ds_write2_b32 v37, v60, v61 offset0:140 offset1:206
	s_waitcnt vmcnt(22)
	ds_write2_b32 v38, v62, v63 offset0:16 offset1:82
	s_waitcnt vmcnt(20)
	ds_write2_b32 v38, v64, v65 offset0:148 offset1:214
	s_waitcnt vmcnt(18)
	ds_write2_b32 v39, v66, v67 offset0:24 offset1:90
	s_waitcnt vmcnt(16)
	ds_write2_b32 v39, v68, v69 offset0:156 offset1:222
	s_waitcnt vmcnt(14)
	ds_write2_b32 v40, v70, v71 offset0:32 offset1:98
	s_waitcnt vmcnt(12)
	ds_write2_b32 v40, v72, v73 offset0:164 offset1:230
	s_waitcnt vmcnt(10)
	ds_write2_b32 v41, v74, v75 offset0:40 offset1:106
	s_waitcnt vmcnt(8)
	ds_write2_b32 v41, v76, v52 offset0:172 offset1:238
	s_waitcnt vmcnt(6)
	ds_write2_b32 v42, v2, v3 offset0:48 offset1:114
	s_waitcnt vmcnt(4)
	ds_write2_b32 v42, v4, v5 offset0:180 offset1:246
	s_waitcnt vmcnt(2)
	ds_write2_b32 v43, v6, v7 offset0:56 offset1:122
	s_waitcnt vmcnt(0)
	ds_write2_b32 v43, v44, v0 offset0:188 offset1:254
	s_waitcnt lgkmcnt(0)
	ds_read2_b32 v[0:1], v33 offset1:33
	ds_read2_b32 v[2:3], v33 offset0:66 offset1:99
	ds_read2_b32 v[4:5], v33 offset0:132 offset1:165
	ds_read2_b32 v[6:7], v33 offset0:198 offset1:231
	v_lshl_add_u64 v[44:45], s[8:9], 1, v[22:23]
	s_waitcnt lgkmcnt(3)
	v_cvt_pk_bf16_f32 v0, v0, v1
	s_waitcnt lgkmcnt(2)
	v_cvt_pk_bf16_f32 v1, v2, v3
	s_waitcnt lgkmcnt(1)
	v_cvt_pk_bf16_f32 v2, v4, v5
	v_or_b32_e32 v4, s10, v32
	v_lshlrev_b32_e32 v4, 10, v4
	v_mov_b32_e32 v5, v9
	s_waitcnt lgkmcnt(0)
	v_cvt_pk_bf16_f32 v3, v6, v7
	v_lshl_add_u64 v[4:5], v[44:45], 0, v[4:5]
	global_store_dwordx4 v[4:5], v[0:3], off sc1 nt
	s_nop 1
	ds_read2_b32 v[0:1], v33 offset0:8 offset1:41
	ds_read2_b32 v[2:3], v33 offset0:74 offset1:107
	ds_read2_b32 v[4:5], v33 offset0:140 offset1:173
	ds_read2_b32 v[6:7], v33 offset0:206 offset1:239
	s_waitcnt lgkmcnt(3)
	v_cvt_pk_bf16_f32 v0, v0, v1
	s_waitcnt lgkmcnt(2)
	v_cvt_pk_bf16_f32 v1, v2, v3
	s_waitcnt lgkmcnt(1)
	v_cvt_pk_bf16_f32 v2, v4, v5
	v_or_b32_e32 v4, s10, v34
	v_lshlrev_b32_e32 v4, 10, v4
	v_mov_b32_e32 v5, v9
	s_waitcnt lgkmcnt(0)
	v_cvt_pk_bf16_f32 v3, v6, v7
	v_lshl_add_u64 v[4:5], v[44:45], 0, v[4:5]
	global_store_dwordx4 v[4:5], v[0:3], off sc1 nt
	s_nop 1
	ds_read2_b32 v[0:1], v33 offset0:16 offset1:49
	ds_read2_b32 v[2:3], v33 offset0:82 offset1:115
	ds_read2_b32 v[4:5], v33 offset0:148 offset1:181
	ds_read2_b32 v[6:7], v33 offset0:214 offset1:247
	s_waitcnt lgkmcnt(3)
	v_cvt_pk_bf16_f32 v0, v0, v1
	s_waitcnt lgkmcnt(2)
	v_cvt_pk_bf16_f32 v1, v2, v3
	s_waitcnt lgkmcnt(1)
	v_cvt_pk_bf16_f32 v2, v4, v5
	v_or_b32_e32 v4, s10, v35
	v_lshlrev_b32_e32 v4, 10, v4
	v_mov_b32_e32 v5, v9
	s_waitcnt lgkmcnt(0)
	v_cvt_pk_bf16_f32 v3, v6, v7
	v_lshl_add_u64 v[4:5], v[44:45], 0, v[4:5]
	global_store_dwordx4 v[4:5], v[0:3], off sc1 nt
	s_nop 1
	ds_read2_b32 v[0:1], v33 offset0:24 offset1:57
	ds_read2_b32 v[2:3], v33 offset0:90 offset1:123
	ds_read2_b32 v[4:5], v33 offset0:156 offset1:189
	ds_read2_b32 v[6:7], v33 offset0:222 offset1:255
	s_waitcnt lgkmcnt(3)
	v_cvt_pk_bf16_f32 v0, v0, v1
	s_waitcnt lgkmcnt(2)
	v_cvt_pk_bf16_f32 v1, v2, v3
	s_waitcnt lgkmcnt(1)
	v_cvt_pk_bf16_f32 v2, v4, v5
	v_or_b32_e32 v4, s10, v36
	v_lshlrev_b32_e32 v4, 10, v4
	v_mov_b32_e32 v5, v9
	s_waitcnt lgkmcnt(0)
	v_cvt_pk_bf16_f32 v3, v6, v7
	v_lshl_add_u64 v[4:5], v[44:45], 0, v[4:5]
	global_store_dwordx4 v[4:5], v[0:3], off sc1 nt
	s_nop 1
	s_waitcnt lgkmcnt(0)

; __device__ __forceinline__ void transpose_item(const float* W, int K, int N, bf16_t* WT, int kb, int nb, int drow0, const float* kscale, LAS float* scr, int lane) {
;     const int k0 = 64 * kb, n0 = 32 * nb, c = lane & 7;
;     f32x4 s0 = {1.f, 1.f, 1.f, 1.f}, s1 = {1.f, 1.f, 1.f, 1.f};
;     if (kscale) { s0 = *(const f32x4*)(kscale + k0 + 8 * c); s1 = *(const f32x4*)(kscale + k0 + 8 * c + 4); }
;     const float* src = W + (size_t)(k0 + (lane >> 5)) * N + n0 + (lane & 31);
;     float w[32];
; #pragma unroll
;     for (int i = 0; i < 32; ++i) w[i] = __builtin_nontemporal_load(src + (size_t)(2 * i) * N);
; __device__ __forceinline__ void prep_weights(Frame& F, const Args& a, int l, int it_lo, int it_hi, int gw, int ngw) {
;     ...
;         if (r < I0) { const int kb = r / 184, nb = r % 184, n0 = 32 * nb; int d0 = n0;
;             if (n0 >= C_CC && n0 < C_CX) { const int c = n0 - C_CC; d0 = 256 * (5 + c / 128) + (c % 128); }
;             else if (n0 >= C_CX && n0 < C_U) { const int c = n0 - C_CX; d0 = 256 * (5 + c / 128) + 128 + (c % 128); }
;             else if (n0 >= C_G && n0 < C_G + 1024) { const int c = n0 - C_G; d0 = 256 * (11 + c / 128) + (c % 128); }
;             else if (n0 >= C_G + 1024 && n0 < C_G + 2048) { const int c = n0 - C_G - 1024; d0 = 256 * (11 + c / 128) + 128 + (c % 128); }
;             transpose_item(w_in, DM, INCOLS, W + WO_IN, kb, nb, d0, nmix, scr, F.lane); continue; } r -= I0;
.LBB0_1346:
	v_or_b32_e32 v0, s18, v11
	v_mov_b64_e32 v[32:33], s[2:3]
	s_movk_i32 s21, 0x5c00
	v_mad_i64_i32 v[32:33], s[34:35], v0, s21, v[32:33]
	s_ashr_i32 s21, s20, 31
	v_lshl_add_u64 v[32:33], s[20:21], 2, v[32:33]
	v_lshlrev_b32_e32 v0, 2, v10
	v_lshl_add_u64 v[32:33], v[32:33], 0, v[0:1]
	s_mov_b32 s20, 0xb000
	v_add_co_u32_e32 v40, vcc, s20, v32
	s_mov_b32 s20, 0x17000
	s_nop 0
	v_addc_co_u32_e32 v41, vcc, 0, v33, vcc
	global_load_dword v42, v[40:41], off offset:2048 nt
	v_add_co_u32_e32 v40, vcc, s20, v32
	s_mov_b32 s20, 0x22000
	s_nop 0
	v_addc_co_u32_e32 v41, vcc, 0, v33, vcc
	global_load_dword v0, v[32:33], off nt
	global_load_dword v43, v[40:41], off nt
	v_add_co_u32_e32 v40, vcc, s20, v32
	s_mov_b32 s20, 0x2e000
	s_nop 0
	v_addc_co_u32_e32 v41, vcc, 0, v33, vcc
	global_load_dword v44, v[40:41], off offset:2048 nt
	v_add_co_u32_e32 v40, vcc, s20, v32
	s_mov_b32 s20, 0x39000
	s_nop 0
	v_addc_co_u32_e32 v41, vcc, 0, v33, vcc
	global_load_dword v45, v[40:41], off nt
	v_add_co_u32_e32 v40, vcc, s20, v32
	s_mov_b32 s20, 0x45000
	s_nop 0
	v_addc_co_u32_e32 v41, vcc, 0, v33, vcc
	global_load_dword v46, v[40:41], off offset:2048 nt
	v_add_co_u32_e32 v40, vcc, s20, v32
	s_mov_b32 s20, 0x50000
	s_nop 0
	v_addc_co_u32_e32 v41, vcc, 0, v33, vcc
	global_load_dword v47, v[40:41], off nt
	v_add_co_u32_e32 v40, vcc, s20, v32
	s_mov_b32 s20, 0x5c000
	s_nop 0
	v_addc_co_u32_e32 v41, vcc, 0, v33, vcc
	global_load_dword v48, v[40:41], off offset:2048 nt
	v_add_co_u32_e32 v40, vcc, s20, v32
	s_mov_b32 s20, 0x67000
	s_nop 0
	v_addc_co_u32_e32 v41, vcc, 0, v33, vcc
	global_load_dword v49, v[40:41], off nt
	v_add_co_u32_e32 v40, vcc, s20, v32
	s_mov_b32 s20, 0x73000
	s_nop 0
	v_addc_co_u32_e32 v41, vcc, 0, v33, vcc
	global_load_dword v50, v[40:41], off offset:2048 nt
	v_add_co_u32_e32 v40, vcc, s20, v32
	s_mov_b32 s20, 0x7e000
	s_nop 0
	v_addc_co_u32_e32 v41, vcc, 0, v33, vcc
	global_load_dword v51, v[40:41], off nt
	v_add_co_u32_e32 v40, vcc, s20, v32
	s_mov_b32 s20, 0x8a000
	s_nop 0
	v_addc_co_u32_e32 v41, vcc, 0, v33, vcc
	global_load_dword v52, v[40:41], off offset:2048 nt
	v_add_co_u32_e32 v40, vcc, s20, v32
	s_mov_b32 s20, 0x95000
	s_nop 0
	v_addc_co_u32_e32 v41, vcc, 0, v33, vcc
	global_load_dword v53, v[40:41], off nt
	v_add_co_u32_e32 v40, vcc, s20, v32
	s_mov_b32 s20, 0xa1000
	s_nop 0
	v_addc_co_u32_e32 v41, vcc, 0, v33, vcc
	global_load_dword v54, v[40:41], off offset:2048 nt
	v_add_co_u32_e32 v40, vcc, s20, v32
	s_mov_b32 s20, 0xac000
	s_nop 0
	v_addc_co_u32_e32 v41, vcc, 0, v33, vcc
	global_load_dword v55, v[40:41], off nt
	v_add_co_u32_e32 v40, vcc, s20, v32
	s_mov_b32 s20, 0xb8000
	s_nop 0
	v_addc_co_u32_e32 v41, vcc, 0, v33, vcc
	global_load_dword v56, v[40:41], off offset:2048 nt
	v_add_co_u32_e32 v40, vcc, s20, v32
	s_mov_b32 s20, 0xc3000
	s_nop 0
	v_addc_co_u32_e32 v41, vcc, 0, v33, vcc
	global_load_dword v57, v[40:41], off nt
	v_add_co_u32_e32 v40, vcc, s20, v32
	s_mov_b32 s20, 0xcf000
	s_nop 0
	v_addc_co_u32_e32 v41, vcc, 0, v33, vcc
	global_load_dword v58, v[40:41], off offset:2048 nt
	v_add_co_u32_e32 v40, vcc, s20, v32
	s_mov_b32 s20, 0xda000
	s_nop 0
	v_addc_co_u32_e32 v41, vcc, 0, v33, vcc
	global_load_dword v59, v[40:41], off nt
	v_add_co_u32_e32 v40, vcc, s20, v32
	s_mov_b32 s20, 0xe6000
	s_nop 0
	v_addc_co_u32_e32 v41, vcc, 0, v33, vcc
	global_load_dword v60, v[40:41], off offset:2048 nt
	v_add_co_u32_e32 v40, vcc, s20, v32
	s_mov_b32 s20, 0xf1000
	s_nop 0
	v_addc_co_u32_e32 v41, vcc, 0, v33, vcc
	global_load_dword v61, v[40:41], off nt
	v_add_co_u32_e32 v40, vcc, s20, v32
	s_mov_b32 s20, 0xfd000
	s_nop 0
	v_addc_co_u32_e32 v41, vcc, 0, v33, vcc
	global_load_dword v62, v[40:41], off offset:2048 nt
	v_add_co_u32_e32 v40, vcc, s20, v32
	s_mov_b32 s20, 0x108000
	s_nop 0
	v_addc_co_u32_e32 v41, vcc, 0, v33, vcc
	global_load_dword v63, v[40:41], off nt
	v_add_co_u32_e32 v40, vcc, s20, v32
	s_mov_b32 s20, 0x114000
	s_nop 0
	v_addc_co_u32_e32 v41, vcc, 0, v33, vcc
	global_load_dword v64, v[40:41], off offset:2048 nt
	v_add_co_u32_e32 v40, vcc, s20, v32
	s_mov_b32 s20, 0x11f000
	s_nop 0
	v_addc_co_u32_e32 v41, vcc, 0, v33, vcc
	global_load_dword v65, v[40:41], off nt
	v_add_co_u32_e32 v40, vcc, s20, v32
	s_mov_b32 s20, 0x12b000
	s_nop 0
	v_addc_co_u32_e32 v41, vcc, 0, v33, vcc
	global_load_dword v66, v[40:41], off offset:2048 nt
	v_add_co_u32_e32 v40, vcc, s20, v32
	s_mov_b32 s20, 0x136000
	s_nop 0
	v_addc_co_u32_e32 v41, vcc, 0, v33, vcc
	global_load_dword v67, v[40:41], off nt
	v_add_co_u32_e32 v40, vcc, s20, v32
	s_mov_b32 s20, 0x142000
	s_nop 0
	v_addc_co_u32_e32 v41, vcc, 0, v33, vcc
	global_load_dword v68, v[40:41], off offset:2048 nt
	v_add_co_u32_e32 v40, vcc, s20, v32
	s_mov_b32 s20, 0x14d000
	s_nop 0
	v_addc_co_u32_e32 v41, vcc, 0, v33, vcc
	global_load_dword v69, v[40:41], off nt
	v_add_co_u32_e32 v40, vcc, s20, v32
	s_mov_b32 s20, 0x159000
	s_nop 0
	v_addc_co_u32_e32 v41, vcc, 0, v33, vcc
	global_load_dword v70, v[40:41], off offset:2048 nt
	v_add_co_u32_e32 v40, vcc, s20, v32
	s_mov_b32 s20, 0x164000
	s_nop 0
	v_addc_co_u32_e32 v41, vcc, 0, v33, vcc
	v_add_co_u32_e32 v32, vcc, s20, v32
	global_load_dword v40, v[40:41], off nt
	s_nop 0
	v_addc_co_u32_e32 v33, vcc, 0, v33, vcc
	global_load_dword v32, v[32:33], off offset:2048 nt
	s_waitcnt vmcnt(30)
; #define LAS __attribute__((address_space(3)))
; __device__ __forceinline__ unsigned pk2(float lo, float hi) { const f32x2 v = {lo, hi}; const bf16x2_hw b = __builtin_convertvector(v, bf16x2_hw); return __builtin_bit_cast(unsigned, b); }
; __device__ __forceinline__ void gst_wt16(void* p, const u32x4 v) { asm volatile("global_store_dwordx4 %0, %1, off sc1\n\ts_nop 1" :: "v"(p), "v"(v) : "memory"); }
; __device__ __forceinline__ void transpose_item(const float* W, int K, int N, bf16_t* WT, int kb, int nb, int drow0, const float* kscale, LAS float* scr, int lane) {
;     ...
; #pragma unroll
;     for (int i = 0; i < 32; ++i) scr[(2 * i + (lane >> 5)) * 33 + (lane & 31)] = w[i];
;     asm volatile("s_waitcnt lgkmcnt(0)" ::: "memory");
; #pragma unroll
;     for (int j = 0; j < 4; ++j) { const int n = (lane >> 3) + 8 * j; const LAS float* s = scr + (8 * c) * 33 + n;
;         u32x4 o; o.x = pk2(s[0 * 33] * s0[0], s[1 * 33] * s0[1]); o.y = pk2(s[2 * 33] * s0[2], s[3 * 33] * s0[3]); o.z = pk2(s[4 * 33] * s1[0], s[5 * 33] * s1[1]); o.w = pk2(s[6 * 33] * s1[2], s[7 * 33] * s1[3]);
;         gst_wt16(WT + (size_t)(drow0 + n) * K + k0 + 8 * c, o); }
;     asm volatile("s_waitcnt lgkmcnt(0)" ::: "memory");
	ds_write2_b32 v34, v0, v42 offset1:66
	s_waitcnt vmcnt(28)
	ds_write2_b32 v34, v43, v44 offset0:132 offset1:198
	v_add_u32_e32 v0, 0x400, v34
	s_waitcnt vmcnt(26)
	ds_write2_b32 v0, v45, v46 offset0:8 offset1:74
	s_waitcnt vmcnt(24)
	ds_write2_b32 v0, v47, v48 offset0:140 offset1:206
	v_add_u32_e32 v0, 0x800, v34
	s_waitcnt vmcnt(22)
	ds_write2_b32 v0, v49, v50 offset0:16 offset1:82
	s_waitcnt vmcnt(20)
	ds_write2_b32 v0, v51, v52 offset0:148 offset1:214
	v_add_u32_e32 v0, 0xc00, v34
	s_waitcnt vmcnt(18)
	ds_write2_b32 v0, v53, v54 offset0:24 offset1:90
	s_waitcnt vmcnt(16)
	ds_write2_b32 v0, v55, v56 offset0:156 offset1:222
	v_add_u32_e32 v0, 0x1000, v34
	s_waitcnt vmcnt(14)
	ds_write2_b32 v0, v57, v58 offset0:32 offset1:98
	s_waitcnt vmcnt(12)
	ds_write2_b32 v0, v59, v60 offset0:164 offset1:230
	v_add_u32_e32 v0, 0x1400, v34
	s_waitcnt vmcnt(10)
	ds_write2_b32 v0, v61, v62 offset0:40 offset1:106
	s_waitcnt vmcnt(8)
	ds_write2_b32 v0, v63, v64 offset0:172 offset1:238
	v_add_u32_e32 v0, 0x1800, v34
	s_waitcnt vmcnt(6)
	ds_write2_b32 v0, v65, v66 offset0:48 offset1:114
	s_waitcnt vmcnt(4)
	ds_write2_b32 v0, v67, v68 offset0:180 offset1:246
	v_add_u32_e32 v0, 0x1c00, v34
	s_waitcnt vmcnt(2)
	ds_write2_b32 v0, v69, v70 offset0:56 offset1:122
	s_waitcnt vmcnt(0)
	ds_write2_b32 v0, v40, v32 offset0:188 offset1:254
	s_waitcnt lgkmcnt(0)
	ds_read2_b32 v[40:41], v36 offset1:33
	ds_read2_b32 v[42:43], v36 offset0:66 offset1:99
	ds_read2_b32 v[44:45], v36 offset0:198 offset1:231
	v_lshl_add_u64 v[32:33], s[18:19], 1, v[12:13]
	s_waitcnt lgkmcnt(2)
	v_pk_mul_f32 v[40:41], v[6:7], v[40:41]
	s_waitcnt lgkmcnt(1)
	v_pk_mul_f32 v[42:43], v[8:9], v[42:43]
	v_cvt_pk_bf16_f32 v40, v40, v41
	v_cvt_pk_bf16_f32 v41, v42, v43
	ds_read2_b32 v[42:43], v36 offset0:132 offset1:165
	s_waitcnt lgkmcnt(1)
	v_pk_mul_f32 v[44:45], v[4:5], v[44:45]
	s_waitcnt lgkmcnt(0)
	v_pk_mul_f32 v[42:43], v[2:3], v[42:43]
	s_nop 0
	v_cvt_pk_bf16_f32 v42, v42, v43
	v_cvt_pk_bf16_f32 v43, v44, v45
	v_add_u32_e32 v44, s31, v35
	v_ashrrev_i32_e32 v45, 31, v44
	v_lshlrev_b64 v[44:45], 11, v[44:45]
	v_lshl_add_u64 v[44:45], v[32:33], 0, v[44:45]
	global_store_dwordx4 v[44:45], v[40:43], off sc1 nt
	s_nop 1
	ds_read2_b32 v[40:41], v36 offset0:8 offset1:41
	ds_read2_b32 v[42:43], v36 offset0:74 offset1:107
	ds_read2_b32 v[44:45], v36 offset0:206 offset1:239
	s_waitcnt lgkmcnt(2)
	v_pk_mul_f32 v[40:41], v[6:7], v[40:41]
	s_waitcnt lgkmcnt(1)
	v_pk_mul_f32 v[42:43], v[8:9], v[42:43]
	v_cvt_pk_bf16_f32 v40, v40, v41
	v_cvt_pk_bf16_f32 v41, v42, v43
	ds_read2_b32 v[42:43], v36 offset0:140 offset1:173
	s_waitcnt lgkmcnt(1)
	v_pk_mul_f32 v[44:45], v[4:5], v[44:45]
	s_waitcnt lgkmcnt(0)
	v_pk_mul_f32 v[42:43], v[2:3], v[42:43]
	s_nop 0
	v_cvt_pk_bf16_f32 v42, v42, v43
	v_cvt_pk_bf16_f32 v43, v44, v45
	v_add_u32_e32 v44, s31, v37
	v_ashrrev_i32_e32 v45, 31, v44
	v_lshlrev_b64 v[44:45], 11, v[44:45]
	v_lshl_add_u64 v[44:45], v[32:33], 0, v[44:45]
	global_store_dwordx4 v[44:45], v[40:43], off sc1 nt
	s_nop 1
	ds_read2_b32 v[40:41], v36 offset0:16 offset1:49
	ds_read2_b32 v[42:43], v36 offset0:82 offset1:115
	ds_read2_b32 v[44:45], v36 offset0:214 offset1:247
	s_waitcnt lgkmcnt(2)
	v_pk_mul_f32 v[40:41], v[6:7], v[40:41]
	s_waitcnt lgkmcnt(1)
	v_pk_mul_f32 v[42:43], v[8:9], v[42:43]
	v_cvt_pk_bf16_f32 v40, v40, v41
	v_cvt_pk_bf16_f32 v41, v42, v43
	ds_read2_b32 v[42:43], v36 offset0:148 offset1:181
	s_waitcnt lgkmcnt(1)
	v_pk_mul_f32 v[44:45], v[4:5], v[44:45]
	s_waitcnt lgkmcnt(0)
	v_pk_mul_f32 v[42:43], v[2:3], v[42:43]
	s_nop 0
	v_cvt_pk_bf16_f32 v42, v42, v43
	v_cvt_pk_bf16_f32 v43, v44, v45
	v_add_u32_e32 v44, s31, v38
	v_ashrrev_i32_e32 v45, 31, v44
	v_lshlrev_b64 v[44:45], 11, v[44:45]
	v_lshl_add_u64 v[44:45], v[32:33], 0, v[44:45]
	global_store_dwordx4 v[44:45], v[40:43], off sc1 nt
	s_nop 1
	ds_read2_b32 v[40:41], v36 offset0:24 offset1:57
	s_waitcnt lgkmcnt(0)
	v_pk_mul_f32 v[6:7], v[6:7], v[40:41]
	ds_read2_b32 v[40:41], v36 offset0:90 offset1:123
	v_cvt_pk_bf16_f32 v6, v6, v7
	s_waitcnt lgkmcnt(0)
	v_pk_mul_f32 v[8:9], v[8:9], v[40:41]
	s_nop 0
	v_cvt_pk_bf16_f32 v7, v8, v9
	ds_read2_b32 v[8:9], v36 offset0:156 offset1:189
	s_waitcnt lgkmcnt(0)
	v_pk_mul_f32 v[2:3], v[2:3], v[8:9]
	s_nop 0
	v_cvt_pk_bf16_f32 v8, v2, v3
	ds_read2_b32 v[2:3], v36 offset0:222 offset1:255
	s_waitcnt lgkmcnt(0)
	v_pk_mul_f32 v[2:3], v[4:5], v[2:3]
	s_nop 0
	v_cvt_pk_bf16_f32 v9, v2, v3
	v_add_u32_e32 v2, s31, v39
	v_ashrrev_i32_e32 v3, 31, v2
	v_lshlrev_b64 v[2:3], 11, v[2:3]
	v_lshl_add_u64 v[2:3], v[32:33], 0, v[2:3]
	global_store_dwordx4 v[2:3], v[6:9], off sc1 nt
	s_nop 1
	s_waitcnt lgkmcnt(0)

; __device__ __forceinline__ void transpose_item(const float* W, int K, int N, bf16_t* WT, int kb, int nb, int drow0, const float* kscale, LAS float* scr, int lane) {
;     const int k0 = 64 * kb, n0 = 32 * nb, c = lane & 7;
;     f32x4 s0 = {1.f, 1.f, 1.f, 1.f}, s1 = {1.f, 1.f, 1.f, 1.f};
;     if (kscale) { s0 = *(const f32x4*)(kscale + k0 + 8 * c); s1 = *(const f32x4*)(kscale + k0 + 8 * c + 4); }
;     const float* src = W + (size_t)(k0 + (lane >> 5)) * N + n0 + (lane & 31);
;     float w[32];
; #pragma unroll
;     for (int i = 0; i < 32; ++i) w[i] = __builtin_nontemporal_load(src + (size_t)(2 * i) * N);
; __device__ __forceinline__ void prep_weights(Frame& F, const Args& a, int l, int it_lo, int it_hi, int gw, int ngw) {
;     ...
;         if (r < I1) { const int kb = r / 32, nb = r % 32; transpose_item(w_ao, 512, DM, W + WO_AO, kb, nb, 32 * nb, nullptr, scr, F.lane); continue; } r -= I1;
;         if (r < I2) { const int kb = r / 32, nb = r % 32; transpose_item(w_co, 512, DM, W + WO_CO, kb, nb, 32 * nb, nullptr, scr, F.lane); continue; } r -= I2;
;         if (r < I3) { const int kb = r / 16, nb = r % 16; transpose_item(w_gl, 512, 512, W + WO_GLU, kb, nb, 32 * nb, nullptr, scr, F.lane); continue; } r -= I3;
;         if (r < I4) { const int kb = r / 32, nb = r % 32; transpose_item(w_so, 512, DM, W + WO_SO, kb, nb, 32 * nb, nullptr, scr, F.lane); continue; } r -= I4;
;         if (r < I5) { const int kb = r / 32, nb = r % 32; transpose_item(w_mx, DM, DM, W + WO_MIX, kb, nb, 32 * nb, nullptr, scr, F.lane); continue; } r -= I5;
;         if (r < I6) { const int kb = r / 176, nb = r % 176; const int n0 = 32 * nb; const int j0 = n0 < FFN ? n0 : n0 - FFN; const int drow0 = 256 * (j0 / 128) + (n0 < FFN ? 0 : 128) + (j0 % 128);
;             transpose_item(w_fi, DM, FFN2, W + WO_FI, kb, nb, drow0, nffn, scr, F.lane); continue; } r -= I6;
;         { const int kb = r / 32, nb = r % 32; transpose_item(w_fo, FFN, DM, W + WO_FO, kb, nb, 32 * nb, nullptr, scr, F.lane); }
.LBB0_1348:
	s_cmpk_gt_i32 s22, 0xb7f
	s_mov_b64 s[18:19], -1
	s_cbranch_scc0 .LBB0_1378
	s_cmpk_gt_u32 s22, 0xc7f
	s_cbranch_scc0 .LBB0_1375
	s_cmpk_gt_u32 s22, 0xd7f
	s_cbranch_scc0 .LBB0_1372
	s_cmpk_gt_u32 s22, 0xdff
	s_cbranch_scc0 .LBB0_1369
	s_cmpk_gt_u32 s22, 0xeff
	s_cbranch_scc0 .LBB0_1366
	s_cmpk_gt_u32 s22, 0x10ff
	s_cbranch_scc0 .LBB0_1363
	s_cmpk_gt_u32 s22, 0x1bff
	s_cbranch_scc0 .LBB0_1356
	s_and_b32 s19, s27, 0x7fffffc0
	s_add_i32 s72, s19, 0xffffc800
	v_or_b32_e32 v0, s72, v11
	s_and_b32 s18, s1, 0x3e0
	v_lshlrev_b64 v[2:3], 12, v[0:1]
	v_lshl_add_u64 v[2:3], s[16:17], 0, v[2:3]
	s_lshl_b32 s20, s18, 2
	s_mov_b32 s21, s73
	v_lshl_add_u64 v[2:3], v[2:3], 0, s[20:21]
	v_lshlrev_b32_e32 v0, 2, v10
	v_lshl_add_u64 v[2:3], v[2:3], 0, v[0:1]
	s_movk_i32 s19, 0x2000
	v_add_co_u32_e32 v4, vcc, s19, v2
	s_movk_i32 s19, 0x4000
	s_nop 0
	v_addc_co_u32_e32 v5, vcc, 0, v3, vcc
	global_load_dword v0, v[2:3], off nt
	global_load_dword v6, v[4:5], off nt
	v_add_co_u32_e32 v4, vcc, s19, v2
	s_movk_i32 s19, 0x6000
	s_nop 0
	v_addc_co_u32_e32 v5, vcc, 0, v3, vcc
	global_load_dword v7, v[4:5], off nt
	v_add_co_u32_e32 v4, vcc, s19, v2
	s_mov_b32 s19, 0x8000
	s_nop 0
	v_addc_co_u32_e32 v5, vcc, 0, v3, vcc
	global_load_dword v8, v[4:5], off nt
	v_add_co_u32_e32 v4, vcc, s19, v2
	s_mov_b32 s19, 0xa000
	s_nop 0
	v_addc_co_u32_e32 v5, vcc, 0, v3, vcc
	global_load_dword v9, v[4:5], off nt
	v_add_co_u32_e32 v4, vcc, s19, v2
	s_mov_b32 s19, 0xc000
	s_nop 0
	v_addc_co_u32_e32 v5, vcc, 0, v3, vcc
	global_load_dword v32, v[4:5], off nt
	v_add_co_u32_e32 v4, vcc, s19, v2
	s_mov_b32 s19, 0xe000
	s_nop 0
	v_addc_co_u32_e32 v5, vcc, 0, v3, vcc
	global_load_dword v33, v[4:5], off nt
	v_add_co_u32_e32 v4, vcc, s19, v2
	s_mov_b32 s19, 0x10000
	s_nop 0
	v_addc_co_u32_e32 v5, vcc, 0, v3, vcc
	global_load_dword v40, v[4:5], off nt
	v_add_co_u32_e32 v4, vcc, s19, v2
	s_mov_b32 s19, 0x12000
	s_nop 0
	v_addc_co_u32_e32 v5, vcc, 0, v3, vcc
	global_load_dword v41, v[4:5], off nt
	v_add_co_u32_e32 v4, vcc, s19, v2
	s_mov_b32 s19, 0x14000
	s_nop 0
	v_addc_co_u32_e32 v5, vcc, 0, v3, vcc
	global_load_dword v42, v[4:5], off nt
	v_add_co_u32_e32 v4, vcc, s19, v2
	s_mov_b32 s19, 0x16000
	s_nop 0
	v_addc_co_u32_e32 v5, vcc, 0, v3, vcc
	global_load_dword v43, v[4:5], off nt
	v_add_co_u32_e32 v4, vcc, s19, v2
	s_mov_b32 s19, 0x18000
	s_nop 0
	v_addc_co_u32_e32 v5, vcc, 0, v3, vcc
	global_load_dword v44, v[4:5], off nt
	v_add_co_u32_e32 v4, vcc, s19, v2
	s_mov_b32 s19, 0x1a000
	s_nop 0
	v_addc_co_u32_e32 v5, vcc, 0, v3, vcc
	global_load_dword v45, v[4:5], off nt
	v_add_co_u32_e32 v4, vcc, s19, v2
	s_mov_b32 s19, 0x1c000
	s_nop 0
	v_addc_co_u32_e32 v5, vcc, 0, v3, vcc
	global_load_dword v46, v[4:5], off nt
	v_add_co_u32_e32 v4, vcc, s19, v2
	s_mov_b32 s19, 0x1e000
	s_nop 0
	v_addc_co_u32_e32 v5, vcc, 0, v3, vcc
	global_load_dword v47, v[4:5], off nt
	v_add_co_u32_e32 v4, vcc, s19, v2
	s_mov_b32 s19, 0x22000
	s_nop 0
	v_addc_co_u32_e32 v5, vcc, 0, v3, vcc
	global_load_dword v48, v[4:5], off nt
	v_add_co_u32_e32 v4, vcc, s79, v2
	s_nop 1
	v_addc_co_u32_e32 v5, vcc, 0, v3, vcc
	global_load_dword v49, v[4:5], off nt
	v_add_co_u32_e32 v4, vcc, s19, v2
	s_mov_b32 s19, 0x24000
	s_nop 0
	v_addc_co_u32_e32 v5, vcc, 0, v3, vcc
	global_load_dword v50, v[4:5], off nt
	v_add_co_u32_e32 v4, vcc, s19, v2
	s_mov_b32 s19, 0x26000
	s_nop 0
	v_addc_co_u32_e32 v5, vcc, 0, v3, vcc
	global_load_dword v51, v[4:5], off nt
	v_add_co_u32_e32 v4, vcc, s19, v2
	s_mov_b32 s19, 0x28000
	s_nop 0
	v_addc_co_u32_e32 v5, vcc, 0, v3, vcc
	global_load_dword v52, v[4:5], off nt
	v_add_co_u32_e32 v4, vcc, s19, v2
	s_mov_b32 s19, 0x2a000
	s_nop 0
	v_addc_co_u32_e32 v5, vcc, 0, v3, vcc
	global_load_dword v53, v[4:5], off nt
	v_add_co_u32_e32 v4, vcc, s19, v2
	s_mov_b32 s19, 0x2c000
	s_nop 0
	v_addc_co_u32_e32 v5, vcc, 0, v3, vcc
	global_load_dword v54, v[4:5], off nt
	v_add_co_u32_e32 v4, vcc, s19, v2
	s_mov_b32 s19, 0x2e000
	s_nop 0
	v_addc_co_u32_e32 v5, vcc, 0, v3, vcc
	global_load_dword v55, v[4:5], off nt
	v_add_co_u32_e32 v4, vcc, s19, v2
	s_mov_b32 s19, 0x30000
	s_nop 0
	v_addc_co_u32_e32 v5, vcc, 0, v3, vcc
	global_load_dword v56, v[4:5], off nt
	v_add_co_u32_e32 v4, vcc, s19, v2
	s_mov_b32 s19, 0x32000
	s_nop 0
	v_addc_co_u32_e32 v5, vcc, 0, v3, vcc
	global_load_dword v57, v[4:5], off nt
	v_add_co_u32_e32 v4, vcc, s19, v2
	s_mov_b32 s19, 0x34000
	s_nop 0
	v_addc_co_u32_e32 v5, vcc, 0, v3, vcc
	global_load_dword v58, v[4:5], off nt
	v_add_co_u32_e32 v4, vcc, s19, v2
	s_mov_b32 s19, 0x36000
	s_nop 0
	v_addc_co_u32_e32 v5, vcc, 0, v3, vcc
	global_load_dword v59, v[4:5], off nt
	v_add_co_u32_e32 v4, vcc, s19, v2
	s_mov_b32 s19, 0x38000
	s_nop 0
	v_addc_co_u32_e32 v5, vcc, 0, v3, vcc
	global_load_dword v60, v[4:5], off nt
	v_add_co_u32_e32 v4, vcc, s19, v2
	s_mov_b32 s19, 0x3a000
	s_nop 0
	v_addc_co_u32_e32 v5, vcc, 0, v3, vcc
	global_load_dword v61, v[4:5], off nt
	v_add_co_u32_e32 v4, vcc, s19, v2
	s_mov_b32 s19, 0x3c000
	s_nop 0
	v_addc_co_u32_e32 v5, vcc, 0, v3, vcc
	global_load_dword v62, v[4:5], off nt
	v_add_co_u32_e32 v4, vcc, s19, v2
	s_mov_b32 s19, 0x3e000
	s_nop 0
	v_addc_co_u32_e32 v5, vcc, 0, v3, vcc
	v_add_co_u32_e32 v2, vcc, s19, v2
	global_load_dword v4, v[4:5], off nt
	s_nop 0
	v_addc_co_u32_e32 v3, vcc, 0, v3, vcc
	global_load_dword v2, v[2:3], off nt
	s_waitcnt vmcnt(30)
; #define LAS __attribute__((address_space(3)))
; __device__ __forceinline__ unsigned pk2(float lo, float hi) { const f32x2 v = {lo, hi}; const bf16x2_hw b = __builtin_convertvector(v, bf16x2_hw); return __builtin_bit_cast(unsigned, b); }
; __device__ __forceinline__ void gst_wt16(void* p, const u32x4 v) { asm volatile("global_store_dwordx4 %0, %1, off sc1\n\ts_nop 1" :: "v"(p), "v"(v) : "memory"); }
; __device__ __forceinline__ void transpose_item(const float* W, int K, int N, bf16_t* WT, int kb, int nb, int drow0, const float* kscale, LAS float* scr, int lane) {
;     ...
;     for (int i = 0; i < 32; ++i) scr[(2 * i + (lane >> 5)) * 33 + (lane & 31)] = w[i];
;     asm volatile("s_waitcnt lgkmcnt(0)" ::: "memory");
; #pragma unroll
;     for (int j = 0; j < 4; ++j) { const int n = (lane >> 3) + 8 * j; const LAS float* s = scr + (8 * c) * 33 + n;
;         u32x4 o; o.x = pk2(s[0 * 33] * s0[0], s[1 * 33] * s0[1]); o.y = pk2(s[2 * 33] * s0[2], s[3 * 33] * s0[3]); o.z = pk2(s[4 * 33] * s1[0], s[5 * 33] * s1[1]); o.w = pk2(s[6 * 33] * s1[2], s[7 * 33] * s1[3]);
;         gst_wt16(WT + (size_t)(drow0 + n) * K + k0 + 8 * c, o); }
;     asm volatile("s_waitcnt lgkmcnt(0)" ::: "memory");
	ds_write2_b32 v34, v0, v6 offset1:66
	s_waitcnt vmcnt(28)
	ds_write2_b32 v34, v7, v8 offset0:132 offset1:198
	v_add_u32_e32 v0, 0x400, v34
	s_waitcnt vmcnt(26)
	ds_write2_b32 v0, v9, v32 offset0:8 offset1:74
	s_waitcnt vmcnt(24)
	ds_write2_b32 v0, v33, v40 offset0:140 offset1:206
	v_add_u32_e32 v0, 0x800, v34
	s_waitcnt vmcnt(22)
	ds_write2_b32 v0, v41, v42 offset0:16 offset1:82
	s_waitcnt vmcnt(20)
	ds_write2_b32 v0, v43, v44 offset0:148 offset1:214
	v_add_u32_e32 v0, 0xc00, v34
	s_waitcnt vmcnt(18)
	ds_write2_b32 v0, v45, v46 offset0:24 offset1:90
	s_waitcnt vmcnt(16)
	ds_write2_b32 v0, v47, v48 offset0:156 offset1:222
	v_add_u32_e32 v0, 0x1000, v34
	s_waitcnt vmcnt(14)
	ds_write2_b32 v0, v49, v50 offset0:32 offset1:98
	s_waitcnt vmcnt(12)
	ds_write2_b32 v0, v51, v52 offset0:164 offset1:230
	v_add_u32_e32 v0, 0x1400, v34
	s_waitcnt vmcnt(10)
	ds_write2_b32 v0, v53, v54 offset0:40 offset1:106
	s_waitcnt vmcnt(8)
	ds_write2_b32 v0, v55, v56 offset0:172 offset1:238
	v_add_u32_e32 v0, 0x1800, v34
	s_waitcnt vmcnt(6)
	ds_write2_b32 v0, v57, v58 offset0:48 offset1:114
	s_waitcnt vmcnt(4)
	ds_write2_b32 v0, v59, v60 offset0:180 offset1:246
	v_add_u32_e32 v0, 0x1c00, v34
	s_waitcnt vmcnt(2)
	ds_write2_b32 v0, v61, v62 offset0:56 offset1:122
	s_waitcnt vmcnt(0)
	ds_write2_b32 v0, v4, v2 offset0:188 offset1:254
	s_waitcnt lgkmcnt(0)
	ds_read2_b32 v[2:3], v36 offset1:33
	ds_read2_b32 v[4:5], v36 offset0:66 offset1:99
	ds_read2_b32 v[8:9], v36 offset0:198 offset1:231
	v_or_b32_e32 v0, s18, v35
	v_lshl_add_u64 v[6:7], s[72:73], 1, v[14:15]
	s_waitcnt lgkmcnt(2)
	v_cvt_pk_bf16_f32 v2, v2, v3
	s_waitcnt lgkmcnt(1)
	v_cvt_pk_bf16_f32 v3, v4, v5
	ds_read2_b32 v[4:5], v36 offset0:132 offset1:165
	v_mul_u32_u24_e32 v0, 0x1600, v0
	s_waitcnt lgkmcnt(0)
	v_cvt_pk_bf16_f32 v4, v4, v5
	v_cvt_pk_bf16_f32 v5, v8, v9
	v_lshl_add_u64 v[8:9], v[6:7], 0, v[0:1]
	global_store_dwordx4 v[8:9], v[2:5], off sc1 nt
	s_nop 1
	ds_read2_b32 v[2:3], v36 offset0:8 offset1:41
	ds_read2_b32 v[4:5], v36 offset0:74 offset1:107
	ds_read2_b32 v[8:9], v36 offset0:206 offset1:239
	v_or_b32_e32 v0, s18, v37
	v_mul_u32_u24_e32 v0, 0x1600, v0
	s_waitcnt lgkmcnt(2)
	v_cvt_pk_bf16_f32 v2, v2, v3
	s_waitcnt lgkmcnt(1)
	v_cvt_pk_bf16_f32 v3, v4, v5
	ds_read2_b32 v[4:5], v36 offset0:140 offset1:173
	s_waitcnt lgkmcnt(0)
	v_cvt_pk_bf16_f32 v4, v4, v5
	v_cvt_pk_bf16_f32 v5, v8, v9
	v_lshl_add_u64 v[8:9], v[6:7], 0, v[0:1]
	global_store_dwordx4 v[8:9], v[2:5], off sc1 nt
	s_nop 1
	ds_read2_b32 v[2:3], v36 offset0:16 offset1:49
	ds_read2_b32 v[4:5], v36 offset0:82 offset1:115
	ds_read2_b32 v[8:9], v36 offset0:214 offset1:247
	v_or_b32_e32 v0, s18, v38
	v_mul_u32_u24_e32 v0, 0x1600, v0
	s_waitcnt lgkmcnt(2)
	v_cvt_pk_bf16_f32 v2, v2, v3
	s_waitcnt lgkmcnt(1)
	v_cvt_pk_bf16_f32 v3, v4, v5
	ds_read2_b32 v[4:5], v36 offset0:148 offset1:181
	s_waitcnt lgkmcnt(0)
	v_cvt_pk_bf16_f32 v4, v4, v5
	v_cvt_pk_bf16_f32 v5, v8, v9
	v_lshl_add_u64 v[8:9], v[6:7], 0, v[0:1]
	global_store_dwordx4 v[8:9], v[2:5], off sc1 nt
	s_nop 1
	ds_read2_b32 v[2:3], v36 offset0:24 offset1:57
	ds_read2_b32 v[4:5], v36 offset0:90 offset1:123
	ds_read2_b32 v[8:9], v36 offset0:222 offset1:255
	v_or_b32_e32 v0, s18, v39
	v_mul_u32_u24_e32 v0, 0x1600, v0
	s_waitcnt lgkmcnt(2)
	v_cvt_pk_bf16_f32 v2, v2, v3
	s_waitcnt lgkmcnt(1)
	v_cvt_pk_bf16_f32 v3, v4, v5
	ds_read2_b32 v[4:5], v36 offset0:156 offset1:189
	v_lshl_add_u64 v[6:7], v[6:7], 0, v[0:1]
	s_mov_b64 s[18:19], 0
	s_waitcnt lgkmcnt(0)
	v_cvt_pk_bf16_f32 v4, v4, v5
	v_cvt_pk_bf16_f32 v5, v8, v9
	global_store_dwordx4 v[6:7], v[2:5], off sc1 nt
	s_nop 1
	s_waitcnt lgkmcnt(0)

; __device__ __forceinline__ void transpose_item(const float* W, int K, int N, bf16_t* WT, int kb, int nb, int drow0, const float* kscale, LAS float* scr, int lane) {
;     const int k0 = 64 * kb, n0 = 32 * nb, c = lane & 7;
;     f32x4 s0 = {1.f, 1.f, 1.f, 1.f}, s1 = {1.f, 1.f, 1.f, 1.f};
;     if (kscale) { s0 = *(const f32x4*)(kscale + k0 + 8 * c); s1 = *(const f32x4*)(kscale + k0 + 8 * c + 4); }
;     const float* src = W + (size_t)(k0 + (lane >> 5)) * N + n0 + (lane & 31);
;     float w[32];
; #pragma unroll
;     for (int i = 0; i < 32; ++i) w[i] = __builtin_nontemporal_load(src + (size_t)(2 * i) * N);
; #pragma unroll
;     for (int i = 0; i < 32; ++i) scr[(2 * i + (lane >> 5)) * 33 + (lane & 31)] = w[i];
; __device__ __forceinline__ void prep_weights(Frame& F, const Args& a, int l, int it_lo, int it_hi, int gw, int ngw) {
;     ...
;         if (r < I6) { const int kb = r / 176, nb = r % 176; const int n0 = 32 * nb; const int j0 = n0 < FFN ? n0 : n0 - FFN; const int drow0 = 256 * (j0 / 128) + (n0 < FFN ? 0 : 128) + (j0 % 128);
;             transpose_item(w_fi, DM, FFN2, W + WO_FI, kb, nb, drow0, nffn, scr, F.lane); continue; } r -= I6;
.LBB0_1361:
	s_mulk_i32 s20, 0xb0
	s_sub_i32 s20, s18, s20
	s_lshl_b32 s18, s20, 5
	s_and_b32 s21, s20, 0xffff
	s_add_i32 s31, s18, 0xf500
	s_cmpk_lt_u32 s21, 0x58
	s_cselect_b32 s18, s18, s31
	s_sext_i32_i16 s21, s18
	s_cselect_b32 s31, 0, 0x80
	s_bfe_u32 s21, s21, 0x70018
	s_add_i32 s21, s18, s21
	s_sext_i32_i16 s34, s21
	s_and_b32 s21, s21, 0xff80
	s_sub_i32 s18, s18, s21
	s_and_b32 s21, 0xffff, s19
	v_or_b32_e32 v0, s21, v11
	v_mul_u32_u24_e32 v0, 0x5800, v0
	s_lshl_b32 s20, s20, 7
	v_lshl_add_u64 v[32:33], s[14:15], 0, v[0:1]
	s_and_b32 s72, s20, 0x3ff80
	v_lshl_add_u64 v[32:33], v[32:33], 0, s[72:73]
	v_lshlrev_b32_e32 v0, 2, v10
	v_lshl_add_u64 v[32:33], v[32:33], 0, v[0:1]
	s_mov_b32 s20, 0xb000
	v_add_co_u32_e32 v40, vcc, s20, v32
	s_mov_b32 s20, 0x16000
	s_nop 0
	v_addc_co_u32_e32 v41, vcc, 0, v33, vcc
	global_load_dword v0, v[32:33], off nt
	global_load_dword v42, v[40:41], off nt
	v_add_co_u32_e32 v40, vcc, s20, v32
	s_mov_b32 s20, 0x21000
	s_nop 0
	v_addc_co_u32_e32 v41, vcc, 0, v33, vcc
	global_load_dword v43, v[40:41], off nt
	v_add_co_u32_e32 v40, vcc, s20, v32
	s_mov_b32 s20, 0x2c000
	s_nop 0
	v_addc_co_u32_e32 v41, vcc, 0, v33, vcc
	global_load_dword v44, v[40:41], off nt
	v_add_co_u32_e32 v40, vcc, s20, v32
	s_mov_b32 s20, 0x37000
	s_nop 0
	v_addc_co_u32_e32 v41, vcc, 0, v33, vcc
	global_load_dword v45, v[40:41], off nt
	v_add_co_u32_e32 v40, vcc, s20, v32
	s_mov_b32 s20, 0x42000
	s_nop 0
	v_addc_co_u32_e32 v41, vcc, 0, v33, vcc
	global_load_dword v46, v[40:41], off nt
	v_add_co_u32_e32 v40, vcc, s20, v32
	s_mov_b32 s20, 0x4d000
	s_nop 0
	v_addc_co_u32_e32 v41, vcc, 0, v33, vcc
	global_load_dword v47, v[40:41], off nt
	v_add_co_u32_e32 v40, vcc, s20, v32
	s_mov_b32 s20, 0x58000
	s_nop 0
	v_addc_co_u32_e32 v41, vcc, 0, v33, vcc
	global_load_dword v48, v[40:41], off nt
	v_add_co_u32_e32 v40, vcc, s20, v32
	s_mov_b32 s20, 0x63000
	s_nop 0
	v_addc_co_u32_e32 v41, vcc, 0, v33, vcc
	global_load_dword v49, v[40:41], off nt
	v_add_co_u32_e32 v40, vcc, s20, v32
	s_mov_b32 s20, 0x6e000
	s_nop 0
	v_addc_co_u32_e32 v41, vcc, 0, v33, vcc
	global_load_dword v50, v[40:41], off nt
	v_add_co_u32_e32 v40, vcc, s20, v32
	s_mov_b32 s20, 0x79000
	s_nop 0
	v_addc_co_u32_e32 v41, vcc, 0, v33, vcc
	global_load_dword v51, v[40:41], off nt
	v_add_co_u32_e32 v40, vcc, s20, v32
	s_mov_b32 s20, 0x84000
	s_nop 0
	v_addc_co_u32_e32 v41, vcc, 0, v33, vcc
	global_load_dword v52, v[40:41], off nt
	v_add_co_u32_e32 v40, vcc, s20, v32
	s_mov_b32 s20, 0x8f000
	s_nop 0
	v_addc_co_u32_e32 v41, vcc, 0, v33, vcc
	global_load_dword v53, v[40:41], off nt
	v_add_co_u32_e32 v40, vcc, s20, v32
	s_mov_b32 s20, 0x9a000
	s_nop 0
	v_addc_co_u32_e32 v41, vcc, 0, v33, vcc
	global_load_dword v54, v[40:41], off nt
	v_add_co_u32_e32 v40, vcc, s20, v32
	s_mov_b32 s20, 0xa5000
	s_nop 0
	v_addc_co_u32_e32 v41, vcc, 0, v33, vcc
	global_load_dword v55, v[40:41], off nt
	v_add_co_u32_e32 v40, vcc, s20, v32
	s_mov_b32 s20, 0xb0000
	s_nop 0
	v_addc_co_u32_e32 v41, vcc, 0, v33, vcc
	global_load_dword v56, v[40:41], off nt
	v_add_co_u32_e32 v40, vcc, s20, v32
	s_mov_b32 s20, 0xbb000
	s_nop 0
	v_addc_co_u32_e32 v41, vcc, 0, v33, vcc
	global_load_dword v57, v[40:41], off nt
	v_add_co_u32_e32 v40, vcc, s20, v32
	s_mov_b32 s20, 0xc6000
	s_nop 0
	v_addc_co_u32_e32 v41, vcc, 0, v33, vcc
	global_load_dword v58, v[40:41], off nt
	v_add_co_u32_e32 v40, vcc, s20, v32
	s_mov_b32 s20, 0xd1000
	s_nop 0
	v_addc_co_u32_e32 v41, vcc, 0, v33, vcc
	global_load_dword v59, v[40:41], off nt
	v_add_co_u32_e32 v40, vcc, s20, v32
	s_mov_b32 s20, 0xdc000
	s_nop 0
	v_addc_co_u32_e32 v41, vcc, 0, v33, vcc
	global_load_dword v60, v[40:41], off nt
	v_add_co_u32_e32 v40, vcc, s20, v32
	s_mov_b32 s20, 0xe7000
	s_nop 0
	v_addc_co_u32_e32 v41, vcc, 0, v33, vcc
	global_load_dword v61, v[40:41], off nt
	v_add_co_u32_e32 v40, vcc, s20, v32
	s_mov_b32 s20, 0xf2000
	s_nop 0
	v_addc_co_u32_e32 v41, vcc, 0, v33, vcc
	global_load_dword v62, v[40:41], off nt
	v_add_co_u32_e32 v40, vcc, s20, v32
	s_mov_b32 s20, 0xfd000
	s_nop 0
	v_addc_co_u32_e32 v41, vcc, 0, v33, vcc
	global_load_dword v63, v[40:41], off nt
	v_add_co_u32_e32 v40, vcc, s20, v32
	s_mov_b32 s20, 0x108000
	s_nop 0
	v_addc_co_u32_e32 v41, vcc, 0, v33, vcc
	global_load_dword v64, v[40:41], off nt
	v_add_co_u32_e32 v40, vcc, s20, v32
	s_mov_b32 s20, 0x113000
	s_nop 0
	v_addc_co_u32_e32 v41, vcc, 0, v33, vcc
	global_load_dword v65, v[40:41], off nt
	v_add_co_u32_e32 v40, vcc, s20, v32
	s_mov_b32 s20, 0x11e000
	s_nop 0
	v_addc_co_u32_e32 v41, vcc, 0, v33, vcc
	global_load_dword v66, v[40:41], off nt
	v_add_co_u32_e32 v40, vcc, s20, v32
	s_mov_b32 s20, 0x129000
	s_nop 0
	v_addc_co_u32_e32 v41, vcc, 0, v33, vcc
	global_load_dword v67, v[40:41], off nt
	v_add_co_u32_e32 v40, vcc, s20, v32
	s_mov_b32 s20, 0x134000
	s_nop 0
	v_addc_co_u32_e32 v41, vcc, 0, v33, vcc
	global_load_dword v68, v[40:41], off nt
	v_add_co_u32_e32 v40, vcc, s20, v32
	s_mov_b32 s20, 0x13f000
	s_nop 0
	v_addc_co_u32_e32 v41, vcc, 0, v33, vcc
	global_load_dword v69, v[40:41], off nt
	v_add_co_u32_e32 v40, vcc, s20, v32
	s_mov_b32 s20, 0x14a000
	s_nop 0
	v_addc_co_u32_e32 v41, vcc, 0, v33, vcc
	global_load_dword v70, v[40:41], off nt
	v_add_co_u32_e32 v40, vcc, s20, v32
	s_mov_b32 s20, 0x155000
	s_nop 0
	v_addc_co_u32_e32 v41, vcc, 0, v33, vcc
	v_add_co_u32_e32 v32, vcc, s20, v32
	global_load_dword v40, v[40:41], off nt
	s_nop 0
	v_addc_co_u32_e32 v33, vcc, 0, v33, vcc
	global_load_dword v32, v[32:33], off nt
	s_waitcnt vmcnt(30)
; #define LAS __attribute__((address_space(3)))
; __device__ __forceinline__ unsigned pk2(float lo, float hi) { const f32x2 v = {lo, hi}; const bf16x2_hw b = __builtin_convertvector(v, bf16x2_hw); return __builtin_bit_cast(unsigned, b); }
; __device__ __forceinline__ void gst_wt16(void* p, const u32x4 v) { asm volatile("global_store_dwordx4 %0, %1, off sc1\n\ts_nop 1" :: "v"(p), "v"(v) : "memory"); }
; __device__ __forceinline__ void transpose_item(const float* W, int K, int N, bf16_t* WT, int kb, int nb, int drow0, const float* kscale, LAS float* scr, int lane) {
;     ...
;     for (int i = 0; i < 32; ++i) scr[(2 * i + (lane >> 5)) * 33 + (lane & 31)] = w[i];
;     asm volatile("s_waitcnt lgkmcnt(0)" ::: "memory");
; #pragma unroll
;     for (int j = 0; j < 4; ++j) { const int n = (lane >> 3) + 8 * j; const LAS float* s = scr + (8 * c) * 33 + n;
;         u32x4 o; o.x = pk2(s[0 * 33] * s0[0], s[1 * 33] * s0[1]); o.y = pk2(s[2 * 33] * s0[2], s[3 * 33] * s0[3]); o.z = pk2(s[4 * 33] * s1[0], s[5 * 33] * s1[1]); o.w = pk2(s[6 * 33] * s1[2], s[7 * 33] * s1[3]);
;         gst_wt16(WT + (size_t)(drow0 + n) * K + k0 + 8 * c, o); }
;     asm volatile("s_waitcnt lgkmcnt(0)" ::: "memory");
	ds_write2_b32 v34, v0, v42 offset1:66
	s_waitcnt vmcnt(28)
	ds_write2_b32 v34, v43, v44 offset0:132 offset1:198
	v_add_u32_e32 v0, 0x400, v34
	s_waitcnt vmcnt(26)
	ds_write2_b32 v0, v45, v46 offset0:8 offset1:74
	s_waitcnt vmcnt(24)
	ds_write2_b32 v0, v47, v48 offset0:140 offset1:206
	v_add_u32_e32 v0, 0x800, v34
	s_waitcnt vmcnt(22)
	ds_write2_b32 v0, v49, v50 offset0:16 offset1:82
	s_waitcnt vmcnt(20)
	ds_write2_b32 v0, v51, v52 offset0:148 offset1:214
	v_add_u32_e32 v0, 0xc00, v34
	s_waitcnt vmcnt(18)
	ds_write2_b32 v0, v53, v54 offset0:24 offset1:90
	s_waitcnt vmcnt(16)
	ds_write2_b32 v0, v55, v56 offset0:156 offset1:222
	v_add_u32_e32 v0, 0x1000, v34
	s_waitcnt vmcnt(14)
	ds_write2_b32 v0, v57, v58 offset0:32 offset1:98
	s_waitcnt vmcnt(12)
	ds_write2_b32 v0, v59, v60 offset0:164 offset1:230
	v_add_u32_e32 v0, 0x1400, v34
	s_waitcnt vmcnt(10)
	ds_write2_b32 v0, v61, v62 offset0:40 offset1:106
	s_waitcnt vmcnt(8)
	ds_write2_b32 v0, v63, v64 offset0:172 offset1:238
	v_add_u32_e32 v0, 0x1800, v34
	s_waitcnt vmcnt(6)
	ds_write2_b32 v0, v65, v66 offset0:48 offset1:114
	s_waitcnt vmcnt(4)
	ds_write2_b32 v0, v67, v68 offset0:180 offset1:246
	v_add_u32_e32 v0, 0x1c00, v34
	s_waitcnt vmcnt(2)
	ds_write2_b32 v0, v69, v70 offset0:56 offset1:122
	s_waitcnt vmcnt(0)
	ds_write2_b32 v0, v40, v32 offset0:188 offset1:254
	s_waitcnt lgkmcnt(0)
	ds_read2_b32 v[40:41], v36 offset1:33
	ds_read2_b32 v[42:43], v36 offset0:66 offset1:99
	ds_read2_b32 v[44:45], v36 offset0:198 offset1:231
	s_lshl_b32 s34, s34, 1
	s_sext_i32_i16 s18, s18
	s_waitcnt lgkmcnt(2)
	v_pk_mul_f32 v[40:41], v[6:7], v[40:41]
	s_waitcnt lgkmcnt(1)
	v_pk_mul_f32 v[42:43], v[8:9], v[42:43]
	v_cvt_pk_bf16_f32 v40, v40, v41
	v_cvt_pk_bf16_f32 v41, v42, v43
	ds_read2_b32 v[42:43], v36 offset0:132 offset1:165
	s_and_b32 s34, s34, 0xffffff00
	s_add_i32 s18, s31, s18
	s_add_i32 s18, s18, s34
	s_waitcnt lgkmcnt(1)
	v_pk_mul_f32 v[44:45], v[4:5], v[44:45]
	s_waitcnt lgkmcnt(0)
	v_pk_mul_f32 v[42:43], v[2:3], v[42:43]
	s_lshl_b32 s72, s19, 1
	v_cvt_pk_bf16_f32 v42, v42, v43
	v_cvt_pk_bf16_f32 v43, v44, v45
	v_add_u32_e32 v44, s18, v35
	v_ashrrev_i32_e32 v45, 31, v44
	v_lshl_add_u64 v[32:33], v[30:31], 0, s[72:73]
	v_lshlrev_b64 v[44:45], 11, v[44:45]
	v_lshl_add_u64 v[44:45], v[32:33], 0, v[44:45]
	global_store_dwordx4 v[44:45], v[40:43], off sc1 nt
	s_nop 1
	ds_read2_b32 v[40:41], v36 offset0:8 offset1:41
	ds_read2_b32 v[42:43], v36 offset0:74 offset1:107
	ds_read2_b32 v[44:45], v36 offset0:206 offset1:239
	s_waitcnt lgkmcnt(2)
	v_pk_mul_f32 v[40:41], v[6:7], v[40:41]
	s_waitcnt lgkmcnt(1)
	v_pk_mul_f32 v[42:43], v[8:9], v[42:43]
	v_cvt_pk_bf16_f32 v40, v40, v41
	v_cvt_pk_bf16_f32 v41, v42, v43
	ds_read2_b32 v[42:43], v36 offset0:140 offset1:173
	s_waitcnt lgkmcnt(1)
	v_pk_mul_f32 v[44:45], v[4:5], v[44:45]
	s_waitcnt lgkmcnt(0)
	v_pk_mul_f32 v[42:43], v[2:3], v[42:43]
	s_nop 0
	v_cvt_pk_bf16_f32 v42, v42, v43
	v_cvt_pk_bf16_f32 v43, v44, v45
	v_add_u32_e32 v44, s18, v37
	v_ashrrev_i32_e32 v45, 31, v44
	v_lshlrev_b64 v[44:45], 11, v[44:45]
	v_lshl_add_u64 v[44:45], v[32:33], 0, v[44:45]
	global_store_dwordx4 v[44:45], v[40:43], off sc1 nt
	s_nop 1
	ds_read2_b32 v[40:41], v36 offset0:16 offset1:49
	ds_read2_b32 v[42:43], v36 offset0:82 offset1:115
	ds_read2_b32 v[44:45], v36 offset0:214 offset1:247
	s_waitcnt lgkmcnt(2)
	v_pk_mul_f32 v[40:41], v[6:7], v[40:41]
	s_waitcnt lgkmcnt(1)
	v_pk_mul_f32 v[42:43], v[8:9], v[42:43]
	v_cvt_pk_bf16_f32 v40, v40, v41
	v_cvt_pk_bf16_f32 v41, v42, v43
	ds_read2_b32 v[42:43], v36 offset0:148 offset1:181
	s_waitcnt lgkmcnt(1)
	v_pk_mul_f32 v[44:45], v[4:5], v[44:45]
	s_waitcnt lgkmcnt(0)
	v_pk_mul_f32 v[42:43], v[2:3], v[42:43]
	s_nop 0
	v_cvt_pk_bf16_f32 v42, v42, v43
	v_cvt_pk_bf16_f32 v43, v44, v45
	v_add_u32_e32 v44, s18, v38
	v_ashrrev_i32_e32 v45, 31, v44
	v_lshlrev_b64 v[44:45], 11, v[44:45]
	v_lshl_add_u64 v[44:45], v[32:33], 0, v[44:45]
	global_store_dwordx4 v[44:45], v[40:43], off sc1 nt
	s_nop 1
	ds_read2_b32 v[40:41], v36 offset0:24 offset1:57
	s_waitcnt lgkmcnt(0)
	v_pk_mul_f32 v[6:7], v[6:7], v[40:41]
	ds_read2_b32 v[40:41], v36 offset0:90 offset1:123
	v_cvt_pk_bf16_f32 v6, v6, v7
	s_waitcnt lgkmcnt(0)
	v_pk_mul_f32 v[8:9], v[8:9], v[40:41]
	s_nop 0
	v_cvt_pk_bf16_f32 v7, v8, v9
	ds_read2_b32 v[8:9], v36 offset0:156 offset1:189
	s_waitcnt lgkmcnt(0)
	v_pk_mul_f32 v[2:3], v[2:3], v[8:9]
	s_nop 0
	v_cvt_pk_bf16_f32 v8, v2, v3
	ds_read2_b32 v[2:3], v36 offset0:222 offset1:255
	s_waitcnt lgkmcnt(0)
	v_pk_mul_f32 v[2:3], v[4:5], v[2:3]
	s_nop 0
	v_cvt_pk_bf16_f32 v9, v2, v3
	v_add_u32_e32 v2, s18, v39
	v_ashrrev_i32_e32 v3, 31, v2
	v_lshlrev_b64 v[2:3], 11, v[2:3]
	v_lshl_add_u64 v[2:3], v[32:33], 0, v[2:3]
	global_store_dwordx4 v[2:3], v[6:9], off sc1 nt
	s_nop 1
	s_waitcnt lgkmcnt(0)

; __device__ __forceinline__ void transpose_item(const float* W, int K, int N, bf16_t* WT, int kb, int nb, int drow0, const float* kscale, LAS float* scr, int lane) {
;     const int k0 = 64 * kb, n0 = 32 * nb, c = lane & 7;
;     f32x4 s0 = {1.f, 1.f, 1.f, 1.f}, s1 = {1.f, 1.f, 1.f, 1.f};
;     if (kscale) { s0 = *(const f32x4*)(kscale + k0 + 8 * c); s1 = *(const f32x4*)(kscale + k0 + 8 * c + 4); }
;     const float* src = W + (size_t)(k0 + (lane >> 5)) * N + n0 + (lane & 31);
;     float w[32];
; #pragma unroll
;     for (int i = 0; i < 32; ++i) w[i] = __builtin_nontemporal_load(src + (size_t)(2 * i) * N);
; __device__ __forceinline__ void prep_weights(Frame& F, const Args& a, int l, int it_lo, int it_hi, int gw, int ngw) {
;     ...
;         if (r < I5) { const int kb = r / 32, nb = r % 32; transpose_item(w_mx, DM, DM, W + WO_MIX, kb, nb, 32 * nb, nullptr, scr, F.lane); continue; } r -= I5;
.LBB0_1363:
	s_andn2_b64 vcc, exec, s[18:19]
	s_cbranch_vccnz .LBB0_1365
	s_and_b32 s19, s27, 0x3fc0
	s_add_i32 s72, s19, 0xffffe200
	v_or_b32_e32 v0, s72, v11
	s_and_b32 s18, s1, 0x3e0
	v_lshlrev_b64 v[2:3], 12, v[0:1]
	v_lshl_add_u64 v[2:3], s[12:13], 0, v[2:3]
	s_lshl_b32 s20, s18, 2
	s_mov_b32 s21, s73
	v_lshl_add_u64 v[2:3], v[2:3], 0, s[20:21]
	v_lshlrev_b32_e32 v0, 2, v10
	v_lshl_add_u64 v[2:3], v[2:3], 0, v[0:1]
	s_movk_i32 s19, 0x2000
	v_add_co_u32_e32 v4, vcc, s19, v2
	s_movk_i32 s19, 0x4000
	s_nop 0
	v_addc_co_u32_e32 v5, vcc, 0, v3, vcc
	global_load_dword v0, v[2:3], off nt
	global_load_dword v6, v[4:5], off nt
	v_add_co_u32_e32 v4, vcc, s19, v2
	s_movk_i32 s19, 0x6000
	s_nop 0
	v_addc_co_u32_e32 v5, vcc, 0, v3, vcc
	global_load_dword v7, v[4:5], off nt
	v_add_co_u32_e32 v4, vcc, s19, v2
	s_mov_b32 s19, 0x8000
	s_nop 0
	v_addc_co_u32_e32 v5, vcc, 0, v3, vcc
	global_load_dword v8, v[4:5], off nt
	v_add_co_u32_e32 v4, vcc, s19, v2
	s_mov_b32 s19, 0xa000
	s_nop 0
	v_addc_co_u32_e32 v5, vcc, 0, v3, vcc
	global_load_dword v9, v[4:5], off nt
	v_add_co_u32_e32 v4, vcc, s19, v2
	s_mov_b32 s19, 0xc000
	s_nop 0
	v_addc_co_u32_e32 v5, vcc, 0, v3, vcc
	global_load_dword v32, v[4:5], off nt
	v_add_co_u32_e32 v4, vcc, s19, v2
	s_mov_b32 s19, 0xe000
	s_nop 0
	v_addc_co_u32_e32 v5, vcc, 0, v3, vcc
	global_load_dword v33, v[4:5], off nt
	v_add_co_u32_e32 v4, vcc, s19, v2
	s_mov_b32 s19, 0x10000
	s_nop 0
	v_addc_co_u32_e32 v5, vcc, 0, v3, vcc
	global_load_dword v40, v[4:5], off nt
	v_add_co_u32_e32 v4, vcc, s19, v2
	s_mov_b32 s19, 0x12000
	s_nop 0
	v_addc_co_u32_e32 v5, vcc, 0, v3, vcc
	global_load_dword v41, v[4:5], off nt
	v_add_co_u32_e32 v4, vcc, s19, v2
	s_mov_b32 s19, 0x14000
	s_nop 0
	v_addc_co_u32_e32 v5, vcc, 0, v3, vcc
	global_load_dword v42, v[4:5], off nt
	v_add_co_u32_e32 v4, vcc, s19, v2
	s_mov_b32 s19, 0x16000
	s_nop 0
	v_addc_co_u32_e32 v5, vcc, 0, v3, vcc
	global_load_dword v43, v[4:5], off nt
	v_add_co_u32_e32 v4, vcc, s19, v2
	s_mov_b32 s19, 0x18000
	s_nop 0
	v_addc_co_u32_e32 v5, vcc, 0, v3, vcc
	global_load_dword v44, v[4:5], off nt
	v_add_co_u32_e32 v4, vcc, s19, v2
	s_mov_b32 s19, 0x1a000
	s_nop 0
	v_addc_co_u32_e32 v5, vcc, 0, v3, vcc
	global_load_dword v45, v[4:5], off nt
	v_add_co_u32_e32 v4, vcc, s19, v2
	s_mov_b32 s19, 0x1c000
	s_nop 0
	v_addc_co_u32_e32 v5, vcc, 0, v3, vcc
	global_load_dword v46, v[4:5], off nt
	v_add_co_u32_e32 v4, vcc, s19, v2
	s_mov_b32 s19, 0x1e000
	s_nop 0
	v_addc_co_u32_e32 v5, vcc, 0, v3, vcc
	global_load_dword v47, v[4:5], off nt
	v_add_co_u32_e32 v4, vcc, s19, v2
	s_mov_b32 s19, 0x22000
	s_nop 0
	v_addc_co_u32_e32 v5, vcc, 0, v3, vcc
	global_load_dword v48, v[4:5], off nt
	v_add_co_u32_e32 v4, vcc, s79, v2
	s_nop 1
	v_addc_co_u32_e32 v5, vcc, 0, v3, vcc
	global_load_dword v49, v[4:5], off nt
	v_add_co_u32_e32 v4, vcc, s19, v2
	s_mov_b32 s19, 0x24000
	s_nop 0
	v_addc_co_u32_e32 v5, vcc, 0, v3, vcc
	global_load_dword v50, v[4:5], off nt
	v_add_co_u32_e32 v4, vcc, s19, v2
	s_mov_b32 s19, 0x26000
	s_nop 0
	v_addc_co_u32_e32 v5, vcc, 0, v3, vcc
	global_load_dword v51, v[4:5], off nt
	v_add_co_u32_e32 v4, vcc, s19, v2
	s_mov_b32 s19, 0x28000
	s_nop 0
	v_addc_co_u32_e32 v5, vcc, 0, v3, vcc
	global_load_dword v52, v[4:5], off nt
	v_add_co_u32_e32 v4, vcc, s19, v2
	s_mov_b32 s19, 0x2a000
	s_nop 0
	v_addc_co_u32_e32 v5, vcc, 0, v3, vcc
	global_load_dword v53, v[4:5], off nt
	v_add_co_u32_e32 v4, vcc, s19, v2
	s_mov_b32 s19, 0x2c000
	s_nop 0
	v_addc_co_u32_e32 v5, vcc, 0, v3, vcc
	global_load_dword v54, v[4:5], off nt
	v_add_co_u32_e32 v4, vcc, s19, v2
	s_mov_b32 s19, 0x2e000
	s_nop 0
	v_addc_co_u32_e32 v5, vcc, 0, v3, vcc
	global_load_dword v55, v[4:5], off nt
	v_add_co_u32_e32 v4, vcc, s19, v2
	s_mov_b32 s19, 0x30000
	s_nop 0
	v_addc_co_u32_e32 v5, vcc, 0, v3, vcc
	global_load_dword v56, v[4:5], off nt
	v_add_co_u32_e32 v4, vcc, s19, v2
	s_mov_b32 s19, 0x32000
	s_nop 0
	v_addc_co_u32_e32 v5, vcc, 0, v3, vcc
	global_load_dword v57, v[4:5], off nt
	v_add_co_u32_e32 v4, vcc, s19, v2
	s_mov_b32 s19, 0x34000
	s_nop 0
	v_addc_co_u32_e32 v5, vcc, 0, v3, vcc
	global_load_dword v58, v[4:5], off nt
	v_add_co_u32_e32 v4, vcc, s19, v2
	s_mov_b32 s19, 0x36000
	s_nop 0
	v_addc_co_u32_e32 v5, vcc, 0, v3, vcc
	global_load_dword v59, v[4:5], off nt
	v_add_co_u32_e32 v4, vcc, s19, v2
	s_mov_b32 s19, 0x38000
	s_nop 0
	v_addc_co_u32_e32 v5, vcc, 0, v3, vcc
	global_load_dword v60, v[4:5], off nt
	v_add_co_u32_e32 v4, vcc, s19, v2
	s_mov_b32 s19, 0x3a000
	s_nop 0
	v_addc_co_u32_e32 v5, vcc, 0, v3, vcc
	global_load_dword v61, v[4:5], off nt
	v_add_co_u32_e32 v4, vcc, s19, v2
	s_mov_b32 s19, 0x3c000
	s_nop 0
	v_addc_co_u32_e32 v5, vcc, 0, v3, vcc
	global_load_dword v62, v[4:5], off nt
	v_add_co_u32_e32 v4, vcc, s19, v2
	s_mov_b32 s19, 0x3e000
	s_nop 0
	v_addc_co_u32_e32 v5, vcc, 0, v3, vcc
	v_add_co_u32_e32 v2, vcc, s19, v2
	global_load_dword v4, v[4:5], off nt
	s_nop 0
	v_addc_co_u32_e32 v3, vcc, 0, v3, vcc
	global_load_dword v2, v[2:3], off nt
	s_waitcnt vmcnt(30)
; #define LAS __attribute__((address_space(3)))
; __device__ __forceinline__ unsigned pk2(float lo, float hi) { const f32x2 v = {lo, hi}; const bf16x2_hw b = __builtin_convertvector(v, bf16x2_hw); return __builtin_bit_cast(unsigned, b); }
; __device__ __forceinline__ void gst_wt16(void* p, const u32x4 v) { asm volatile("global_store_dwordx4 %0, %1, off sc1\n\ts_nop 1" :: "v"(p), "v"(v) : "memory"); }
; __device__ __forceinline__ void transpose_item(const float* W, int K, int N, bf16_t* WT, int kb, int nb, int drow0, const float* kscale, LAS float* scr, int lane) {
;     ...
;     for (int i = 0; i < 32; ++i) scr[(2 * i + (lane >> 5)) * 33 + (lane & 31)] = w[i];
;     asm volatile("s_waitcnt lgkmcnt(0)" ::: "memory");
; #pragma unroll
;     for (int j = 0; j < 4; ++j) { const int n = (lane >> 3) + 8 * j; const LAS float* s = scr + (8 * c) * 33 + n;
;         u32x4 o; o.x = pk2(s[0 * 33] * s0[0], s[1 * 33] * s0[1]); o.y = pk2(s[2 * 33] * s0[2], s[3 * 33] * s0[3]); o.z = pk2(s[4 * 33] * s1[0], s[5 * 33] * s1[1]); o.w = pk2(s[6 * 33] * s1[2], s[7 * 33] * s1[3]);
;         gst_wt16(WT + (size_t)(drow0 + n) * K + k0 + 8 * c, o); }
;     asm volatile("s_waitcnt lgkmcnt(0)" ::: "memory");
	ds_write2_b32 v34, v0, v6 offset1:66
	s_waitcnt vmcnt(28)
	ds_write2_b32 v34, v7, v8 offset0:132 offset1:198
	v_add_u32_e32 v0, 0x400, v34
	s_waitcnt vmcnt(26)
	ds_write2_b32 v0, v9, v32 offset0:8 offset1:74
	s_waitcnt vmcnt(24)
	ds_write2_b32 v0, v33, v40 offset0:140 offset1:206
	v_add_u32_e32 v0, 0x800, v34
	s_waitcnt vmcnt(22)
	ds_write2_b32 v0, v41, v42 offset0:16 offset1:82
	s_waitcnt vmcnt(20)
	ds_write2_b32 v0, v43, v44 offset0:148 offset1:214
	v_add_u32_e32 v0, 0xc00, v34
	s_waitcnt vmcnt(18)
	ds_write2_b32 v0, v45, v46 offset0:24 offset1:90
	s_waitcnt vmcnt(16)
	ds_write2_b32 v0, v47, v48 offset0:156 offset1:222
	v_add_u32_e32 v0, 0x1000, v34
	s_waitcnt vmcnt(14)
	ds_write2_b32 v0, v49, v50 offset0:32 offset1:98
	s_waitcnt vmcnt(12)
	ds_write2_b32 v0, v51, v52 offset0:164 offset1:230
	v_add_u32_e32 v0, 0x1400, v34
	s_waitcnt vmcnt(10)
	ds_write2_b32 v0, v53, v54 offset0:40 offset1:106
	s_waitcnt vmcnt(8)
	ds_write2_b32 v0, v55, v56 offset0:172 offset1:238
	v_add_u32_e32 v0, 0x1800, v34
	s_waitcnt vmcnt(6)
	ds_write2_b32 v0, v57, v58 offset0:48 offset1:114
	s_waitcnt vmcnt(4)
	ds_write2_b32 v0, v59, v60 offset0:180 offset1:246
	v_add_u32_e32 v0, 0x1c00, v34
	s_waitcnt vmcnt(2)
	ds_write2_b32 v0, v61, v62 offset0:56 offset1:122
	s_waitcnt vmcnt(0)
	ds_write2_b32 v0, v4, v2 offset0:188 offset1:254
	s_waitcnt lgkmcnt(0)
	ds_read2_b32 v[2:3], v36 offset1:33
	ds_read2_b32 v[4:5], v36 offset0:66 offset1:99
	ds_read2_b32 v[8:9], v36 offset0:198 offset1:231
	v_or_b32_e32 v0, s18, v35
	v_lshl_add_u64 v[6:7], s[72:73], 1, v[18:19]
	s_waitcnt lgkmcnt(2)
	v_cvt_pk_bf16_f32 v2, v2, v3
	s_waitcnt lgkmcnt(1)
	v_cvt_pk_bf16_f32 v3, v4, v5
	ds_read2_b32 v[4:5], v36 offset0:132 offset1:165
	v_lshlrev_b32_e32 v0, 11, v0
	s_waitcnt lgkmcnt(0)
	v_cvt_pk_bf16_f32 v4, v4, v5
	v_cvt_pk_bf16_f32 v5, v8, v9
	v_lshl_add_u64 v[8:9], v[6:7], 0, v[0:1]
	global_store_dwordx4 v[8:9], v[2:5], off sc1 nt
	s_nop 1
	ds_read2_b32 v[2:3], v36 offset0:8 offset1:41
	ds_read2_b32 v[4:5], v36 offset0:74 offset1:107
	ds_read2_b32 v[8:9], v36 offset0:206 offset1:239
	v_or_b32_e32 v0, s18, v37
	v_lshlrev_b32_e32 v0, 11, v0
	s_waitcnt lgkmcnt(2)
	v_cvt_pk_bf16_f32 v2, v2, v3
	s_waitcnt lgkmcnt(1)
	v_cvt_pk_bf16_f32 v3, v4, v5
	ds_read2_b32 v[4:5], v36 offset0:140 offset1:173
	s_waitcnt lgkmcnt(0)
	v_cvt_pk_bf16_f32 v4, v4, v5
	v_cvt_pk_bf16_f32 v5, v8, v9
	v_lshl_add_u64 v[8:9], v[6:7], 0, v[0:1]
	global_store_dwordx4 v[8:9], v[2:5], off sc1 nt
	s_nop 1
	ds_read2_b32 v[2:3], v36 offset0:16 offset1:49
	ds_read2_b32 v[4:5], v36 offset0:82 offset1:115
	ds_read2_b32 v[8:9], v36 offset0:214 offset1:247
	v_or_b32_e32 v0, s18, v38
	v_lshlrev_b32_e32 v0, 11, v0
	s_waitcnt lgkmcnt(2)
	v_cvt_pk_bf16_f32 v2, v2, v3
	s_waitcnt lgkmcnt(1)
	v_cvt_pk_bf16_f32 v3, v4, v5
	ds_read2_b32 v[4:5], v36 offset0:148 offset1:181
	s_waitcnt lgkmcnt(0)
	v_cvt_pk_bf16_f32 v4, v4, v5
	v_cvt_pk_bf16_f32 v5, v8, v9
	v_lshl_add_u64 v[8:9], v[6:7], 0, v[0:1]
	global_store_dwordx4 v[8:9], v[2:5], off sc1 nt
	s_nop 1
	ds_read2_b32 v[2:3], v36 offset0:24 offset1:57
	ds_read2_b32 v[4:5], v36 offset0:90 offset1:123
	ds_read2_b32 v[8:9], v36 offset0:222 offset1:255
	v_or_b32_e32 v0, s18, v39
	v_lshlrev_b32_e32 v0, 11, v0
	s_waitcnt lgkmcnt(2)
	v_cvt_pk_bf16_f32 v2, v2, v3
	s_waitcnt lgkmcnt(1)
	v_cvt_pk_bf16_f32 v3, v4, v5
	ds_read2_b32 v[4:5], v36 offset0:156 offset1:189
	v_lshl_add_u64 v[6:7], v[6:7], 0, v[0:1]
	s_waitcnt lgkmcnt(0)
	v_cvt_pk_bf16_f32 v4, v4, v5
	v_cvt_pk_bf16_f32 v5, v8, v9
	global_store_dwordx4 v[6:7], v[2:5], off sc1 nt
	s_nop 1
	s_waitcnt lgkmcnt(0)

; __device__ __forceinline__ void transpose_item(const float* W, int K, int N, bf16_t* WT, int kb, int nb, int drow0, const float* kscale, LAS float* scr, int lane) {
;     const int k0 = 64 * kb, n0 = 32 * nb, c = lane & 7;
;     f32x4 s0 = {1.f, 1.f, 1.f, 1.f}, s1 = {1.f, 1.f, 1.f, 1.f};
;     if (kscale) { s0 = *(const f32x4*)(kscale + k0 + 8 * c); s1 = *(const f32x4*)(kscale + k0 + 8 * c + 4); }
;     const float* src = W + (size_t)(k0 + (lane >> 5)) * N + n0 + (lane & 31);
;     float w[32];
; #pragma unroll
;     for (int i = 0; i < 32; ++i) w[i] = __builtin_nontemporal_load(src + (size_t)(2 * i) * N);
; __device__ __forceinline__ void prep_weights(Frame& F, const Args& a, int l, int it_lo, int it_hi, int gw, int ngw) {
;     ...
;         if (r < I4) { const int kb = r / 32, nb = r % 32; transpose_item(w_so, 512, DM, W + WO_SO, kb, nb, 32 * nb, nullptr, scr, F.lane); continue; } r -= I4;
.LBB0_1366:
	s_andn2_b64 vcc, exec, s[18:19]
	s_cbranch_vccnz .LBB0_1368
	s_and_b32 s19, s27, 0x1fc0
	s_add_i32 s72, s19, 0xffffe400
	v_or_b32_e32 v0, s72, v11
	s_and_b32 s18, s1, 0x3e0
	v_lshlrev_b64 v[2:3], 12, v[0:1]
	v_lshl_add_u64 v[2:3], s[10:11], 0, v[2:3]
	s_lshl_b32 s20, s18, 2
	s_mov_b32 s21, s73
	v_lshl_add_u64 v[2:3], v[2:3], 0, s[20:21]
	v_lshlrev_b32_e32 v0, 2, v10
	v_lshl_add_u64 v[2:3], v[2:3], 0, v[0:1]
	s_movk_i32 s19, 0x2000
	v_add_co_u32_e32 v4, vcc, s19, v2
	s_movk_i32 s19, 0x4000
	s_nop 0
	v_addc_co_u32_e32 v5, vcc, 0, v3, vcc
	global_load_dword v0, v[2:3], off nt
	global_load_dword v6, v[4:5], off nt
	v_add_co_u32_e32 v4, vcc, s19, v2
	s_movk_i32 s19, 0x6000
	s_nop 0
	v_addc_co_u32_e32 v5, vcc, 0, v3, vcc
	global_load_dword v7, v[4:5], off nt
	v_add_co_u32_e32 v4, vcc, s19, v2
	s_mov_b32 s19, 0x8000
	s_nop 0
	v_addc_co_u32_e32 v5, vcc, 0, v3, vcc
	global_load_dword v8, v[4:5], off nt
	v_add_co_u32_e32 v4, vcc, s19, v2
	s_mov_b32 s19, 0xa000
	s_nop 0
	v_addc_co_u32_e32 v5, vcc, 0, v3, vcc
	global_load_dword v9, v[4:5], off nt
	v_add_co_u32_e32 v4, vcc, s19, v2
	s_mov_b32 s19, 0xc000
	s_nop 0
	v_addc_co_u32_e32 v5, vcc, 0, v3, vcc
	global_load_dword v32, v[4:5], off nt
	v_add_co_u32_e32 v4, vcc, s19, v2
	s_mov_b32 s19, 0xe000
	s_nop 0
	v_addc_co_u32_e32 v5, vcc, 0, v3, vcc
	global_load_dword v33, v[4:5], off nt
	v_add_co_u32_e32 v4, vcc, s19, v2
	s_mov_b32 s19, 0x10000
	s_nop 0
	v_addc_co_u32_e32 v5, vcc, 0, v3, vcc
	global_load_dword v40, v[4:5], off nt
	v_add_co_u32_e32 v4, vcc, s19, v2
	s_mov_b32 s19, 0x12000
	s_nop 0
	v_addc_co_u32_e32 v5, vcc, 0, v3, vcc
	global_load_dword v41, v[4:5], off nt
	v_add_co_u32_e32 v4, vcc, s19, v2
	s_mov_b32 s19, 0x14000
	s_nop 0
	v_addc_co_u32_e32 v5, vcc, 0, v3, vcc
	global_load_dword v42, v[4:5], off nt
	v_add_co_u32_e32 v4, vcc, s19, v2
	s_mov_b32 s19, 0x16000
	s_nop 0
	v_addc_co_u32_e32 v5, vcc, 0, v3, vcc
	global_load_dword v43, v[4:5], off nt
	v_add_co_u32_e32 v4, vcc, s19, v2
	s_mov_b32 s19, 0x18000
	s_nop 0
	v_addc_co_u32_e32 v5, vcc, 0, v3, vcc
	global_load_dword v44, v[4:5], off nt
	v_add_co_u32_e32 v4, vcc, s19, v2
	s_mov_b32 s19, 0x1a000
	s_nop 0
	v_addc_co_u32_e32 v5, vcc, 0, v3, vcc
	global_load_dword v45, v[4:5], off nt
	v_add_co_u32_e32 v4, vcc, s19, v2
	s_mov_b32 s19, 0x1c000
	s_nop 0
	v_addc_co_u32_e32 v5, vcc, 0, v3, vcc
	global_load_dword v46, v[4:5], off nt
	v_add_co_u32_e32 v4, vcc, s19, v2
	s_mov_b32 s19, 0x1e000
	s_nop 0
	v_addc_co_u32_e32 v5, vcc, 0, v3, vcc
	global_load_dword v47, v[4:5], off nt
	v_add_co_u32_e32 v4, vcc, s19, v2
	s_mov_b32 s19, 0x22000
	s_nop 0
	v_addc_co_u32_e32 v5, vcc, 0, v3, vcc
	global_load_dword v48, v[4:5], off nt
	v_add_co_u32_e32 v4, vcc, s79, v2
	s_nop 1
	v_addc_co_u32_e32 v5, vcc, 0, v3, vcc
	global_load_dword v49, v[4:5], off nt
	v_add_co_u32_e32 v4, vcc, s19, v2
	s_mov_b32 s19, 0x24000
	s_nop 0
	v_addc_co_u32_e32 v5, vcc, 0, v3, vcc
	global_load_dword v50, v[4:5], off nt
	v_add_co_u32_e32 v4, vcc, s19, v2
	s_mov_b32 s19, 0x26000
	s_nop 0
	v_addc_co_u32_e32 v5, vcc, 0, v3, vcc
	global_load_dword v51, v[4:5], off nt
	v_add_co_u32_e32 v4, vcc, s19, v2
	s_mov_b32 s19, 0x28000
	s_nop 0
	v_addc_co_u32_e32 v5, vcc, 0, v3, vcc
	global_load_dword v52, v[4:5], off nt
	v_add_co_u32_e32 v4, vcc, s19, v2
	s_mov_b32 s19, 0x2a000
	s_nop 0
	v_addc_co_u32_e32 v5, vcc, 0, v3, vcc
	global_load_dword v53, v[4:5], off nt
	v_add_co_u32_e32 v4, vcc, s19, v2
	s_mov_b32 s19, 0x2c000
	s_nop 0
	v_addc_co_u32_e32 v5, vcc, 0, v3, vcc
	global_load_dword v54, v[4:5], off nt
	v_add_co_u32_e32 v4, vcc, s19, v2
	s_mov_b32 s19, 0x2e000
	s_nop 0
	v_addc_co_u32_e32 v5, vcc, 0, v3, vcc
	global_load_dword v55, v[4:5], off nt
	v_add_co_u32_e32 v4, vcc, s19, v2
	s_mov_b32 s19, 0x30000
	s_nop 0
	v_addc_co_u32_e32 v5, vcc, 0, v3, vcc
	global_load_dword v56, v[4:5], off nt
	v_add_co_u32_e32 v4, vcc, s19, v2
	s_mov_b32 s19, 0x32000
	s_nop 0
	v_addc_co_u32_e32 v5, vcc, 0, v3, vcc
	global_load_dword v57, v[4:5], off nt
	v_add_co_u32_e32 v4, vcc, s19, v2
	s_mov_b32 s19, 0x34000
	s_nop 0
	v_addc_co_u32_e32 v5, vcc, 0, v3, vcc
	global_load_dword v58, v[4:5], off nt
	v_add_co_u32_e32 v4, vcc, s19, v2
	s_mov_b32 s19, 0x36000
	s_nop 0
	v_addc_co_u32_e32 v5, vcc, 0, v3, vcc
	global_load_dword v59, v[4:5], off nt
	v_add_co_u32_e32 v4, vcc, s19, v2
	s_mov_b32 s19, 0x38000
	s_nop 0
	v_addc_co_u32_e32 v5, vcc, 0, v3, vcc
	global_load_dword v60, v[4:5], off nt
	v_add_co_u32_e32 v4, vcc, s19, v2
	s_mov_b32 s19, 0x3a000
	s_nop 0
	v_addc_co_u32_e32 v5, vcc, 0, v3, vcc
	global_load_dword v61, v[4:5], off nt
	v_add_co_u32_e32 v4, vcc, s19, v2
	s_mov_b32 s19, 0x3c000
	s_nop 0
	v_addc_co_u32_e32 v5, vcc, 0, v3, vcc
	global_load_dword v62, v[4:5], off nt
	v_add_co_u32_e32 v4, vcc, s19, v2
	s_mov_b32 s19, 0x3e000
	s_nop 0
	v_addc_co_u32_e32 v5, vcc, 0, v3, vcc
	v_add_co_u32_e32 v2, vcc, s19, v2
	global_load_dword v4, v[4:5], off nt
	s_nop 0
	v_addc_co_u32_e32 v3, vcc, 0, v3, vcc
	global_load_dword v2, v[2:3], off nt
	s_waitcnt vmcnt(30)
; #define LAS __attribute__((address_space(3)))
; __device__ __forceinline__ unsigned pk2(float lo, float hi) { const f32x2 v = {lo, hi}; const bf16x2_hw b = __builtin_convertvector(v, bf16x2_hw); return __builtin_bit_cast(unsigned, b); }
; __device__ __forceinline__ void gst_wt16(void* p, const u32x4 v) { asm volatile("global_store_dwordx4 %0, %1, off sc1\n\ts_nop 1" :: "v"(p), "v"(v) : "memory"); }
; __device__ __forceinline__ void transpose_item(const float* W, int K, int N, bf16_t* WT, int kb, int nb, int drow0, const float* kscale, LAS float* scr, int lane) {
;     ...
;     for (int i = 0; i < 32; ++i) scr[(2 * i + (lane >> 5)) * 33 + (lane & 31)] = w[i];
;     asm volatile("s_waitcnt lgkmcnt(0)" ::: "memory");
; #pragma unroll
;     for (int j = 0; j < 4; ++j) { const int n = (lane >> 3) + 8 * j; const LAS float* s = scr + (8 * c) * 33 + n;
;         u32x4 o; o.x = pk2(s[0 * 33] * s0[0], s[1 * 33] * s0[1]); o.y = pk2(s[2 * 33] * s0[2], s[3 * 33] * s0[3]); o.z = pk2(s[4 * 33] * s1[0], s[5 * 33] * s1[1]); o.w = pk2(s[6 * 33] * s1[2], s[7 * 33] * s1[3]);
;         gst_wt16(WT + (size_t)(drow0 + n) * K + k0 + 8 * c, o); }
;     asm volatile("s_waitcnt lgkmcnt(0)" ::: "memory");
	ds_write2_b32 v34, v0, v6 offset1:66
	s_waitcnt vmcnt(28)
	ds_write2_b32 v34, v7, v8 offset0:132 offset1:198
	v_add_u32_e32 v0, 0x400, v34
	s_waitcnt vmcnt(26)
	ds_write2_b32 v0, v9, v32 offset0:8 offset1:74
	s_waitcnt vmcnt(24)
	ds_write2_b32 v0, v33, v40 offset0:140 offset1:206
	v_add_u32_e32 v0, 0x800, v34
	s_waitcnt vmcnt(22)
	ds_write2_b32 v0, v41, v42 offset0:16 offset1:82
	s_waitcnt vmcnt(20)
	ds_write2_b32 v0, v43, v44 offset0:148 offset1:214
	v_add_u32_e32 v0, 0xc00, v34
	s_waitcnt vmcnt(18)
	ds_write2_b32 v0, v45, v46 offset0:24 offset1:90
	s_waitcnt vmcnt(16)
	ds_write2_b32 v0, v47, v48 offset0:156 offset1:222
	v_add_u32_e32 v0, 0x1000, v34
	s_waitcnt vmcnt(14)
	ds_write2_b32 v0, v49, v50 offset0:32 offset1:98
	s_waitcnt vmcnt(12)
	ds_write2_b32 v0, v51, v52 offset0:164 offset1:230
	v_add_u32_e32 v0, 0x1400, v34
	s_waitcnt vmcnt(10)
	ds_write2_b32 v0, v53, v54 offset0:40 offset1:106
	s_waitcnt vmcnt(8)
	ds_write2_b32 v0, v55, v56 offset0:172 offset1:238
	v_add_u32_e32 v0, 0x1800, v34
	s_waitcnt vmcnt(6)
	ds_write2_b32 v0, v57, v58 offset0:48 offset1:114
	s_waitcnt vmcnt(4)
	ds_write2_b32 v0, v59, v60 offset0:180 offset1:246
	v_add_u32_e32 v0, 0x1c00, v34
	s_waitcnt vmcnt(2)
	ds_write2_b32 v0, v61, v62 offset0:56 offset1:122
	s_waitcnt vmcnt(0)
	ds_write2_b32 v0, v4, v2 offset0:188 offset1:254
	s_waitcnt lgkmcnt(0)
	ds_read2_b32 v[2:3], v36 offset1:33
	ds_read2_b32 v[4:5], v36 offset0:66 offset1:99
	ds_read2_b32 v[8:9], v36 offset0:198 offset1:231
	v_or_b32_e32 v0, s18, v35
	v_lshl_add_u64 v[6:7], s[72:73], 1, v[20:21]
	s_waitcnt lgkmcnt(2)
	v_cvt_pk_bf16_f32 v2, v2, v3
	s_waitcnt lgkmcnt(1)
	v_cvt_pk_bf16_f32 v3, v4, v5
	ds_read2_b32 v[4:5], v36 offset0:132 offset1:165
	v_lshlrev_b32_e32 v0, 10, v0
	s_waitcnt lgkmcnt(0)
	v_cvt_pk_bf16_f32 v4, v4, v5
	v_cvt_pk_bf16_f32 v5, v8, v9
	v_lshl_add_u64 v[8:9], v[6:7], 0, v[0:1]
	global_store_dwordx4 v[8:9], v[2:5], off sc1 nt
	s_nop 1
	ds_read2_b32 v[2:3], v36 offset0:8 offset1:41
	ds_read2_b32 v[4:5], v36 offset0:74 offset1:107
	ds_read2_b32 v[8:9], v36 offset0:206 offset1:239
	v_or_b32_e32 v0, s18, v37
	v_lshlrev_b32_e32 v0, 10, v0
	s_waitcnt lgkmcnt(2)
	v_cvt_pk_bf16_f32 v2, v2, v3
	s_waitcnt lgkmcnt(1)
	v_cvt_pk_bf16_f32 v3, v4, v5
	ds_read2_b32 v[4:5], v36 offset0:140 offset1:173
	s_waitcnt lgkmcnt(0)
	v_cvt_pk_bf16_f32 v4, v4, v5
	v_cvt_pk_bf16_f32 v5, v8, v9
	v_lshl_add_u64 v[8:9], v[6:7], 0, v[0:1]
	global_store_dwordx4 v[8:9], v[2:5], off sc1 nt
	s_nop 1
	ds_read2_b32 v[2:3], v36 offset0:16 offset1:49
	ds_read2_b32 v[4:5], v36 offset0:82 offset1:115
	ds_read2_b32 v[8:9], v36 offset0:214 offset1:247
	v_or_b32_e32 v0, s18, v38
	v_lshlrev_b32_e32 v0, 10, v0
	s_waitcnt lgkmcnt(2)
	v_cvt_pk_bf16_f32 v2, v2, v3
	s_waitcnt lgkmcnt(1)
	v_cvt_pk_bf16_f32 v3, v4, v5
	ds_read2_b32 v[4:5], v36 offset0:148 offset1:181
	s_waitcnt lgkmcnt(0)
	v_cvt_pk_bf16_f32 v4, v4, v5
	v_cvt_pk_bf16_f32 v5, v8, v9
	v_lshl_add_u64 v[8:9], v[6:7], 0, v[0:1]
	global_store_dwordx4 v[8:9], v[2:5], off sc1 nt
	s_nop 1
	ds_read2_b32 v[2:3], v36 offset0:24 offset1:57
	ds_read2_b32 v[4:5], v36 offset0:90 offset1:123
	ds_read2_b32 v[8:9], v36 offset0:222 offset1:255
	v_or_b32_e32 v0, s18, v39
	v_lshlrev_b32_e32 v0, 10, v0
	s_waitcnt lgkmcnt(2)
	v_cvt_pk_bf16_f32 v2, v2, v3
	s_waitcnt lgkmcnt(1)
	v_cvt_pk_bf16_f32 v3, v4, v5
	ds_read2_b32 v[4:5], v36 offset0:156 offset1:189
	v_lshl_add_u64 v[6:7], v[6:7], 0, v[0:1]
	s_waitcnt lgkmcnt(0)
	v_cvt_pk_bf16_f32 v4, v4, v5
	v_cvt_pk_bf16_f32 v5, v8, v9
	global_store_dwordx4 v[6:7], v[2:5], off sc1 nt
	s_nop 1
	s_waitcnt lgkmcnt(0)

; __device__ __forceinline__ void transpose_item(const float* W, int K, int N, bf16_t* WT, int kb, int nb, int drow0, const float* kscale, LAS float* scr, int lane) {
;     const int k0 = 64 * kb, n0 = 32 * nb, c = lane & 7;
;     f32x4 s0 = {1.f, 1.f, 1.f, 1.f}, s1 = {1.f, 1.f, 1.f, 1.f};
;     if (kscale) { s0 = *(const f32x4*)(kscale + k0 + 8 * c); s1 = *(const f32x4*)(kscale + k0 + 8 * c + 4); }
;     const float* src = W + (size_t)(k0 + (lane >> 5)) * N + n0 + (lane & 31);
;     float w[32];
; #pragma unroll
;     for (int i = 0; i < 32; ++i) w[i] = __builtin_nontemporal_load(src + (size_t)(2 * i) * N);
; __device__ __forceinline__ void prep_weights(Frame& F, const Args& a, int l, int it_lo, int it_hi, int gw, int ngw) {
;     ...
;         if (r < I3) { const int kb = r / 16, nb = r % 16; transpose_item(w_gl, 512, 512, W + WO_GLU, kb, nb, 32 * nb, nullptr, scr, F.lane); continue; } r -= I3;
.LBB0_1369:
	s_andn2_b64 vcc, exec, s[18:19]
	s_cbranch_vccnz .LBB0_1371
	s_and_b32 s19, s29, 0x3fc0
	s_add_i32 s72, s19, 0xffffca00
	v_or_b32_e32 v0, s72, v11
	s_and_b32 s18, s1, 0x1e0
	v_lshlrev_b64 v[2:3], 11, v[0:1]
	v_lshl_add_u64 v[2:3], s[8:9], 0, v[2:3]
	s_lshl_b32 s20, s18, 2
	s_mov_b32 s21, s73
	v_lshl_add_u64 v[2:3], v[2:3], 0, s[20:21]
	v_lshlrev_b32_e32 v0, 2, v10
	v_lshl_add_u64 v[2:3], v[2:3], 0, v[0:1]
	s_movk_i32 s19, 0x2000
	v_add_co_u32_e32 v4, vcc, s19, v2
	s_movk_i32 s19, 0x4000
	s_nop 0
	v_addc_co_u32_e32 v5, vcc, 0, v3, vcc
	global_load_dword v0, v[2:3], off nt
	global_load_dword v6, v[4:5], off offset:-4096 nt
	global_load_dword v7, v[4:5], off nt
	v_add_co_u32_e32 v4, vcc, s19, v2
	s_movk_i32 s19, 0x6000
	s_nop 0
	v_addc_co_u32_e32 v5, vcc, 0, v3, vcc
	global_load_dword v8, v[4:5], off offset:-4096 nt
	global_load_dword v9, v[4:5], off nt
	v_add_co_u32_e32 v4, vcc, s19, v2
	s_mov_b32 s19, 0x8000
	s_nop 0
	v_addc_co_u32_e32 v5, vcc, 0, v3, vcc
	global_load_dword v32, v[4:5], off offset:-4096 nt
	global_load_dword v33, v[4:5], off nt
	v_add_co_u32_e32 v4, vcc, s19, v2
	s_mov_b32 s19, 0xa000
	s_nop 0
	v_addc_co_u32_e32 v5, vcc, 0, v3, vcc
	global_load_dword v40, v[4:5], off offset:-4096 nt
	global_load_dword v41, v[4:5], off nt
	v_add_co_u32_e32 v4, vcc, s19, v2
	s_mov_b32 s19, 0xc000
	s_nop 0
	v_addc_co_u32_e32 v5, vcc, 0, v3, vcc
	global_load_dword v42, v[4:5], off offset:-4096 nt
	global_load_dword v43, v[4:5], off nt
	v_add_co_u32_e32 v4, vcc, s19, v2
	s_mov_b32 s19, 0xe000
	s_nop 0
	v_addc_co_u32_e32 v5, vcc, 0, v3, vcc
	global_load_dword v44, v[4:5], off offset:-4096 nt
	global_load_dword v45, v[4:5], off nt
	v_add_co_u32_e32 v4, vcc, s19, v2
	s_mov_b32 s19, 0x10000
	s_nop 0
	v_addc_co_u32_e32 v5, vcc, 0, v3, vcc
	global_load_dword v46, v[4:5], off offset:-4096 nt
	global_load_dword v47, v[4:5], off nt
	v_add_co_u32_e32 v4, vcc, s19, v2
	s_mov_b32 s19, 0x12000
	s_nop 0
	v_addc_co_u32_e32 v5, vcc, 0, v3, vcc
	global_load_dword v48, v[4:5], off offset:-4096 nt
	global_load_dword v49, v[4:5], off nt
	v_add_co_u32_e32 v4, vcc, s19, v2
	s_mov_b32 s19, 0x14000
	s_nop 0
	v_addc_co_u32_e32 v5, vcc, 0, v3, vcc
	global_load_dword v50, v[4:5], off offset:-4096 nt
	global_load_dword v51, v[4:5], off nt
	v_add_co_u32_e32 v4, vcc, s19, v2
	s_mov_b32 s19, 0x16000
	s_nop 0
	v_addc_co_u32_e32 v5, vcc, 0, v3, vcc
	global_load_dword v52, v[4:5], off offset:-4096 nt
	global_load_dword v53, v[4:5], off nt
	v_add_co_u32_e32 v4, vcc, s19, v2
	s_mov_b32 s19, 0x18000
	s_nop 0
	v_addc_co_u32_e32 v5, vcc, 0, v3, vcc
	global_load_dword v54, v[4:5], off offset:-4096 nt
	global_load_dword v55, v[4:5], off nt
	v_add_co_u32_e32 v4, vcc, s19, v2
	s_mov_b32 s19, 0x1a000
	s_nop 0
	v_addc_co_u32_e32 v5, vcc, 0, v3, vcc
	global_load_dword v56, v[4:5], off offset:-4096 nt
	global_load_dword v57, v[4:5], off nt
	v_add_co_u32_e32 v4, vcc, s19, v2
	s_mov_b32 s19, 0x1c000
	s_nop 0
	v_addc_co_u32_e32 v5, vcc, 0, v3, vcc
	global_load_dword v58, v[4:5], off offset:-4096 nt
	global_load_dword v59, v[4:5], off nt
	v_add_co_u32_e32 v4, vcc, s19, v2
	s_mov_b32 s19, 0x1e000
	s_nop 0
	v_addc_co_u32_e32 v5, vcc, 0, v3, vcc
	global_load_dword v60, v[4:5], off offset:-4096 nt
	global_load_dword v61, v[4:5], off nt
	v_add_co_u32_e32 v4, vcc, s19, v2
	s_mov_b32 s19, 0x1f000
	s_nop 0
	v_addc_co_u32_e32 v5, vcc, 0, v3, vcc
	v_add_co_u32_e32 v2, vcc, s19, v2
	global_load_dword v62, v[4:5], off offset:-4096 nt
	s_nop 0
	global_load_dword v4, v[4:5], off nt
	v_addc_co_u32_e32 v3, vcc, 0, v3, vcc
	global_load_dword v2, v[2:3], off nt
	s_waitcnt vmcnt(30)
; #define LAS __attribute__((address_space(3)))
; __device__ __forceinline__ unsigned pk2(float lo, float hi) { const f32x2 v = {lo, hi}; const bf16x2_hw b = __builtin_convertvector(v, bf16x2_hw); return __builtin_bit_cast(unsigned, b); }
; __device__ __forceinline__ void gst_wt16(void* p, const u32x4 v) { asm volatile("global_store_dwordx4 %0, %1, off sc1\n\ts_nop 1" :: "v"(p), "v"(v) : "memory"); }
; __device__ __forceinline__ void transpose_item(const float* W, int K, int N, bf16_t* WT, int kb, int nb, int drow0, const float* kscale, LAS float* scr, int lane) {
;     ...
;     for (int i = 0; i < 32; ++i) scr[(2 * i + (lane >> 5)) * 33 + (lane & 31)] = w[i];
;     asm volatile("s_waitcnt lgkmcnt(0)" ::: "memory");
; #pragma unroll
;     for (int j = 0; j < 4; ++j) { const int n = (lane >> 3) + 8 * j; const LAS float* s = scr + (8 * c) * 33 + n;
;         u32x4 o; o.x = pk2(s[0 * 33] * s0[0], s[1 * 33] * s0[1]); o.y = pk2(s[2 * 33] * s0[2], s[3 * 33] * s0[3]); o.z = pk2(s[4 * 33] * s1[0], s[5 * 33] * s1[1]); o.w = pk2(s[6 * 33] * s1[2], s[7 * 33] * s1[3]);
;         gst_wt16(WT + (size_t)(drow0 + n) * K + k0 + 8 * c, o); }
;     asm volatile("s_waitcnt lgkmcnt(0)" ::: "memory");
	ds_write2_b32 v34, v0, v6 offset1:66
	s_waitcnt vmcnt(28)
	ds_write2_b32 v34, v7, v8 offset0:132 offset1:198
	v_add_u32_e32 v0, 0x400, v34
	s_waitcnt vmcnt(26)
	ds_write2_b32 v0, v9, v32 offset0:8 offset1:74
	s_waitcnt vmcnt(24)
	ds_write2_b32 v0, v33, v40 offset0:140 offset1:206
	v_add_u32_e32 v0, 0x800, v34
	s_waitcnt vmcnt(22)
	ds_write2_b32 v0, v41, v42 offset0:16 offset1:82
	s_waitcnt vmcnt(20)
	ds_write2_b32 v0, v43, v44 offset0:148 offset1:214
	v_add_u32_e32 v0, 0xc00, v34
	s_waitcnt vmcnt(18)
	ds_write2_b32 v0, v45, v46 offset0:24 offset1:90
	s_waitcnt vmcnt(16)
	ds_write2_b32 v0, v47, v48 offset0:156 offset1:222
	v_add_u32_e32 v0, 0x1000, v34
	s_waitcnt vmcnt(14)
	ds_write2_b32 v0, v49, v50 offset0:32 offset1:98
	s_waitcnt vmcnt(12)
	ds_write2_b32 v0, v51, v52 offset0:164 offset1:230
	v_add_u32_e32 v0, 0x1400, v34
	s_waitcnt vmcnt(10)
	ds_write2_b32 v0, v53, v54 offset0:40 offset1:106
	s_waitcnt vmcnt(8)
	ds_write2_b32 v0, v55, v56 offset0:172 offset1:238
	v_add_u32_e32 v0, 0x1800, v34
	s_waitcnt vmcnt(6)
	ds_write2_b32 v0, v57, v58 offset0:48 offset1:114
	s_waitcnt vmcnt(4)
	ds_write2_b32 v0, v59, v60 offset0:180 offset1:246
	v_add_u32_e32 v0, 0x1c00, v34
	s_waitcnt vmcnt(2)
	ds_write2_b32 v0, v61, v62 offset0:56 offset1:122
	s_waitcnt vmcnt(0)
	ds_write2_b32 v0, v4, v2 offset0:188 offset1:254
	s_waitcnt lgkmcnt(0)
	ds_read2_b32 v[2:3], v36 offset1:33
	ds_read2_b32 v[4:5], v36 offset0:66 offset1:99
	ds_read2_b32 v[8:9], v36 offset0:198 offset1:231
	v_or_b32_e32 v0, s18, v35
	v_lshl_add_u64 v[6:7], s[72:73], 1, v[22:23]
	s_waitcnt lgkmcnt(2)
	v_cvt_pk_bf16_f32 v2, v2, v3
	s_waitcnt lgkmcnt(1)
	v_cvt_pk_bf16_f32 v3, v4, v5
	ds_read2_b32 v[4:5], v36 offset0:132 offset1:165
	v_lshlrev_b32_e32 v0, 10, v0
	s_waitcnt lgkmcnt(0)
	v_cvt_pk_bf16_f32 v4, v4, v5
	v_cvt_pk_bf16_f32 v5, v8, v9
	v_lshl_add_u64 v[8:9], v[6:7], 0, v[0:1]
	global_store_dwordx4 v[8:9], v[2:5], off sc1 nt
	s_nop 1
	ds_read2_b32 v[2:3], v36 offset0:8 offset1:41
	ds_read2_b32 v[4:5], v36 offset0:74 offset1:107
	ds_read2_b32 v[8:9], v36 offset0:206 offset1:239
	v_or_b32_e32 v0, s18, v37
	v_lshlrev_b32_e32 v0, 10, v0
	s_waitcnt lgkmcnt(2)
	v_cvt_pk_bf16_f32 v2, v2, v3
	s_waitcnt lgkmcnt(1)
	v_cvt_pk_bf16_f32 v3, v4, v5
	ds_read2_b32 v[4:5], v36 offset0:140 offset1:173
	s_waitcnt lgkmcnt(0)
	v_cvt_pk_bf16_f32 v4, v4, v5
	v_cvt_pk_bf16_f32 v5, v8, v9
	v_lshl_add_u64 v[8:9], v[6:7], 0, v[0:1]
	global_store_dwordx4 v[8:9], v[2:5], off sc1 nt
	s_nop 1
	ds_read2_b32 v[2:3], v36 offset0:16 offset1:49
	ds_read2_b32 v[4:5], v36 offset0:82 offset1:115
	ds_read2_b32 v[8:9], v36 offset0:214 offset1:247
	v_or_b32_e32 v0, s18, v38
	v_lshlrev_b32_e32 v0, 10, v0
	s_waitcnt lgkmcnt(2)
	v_cvt_pk_bf16_f32 v2, v2, v3
	s_waitcnt lgkmcnt(1)
	v_cvt_pk_bf16_f32 v3, v4, v5
	ds_read2_b32 v[4:5], v36 offset0:148 offset1:181
	s_waitcnt lgkmcnt(0)
	v_cvt_pk_bf16_f32 v4, v4, v5
	v_cvt_pk_bf16_f32 v5, v8, v9
	v_lshl_add_u64 v[8:9], v[6:7], 0, v[0:1]
	global_store_dwordx4 v[8:9], v[2:5], off sc1 nt
	s_nop 1
	ds_read2_b32 v[2:3], v36 offset0:24 offset1:57
	ds_read2_b32 v[4:5], v36 offset0:90 offset1:123
	ds_read2_b32 v[8:9], v36 offset0:222 offset1:255
	v_or_b32_e32 v0, s18, v39
	v_lshlrev_b32_e32 v0, 10, v0
	s_waitcnt lgkmcnt(2)
	v_cvt_pk_bf16_f32 v2, v2, v3
	s_waitcnt lgkmcnt(1)
	v_cvt_pk_bf16_f32 v3, v4, v5
	ds_read2_b32 v[4:5], v36 offset0:156 offset1:189
	v_lshl_add_u64 v[6:7], v[6:7], 0, v[0:1]
	s_waitcnt lgkmcnt(0)
	v_cvt_pk_bf16_f32 v4, v4, v5
	v_cvt_pk_bf16_f32 v5, v8, v9
	global_store_dwordx4 v[6:7], v[2:5], off sc1 nt
	s_nop 1
	s_waitcnt lgkmcnt(0)

; __device__ __forceinline__ void transpose_item(const float* W, int K, int N, bf16_t* WT, int kb, int nb, int drow0, const float* kscale, LAS float* scr, int lane) {
;     const int k0 = 64 * kb, n0 = 32 * nb, c = lane & 7;
;     f32x4 s0 = {1.f, 1.f, 1.f, 1.f}, s1 = {1.f, 1.f, 1.f, 1.f};
;     if (kscale) { s0 = *(const f32x4*)(kscale + k0 + 8 * c); s1 = *(const f32x4*)(kscale + k0 + 8 * c + 4); }
;     const float* src = W + (size_t)(k0 + (lane >> 5)) * N + n0 + (lane & 31);
;     float w[32];
; #pragma unroll
;     for (int i = 0; i < 32; ++i) w[i] = __builtin_nontemporal_load(src + (size_t)(2 * i) * N);
; __device__ __forceinline__ void prep_weights(Frame& F, const Args& a, int l, int it_lo, int it_hi, int gw, int ngw) {
;     ...
;         if (r < I2) { const int kb = r / 32, nb = r % 32; transpose_item(w_co, 512, DM, W + WO_CO, kb, nb, 32 * nb, nullptr, scr, F.lane); continue; } r -= I2;
.LBB0_1372:
	s_andn2_b64 vcc, exec, s[18:19]
	s_cbranch_vccnz .LBB0_1374
	s_and_b32 s19, s27, 0x1fc0
	s_add_i32 s72, s19, 0xffffe700
	v_or_b32_e32 v0, s72, v11
	s_and_b32 s18, s1, 0x3e0
	v_lshlrev_b64 v[2:3], 12, v[0:1]
	v_lshl_add_u64 v[2:3], s[6:7], 0, v[2:3]
	s_lshl_b32 s20, s18, 2
	s_mov_b32 s21, s73
	v_lshl_add_u64 v[2:3], v[2:3], 0, s[20:21]
	v_lshlrev_b32_e32 v0, 2, v10
	v_lshl_add_u64 v[2:3], v[2:3], 0, v[0:1]
	s_movk_i32 s19, 0x2000
	v_add_co_u32_e32 v4, vcc, s19, v2
	s_movk_i32 s19, 0x4000
	s_nop 0
	v_addc_co_u32_e32 v5, vcc, 0, v3, vcc
	global_load_dword v0, v[2:3], off nt
	global_load_dword v6, v[4:5], off nt
	v_add_co_u32_e32 v4, vcc, s19, v2
	s_movk_i32 s19, 0x6000
	s_nop 0
	v_addc_co_u32_e32 v5, vcc, 0, v3, vcc
	global_load_dword v7, v[4:5], off nt
	v_add_co_u32_e32 v4, vcc, s19, v2
	s_mov_b32 s19, 0x8000
	s_nop 0
	v_addc_co_u32_e32 v5, vcc, 0, v3, vcc
	global_load_dword v8, v[4:5], off nt
	v_add_co_u32_e32 v4, vcc, s19, v2
	s_mov_b32 s19, 0xa000
	s_nop 0
	v_addc_co_u32_e32 v5, vcc, 0, v3, vcc
	global_load_dword v9, v[4:5], off nt
	v_add_co_u32_e32 v4, vcc, s19, v2
	s_mov_b32 s19, 0xc000
	s_nop 0
	v_addc_co_u32_e32 v5, vcc, 0, v3, vcc
	global_load_dword v32, v[4:5], off nt
	v_add_co_u32_e32 v4, vcc, s19, v2
	s_mov_b32 s19, 0xe000
	s_nop 0
	v_addc_co_u32_e32 v5, vcc, 0, v3, vcc
	global_load_dword v33, v[4:5], off nt
	v_add_co_u32_e32 v4, vcc, s19, v2
	s_mov_b32 s19, 0x10000
	s_nop 0
	v_addc_co_u32_e32 v5, vcc, 0, v3, vcc
	global_load_dword v40, v[4:5], off nt
	v_add_co_u32_e32 v4, vcc, s19, v2
	s_mov_b32 s19, 0x12000
	s_nop 0
	v_addc_co_u32_e32 v5, vcc, 0, v3, vcc
	global_load_dword v41, v[4:5], off nt
	v_add_co_u32_e32 v4, vcc, s19, v2
	s_mov_b32 s19, 0x14000
	s_nop 0
	v_addc_co_u32_e32 v5, vcc, 0, v3, vcc
	global_load_dword v42, v[4:5], off nt
	v_add_co_u32_e32 v4, vcc, s19, v2
	s_mov_b32 s19, 0x16000
	s_nop 0
	v_addc_co_u32_e32 v5, vcc, 0, v3, vcc
	global_load_dword v43, v[4:5], off nt
	v_add_co_u32_e32 v4, vcc, s19, v2
	s_mov_b32 s19, 0x18000
	s_nop 0
	v_addc_co_u32_e32 v5, vcc, 0, v3, vcc
	global_load_dword v44, v[4:5], off nt
	v_add_co_u32_e32 v4, vcc, s19, v2
	s_mov_b32 s19, 0x1a000
	s_nop 0
	v_addc_co_u32_e32 v5, vcc, 0, v3, vcc
	global_load_dword v45, v[4:5], off nt
	v_add_co_u32_e32 v4, vcc, s19, v2
	s_mov_b32 s19, 0x1c000
	s_nop 0
	v_addc_co_u32_e32 v5, vcc, 0, v3, vcc
	global_load_dword v46, v[4:5], off nt
	v_add_co_u32_e32 v4, vcc, s19, v2
	s_mov_b32 s19, 0x1e000
	s_nop 0
	v_addc_co_u32_e32 v5, vcc, 0, v3, vcc
	global_load_dword v47, v[4:5], off nt
	v_add_co_u32_e32 v4, vcc, s19, v2
	s_mov_b32 s19, 0x22000
	s_nop 0
	v_addc_co_u32_e32 v5, vcc, 0, v3, vcc
	global_load_dword v48, v[4:5], off nt
	v_add_co_u32_e32 v4, vcc, s79, v2
	s_nop 1
	v_addc_co_u32_e32 v5, vcc, 0, v3, vcc
	global_load_dword v49, v[4:5], off nt
	v_add_co_u32_e32 v4, vcc, s19, v2
	s_mov_b32 s19, 0x24000
	s_nop 0
	v_addc_co_u32_e32 v5, vcc, 0, v3, vcc
	global_load_dword v50, v[4:5], off nt
	v_add_co_u32_e32 v4, vcc, s19, v2
	s_mov_b32 s19, 0x26000
	s_nop 0
	v_addc_co_u32_e32 v5, vcc, 0, v3, vcc
	global_load_dword v51, v[4:5], off nt
	v_add_co_u32_e32 v4, vcc, s19, v2
	s_mov_b32 s19, 0x28000
	s_nop 0
	v_addc_co_u32_e32 v5, vcc, 0, v3, vcc
	global_load_dword v52, v[4:5], off nt
	v_add_co_u32_e32 v4, vcc, s19, v2
	s_mov_b32 s19, 0x2a000
	s_nop 0
	v_addc_co_u32_e32 v5, vcc, 0, v3, vcc
	global_load_dword v53, v[4:5], off nt
	v_add_co_u32_e32 v4, vcc, s19, v2
	s_mov_b32 s19, 0x2c000
	s_nop 0
	v_addc_co_u32_e32 v5, vcc, 0, v3, vcc
	global_load_dword v54, v[4:5], off nt
	v_add_co_u32_e32 v4, vcc, s19, v2
	s_mov_b32 s19, 0x2e000
	s_nop 0
	v_addc_co_u32_e32 v5, vcc, 0, v3, vcc
	global_load_dword v55, v[4:5], off nt
	v_add_co_u32_e32 v4, vcc, s19, v2
	s_mov_b32 s19, 0x30000
	s_nop 0
	v_addc_co_u32_e32 v5, vcc, 0, v3, vcc
	global_load_dword v56, v[4:5], off nt
	v_add_co_u32_e32 v4, vcc, s19, v2
	s_mov_b32 s19, 0x32000
	s_nop 0
	v_addc_co_u32_e32 v5, vcc, 0, v3, vcc
	global_load_dword v57, v[4:5], off nt
	v_add_co_u32_e32 v4, vcc, s19, v2
	s_mov_b32 s19, 0x34000
	s_nop 0
	v_addc_co_u32_e32 v5, vcc, 0, v3, vcc
	global_load_dword v58, v[4:5], off nt
	v_add_co_u32_e32 v4, vcc, s19, v2
	s_mov_b32 s19, 0x36000
	s_nop 0
	v_addc_co_u32_e32 v5, vcc, 0, v3, vcc
	global_load_dword v59, v[4:5], off nt
	v_add_co_u32_e32 v4, vcc, s19, v2
	s_mov_b32 s19, 0x38000
	s_nop 0
	v_addc_co_u32_e32 v5, vcc, 0, v3, vcc
	global_load_dword v60, v[4:5], off nt
	v_add_co_u32_e32 v4, vcc, s19, v2
	s_mov_b32 s19, 0x3a000
	s_nop 0
	v_addc_co_u32_e32 v5, vcc, 0, v3, vcc
	global_load_dword v61, v[4:5], off nt
	v_add_co_u32_e32 v4, vcc, s19, v2
	s_mov_b32 s19, 0x3c000
	s_nop 0
	v_addc_co_u32_e32 v5, vcc, 0, v3, vcc
	global_load_dword v62, v[4:5], off nt
	v_add_co_u32_e32 v4, vcc, s19, v2
	s_mov_b32 s19, 0x3e000
	s_nop 0
	v_addc_co_u32_e32 v5, vcc, 0, v3, vcc
	v_add_co_u32_e32 v2, vcc, s19, v2
	global_load_dword v4, v[4:5], off nt
	s_nop 0
	v_addc_co_u32_e32 v3, vcc, 0, v3, vcc
	global_load_dword v2, v[2:3], off nt
	s_waitcnt vmcnt(30)
; #define LAS __attribute__((address_space(3)))
; __device__ __forceinline__ unsigned pk2(float lo, float hi) { const f32x2 v = {lo, hi}; const bf16x2_hw b = __builtin_convertvector(v, bf16x2_hw); return __builtin_bit_cast(unsigned, b); }
; __device__ __forceinline__ void gst_wt16(void* p, const u32x4 v) { asm volatile("global_store_dwordx4 %0, %1, off sc1\n\ts_nop 1" :: "v"(p), "v"(v) : "memory"); }
; __device__ __forceinline__ void transpose_item(const float* W, int K, int N, bf16_t* WT, int kb, int nb, int drow0, const float* kscale, LAS float* scr, int lane) {
;     ...
;     for (int i = 0; i < 32; ++i) scr[(2 * i + (lane >> 5)) * 33 + (lane & 31)] = w[i];
;     asm volatile("s_waitcnt lgkmcnt(0)" ::: "memory");
; #pragma unroll
;     for (int j = 0; j < 4; ++j) { const int n = (lane >> 3) + 8 * j; const LAS float* s = scr + (8 * c) * 33 + n;
;         u32x4 o; o.x = pk2(s[0 * 33] * s0[0], s[1 * 33] * s0[1]); o.y = pk2(s[2 * 33] * s0[2], s[3 * 33] * s0[3]); o.z = pk2(s[4 * 33] * s1[0], s[5 * 33] * s1[1]); o.w = pk2(s[6 * 33] * s1[2], s[7 * 33] * s1[3]);
;         gst_wt16(WT + (size_t)(drow0 + n) * K + k0 + 8 * c, o); }
;     asm volatile("s_waitcnt lgkmcnt(0)" ::: "memory");
	ds_write2_b32 v34, v0, v6 offset1:66
	s_waitcnt vmcnt(28)
	ds_write2_b32 v34, v7, v8 offset0:132 offset1:198
	v_add_u32_e32 v0, 0x400, v34
	s_waitcnt vmcnt(26)
	ds_write2_b32 v0, v9, v32 offset0:8 offset1:74
	s_waitcnt vmcnt(24)
	ds_write2_b32 v0, v33, v40 offset0:140 offset1:206
	v_add_u32_e32 v0, 0x800, v34
	s_waitcnt vmcnt(22)
	ds_write2_b32 v0, v41, v42 offset0:16 offset1:82
	s_waitcnt vmcnt(20)
	ds_write2_b32 v0, v43, v44 offset0:148 offset1:214
	v_add_u32_e32 v0, 0xc00, v34
	s_waitcnt vmcnt(18)
	ds_write2_b32 v0, v45, v46 offset0:24 offset1:90
	s_waitcnt vmcnt(16)
	ds_write2_b32 v0, v47, v48 offset0:156 offset1:222
	v_add_u32_e32 v0, 0x1000, v34
	s_waitcnt vmcnt(14)
	ds_write2_b32 v0, v49, v50 offset0:32 offset1:98
	s_waitcnt vmcnt(12)
	ds_write2_b32 v0, v51, v52 offset0:164 offset1:230
	v_add_u32_e32 v0, 0x1400, v34
	s_waitcnt vmcnt(10)
	ds_write2_b32 v0, v53, v54 offset0:40 offset1:106
	s_waitcnt vmcnt(8)
	ds_write2_b32 v0, v55, v56 offset0:172 offset1:238
	v_add_u32_e32 v0, 0x1800, v34
	s_waitcnt vmcnt(6)
	ds_write2_b32 v0, v57, v58 offset0:48 offset1:114
	s_waitcnt vmcnt(4)
	ds_write2_b32 v0, v59, v60 offset0:180 offset1:246
	v_add_u32_e32 v0, 0x1c00, v34
	s_waitcnt vmcnt(2)
	ds_write2_b32 v0, v61, v62 offset0:56 offset1:122
	s_waitcnt vmcnt(0)
	ds_write2_b32 v0, v4, v2 offset0:188 offset1:254
	s_waitcnt lgkmcnt(0)
	ds_read2_b32 v[2:3], v36 offset1:33
	ds_read2_b32 v[4:5], v36 offset0:66 offset1:99
	ds_read2_b32 v[8:9], v36 offset0:198 offset1:231
	v_or_b32_e32 v0, s18, v35
	v_lshl_add_u64 v[6:7], s[72:73], 1, v[24:25]
	s_waitcnt lgkmcnt(2)
	v_cvt_pk_bf16_f32 v2, v2, v3
	s_waitcnt lgkmcnt(1)
	v_cvt_pk_bf16_f32 v3, v4, v5
	ds_read2_b32 v[4:5], v36 offset0:132 offset1:165
	v_lshlrev_b32_e32 v0, 10, v0
	s_waitcnt lgkmcnt(0)
	v_cvt_pk_bf16_f32 v4, v4, v5
	v_cvt_pk_bf16_f32 v5, v8, v9
	v_lshl_add_u64 v[8:9], v[6:7], 0, v[0:1]
	global_store_dwordx4 v[8:9], v[2:5], off sc1 nt
	s_nop 1
	ds_read2_b32 v[2:3], v36 offset0:8 offset1:41
	ds_read2_b32 v[4:5], v36 offset0:74 offset1:107
	ds_read2_b32 v[8:9], v36 offset0:206 offset1:239
	v_or_b32_e32 v0, s18, v37
	v_lshlrev_b32_e32 v0, 10, v0
	s_waitcnt lgkmcnt(2)
	v_cvt_pk_bf16_f32 v2, v2, v3
	s_waitcnt lgkmcnt(1)
	v_cvt_pk_bf16_f32 v3, v4, v5
	ds_read2_b32 v[4:5], v36 offset0:140 offset1:173
	s_waitcnt lgkmcnt(0)
	v_cvt_pk_bf16_f32 v4, v4, v5
	v_cvt_pk_bf16_f32 v5, v8, v9
	v_lshl_add_u64 v[8:9], v[6:7], 0, v[0:1]
	global_store_dwordx4 v[8:9], v[2:5], off sc1 nt
	s_nop 1
	ds_read2_b32 v[2:3], v36 offset0:16 offset1:49
	ds_read2_b32 v[4:5], v36 offset0:82 offset1:115
	ds_read2_b32 v[8:9], v36 offset0:214 offset1:247
	v_or_b32_e32 v0, s18, v38
	v_lshlrev_b32_e32 v0, 10, v0
	s_waitcnt lgkmcnt(2)
	v_cvt_pk_bf16_f32 v2, v2, v3
	s_waitcnt lgkmcnt(1)
	v_cvt_pk_bf16_f32 v3, v4, v5
	ds_read2_b32 v[4:5], v36 offset0:148 offset1:181
	s_waitcnt lgkmcnt(0)
	v_cvt_pk_bf16_f32 v4, v4, v5
	v_cvt_pk_bf16_f32 v5, v8, v9
	v_lshl_add_u64 v[8:9], v[6:7], 0, v[0:1]
	global_store_dwordx4 v[8:9], v[2:5], off sc1 nt
	s_nop 1
	ds_read2_b32 v[2:3], v36 offset0:24 offset1:57
	ds_read2_b32 v[4:5], v36 offset0:90 offset1:123
	ds_read2_b32 v[8:9], v36 offset0:222 offset1:255
	v_or_b32_e32 v0, s18, v39
	v_lshlrev_b32_e32 v0, 10, v0
	s_waitcnt lgkmcnt(2)
	v_cvt_pk_bf16_f32 v2, v2, v3
	s_waitcnt lgkmcnt(1)
	v_cvt_pk_bf16_f32 v3, v4, v5
	ds_read2_b32 v[4:5], v36 offset0:156 offset1:189
	v_lshl_add_u64 v[6:7], v[6:7], 0, v[0:1]
	s_waitcnt lgkmcnt(0)
	v_cvt_pk_bf16_f32 v4, v4, v5
	v_cvt_pk_bf16_f32 v5, v8, v9
	global_store_dwordx4 v[6:7], v[2:5], off sc1 nt
	s_nop 1
	s_waitcnt lgkmcnt(0)

; __device__ __forceinline__ void transpose_item(const float* W, int K, int N, bf16_t* WT, int kb, int nb, int drow0, const float* kscale, LAS float* scr, int lane) {
;     const int k0 = 64 * kb, n0 = 32 * nb, c = lane & 7;
;     f32x4 s0 = {1.f, 1.f, 1.f, 1.f}, s1 = {1.f, 1.f, 1.f, 1.f};
;     if (kscale) { s0 = *(const f32x4*)(kscale + k0 + 8 * c); s1 = *(const f32x4*)(kscale + k0 + 8 * c + 4); }
;     const float* src = W + (size_t)(k0 + (lane >> 5)) * N + n0 + (lane & 31);
;     float w[32];
; #pragma unroll
;     for (int i = 0; i < 32; ++i) w[i] = __builtin_nontemporal_load(src + (size_t)(2 * i) * N);
; __device__ __forceinline__ void prep_weights(Frame& F, const Args& a, int l, int it_lo, int it_hi, int gw, int ngw) {
;     ...
;         if (r < I1) { const int kb = r / 32, nb = r % 32; transpose_item(w_ao, 512, DM, W + WO_AO, kb, nb, 32 * nb, nullptr, scr, F.lane); continue; } r -= I1;
.LBB0_1375:
	s_andn2_b64 vcc, exec, s[18:19]
	s_cbranch_vccnz .LBB0_1377
	s_and_b32 s19, s27, 0x1fc0
	s_add_i32 s72, s19, 0xffffe900
	v_or_b32_e32 v0, s72, v11
	s_and_b32 s18, s1, 0x3e0
	v_lshlrev_b64 v[2:3], 12, v[0:1]
	v_lshl_add_u64 v[2:3], s[4:5], 0, v[2:3]
	s_lshl_b32 s20, s18, 2
	s_mov_b32 s21, s73
	v_lshl_add_u64 v[2:3], v[2:3], 0, s[20:21]
	v_lshlrev_b32_e32 v0, 2, v10
	v_lshl_add_u64 v[2:3], v[2:3], 0, v[0:1]
	s_movk_i32 s19, 0x2000
	v_add_co_u32_e32 v4, vcc, s19, v2
	s_movk_i32 s19, 0x4000
	s_nop 0
	v_addc_co_u32_e32 v5, vcc, 0, v3, vcc
	global_load_dword v0, v[2:3], off nt
	global_load_dword v6, v[4:5], off nt
	v_add_co_u32_e32 v4, vcc, s19, v2
	s_movk_i32 s19, 0x6000
	s_nop 0
	v_addc_co_u32_e32 v5, vcc, 0, v3, vcc
	global_load_dword v7, v[4:5], off nt
	v_add_co_u32_e32 v4, vcc, s19, v2
	s_mov_b32 s19, 0x8000
	s_nop 0
	v_addc_co_u32_e32 v5, vcc, 0, v3, vcc
	global_load_dword v8, v[4:5], off nt
	v_add_co_u32_e32 v4, vcc, s19, v2
	s_mov_b32 s19, 0xa000
	s_nop 0
	v_addc_co_u32_e32 v5, vcc, 0, v3, vcc
	global_load_dword v9, v[4:5], off nt
	v_add_co_u32_e32 v4, vcc, s19, v2
	s_mov_b32 s19, 0xc000
	s_nop 0
	v_addc_co_u32_e32 v5, vcc, 0, v3, vcc
	global_load_dword v32, v[4:5], off nt
	v_add_co_u32_e32 v4, vcc, s19, v2
	s_mov_b32 s19, 0xe000
	s_nop 0
	v_addc_co_u32_e32 v5, vcc, 0, v3, vcc
	global_load_dword v33, v[4:5], off nt
	v_add_co_u32_e32 v4, vcc, s19, v2
	s_mov_b32 s19, 0x10000
	s_nop 0
	v_addc_co_u32_e32 v5, vcc, 0, v3, vcc
	global_load_dword v40, v[4:5], off nt
	v_add_co_u32_e32 v4, vcc, s19, v2
	s_mov_b32 s19, 0x12000
	s_nop 0
	v_addc_co_u32_e32 v5, vcc, 0, v3, vcc
	global_load_dword v41, v[4:5], off nt
	v_add_co_u32_e32 v4, vcc, s19, v2
	s_mov_b32 s19, 0x14000
	s_nop 0
	v_addc_co_u32_e32 v5, vcc, 0, v3, vcc
	global_load_dword v42, v[4:5], off nt
	v_add_co_u32_e32 v4, vcc, s19, v2
	s_mov_b32 s19, 0x16000
	s_nop 0
	v_addc_co_u32_e32 v5, vcc, 0, v3, vcc
	global_load_dword v43, v[4:5], off nt
	v_add_co_u32_e32 v4, vcc, s19, v2
	s_mov_b32 s19, 0x18000
	s_nop 0
	v_addc_co_u32_e32 v5, vcc, 0, v3, vcc
	global_load_dword v44, v[4:5], off nt
	v_add_co_u32_e32 v4, vcc, s19, v2
	s_mov_b32 s19, 0x1a000
	s_nop 0
	v_addc_co_u32_e32 v5, vcc, 0, v3, vcc
	global_load_dword v45, v[4:5], off nt
	v_add_co_u32_e32 v4, vcc, s19, v2
	s_mov_b32 s19, 0x1c000
	s_nop 0
	v_addc_co_u32_e32 v5, vcc, 0, v3, vcc
	global_load_dword v46, v[4:5], off nt
	v_add_co_u32_e32 v4, vcc, s19, v2
	s_mov_b32 s19, 0x1e000
	s_nop 0
	v_addc_co_u32_e32 v5, vcc, 0, v3, vcc
	global_load_dword v47, v[4:5], off nt
	v_add_co_u32_e32 v4, vcc, s19, v2
	s_mov_b32 s19, 0x22000
	s_nop 0
	v_addc_co_u32_e32 v5, vcc, 0, v3, vcc
	global_load_dword v48, v[4:5], off nt
	v_add_co_u32_e32 v4, vcc, s79, v2
	s_nop 1
	v_addc_co_u32_e32 v5, vcc, 0, v3, vcc
	global_load_dword v49, v[4:5], off nt
	v_add_co_u32_e32 v4, vcc, s19, v2
	s_mov_b32 s19, 0x24000
	s_nop 0
	v_addc_co_u32_e32 v5, vcc, 0, v3, vcc
	global_load_dword v50, v[4:5], off nt
	v_add_co_u32_e32 v4, vcc, s19, v2
	s_mov_b32 s19, 0x26000
	s_nop 0
	v_addc_co_u32_e32 v5, vcc, 0, v3, vcc
	global_load_dword v51, v[4:5], off nt
	v_add_co_u32_e32 v4, vcc, s19, v2
	s_mov_b32 s19, 0x28000
	s_nop 0
	v_addc_co_u32_e32 v5, vcc, 0, v3, vcc
	global_load_dword v52, v[4:5], off nt
	v_add_co_u32_e32 v4, vcc, s19, v2
	s_mov_b32 s19, 0x2a000
	s_nop 0
	v_addc_co_u32_e32 v5, vcc, 0, v3, vcc
	global_load_dword v53, v[4:5], off nt
	v_add_co_u32_e32 v4, vcc, s19, v2
	s_mov_b32 s19, 0x2c000
	s_nop 0
	v_addc_co_u32_e32 v5, vcc, 0, v3, vcc
	global_load_dword v54, v[4:5], off nt
	v_add_co_u32_e32 v4, vcc, s19, v2
	s_mov_b32 s19, 0x2e000
	s_nop 0
	v_addc_co_u32_e32 v5, vcc, 0, v3, vcc
	global_load_dword v55, v[4:5], off nt
	v_add_co_u32_e32 v4, vcc, s19, v2
	s_mov_b32 s19, 0x30000
	s_nop 0
	v_addc_co_u32_e32 v5, vcc, 0, v3, vcc
	global_load_dword v56, v[4:5], off nt
	v_add_co_u32_e32 v4, vcc, s19, v2
	s_mov_b32 s19, 0x32000
	s_nop 0
	v_addc_co_u32_e32 v5, vcc, 0, v3, vcc
	global_load_dword v57, v[4:5], off nt
	v_add_co_u32_e32 v4, vcc, s19, v2
	s_mov_b32 s19, 0x34000
	s_nop 0
	v_addc_co_u32_e32 v5, vcc, 0, v3, vcc
	global_load_dword v58, v[4:5], off nt
	v_add_co_u32_e32 v4, vcc, s19, v2
	s_mov_b32 s19, 0x36000
	s_nop 0
	v_addc_co_u32_e32 v5, vcc, 0, v3, vcc
	global_load_dword v59, v[4:5], off nt
	v_add_co_u32_e32 v4, vcc, s19, v2
	s_mov_b32 s19, 0x38000
	s_nop 0
	v_addc_co_u32_e32 v5, vcc, 0, v3, vcc
	global_load_dword v60, v[4:5], off nt
	v_add_co_u32_e32 v4, vcc, s19, v2
	s_mov_b32 s19, 0x3a000
	s_nop 0
	v_addc_co_u32_e32 v5, vcc, 0, v3, vcc
	global_load_dword v61, v[4:5], off nt
	v_add_co_u32_e32 v4, vcc, s19, v2
	s_mov_b32 s19, 0x3c000
	s_nop 0
	v_addc_co_u32_e32 v5, vcc, 0, v3, vcc
	global_load_dword v62, v[4:5], off nt
	v_add_co_u32_e32 v4, vcc, s19, v2
	s_mov_b32 s19, 0x3e000
	s_nop 0
	v_addc_co_u32_e32 v5, vcc, 0, v3, vcc
	v_add_co_u32_e32 v2, vcc, s19, v2
	global_load_dword v4, v[4:5], off nt
	s_nop 0
	v_addc_co_u32_e32 v3, vcc, 0, v3, vcc
	global_load_dword v2, v[2:3], off nt
	s_waitcnt vmcnt(30)
; #define LAS __attribute__((address_space(3)))
; __device__ __forceinline__ unsigned pk2(float lo, float hi) { const f32x2 v = {lo, hi}; const bf16x2_hw b = __builtin_convertvector(v, bf16x2_hw); return __builtin_bit_cast(unsigned, b); }
; __device__ __forceinline__ void gst_wt16(void* p, const u32x4 v) { asm volatile("global_store_dwordx4 %0, %1, off sc1\n\ts_nop 1" :: "v"(p), "v"(v) : "memory"); }
; __device__ __forceinline__ void transpose_item(const float* W, int K, int N, bf16_t* WT, int kb, int nb, int drow0, const float* kscale, LAS float* scr, int lane) {
;     ...
;     for (int i = 0; i < 32; ++i) scr[(2 * i + (lane >> 5)) * 33 + (lane & 31)] = w[i];
;     asm volatile("s_waitcnt lgkmcnt(0)" ::: "memory");
; #pragma unroll
;     for (int j = 0; j < 4; ++j) { const int n = (lane >> 3) + 8 * j; const LAS float* s = scr + (8 * c) * 33 + n;
;         u32x4 o; o.x = pk2(s[0 * 33] * s0[0], s[1 * 33] * s0[1]); o.y = pk2(s[2 * 33] * s0[2], s[3 * 33] * s0[3]); o.z = pk2(s[4 * 33] * s1[0], s[5 * 33] * s1[1]); o.w = pk2(s[6 * 33] * s1[2], s[7 * 33] * s1[3]);
;         gst_wt16(WT + (size_t)(drow0 + n) * K + k0 + 8 * c, o); }
;     asm volatile("s_waitcnt lgkmcnt(0)" ::: "memory");
	ds_write2_b32 v34, v0, v6 offset1:66
	s_waitcnt vmcnt(28)
	ds_write2_b32 v34, v7, v8 offset0:132 offset1:198
	v_add_u32_e32 v0, 0x400, v34
	s_waitcnt vmcnt(26)
	ds_write2_b32 v0, v9, v32 offset0:8 offset1:74
	s_waitcnt vmcnt(24)
	ds_write2_b32 v0, v33, v40 offset0:140 offset1:206
	v_add_u32_e32 v0, 0x800, v34
	s_waitcnt vmcnt(22)
	ds_write2_b32 v0, v41, v42 offset0:16 offset1:82
	s_waitcnt vmcnt(20)
	ds_write2_b32 v0, v43, v44 offset0:148 offset1:214
	v_add_u32_e32 v0, 0xc00, v34
	s_waitcnt vmcnt(18)
	ds_write2_b32 v0, v45, v46 offset0:24 offset1:90
	s_waitcnt vmcnt(16)
	ds_write2_b32 v0, v47, v48 offset0:156 offset1:222
	v_add_u32_e32 v0, 0x1000, v34
	s_waitcnt vmcnt(14)
	ds_write2_b32 v0, v49, v50 offset0:32 offset1:98
	s_waitcnt vmcnt(12)
	ds_write2_b32 v0, v51, v52 offset0:164 offset1:230
	v_add_u32_e32 v0, 0x1400, v34
	s_waitcnt vmcnt(10)
	ds_write2_b32 v0, v53, v54 offset0:40 offset1:106
	s_waitcnt vmcnt(8)
	ds_write2_b32 v0, v55, v56 offset0:172 offset1:238
	v_add_u32_e32 v0, 0x1800, v34
	s_waitcnt vmcnt(6)
	ds_write2_b32 v0, v57, v58 offset0:48 offset1:114
	s_waitcnt vmcnt(4)
	ds_write2_b32 v0, v59, v60 offset0:180 offset1:246
	v_add_u32_e32 v0, 0x1c00, v34
	s_waitcnt vmcnt(2)
	ds_write2_b32 v0, v61, v62 offset0:56 offset1:122
	s_waitcnt vmcnt(0)
	ds_write2_b32 v0, v4, v2 offset0:188 offset1:254
	s_waitcnt lgkmcnt(0)
	ds_read2_b32 v[2:3], v36 offset1:33
	ds_read2_b32 v[4:5], v36 offset0:66 offset1:99
	ds_read2_b32 v[8:9], v36 offset0:198 offset1:231
	v_or_b32_e32 v0, s18, v35
	v_lshl_add_u64 v[6:7], s[72:73], 1, v[26:27]
	s_waitcnt lgkmcnt(2)
	v_cvt_pk_bf16_f32 v2, v2, v3
	s_waitcnt lgkmcnt(1)
	v_cvt_pk_bf16_f32 v3, v4, v5
	ds_read2_b32 v[4:5], v36 offset0:132 offset1:165
	v_lshlrev_b32_e32 v0, 10, v0
	s_waitcnt lgkmcnt(0)
	v_cvt_pk_bf16_f32 v4, v4, v5
	v_cvt_pk_bf16_f32 v5, v8, v9
	v_lshl_add_u64 v[8:9], v[6:7], 0, v[0:1]
	global_store_dwordx4 v[8:9], v[2:5], off sc1 nt
	s_nop 1
	ds_read2_b32 v[2:3], v36 offset0:8 offset1:41
	ds_read2_b32 v[4:5], v36 offset0:74 offset1:107
	ds_read2_b32 v[8:9], v36 offset0:206 offset1:239
	v_or_b32_e32 v0, s18, v37
	v_lshlrev_b32_e32 v0, 10, v0
	s_waitcnt lgkmcnt(2)
	v_cvt_pk_bf16_f32 v2, v2, v3
	s_waitcnt lgkmcnt(1)
	v_cvt_pk_bf16_f32 v3, v4, v5
	ds_read2_b32 v[4:5], v36 offset0:140 offset1:173
	s_waitcnt lgkmcnt(0)
	v_cvt_pk_bf16_f32 v4, v4, v5
	v_cvt_pk_bf16_f32 v5, v8, v9
	v_lshl_add_u64 v[8:9], v[6:7], 0, v[0:1]
	global_store_dwordx4 v[8:9], v[2:5], off sc1 nt
	s_nop 1
	ds_read2_b32 v[2:3], v36 offset0:16 offset1:49
	ds_read2_b32 v[4:5], v36 offset0:82 offset1:115
	ds_read2_b32 v[8:9], v36 offset0:214 offset1:247
	v_or_b32_e32 v0, s18, v38
	v_lshlrev_b32_e32 v0, 10, v0
	s_waitcnt lgkmcnt(2)
	v_cvt_pk_bf16_f32 v2, v2, v3
	s_waitcnt lgkmcnt(1)
	v_cvt_pk_bf16_f32 v3, v4, v5
	ds_read2_b32 v[4:5], v36 offset0:148 offset1:181
	s_waitcnt lgkmcnt(0)
	v_cvt_pk_bf16_f32 v4, v4, v5
	v_cvt_pk_bf16_f32 v5, v8, v9
	v_lshl_add_u64 v[8:9], v[6:7], 0, v[0:1]
	global_store_dwordx4 v[8:9], v[2:5], off sc1 nt
	s_nop 1
	ds_read2_b32 v[2:3], v36 offset0:24 offset1:57
	ds_read2_b32 v[4:5], v36 offset0:90 offset1:123
	ds_read2_b32 v[8:9], v36 offset0:222 offset1:255
	v_or_b32_e32 v0, s18, v39
	v_lshlrev_b32_e32 v0, 10, v0
	s_waitcnt lgkmcnt(2)
	v_cvt_pk_bf16_f32 v2, v2, v3
	s_waitcnt lgkmcnt(1)
	v_cvt_pk_bf16_f32 v3, v4, v5
	ds_read2_b32 v[4:5], v36 offset0:156 offset1:189
	v_lshl_add_u64 v[6:7], v[6:7], 0, v[0:1]
	s_waitcnt lgkmcnt(0)
	v_cvt_pk_bf16_f32 v4, v4, v5
	v_cvt_pk_bf16_f32 v5, v8, v9
	global_store_dwordx4 v[6:7], v[2:5], off sc1 nt
	s_nop 1
	s_waitcnt lgkmcnt(0)

; __device__ __forceinline__ void transpose_item(const float* W, int K, int N, bf16_t* WT, int kb, int nb, int drow0, const float* kscale, LAS float* scr, int lane) {
;     const int k0 = 64 * kb, n0 = 32 * nb, c = lane & 7;
;     f32x4 s0 = {1.f, 1.f, 1.f, 1.f}, s1 = {1.f, 1.f, 1.f, 1.f};
;     if (kscale) { s0 = *(const f32x4*)(kscale + k0 + 8 * c); s1 = *(const f32x4*)(kscale + k0 + 8 * c + 4); }
;     const float* src = W + (size_t)(k0 + (lane >> 5)) * N + n0 + (lane & 31);
;     float w[32];
; #pragma unroll
;     for (int i = 0; i < 32; ++i) w[i] = __builtin_nontemporal_load(src + (size_t)(2 * i) * N);
; __device__ __forceinline__ void prep_weights(Frame& F, const Args& a, int l, int it_lo, int it_hi, int gw, int ngw) {
;     ...
;         if (r < I0) { const int kb = r / 184, nb = r % 184, n0 = 32 * nb; int d0 = n0;
;             if (n0 >= C_CC && n0 < C_CX) { const int c = n0 - C_CC; d0 = 256 * (5 + c / 128) + (c % 128); }
;             else if (n0 >= C_CX && n0 < C_U) { const int c = n0 - C_CX; d0 = 256 * (5 + c / 128) + 128 + (c % 128); }
;             else if (n0 >= C_G && n0 < C_G + 1024) { const int c = n0 - C_G; d0 = 256 * (11 + c / 128) + (c % 128); }
;             else if (n0 >= C_G + 1024 && n0 < C_G + 2048) { const int c = n0 - C_G - 1024; d0 = 256 * (11 + c / 128) + 128 + (c % 128); }
;             transpose_item(w_in, DM, INCOLS, W + WO_IN, kb, nb, d0, nmix, scr, F.lane); continue; } r -= I0;
.LBB0_1398:
	v_or_b32_e32 v0, s0, v11
	v_mov_b64_e32 v[32:33], s[2:3]
	s_movk_i32 s19, 0x5c00
	v_mad_i64_i32 v[32:33], s[26:27], v0, s19, v[32:33]
	s_ashr_i32 s19, s18, 31
	v_lshl_add_u64 v[32:33], s[18:19], 2, v[32:33]
	v_lshlrev_b32_e32 v0, 2, v10
	v_lshl_add_u64 v[32:33], v[32:33], 0, v[0:1]
	s_mov_b32 s18, 0xb000
	v_add_co_u32_e32 v40, vcc, s18, v32
	s_mov_b32 s18, 0x17000
	s_nop 0
	v_addc_co_u32_e32 v41, vcc, 0, v33, vcc
	global_load_dword v42, v[40:41], off offset:2048 nt
	v_add_co_u32_e32 v40, vcc, s18, v32
	s_mov_b32 s18, 0x22000
	s_nop 0
	v_addc_co_u32_e32 v41, vcc, 0, v33, vcc
	global_load_dword v0, v[32:33], off nt
	global_load_dword v43, v[40:41], off nt
	v_add_co_u32_e32 v40, vcc, s18, v32
	s_mov_b32 s18, 0x2e000
	s_nop 0
	v_addc_co_u32_e32 v41, vcc, 0, v33, vcc
	global_load_dword v44, v[40:41], off offset:2048 nt
	v_add_co_u32_e32 v40, vcc, s18, v32
	s_mov_b32 s18, 0x39000
	s_nop 0
	v_addc_co_u32_e32 v41, vcc, 0, v33, vcc
	global_load_dword v45, v[40:41], off nt
	v_add_co_u32_e32 v40, vcc, s18, v32
	s_mov_b32 s18, 0x45000
	s_nop 0
	v_addc_co_u32_e32 v41, vcc, 0, v33, vcc
	global_load_dword v46, v[40:41], off offset:2048 nt
	v_add_co_u32_e32 v40, vcc, s18, v32
	s_mov_b32 s18, 0x50000
	s_nop 0
	v_addc_co_u32_e32 v41, vcc, 0, v33, vcc
	global_load_dword v47, v[40:41], off nt
	v_add_co_u32_e32 v40, vcc, s18, v32
	s_mov_b32 s18, 0x5c000
	s_nop 0
	v_addc_co_u32_e32 v41, vcc, 0, v33, vcc
	global_load_dword v48, v[40:41], off offset:2048 nt
	v_add_co_u32_e32 v40, vcc, s18, v32
	s_mov_b32 s18, 0x67000
	s_nop 0
	v_addc_co_u32_e32 v41, vcc, 0, v33, vcc
	global_load_dword v49, v[40:41], off nt
	v_add_co_u32_e32 v40, vcc, s18, v32
	s_mov_b32 s18, 0x73000
	s_nop 0
	v_addc_co_u32_e32 v41, vcc, 0, v33, vcc
	global_load_dword v50, v[40:41], off offset:2048 nt
	v_add_co_u32_e32 v40, vcc, s18, v32
	s_mov_b32 s18, 0x7e000
	s_nop 0
	v_addc_co_u32_e32 v41, vcc, 0, v33, vcc
	global_load_dword v51, v[40:41], off nt
	v_add_co_u32_e32 v40, vcc, s18, v32
	s_mov_b32 s18, 0x8a000
	s_nop 0
	v_addc_co_u32_e32 v41, vcc, 0, v33, vcc
	global_load_dword v52, v[40:41], off offset:2048 nt
	v_add_co_u32_e32 v40, vcc, s18, v32
	s_mov_b32 s18, 0x95000
	s_nop 0
	v_addc_co_u32_e32 v41, vcc, 0, v33, vcc
	global_load_dword v53, v[40:41], off nt
	v_add_co_u32_e32 v40, vcc, s18, v32
	s_mov_b32 s18, 0xa1000
	s_nop 0
	v_addc_co_u32_e32 v41, vcc, 0, v33, vcc
	global_load_dword v54, v[40:41], off offset:2048 nt
	v_add_co_u32_e32 v40, vcc, s18, v32
	s_mov_b32 s18, 0xac000
	s_nop 0
	v_addc_co_u32_e32 v41, vcc, 0, v33, vcc
	global_load_dword v55, v[40:41], off nt
	v_add_co_u32_e32 v40, vcc, s18, v32
	s_mov_b32 s18, 0xb8000
	s_nop 0
	v_addc_co_u32_e32 v41, vcc, 0, v33, vcc
	global_load_dword v56, v[40:41], off offset:2048 nt
	v_add_co_u32_e32 v40, vcc, s18, v32
	s_mov_b32 s18, 0xc3000
	s_nop 0
	v_addc_co_u32_e32 v41, vcc, 0, v33, vcc
	global_load_dword v57, v[40:41], off nt
	v_add_co_u32_e32 v40, vcc, s18, v32
	s_mov_b32 s18, 0xcf000
	s_nop 0
	v_addc_co_u32_e32 v41, vcc, 0, v33, vcc
	global_load_dword v58, v[40:41], off offset:2048 nt
	v_add_co_u32_e32 v40, vcc, s18, v32
	s_mov_b32 s18, 0xda000
	s_nop 0
	v_addc_co_u32_e32 v41, vcc, 0, v33, vcc
	global_load_dword v59, v[40:41], off nt
	v_add_co_u32_e32 v40, vcc, s18, v32
	s_mov_b32 s18, 0xe6000
	s_nop 0
	v_addc_co_u32_e32 v41, vcc, 0, v33, vcc
	global_load_dword v60, v[40:41], off offset:2048 nt
	v_add_co_u32_e32 v40, vcc, s18, v32
	s_mov_b32 s18, 0xf1000
	s_nop 0
	v_addc_co_u32_e32 v41, vcc, 0, v33, vcc
	global_load_dword v61, v[40:41], off nt
	v_add_co_u32_e32 v40, vcc, s18, v32
	s_mov_b32 s18, 0xfd000
	s_nop 0
	v_addc_co_u32_e32 v41, vcc, 0, v33, vcc
	global_load_dword v62, v[40:41], off offset:2048 nt
	v_add_co_u32_e32 v40, vcc, s18, v32
	s_mov_b32 s18, 0x108000
	s_nop 0
	v_addc_co_u32_e32 v41, vcc, 0, v33, vcc
	global_load_dword v63, v[40:41], off nt
	v_add_co_u32_e32 v40, vcc, s18, v32
	s_mov_b32 s18, 0x114000
	s_nop 0
	v_addc_co_u32_e32 v41, vcc, 0, v33, vcc
	global_load_dword v64, v[40:41], off offset:2048 nt
	v_add_co_u32_e32 v40, vcc, s18, v32
	s_mov_b32 s18, 0x11f000
	s_nop 0
	v_addc_co_u32_e32 v41, vcc, 0, v33, vcc
	global_load_dword v65, v[40:41], off nt
	v_add_co_u32_e32 v40, vcc, s18, v32
	s_mov_b32 s18, 0x12b000
	s_nop 0
	v_addc_co_u32_e32 v41, vcc, 0, v33, vcc
	global_load_dword v66, v[40:41], off offset:2048 nt
	v_add_co_u32_e32 v40, vcc, s18, v32
	s_mov_b32 s18, 0x136000
	s_nop 0
	v_addc_co_u32_e32 v41, vcc, 0, v33, vcc
	global_load_dword v67, v[40:41], off nt
	v_add_co_u32_e32 v40, vcc, s18, v32
	s_mov_b32 s18, 0x142000
	s_nop 0
	v_addc_co_u32_e32 v41, vcc, 0, v33, vcc
	global_load_dword v68, v[40:41], off offset:2048 nt
	v_add_co_u32_e32 v40, vcc, s18, v32
	s_mov_b32 s18, 0x14d000
	s_nop 0
	v_addc_co_u32_e32 v41, vcc, 0, v33, vcc
	global_load_dword v69, v[40:41], off nt
	v_add_co_u32_e32 v40, vcc, s18, v32
	s_mov_b32 s18, 0x159000
	s_nop 0
	v_addc_co_u32_e32 v41, vcc, 0, v33, vcc
	global_load_dword v70, v[40:41], off offset:2048 nt
	v_add_co_u32_e32 v40, vcc, s18, v32
	s_mov_b32 s18, 0x164000
	s_nop 0
	v_addc_co_u32_e32 v41, vcc, 0, v33, vcc
	v_add_co_u32_e32 v32, vcc, s18, v32
	global_load_dword v40, v[40:41], off nt
	s_nop 0
	v_addc_co_u32_e32 v33, vcc, 0, v33, vcc
	global_load_dword v32, v[32:33], off offset:2048 nt
	s_waitcnt vmcnt(30)
; #define LAS __attribute__((address_space(3)))
; __device__ __forceinline__ unsigned pk2(float lo, float hi) { const f32x2 v = {lo, hi}; const bf16x2_hw b = __builtin_convertvector(v, bf16x2_hw); return __builtin_bit_cast(unsigned, b); }
; __device__ __forceinline__ void gst_wt16(void* p, const u32x4 v) { asm volatile("global_store_dwordx4 %0, %1, off sc1\n\ts_nop 1" :: "v"(p), "v"(v) : "memory"); }
; __device__ __forceinline__ void transpose_item(const float* W, int K, int N, bf16_t* WT, int kb, int nb, int drow0, const float* kscale, LAS float* scr, int lane) {
;     ...
;     for (int i = 0; i < 32; ++i) scr[(2 * i + (lane >> 5)) * 33 + (lane & 31)] = w[i];
;     asm volatile("s_waitcnt lgkmcnt(0)" ::: "memory");
; #pragma unroll
;     for (int j = 0; j < 4; ++j) { const int n = (lane >> 3) + 8 * j; const LAS float* s = scr + (8 * c) * 33 + n;
;         u32x4 o; o.x = pk2(s[0 * 33] * s0[0], s[1 * 33] * s0[1]); o.y = pk2(s[2 * 33] * s0[2], s[3 * 33] * s0[3]); o.z = pk2(s[4 * 33] * s1[0], s[5 * 33] * s1[1]); o.w = pk2(s[6 * 33] * s1[2], s[7 * 33] * s1[3]);
;         gst_wt16(WT + (size_t)(drow0 + n) * K + k0 + 8 * c, o); }
;     asm volatile("s_waitcnt lgkmcnt(0)" ::: "memory");
	ds_write2_b32 v34, v0, v42 offset1:66
	s_waitcnt vmcnt(28)
	ds_write2_b32 v34, v43, v44 offset0:132 offset1:198
	v_add_u32_e32 v0, 0x400, v34
	s_waitcnt vmcnt(26)
	ds_write2_b32 v0, v45, v46 offset0:8 offset1:74
	s_waitcnt vmcnt(24)
	ds_write2_b32 v0, v47, v48 offset0:140 offset1:206
	v_add_u32_e32 v0, 0x800, v34
	s_waitcnt vmcnt(22)
	ds_write2_b32 v0, v49, v50 offset0:16 offset1:82
	s_waitcnt vmcnt(20)
	ds_write2_b32 v0, v51, v52 offset0:148 offset1:214
	v_add_u32_e32 v0, 0xc00, v34
	s_waitcnt vmcnt(18)
	ds_write2_b32 v0, v53, v54 offset0:24 offset1:90
	s_waitcnt vmcnt(16)
	ds_write2_b32 v0, v55, v56 offset0:156 offset1:222
	v_add_u32_e32 v0, 0x1000, v34
	s_waitcnt vmcnt(14)
	ds_write2_b32 v0, v57, v58 offset0:32 offset1:98
	s_waitcnt vmcnt(12)
	ds_write2_b32 v0, v59, v60 offset0:164 offset1:230
	v_add_u32_e32 v0, 0x1400, v34
	s_waitcnt vmcnt(10)
	ds_write2_b32 v0, v61, v62 offset0:40 offset1:106
	s_waitcnt vmcnt(8)
	ds_write2_b32 v0, v63, v64 offset0:172 offset1:238
	v_add_u32_e32 v0, 0x1800, v34
	s_waitcnt vmcnt(6)
	ds_write2_b32 v0, v65, v66 offset0:48 offset1:114
	s_waitcnt vmcnt(4)
	ds_write2_b32 v0, v67, v68 offset0:180 offset1:246
	v_add_u32_e32 v0, 0x1c00, v34
	s_waitcnt vmcnt(2)
	ds_write2_b32 v0, v69, v70 offset0:56 offset1:122
	s_waitcnt vmcnt(0)
	ds_write2_b32 v0, v40, v32 offset0:188 offset1:254
	s_waitcnt lgkmcnt(0)
	ds_read2_b32 v[40:41], v36 offset1:33
	ds_read2_b32 v[42:43], v36 offset0:66 offset1:99
	ds_read2_b32 v[44:45], v36 offset0:198 offset1:231
	v_lshl_add_u64 v[32:33], s[0:1], 1, v[12:13]
	s_waitcnt lgkmcnt(2)
	v_pk_mul_f32 v[40:41], v[6:7], v[40:41]
	s_waitcnt lgkmcnt(1)
	v_pk_mul_f32 v[42:43], v[8:9], v[42:43]
	v_cvt_pk_bf16_f32 v40, v40, v41
	v_cvt_pk_bf16_f32 v41, v42, v43
	ds_read2_b32 v[42:43], v36 offset0:132 offset1:165
	s_waitcnt lgkmcnt(1)
	v_pk_mul_f32 v[44:45], v[4:5], v[44:45]
	s_waitcnt lgkmcnt(0)
	v_pk_mul_f32 v[42:43], v[2:3], v[42:43]
	s_nop 0
	v_cvt_pk_bf16_f32 v42, v42, v43
	v_cvt_pk_bf16_f32 v43, v44, v45
	v_add_u32_e32 v44, s25, v35
	v_ashrrev_i32_e32 v45, 31, v44
	v_lshlrev_b64 v[44:45], 11, v[44:45]
	v_lshl_add_u64 v[44:45], v[32:33], 0, v[44:45]
	global_store_dwordx4 v[44:45], v[40:43], off sc1 nt
	s_nop 1
	ds_read2_b32 v[40:41], v36 offset0:8 offset1:41
	ds_read2_b32 v[42:43], v36 offset0:74 offset1:107
	ds_read2_b32 v[44:45], v36 offset0:206 offset1:239
	s_waitcnt lgkmcnt(2)
	v_pk_mul_f32 v[40:41], v[6:7], v[40:41]
	s_waitcnt lgkmcnt(1)
	v_pk_mul_f32 v[42:43], v[8:9], v[42:43]
	v_cvt_pk_bf16_f32 v40, v40, v41
	v_cvt_pk_bf16_f32 v41, v42, v43
	ds_read2_b32 v[42:43], v36 offset0:140 offset1:173
	s_waitcnt lgkmcnt(1)
	v_pk_mul_f32 v[44:45], v[4:5], v[44:45]
	s_waitcnt lgkmcnt(0)
	v_pk_mul_f32 v[42:43], v[2:3], v[42:43]
	s_nop 0
	v_cvt_pk_bf16_f32 v42, v42, v43
	v_cvt_pk_bf16_f32 v43, v44, v45
	v_add_u32_e32 v44, s25, v37
	v_ashrrev_i32_e32 v45, 31, v44
	v_lshlrev_b64 v[44:45], 11, v[44:45]
	v_lshl_add_u64 v[44:45], v[32:33], 0, v[44:45]
	global_store_dwordx4 v[44:45], v[40:43], off sc1 nt
	s_nop 1
	ds_read2_b32 v[40:41], v36 offset0:16 offset1:49
	ds_read2_b32 v[42:43], v36 offset0:82 offset1:115
	ds_read2_b32 v[44:45], v36 offset0:214 offset1:247
	s_waitcnt lgkmcnt(2)
	v_pk_mul_f32 v[40:41], v[6:7], v[40:41]
	s_waitcnt lgkmcnt(1)
	v_pk_mul_f32 v[42:43], v[8:9], v[42:43]
	v_cvt_pk_bf16_f32 v40, v40, v41
	v_cvt_pk_bf16_f32 v41, v42, v43
	ds_read2_b32 v[42:43], v36 offset0:148 offset1:181
	s_waitcnt lgkmcnt(1)
	v_pk_mul_f32 v[44:45], v[4:5], v[44:45]
	s_waitcnt lgkmcnt(0)
	v_pk_mul_f32 v[42:43], v[2:3], v[42:43]
	s_nop 0
	v_cvt_pk_bf16_f32 v42, v42, v43
	v_cvt_pk_bf16_f32 v43, v44, v45
	v_add_u32_e32 v44, s25, v38
	v_ashrrev_i32_e32 v45, 31, v44
	v_lshlrev_b64 v[44:45], 11, v[44:45]
	v_lshl_add_u64 v[44:45], v[32:33], 0, v[44:45]
	global_store_dwordx4 v[44:45], v[40:43], off sc1 nt
	s_nop 1
	ds_read2_b32 v[40:41], v36 offset0:24 offset1:57
	s_waitcnt lgkmcnt(0)
	v_pk_mul_f32 v[6:7], v[6:7], v[40:41]
	ds_read2_b32 v[40:41], v36 offset0:90 offset1:123
	v_cvt_pk_bf16_f32 v6, v6, v7
	s_waitcnt lgkmcnt(0)
	v_pk_mul_f32 v[8:9], v[8:9], v[40:41]
	s_nop 0
	v_cvt_pk_bf16_f32 v7, v8, v9
	ds_read2_b32 v[8:9], v36 offset0:156 offset1:189
	s_waitcnt lgkmcnt(0)
	v_pk_mul_f32 v[2:3], v[2:3], v[8:9]
	s_nop 0
	v_cvt_pk_bf16_f32 v8, v2, v3
	ds_read2_b32 v[2:3], v36 offset0:222 offset1:255
	s_waitcnt lgkmcnt(0)
	v_pk_mul_f32 v[2:3], v[4:5], v[2:3]
	s_nop 0
	v_cvt_pk_bf16_f32 v9, v2, v3
	v_add_u32_e32 v2, s25, v39
	v_ashrrev_i32_e32 v3, 31, v2
	v_lshlrev_b64 v[2:3], 11, v[2:3]
	v_lshl_add_u64 v[2:3], v[32:33], 0, v[2:3]
	global_store_dwordx4 v[2:3], v[6:9], off sc1 nt
	s_nop 1
	s_waitcnt lgkmcnt(0)

; __device__ __forceinline__ void transpose_item(const float* W, int K, int N, bf16_t* WT, int kb, int nb, int drow0, const float* kscale, LAS float* scr, int lane) {
;     const int k0 = 64 * kb, n0 = 32 * nb, c = lane & 7;
; __device__ __forceinline__ void prep_weights(Frame& F, const Args& a, int l, int it_lo, int it_hi, int gw, int ngw) {
;     ...
;     for (int it = it_lo + gw; it < it_hi; it += ngw) {
;         int r = it;
;         if (r < I0) { const int kb = r / 184, nb = r % 184, n0 = 32 * nb; int d0 = n0;
;             if (n0 >= C_CC && n0 < C_CX) { const int c = n0 - C_CC; d0 = 256 * (5 + c / 128) + (c % 128); }
;             else if (n0 >= C_CX && n0 < C_U) { const int c = n0 - C_CX; d0 = 256 * (5 + c / 128) + 128 + (c % 128); }
;             else if (n0 >= C_G && n0 < C_G + 1024) { const int c = n0 - C_G; d0 = 256 * (11 + c / 128) + (c % 128); }
;             else if (n0 >= C_G + 1024 && n0 < C_G + 2048) { const int c = n0 - C_G - 1024; d0 = 256 * (11 + c / 128) + 128 + (c % 128); }
;             transpose_item(w_in, DM, INCOLS, W + WO_IN, kb, nb, d0, nmix, scr, F.lane); continue; } r -= I0;
;         if (r < I1) { const int kb = r / 32, nb = r % 32; transpose_item(w_ao, 512, DM, W + WO_AO, kb, nb, 32 * nb, nullptr, scr, F.lane); continue; } r -= I1;
;         if (r < I2) { const int kb = r / 32, nb = r % 32; transpose_item(w_co, 512, DM, W + WO_CO, kb, nb, 32 * nb, nullptr, scr, F.lane); continue; } r -= I2;
;         if (r < I3) { const int kb = r / 16, nb = r % 16; transpose_item(w_gl, 512, 512, W + WO_GLU, kb, nb, 32 * nb, nullptr, scr, F.lane); continue; } r -= I3;
;         if (r < I4) { const int kb = r / 32, nb = r % 32; transpose_item(w_so, 512, DM, W + WO_SO, kb, nb, 32 * nb, nullptr, scr, F.lane); continue; } r -= I4;
;         if (r < I5) { const int kb = r / 32, nb = r % 32; transpose_item(w_mx, DM, DM, W + WO_MIX, kb, nb, 32 * nb, nullptr, scr, F.lane); continue; } r -= I5;
;         if (r < I6) { const int kb = r / 176, nb = r % 176; const int n0 = 32 * nb; const int j0 = n0 < FFN ? n0 : n0 - FFN; const int drow0 = 256 * (j0 / 128) + (n0 < FFN ? 0 : 128) + (j0 % 128);
;             transpose_item(w_fi, DM, FFN2, W + WO_FI, kb, nb, drow0, nffn, scr, F.lane); continue; } r -= I6;
;         { const int kb = r / 32, nb = r % 32; transpose_item(w_fo, FFN, DM, W + WO_FO, kb, nb, 32 * nb, nullptr, scr, F.lane); }
.LBB0_1400:
	s_cmpk_gt_i32 s20, 0xb7f
	s_mov_b64 s[0:1], -1
	s_cbranch_scc0 .LBB0_1430
	s_cmpk_gt_u32 s20, 0xc7f
	s_cbranch_scc0 .LBB0_1427
	s_cmpk_gt_u32 s20, 0xd7f
	s_cbranch_scc0 .LBB0_1424
	s_cmpk_gt_u32 s20, 0xdff
	s_cbranch_scc0 .LBB0_1421
	s_cmpk_gt_u32 s20, 0xeff
	s_cbranch_scc0 .LBB0_1418
	s_cmpk_gt_u32 s20, 0x10ff
	s_cbranch_scc0 .LBB0_1415
	s_cmpk_gt_u32 s20, 0x1bff
	s_cbranch_scc0 .LBB0_1408
	s_and_b32 s1, s23, 0x7fffffc0
	s_add_i32 s72, s1, 0xffffc800
	v_or_b32_e32 v0, s72, v11
	s_and_b32 s0, s21, 0x3e0
	v_lshlrev_b64 v[2:3], 12, v[0:1]
	v_lshl_add_u64 v[2:3], s[16:17], 0, v[2:3]
	s_lshl_b32 s18, s0, 2
	s_mov_b32 s19, s73
	v_lshl_add_u64 v[2:3], v[2:3], 0, s[18:19]
	v_lshlrev_b32_e32 v0, 2, v10
	v_lshl_add_u64 v[2:3], v[2:3], 0, v[0:1]
	s_movk_i32 s1, 0x2000
	v_add_co_u32_e32 v4, vcc, s1, v2
	s_movk_i32 s1, 0x4000
	s_nop 0
	v_addc_co_u32_e32 v5, vcc, 0, v3, vcc
	global_load_dword v0, v[2:3], off nt
	global_load_dword v6, v[4:5], off nt
	v_add_co_u32_e32 v4, vcc, s1, v2
	s_movk_i32 s1, 0x6000
	s_nop 0
	v_addc_co_u32_e32 v5, vcc, 0, v3, vcc
	global_load_dword v7, v[4:5], off nt
	v_add_co_u32_e32 v4, vcc, s1, v2
	s_mov_b32 s1, 0x8000
	s_nop 0
	v_addc_co_u32_e32 v5, vcc, 0, v3, vcc
	global_load_dword v8, v[4:5], off nt
	v_add_co_u32_e32 v4, vcc, s1, v2
	s_mov_b32 s1, 0xa000
	s_nop 0
	v_addc_co_u32_e32 v5, vcc, 0, v3, vcc
	global_load_dword v9, v[4:5], off nt
	v_add_co_u32_e32 v4, vcc, s1, v2
	s_mov_b32 s1, 0xc000
	s_nop 0
	v_addc_co_u32_e32 v5, vcc, 0, v3, vcc
	global_load_dword v32, v[4:5], off nt
	v_add_co_u32_e32 v4, vcc, s1, v2
	s_mov_b32 s1, 0xe000
	s_nop 0
	v_addc_co_u32_e32 v5, vcc, 0, v3, vcc
	global_load_dword v33, v[4:5], off nt
	v_add_co_u32_e32 v4, vcc, s1, v2
	s_mov_b32 s1, 0x10000
	s_nop 0
	v_addc_co_u32_e32 v5, vcc, 0, v3, vcc
	global_load_dword v40, v[4:5], off nt
	v_add_co_u32_e32 v4, vcc, s1, v2
	s_mov_b32 s1, 0x12000
	s_nop 0
	v_addc_co_u32_e32 v5, vcc, 0, v3, vcc
	global_load_dword v41, v[4:5], off nt
	v_add_co_u32_e32 v4, vcc, s1, v2
	s_mov_b32 s1, 0x14000
	s_nop 0
	v_addc_co_u32_e32 v5, vcc, 0, v3, vcc
	global_load_dword v42, v[4:5], off nt
	v_add_co_u32_e32 v4, vcc, s1, v2
	s_mov_b32 s1, 0x16000
	s_nop 0
	v_addc_co_u32_e32 v5, vcc, 0, v3, vcc
	global_load_dword v43, v[4:5], off nt
	v_add_co_u32_e32 v4, vcc, s1, v2
	s_mov_b32 s1, 0x18000
	s_nop 0
	v_addc_co_u32_e32 v5, vcc, 0, v3, vcc
	global_load_dword v44, v[4:5], off nt
	v_add_co_u32_e32 v4, vcc, s1, v2
	s_mov_b32 s1, 0x1a000
	s_nop 0
	v_addc_co_u32_e32 v5, vcc, 0, v3, vcc
	global_load_dword v45, v[4:5], off nt
	v_add_co_u32_e32 v4, vcc, s1, v2
	s_mov_b32 s1, 0x1c000
	s_nop 0
	v_addc_co_u32_e32 v5, vcc, 0, v3, vcc
	global_load_dword v46, v[4:5], off nt
	v_add_co_u32_e32 v4, vcc, s1, v2
	s_mov_b32 s1, 0x1e000
	s_nop 0
	v_addc_co_u32_e32 v5, vcc, 0, v3, vcc
	global_load_dword v47, v[4:5], off nt
	v_add_co_u32_e32 v4, vcc, s1, v2
	s_mov_b32 s1, 0x22000
	s_nop 0
	v_addc_co_u32_e32 v5, vcc, 0, v3, vcc
	global_load_dword v48, v[4:5], off nt
	v_add_co_u32_e32 v4, vcc, s79, v2
	s_nop 1
	v_addc_co_u32_e32 v5, vcc, 0, v3, vcc
	global_load_dword v49, v[4:5], off nt
	v_add_co_u32_e32 v4, vcc, s1, v2
	s_mov_b32 s1, 0x24000
	s_nop 0
	v_addc_co_u32_e32 v5, vcc, 0, v3, vcc
	global_load_dword v50, v[4:5], off nt
	v_add_co_u32_e32 v4, vcc, s1, v2
	s_mov_b32 s1, 0x26000
	s_nop 0
	v_addc_co_u32_e32 v5, vcc, 0, v3, vcc
	global_load_dword v51, v[4:5], off nt
	v_add_co_u32_e32 v4, vcc, s1, v2
	s_mov_b32 s1, 0x28000
	s_nop 0
	v_addc_co_u32_e32 v5, vcc, 0, v3, vcc
	global_load_dword v52, v[4:5], off nt
	v_add_co_u32_e32 v4, vcc, s1, v2
	s_mov_b32 s1, 0x2a000
	s_nop 0
	v_addc_co_u32_e32 v5, vcc, 0, v3, vcc
	global_load_dword v53, v[4:5], off nt
	v_add_co_u32_e32 v4, vcc, s1, v2
	s_mov_b32 s1, 0x2c000
	s_nop 0
	v_addc_co_u32_e32 v5, vcc, 0, v3, vcc
	global_load_dword v54, v[4:5], off nt
	v_add_co_u32_e32 v4, vcc, s1, v2
	s_mov_b32 s1, 0x2e000
	s_nop 0
	v_addc_co_u32_e32 v5, vcc, 0, v3, vcc
	global_load_dword v55, v[4:5], off nt
	v_add_co_u32_e32 v4, vcc, s1, v2
	s_mov_b32 s1, 0x30000
	s_nop 0
	v_addc_co_u32_e32 v5, vcc, 0, v3, vcc
	global_load_dword v56, v[4:5], off nt
	v_add_co_u32_e32 v4, vcc, s1, v2
	s_mov_b32 s1, 0x32000
	s_nop 0
	v_addc_co_u32_e32 v5, vcc, 0, v3, vcc
	global_load_dword v57, v[4:5], off nt
	v_add_co_u32_e32 v4, vcc, s1, v2
	s_mov_b32 s1, 0x34000
	s_nop 0
	v_addc_co_u32_e32 v5, vcc, 0, v3, vcc
	global_load_dword v58, v[4:5], off nt
	v_add_co_u32_e32 v4, vcc, s1, v2
	s_mov_b32 s1, 0x36000
	s_nop 0
	v_addc_co_u32_e32 v5, vcc, 0, v3, vcc
	global_load_dword v59, v[4:5], off nt
	v_add_co_u32_e32 v4, vcc, s1, v2
	s_mov_b32 s1, 0x38000
	s_nop 0
	v_addc_co_u32_e32 v5, vcc, 0, v3, vcc
	global_load_dword v60, v[4:5], off nt
	v_add_co_u32_e32 v4, vcc, s1, v2
	s_mov_b32 s1, 0x3a000
	s_nop 0
	v_addc_co_u32_e32 v5, vcc, 0, v3, vcc
	global_load_dword v61, v[4:5], off nt
	v_add_co_u32_e32 v4, vcc, s1, v2
	s_mov_b32 s1, 0x3c000
	s_nop 0
	v_addc_co_u32_e32 v5, vcc, 0, v3, vcc
	global_load_dword v62, v[4:5], off nt
	v_add_co_u32_e32 v4, vcc, s1, v2
	s_mov_b32 s1, 0x3e000
	s_nop 0
	v_addc_co_u32_e32 v5, vcc, 0, v3, vcc
	v_add_co_u32_e32 v2, vcc, s1, v2
	global_load_dword v4, v[4:5], off nt
	s_nop 0
	v_addc_co_u32_e32 v3, vcc, 0, v3, vcc
	global_load_dword v2, v[2:3], off nt
	s_waitcnt vmcnt(30)
; #define LAS __attribute__((address_space(3)))
; __device__ __forceinline__ unsigned pk2(float lo, float hi) { const f32x2 v = {lo, hi}; const bf16x2_hw b = __builtin_convertvector(v, bf16x2_hw); return __builtin_bit_cast(unsigned, b); }
; __device__ __forceinline__ void gst_wt16(void* p, const u32x4 v) { asm volatile("global_store_dwordx4 %0, %1, off sc1\n\ts_nop 1" :: "v"(p), "v"(v) : "memory"); }
; __device__ __forceinline__ void transpose_item(const float* W, int K, int N, bf16_t* WT, int kb, int nb, int drow0, const float* kscale, LAS float* scr, int lane) {
;     ...
;     for (int i = 0; i < 32; ++i) scr[(2 * i + (lane >> 5)) * 33 + (lane & 31)] = w[i];
;     asm volatile("s_waitcnt lgkmcnt(0)" ::: "memory");
; #pragma unroll
;     for (int j = 0; j < 4; ++j) { const int n = (lane >> 3) + 8 * j; const LAS float* s = scr + (8 * c) * 33 + n;
;         u32x4 o; o.x = pk2(s[0 * 33] * s0[0], s[1 * 33] * s0[1]); o.y = pk2(s[2 * 33] * s0[2], s[3 * 33] * s0[3]); o.z = pk2(s[4 * 33] * s1[0], s[5 * 33] * s1[1]); o.w = pk2(s[6 * 33] * s1[2], s[7 * 33] * s1[3]);
;         gst_wt16(WT + (size_t)(drow0 + n) * K + k0 + 8 * c, o); }
;     asm volatile("s_waitcnt lgkmcnt(0)" ::: "memory");
	ds_write2_b32 v34, v0, v6 offset1:66
	s_waitcnt vmcnt(28)
	ds_write2_b32 v34, v7, v8 offset0:132 offset1:198
	v_add_u32_e32 v0, 0x400, v34
	s_waitcnt vmcnt(26)
	ds_write2_b32 v0, v9, v32 offset0:8 offset1:74
	s_waitcnt vmcnt(24)
	ds_write2_b32 v0, v33, v40 offset0:140 offset1:206
	v_add_u32_e32 v0, 0x800, v34
	s_waitcnt vmcnt(22)
	ds_write2_b32 v0, v41, v42 offset0:16 offset1:82
	s_waitcnt vmcnt(20)
	ds_write2_b32 v0, v43, v44 offset0:148 offset1:214
	v_add_u32_e32 v0, 0xc00, v34
	s_waitcnt vmcnt(18)
	ds_write2_b32 v0, v45, v46 offset0:24 offset1:90
	s_waitcnt vmcnt(16)
	ds_write2_b32 v0, v47, v48 offset0:156 offset1:222
	v_add_u32_e32 v0, 0x1000, v34
	s_waitcnt vmcnt(14)
	ds_write2_b32 v0, v49, v50 offset0:32 offset1:98
	s_waitcnt vmcnt(12)
	ds_write2_b32 v0, v51, v52 offset0:164 offset1:230
	v_add_u32_e32 v0, 0x1400, v34
	s_waitcnt vmcnt(10)
	ds_write2_b32 v0, v53, v54 offset0:40 offset1:106
	s_waitcnt vmcnt(8)
	ds_write2_b32 v0, v55, v56 offset0:172 offset1:238
	v_add_u32_e32 v0, 0x1800, v34
	s_waitcnt vmcnt(6)
	ds_write2_b32 v0, v57, v58 offset0:48 offset1:114
	s_waitcnt vmcnt(4)
	ds_write2_b32 v0, v59, v60 offset0:180 offset1:246
	v_add_u32_e32 v0, 0x1c00, v34
	s_waitcnt vmcnt(2)
	ds_write2_b32 v0, v61, v62 offset0:56 offset1:122
	s_waitcnt vmcnt(0)
	ds_write2_b32 v0, v4, v2 offset0:188 offset1:254
	s_waitcnt lgkmcnt(0)
	ds_read2_b32 v[2:3], v36 offset1:33
	ds_read2_b32 v[4:5], v36 offset0:66 offset1:99
	ds_read2_b32 v[8:9], v36 offset0:198 offset1:231
	v_or_b32_e32 v0, s0, v35
	v_lshl_add_u64 v[6:7], s[72:73], 1, v[14:15]
	s_waitcnt lgkmcnt(2)
	v_cvt_pk_bf16_f32 v2, v2, v3
	s_waitcnt lgkmcnt(1)
	v_cvt_pk_bf16_f32 v3, v4, v5
	ds_read2_b32 v[4:5], v36 offset0:132 offset1:165
	v_mul_u32_u24_e32 v0, 0x1600, v0
	s_waitcnt lgkmcnt(0)
	v_cvt_pk_bf16_f32 v4, v4, v5
	v_cvt_pk_bf16_f32 v5, v8, v9
	v_lshl_add_u64 v[8:9], v[6:7], 0, v[0:1]
	global_store_dwordx4 v[8:9], v[2:5], off sc1 nt
	s_nop 1
	ds_read2_b32 v[2:3], v36 offset0:8 offset1:41
	ds_read2_b32 v[4:5], v36 offset0:74 offset1:107
	ds_read2_b32 v[8:9], v36 offset0:206 offset1:239
	v_or_b32_e32 v0, s0, v37
	v_mul_u32_u24_e32 v0, 0x1600, v0
	s_waitcnt lgkmcnt(2)
	v_cvt_pk_bf16_f32 v2, v2, v3
	s_waitcnt lgkmcnt(1)
	v_cvt_pk_bf16_f32 v3, v4, v5
	ds_read2_b32 v[4:5], v36 offset0:140 offset1:173
	s_waitcnt lgkmcnt(0)
	v_cvt_pk_bf16_f32 v4, v4, v5
	v_cvt_pk_bf16_f32 v5, v8, v9
	v_lshl_add_u64 v[8:9], v[6:7], 0, v[0:1]
	global_store_dwordx4 v[8:9], v[2:5], off sc1 nt
	s_nop 1
	ds_read2_b32 v[2:3], v36 offset0:16 offset1:49
	ds_read2_b32 v[4:5], v36 offset0:82 offset1:115
	ds_read2_b32 v[8:9], v36 offset0:214 offset1:247
	v_or_b32_e32 v0, s0, v38
	v_mul_u32_u24_e32 v0, 0x1600, v0
	s_waitcnt lgkmcnt(2)
	v_cvt_pk_bf16_f32 v2, v2, v3
	s_waitcnt lgkmcnt(1)
	v_cvt_pk_bf16_f32 v3, v4, v5
	ds_read2_b32 v[4:5], v36 offset0:148 offset1:181
	s_waitcnt lgkmcnt(0)
	v_cvt_pk_bf16_f32 v4, v4, v5
	v_cvt_pk_bf16_f32 v5, v8, v9
	v_lshl_add_u64 v[8:9], v[6:7], 0, v[0:1]
	global_store_dwordx4 v[8:9], v[2:5], off sc1 nt
	s_nop 1
	ds_read2_b32 v[2:3], v36 offset0:24 offset1:57
	ds_read2_b32 v[4:5], v36 offset0:90 offset1:123
	ds_read2_b32 v[8:9], v36 offset0:222 offset1:255
	v_or_b32_e32 v0, s0, v39
	v_mul_u32_u24_e32 v0, 0x1600, v0
	s_waitcnt lgkmcnt(2)
	v_cvt_pk_bf16_f32 v2, v2, v3
	s_waitcnt lgkmcnt(1)
	v_cvt_pk_bf16_f32 v3, v4, v5
	ds_read2_b32 v[4:5], v36 offset0:156 offset1:189
	v_lshl_add_u64 v[6:7], v[6:7], 0, v[0:1]
	s_mov_b64 s[0:1], 0
	s_waitcnt lgkmcnt(0)
	v_cvt_pk_bf16_f32 v4, v4, v5
	v_cvt_pk_bf16_f32 v5, v8, v9
	global_store_dwordx4 v[6:7], v[2:5], off sc1 nt
	s_nop 1
	s_waitcnt lgkmcnt(0)

; __device__ __forceinline__ void transpose_item(const float* W, int K, int N, bf16_t* WT, int kb, int nb, int drow0, const float* kscale, LAS float* scr, int lane) {
;     const int k0 = 64 * kb, n0 = 32 * nb, c = lane & 7;
;     f32x4 s0 = {1.f, 1.f, 1.f, 1.f}, s1 = {1.f, 1.f, 1.f, 1.f};
;     if (kscale) { s0 = *(const f32x4*)(kscale + k0 + 8 * c); s1 = *(const f32x4*)(kscale + k0 + 8 * c + 4); }
;     const float* src = W + (size_t)(k0 + (lane >> 5)) * N + n0 + (lane & 31);
;     float w[32];
; #pragma unroll
;     for (int i = 0; i < 32; ++i) w[i] = __builtin_nontemporal_load(src + (size_t)(2 * i) * N);
; #pragma unroll
;     for (int i = 0; i < 32; ++i) scr[(2 * i + (lane >> 5)) * 33 + (lane & 31)] = w[i];
; __device__ __forceinline__ void prep_weights(Frame& F, const Args& a, int l, int it_lo, int it_hi, int gw, int ngw) {
;     ...
;         if (r < I6) { const int kb = r / 176, nb = r % 176; const int n0 = 32 * nb; const int j0 = n0 < FFN ? n0 : n0 - FFN; const int drow0 = 256 * (j0 / 128) + (n0 < FFN ? 0 : 128) + (j0 % 128);
;             transpose_item(w_fi, DM, FFN2, W + WO_FI, kb, nb, drow0, nffn, scr, F.lane); continue; } r -= I6;
.LBB0_1413:
	s_mulk_i32 s18, 0xb0
	s_sub_i32 s18, s0, s18
	s_lshl_b32 s0, s18, 5
	s_and_b32 s19, s18, 0xffff
	s_add_i32 s25, s0, 0xf500
	s_cmpk_lt_u32 s19, 0x58
	s_cselect_b32 s0, s0, s25
	s_sext_i32_i16 s19, s0
	s_cselect_b32 s25, 0, 0x80
	s_bfe_u32 s19, s19, 0x70018
	s_add_i32 s19, s0, s19
	s_sext_i32_i16 s26, s19
	s_and_b32 s19, s19, 0xff80
	s_sub_i32 s0, s0, s19
	s_and_b32 s19, 0xffff, s1
	v_or_b32_e32 v0, s19, v11
	v_mul_u32_u24_e32 v0, 0x5800, v0
	s_lshl_b32 s18, s18, 7
	v_lshl_add_u64 v[32:33], s[14:15], 0, v[0:1]
	s_and_b32 s72, s18, 0x3ff80
	v_lshl_add_u64 v[32:33], v[32:33], 0, s[72:73]
	v_lshlrev_b32_e32 v0, 2, v10
	v_lshl_add_u64 v[32:33], v[32:33], 0, v[0:1]
	s_mov_b32 s18, 0xb000
	v_add_co_u32_e32 v40, vcc, s18, v32
	s_mov_b32 s18, 0x16000
	s_nop 0
	v_addc_co_u32_e32 v41, vcc, 0, v33, vcc
	global_load_dword v0, v[32:33], off nt
	global_load_dword v42, v[40:41], off nt
	v_add_co_u32_e32 v40, vcc, s18, v32
	s_mov_b32 s18, 0x21000
	s_nop 0
	v_addc_co_u32_e32 v41, vcc, 0, v33, vcc
	global_load_dword v43, v[40:41], off nt
	v_add_co_u32_e32 v40, vcc, s18, v32
	s_mov_b32 s18, 0x2c000
	s_nop 0
	v_addc_co_u32_e32 v41, vcc, 0, v33, vcc
	global_load_dword v44, v[40:41], off nt
	v_add_co_u32_e32 v40, vcc, s18, v32
	s_mov_b32 s18, 0x37000
	s_nop 0
	v_addc_co_u32_e32 v41, vcc, 0, v33, vcc
	global_load_dword v45, v[40:41], off nt
	v_add_co_u32_e32 v40, vcc, s18, v32
	s_mov_b32 s18, 0x42000
	s_nop 0
	v_addc_co_u32_e32 v41, vcc, 0, v33, vcc
	global_load_dword v46, v[40:41], off nt
	v_add_co_u32_e32 v40, vcc, s18, v32
	s_mov_b32 s18, 0x4d000
	s_nop 0
	v_addc_co_u32_e32 v41, vcc, 0, v33, vcc
	global_load_dword v47, v[40:41], off nt
	v_add_co_u32_e32 v40, vcc, s18, v32
	s_mov_b32 s18, 0x58000
	s_nop 0
	v_addc_co_u32_e32 v41, vcc, 0, v33, vcc
	global_load_dword v48, v[40:41], off nt
	v_add_co_u32_e32 v40, vcc, s18, v32
	s_mov_b32 s18, 0x63000
	s_nop 0
	v_addc_co_u32_e32 v41, vcc, 0, v33, vcc
	global_load_dword v49, v[40:41], off nt
	v_add_co_u32_e32 v40, vcc, s18, v32
	s_mov_b32 s18, 0x6e000
	s_nop 0
	v_addc_co_u32_e32 v41, vcc, 0, v33, vcc
	global_load_dword v50, v[40:41], off nt
	v_add_co_u32_e32 v40, vcc, s18, v32
	s_mov_b32 s18, 0x79000
	s_nop 0
	v_addc_co_u32_e32 v41, vcc, 0, v33, vcc
	global_load_dword v51, v[40:41], off nt
	v_add_co_u32_e32 v40, vcc, s18, v32
	s_mov_b32 s18, 0x84000
	s_nop 0
	v_addc_co_u32_e32 v41, vcc, 0, v33, vcc
	global_load_dword v52, v[40:41], off nt
	v_add_co_u32_e32 v40, vcc, s18, v32
	s_mov_b32 s18, 0x8f000
	s_nop 0
	v_addc_co_u32_e32 v41, vcc, 0, v33, vcc
	global_load_dword v53, v[40:41], off nt
	v_add_co_u32_e32 v40, vcc, s18, v32
	s_mov_b32 s18, 0x9a000
	s_nop 0
	v_addc_co_u32_e32 v41, vcc, 0, v33, vcc
	global_load_dword v54, v[40:41], off nt
	v_add_co_u32_e32 v40, vcc, s18, v32
	s_mov_b32 s18, 0xa5000
	s_nop 0
	v_addc_co_u32_e32 v41, vcc, 0, v33, vcc
	global_load_dword v55, v[40:41], off nt
	v_add_co_u32_e32 v40, vcc, s18, v32
	s_mov_b32 s18, 0xb0000
	s_nop 0
	v_addc_co_u32_e32 v41, vcc, 0, v33, vcc
	global_load_dword v56, v[40:41], off nt
	v_add_co_u32_e32 v40, vcc, s18, v32
	s_mov_b32 s18, 0xbb000
	s_nop 0
	v_addc_co_u32_e32 v41, vcc, 0, v33, vcc
	global_load_dword v57, v[40:41], off nt
	v_add_co_u32_e32 v40, vcc, s18, v32
	s_mov_b32 s18, 0xc6000
	s_nop 0
	v_addc_co_u32_e32 v41, vcc, 0, v33, vcc
	global_load_dword v58, v[40:41], off nt
	v_add_co_u32_e32 v40, vcc, s18, v32
	s_mov_b32 s18, 0xd1000
	s_nop 0
	v_addc_co_u32_e32 v41, vcc, 0, v33, vcc
	global_load_dword v59, v[40:41], off nt
	v_add_co_u32_e32 v40, vcc, s18, v32
	s_mov_b32 s18, 0xdc000
	s_nop 0
	v_addc_co_u32_e32 v41, vcc, 0, v33, vcc
	global_load_dword v60, v[40:41], off nt
	v_add_co_u32_e32 v40, vcc, s18, v32
	s_mov_b32 s18, 0xe7000
	s_nop 0
	v_addc_co_u32_e32 v41, vcc, 0, v33, vcc
	global_load_dword v61, v[40:41], off nt
	v_add_co_u32_e32 v40, vcc, s18, v32
	s_mov_b32 s18, 0xf2000
	s_nop 0
	v_addc_co_u32_e32 v41, vcc, 0, v33, vcc
	global_load_dword v62, v[40:41], off nt
	v_add_co_u32_e32 v40, vcc, s18, v32
	s_mov_b32 s18, 0xfd000
	s_nop 0
	v_addc_co_u32_e32 v41, vcc, 0, v33, vcc
	global_load_dword v63, v[40:41], off nt
	v_add_co_u32_e32 v40, vcc, s18, v32
	s_mov_b32 s18, 0x108000
	s_nop 0
	v_addc_co_u32_e32 v41, vcc, 0, v33, vcc
	global_load_dword v64, v[40:41], off nt
	v_add_co_u32_e32 v40, vcc, s18, v32
	s_mov_b32 s18, 0x113000
	s_nop 0
	v_addc_co_u32_e32 v41, vcc, 0, v33, vcc
	global_load_dword v65, v[40:41], off nt
	v_add_co_u32_e32 v40, vcc, s18, v32
	s_mov_b32 s18, 0x11e000
	s_nop 0
	v_addc_co_u32_e32 v41, vcc, 0, v33, vcc
	global_load_dword v66, v[40:41], off nt
	v_add_co_u32_e32 v40, vcc, s18, v32
	s_mov_b32 s18, 0x129000
	s_nop 0
	v_addc_co_u32_e32 v41, vcc, 0, v33, vcc
	global_load_dword v67, v[40:41], off nt
	v_add_co_u32_e32 v40, vcc, s18, v32
	s_mov_b32 s18, 0x134000
	s_nop 0
	v_addc_co_u32_e32 v41, vcc, 0, v33, vcc
	global_load_dword v68, v[40:41], off nt
	v_add_co_u32_e32 v40, vcc, s18, v32
	s_mov_b32 s18, 0x13f000
	s_nop 0
	v_addc_co_u32_e32 v41, vcc, 0, v33, vcc
	global_load_dword v69, v[40:41], off nt
	v_add_co_u32_e32 v40, vcc, s18, v32
	s_mov_b32 s18, 0x14a000
	s_nop 0
	v_addc_co_u32_e32 v41, vcc, 0, v33, vcc
	global_load_dword v70, v[40:41], off nt
	v_add_co_u32_e32 v40, vcc, s18, v32
	s_mov_b32 s18, 0x155000
	s_nop 0
	v_addc_co_u32_e32 v41, vcc, 0, v33, vcc
	v_add_co_u32_e32 v32, vcc, s18, v32
	global_load_dword v40, v[40:41], off nt
	s_nop 0
	v_addc_co_u32_e32 v33, vcc, 0, v33, vcc
	global_load_dword v32, v[32:33], off nt
	s_waitcnt vmcnt(30)
; #define LAS __attribute__((address_space(3)))
; __device__ __forceinline__ unsigned pk2(float lo, float hi) { const f32x2 v = {lo, hi}; const bf16x2_hw b = __builtin_convertvector(v, bf16x2_hw); return __builtin_bit_cast(unsigned, b); }
; __device__ __forceinline__ void gst_wt16(void* p, const u32x4 v) { asm volatile("global_store_dwordx4 %0, %1, off sc1\n\ts_nop 1" :: "v"(p), "v"(v) : "memory"); }
; __device__ __forceinline__ void transpose_item(const float* W, int K, int N, bf16_t* WT, int kb, int nb, int drow0, const float* kscale, LAS float* scr, int lane) {
;     ...
;     for (int i = 0; i < 32; ++i) scr[(2 * i + (lane >> 5)) * 33 + (lane & 31)] = w[i];
;     asm volatile("s_waitcnt lgkmcnt(0)" ::: "memory");
; #pragma unroll
;     for (int j = 0; j < 4; ++j) { const int n = (lane >> 3) + 8 * j; const LAS float* s = scr + (8 * c) * 33 + n;
;         u32x4 o; o.x = pk2(s[0 * 33] * s0[0], s[1 * 33] * s0[1]); o.y = pk2(s[2 * 33] * s0[2], s[3 * 33] * s0[3]); o.z = pk2(s[4 * 33] * s1[0], s[5 * 33] * s1[1]); o.w = pk2(s[6 * 33] * s1[2], s[7 * 33] * s1[3]);
;         gst_wt16(WT + (size_t)(drow0 + n) * K + k0 + 8 * c, o); }
;     asm volatile("s_waitcnt lgkmcnt(0)" ::: "memory");
	ds_write2_b32 v34, v0, v42 offset1:66
	s_waitcnt vmcnt(28)
	ds_write2_b32 v34, v43, v44 offset0:132 offset1:198
	v_add_u32_e32 v0, 0x400, v34
	s_waitcnt vmcnt(26)
	ds_write2_b32 v0, v45, v46 offset0:8 offset1:74
	s_waitcnt vmcnt(24)
	ds_write2_b32 v0, v47, v48 offset0:140 offset1:206
	v_add_u32_e32 v0, 0x800, v34
	s_waitcnt vmcnt(22)
	ds_write2_b32 v0, v49, v50 offset0:16 offset1:82
	s_waitcnt vmcnt(20)
	ds_write2_b32 v0, v51, v52 offset0:148 offset1:214
	v_add_u32_e32 v0, 0xc00, v34
	s_waitcnt vmcnt(18)
	ds_write2_b32 v0, v53, v54 offset0:24 offset1:90
	s_waitcnt vmcnt(16)
	ds_write2_b32 v0, v55, v56 offset0:156 offset1:222
	v_add_u32_e32 v0, 0x1000, v34
	s_waitcnt vmcnt(14)
	ds_write2_b32 v0, v57, v58 offset0:32 offset1:98
	s_waitcnt vmcnt(12)
	ds_write2_b32 v0, v59, v60 offset0:164 offset1:230
	v_add_u32_e32 v0, 0x1400, v34
	s_waitcnt vmcnt(10)
	ds_write2_b32 v0, v61, v62 offset0:40 offset1:106
	s_waitcnt vmcnt(8)
	ds_write2_b32 v0, v63, v64 offset0:172 offset1:238
	v_add_u32_e32 v0, 0x1800, v34
	s_waitcnt vmcnt(6)
	ds_write2_b32 v0, v65, v66 offset0:48 offset1:114
	s_waitcnt vmcnt(4)
	ds_write2_b32 v0, v67, v68 offset0:180 offset1:246
	v_add_u32_e32 v0, 0x1c00, v34
	s_waitcnt vmcnt(2)
	ds_write2_b32 v0, v69, v70 offset0:56 offset1:122
	s_waitcnt vmcnt(0)
	ds_write2_b32 v0, v40, v32 offset0:188 offset1:254
	s_waitcnt lgkmcnt(0)
	ds_read2_b32 v[40:41], v36 offset1:33
	ds_read2_b32 v[42:43], v36 offset0:66 offset1:99
	ds_read2_b32 v[44:45], v36 offset0:198 offset1:231
	s_lshl_b32 s26, s26, 1
	s_sext_i32_i16 s0, s0
	s_waitcnt lgkmcnt(2)
	v_pk_mul_f32 v[40:41], v[6:7], v[40:41]
	s_waitcnt lgkmcnt(1)
	v_pk_mul_f32 v[42:43], v[8:9], v[42:43]
	v_cvt_pk_bf16_f32 v40, v40, v41
	v_cvt_pk_bf16_f32 v41, v42, v43
	ds_read2_b32 v[42:43], v36 offset0:132 offset1:165
	s_and_b32 s26, s26, 0xffffff00
	s_add_i32 s0, s25, s0
	s_add_i32 s0, s0, s26
	s_waitcnt lgkmcnt(1)
	v_pk_mul_f32 v[44:45], v[4:5], v[44:45]
	s_waitcnt lgkmcnt(0)
	v_pk_mul_f32 v[42:43], v[2:3], v[42:43]
	s_lshl_b32 s72, s1, 1
	v_cvt_pk_bf16_f32 v42, v42, v43
	v_cvt_pk_bf16_f32 v43, v44, v45
	v_add_u32_e32 v44, s0, v35
	v_ashrrev_i32_e32 v45, 31, v44
	v_lshl_add_u64 v[32:33], v[30:31], 0, s[72:73]
	v_lshlrev_b64 v[44:45], 11, v[44:45]
	v_lshl_add_u64 v[44:45], v[32:33], 0, v[44:45]
	global_store_dwordx4 v[44:45], v[40:43], off sc1 nt
	s_nop 1
	ds_read2_b32 v[40:41], v36 offset0:8 offset1:41
	ds_read2_b32 v[42:43], v36 offset0:74 offset1:107
	ds_read2_b32 v[44:45], v36 offset0:206 offset1:239
	s_waitcnt lgkmcnt(2)
	v_pk_mul_f32 v[40:41], v[6:7], v[40:41]
	s_waitcnt lgkmcnt(1)
	v_pk_mul_f32 v[42:43], v[8:9], v[42:43]
	v_cvt_pk_bf16_f32 v40, v40, v41
	v_cvt_pk_bf16_f32 v41, v42, v43
	ds_read2_b32 v[42:43], v36 offset0:140 offset1:173
	s_waitcnt lgkmcnt(1)
	v_pk_mul_f32 v[44:45], v[4:5], v[44:45]
	s_waitcnt lgkmcnt(0)
	v_pk_mul_f32 v[42:43], v[2:3], v[42:43]
	s_nop 0
	v_cvt_pk_bf16_f32 v42, v42, v43
	v_cvt_pk_bf16_f32 v43, v44, v45
	v_add_u32_e32 v44, s0, v37
	v_ashrrev_i32_e32 v45, 31, v44
	v_lshlrev_b64 v[44:45], 11, v[44:45]
	v_lshl_add_u64 v[44:45], v[32:33], 0, v[44:45]
	global_store_dwordx4 v[44:45], v[40:43], off sc1 nt
	s_nop 1
	ds_read2_b32 v[40:41], v36 offset0:16 offset1:49
	ds_read2_b32 v[42:43], v36 offset0:82 offset1:115
	ds_read2_b32 v[44:45], v36 offset0:214 offset1:247
	s_waitcnt lgkmcnt(2)
	v_pk_mul_f32 v[40:41], v[6:7], v[40:41]
	s_waitcnt lgkmcnt(1)
	v_pk_mul_f32 v[42:43], v[8:9], v[42:43]
	v_cvt_pk_bf16_f32 v40, v40, v41
	v_cvt_pk_bf16_f32 v41, v42, v43
	ds_read2_b32 v[42:43], v36 offset0:148 offset1:181
	s_waitcnt lgkmcnt(1)
	v_pk_mul_f32 v[44:45], v[4:5], v[44:45]
	s_waitcnt lgkmcnt(0)
	v_pk_mul_f32 v[42:43], v[2:3], v[42:43]
	s_nop 0
	v_cvt_pk_bf16_f32 v42, v42, v43
	v_cvt_pk_bf16_f32 v43, v44, v45
	v_add_u32_e32 v44, s0, v38
	v_ashrrev_i32_e32 v45, 31, v44
	v_lshlrev_b64 v[44:45], 11, v[44:45]
	v_lshl_add_u64 v[44:45], v[32:33], 0, v[44:45]
	global_store_dwordx4 v[44:45], v[40:43], off sc1 nt
	s_nop 1
	ds_read2_b32 v[40:41], v36 offset0:24 offset1:57
	s_waitcnt lgkmcnt(0)
	v_pk_mul_f32 v[6:7], v[6:7], v[40:41]
	ds_read2_b32 v[40:41], v36 offset0:90 offset1:123
	v_cvt_pk_bf16_f32 v6, v6, v7
	s_waitcnt lgkmcnt(0)
	v_pk_mul_f32 v[8:9], v[8:9], v[40:41]
	s_nop 0
	v_cvt_pk_bf16_f32 v7, v8, v9
	ds_read2_b32 v[8:9], v36 offset0:156 offset1:189
	s_waitcnt lgkmcnt(0)
	v_pk_mul_f32 v[2:3], v[2:3], v[8:9]
	s_nop 0
	v_cvt_pk_bf16_f32 v8, v2, v3
	ds_read2_b32 v[2:3], v36 offset0:222 offset1:255
	s_waitcnt lgkmcnt(0)
	v_pk_mul_f32 v[2:3], v[4:5], v[2:3]
	s_nop 0
	v_cvt_pk_bf16_f32 v9, v2, v3
	v_add_u32_e32 v2, s0, v39
	v_ashrrev_i32_e32 v3, 31, v2
	v_lshlrev_b64 v[2:3], 11, v[2:3]
	v_lshl_add_u64 v[2:3], v[32:33], 0, v[2:3]
	global_store_dwordx4 v[2:3], v[6:9], off sc1 nt
	s_nop 1
	s_waitcnt lgkmcnt(0)

; __device__ __forceinline__ void transpose_item(const float* W, int K, int N, bf16_t* WT, int kb, int nb, int drow0, const float* kscale, LAS float* scr, int lane) {
;     const int k0 = 64 * kb, n0 = 32 * nb, c = lane & 7;
;     f32x4 s0 = {1.f, 1.f, 1.f, 1.f}, s1 = {1.f, 1.f, 1.f, 1.f};
;     if (kscale) { s0 = *(const f32x4*)(kscale + k0 + 8 * c); s1 = *(const f32x4*)(kscale + k0 + 8 * c + 4); }
;     const float* src = W + (size_t)(k0 + (lane >> 5)) * N + n0 + (lane & 31);
;     float w[32];
; #pragma unroll
;     for (int i = 0; i < 32; ++i) w[i] = __builtin_nontemporal_load(src + (size_t)(2 * i) * N);
; __device__ __forceinline__ void prep_weights(Frame& F, const Args& a, int l, int it_lo, int it_hi, int gw, int ngw) {
;     ...
;         if (r < I5) { const int kb = r / 32, nb = r % 32; transpose_item(w_mx, DM, DM, W + WO_MIX, kb, nb, 32 * nb, nullptr, scr, F.lane); continue; } r -= I5;
.LBB0_1415:
	s_andn2_b64 vcc, exec, s[0:1]
	s_cbranch_vccnz .LBB0_1417
	s_and_b32 s1, s23, 0x3fc0
	s_add_i32 s72, s1, 0xffffe200
	v_or_b32_e32 v0, s72, v11
	s_and_b32 s0, s21, 0x3e0
	v_lshlrev_b64 v[2:3], 12, v[0:1]
	v_lshl_add_u64 v[2:3], s[12:13], 0, v[2:3]
	s_lshl_b32 s18, s0, 2
	s_mov_b32 s19, s73
	v_lshl_add_u64 v[2:3], v[2:3], 0, s[18:19]
	v_lshlrev_b32_e32 v0, 2, v10
	v_lshl_add_u64 v[2:3], v[2:3], 0, v[0:1]
	s_movk_i32 s1, 0x2000
	v_add_co_u32_e32 v4, vcc, s1, v2
	s_movk_i32 s1, 0x4000
	s_nop 0
	v_addc_co_u32_e32 v5, vcc, 0, v3, vcc
	global_load_dword v0, v[2:3], off nt
	global_load_dword v6, v[4:5], off nt
	v_add_co_u32_e32 v4, vcc, s1, v2
	s_movk_i32 s1, 0x6000
	s_nop 0
	v_addc_co_u32_e32 v5, vcc, 0, v3, vcc
	global_load_dword v7, v[4:5], off nt
	v_add_co_u32_e32 v4, vcc, s1, v2
	s_mov_b32 s1, 0x8000
	s_nop 0
	v_addc_co_u32_e32 v5, vcc, 0, v3, vcc
	global_load_dword v8, v[4:5], off nt
	v_add_co_u32_e32 v4, vcc, s1, v2
	s_mov_b32 s1, 0xa000
	s_nop 0
	v_addc_co_u32_e32 v5, vcc, 0, v3, vcc
	global_load_dword v9, v[4:5], off nt
	v_add_co_u32_e32 v4, vcc, s1, v2
	s_mov_b32 s1, 0xc000
	s_nop 0
	v_addc_co_u32_e32 v5, vcc, 0, v3, vcc
	global_load_dword v32, v[4:5], off nt
	v_add_co_u32_e32 v4, vcc, s1, v2
	s_mov_b32 s1, 0xe000
	s_nop 0
	v_addc_co_u32_e32 v5, vcc, 0, v3, vcc
	global_load_dword v33, v[4:5], off nt
	v_add_co_u32_e32 v4, vcc, s1, v2
	s_mov_b32 s1, 0x10000
	s_nop 0
	v_addc_co_u32_e32 v5, vcc, 0, v3, vcc
	global_load_dword v40, v[4:5], off nt
	v_add_co_u32_e32 v4, vcc, s1, v2
	s_mov_b32 s1, 0x12000
	s_nop 0
	v_addc_co_u32_e32 v5, vcc, 0, v3, vcc
	global_load_dword v41, v[4:5], off nt
	v_add_co_u32_e32 v4, vcc, s1, v2
	s_mov_b32 s1, 0x14000
	s_nop 0
	v_addc_co_u32_e32 v5, vcc, 0, v3, vcc
	global_load_dword v42, v[4:5], off nt
	v_add_co_u32_e32 v4, vcc, s1, v2
	s_mov_b32 s1, 0x16000
	s_nop 0
	v_addc_co_u32_e32 v5, vcc, 0, v3, vcc
	global_load_dword v43, v[4:5], off nt
	v_add_co_u32_e32 v4, vcc, s1, v2
	s_mov_b32 s1, 0x18000
	s_nop 0
	v_addc_co_u32_e32 v5, vcc, 0, v3, vcc
	global_load_dword v44, v[4:5], off nt
	v_add_co_u32_e32 v4, vcc, s1, v2
	s_mov_b32 s1, 0x1a000
	s_nop 0
	v_addc_co_u32_e32 v5, vcc, 0, v3, vcc
	global_load_dword v45, v[4:5], off nt
	v_add_co_u32_e32 v4, vcc, s1, v2
	s_mov_b32 s1, 0x1c000
	s_nop 0
	v_addc_co_u32_e32 v5, vcc, 0, v3, vcc
	global_load_dword v46, v[4:5], off nt
	v_add_co_u32_e32 v4, vcc, s1, v2
	s_mov_b32 s1, 0x1e000
	s_nop 0
	v_addc_co_u32_e32 v5, vcc, 0, v3, vcc
	global_load_dword v47, v[4:5], off nt
	v_add_co_u32_e32 v4, vcc, s1, v2
	s_mov_b32 s1, 0x22000
	s_nop 0
	v_addc_co_u32_e32 v5, vcc, 0, v3, vcc
	global_load_dword v48, v[4:5], off nt
	v_add_co_u32_e32 v4, vcc, s79, v2
	s_nop 1
	v_addc_co_u32_e32 v5, vcc, 0, v3, vcc
	global_load_dword v49, v[4:5], off nt
	v_add_co_u32_e32 v4, vcc, s1, v2
	s_mov_b32 s1, 0x24000
	s_nop 0
	v_addc_co_u32_e32 v5, vcc, 0, v3, vcc
	global_load_dword v50, v[4:5], off nt
	v_add_co_u32_e32 v4, vcc, s1, v2
	s_mov_b32 s1, 0x26000
	s_nop 0
	v_addc_co_u32_e32 v5, vcc, 0, v3, vcc
	global_load_dword v51, v[4:5], off nt
	v_add_co_u32_e32 v4, vcc, s1, v2
	s_mov_b32 s1, 0x28000
	s_nop 0
	v_addc_co_u32_e32 v5, vcc, 0, v3, vcc
	global_load_dword v52, v[4:5], off nt
	v_add_co_u32_e32 v4, vcc, s1, v2
	s_mov_b32 s1, 0x2a000
	s_nop 0
	v_addc_co_u32_e32 v5, vcc, 0, v3, vcc
	global_load_dword v53, v[4:5], off nt
	v_add_co_u32_e32 v4, vcc, s1, v2
	s_mov_b32 s1, 0x2c000
	s_nop 0
	v_addc_co_u32_e32 v5, vcc, 0, v3, vcc
	global_load_dword v54, v[4:5], off nt
	v_add_co_u32_e32 v4, vcc, s1, v2
	s_mov_b32 s1, 0x2e000
	s_nop 0
	v_addc_co_u32_e32 v5, vcc, 0, v3, vcc
	global_load_dword v55, v[4:5], off nt
	v_add_co_u32_e32 v4, vcc, s1, v2
	s_mov_b32 s1, 0x30000
	s_nop 0
	v_addc_co_u32_e32 v5, vcc, 0, v3, vcc
	global_load_dword v56, v[4:5], off nt
	v_add_co_u32_e32 v4, vcc, s1, v2
	s_mov_b32 s1, 0x32000
	s_nop 0
	v_addc_co_u32_e32 v5, vcc, 0, v3, vcc
	global_load_dword v57, v[4:5], off nt
	v_add_co_u32_e32 v4, vcc, s1, v2
	s_mov_b32 s1, 0x34000
	s_nop 0
	v_addc_co_u32_e32 v5, vcc, 0, v3, vcc
	global_load_dword v58, v[4:5], off nt
	v_add_co_u32_e32 v4, vcc, s1, v2
	s_mov_b32 s1, 0x36000
	s_nop 0
	v_addc_co_u32_e32 v5, vcc, 0, v3, vcc
	global_load_dword v59, v[4:5], off nt
	v_add_co_u32_e32 v4, vcc, s1, v2
	s_mov_b32 s1, 0x38000
	s_nop 0
	v_addc_co_u32_e32 v5, vcc, 0, v3, vcc
	global_load_dword v60, v[4:5], off nt
	v_add_co_u32_e32 v4, vcc, s1, v2
	s_mov_b32 s1, 0x3a000
	s_nop 0
	v_addc_co_u32_e32 v5, vcc, 0, v3, vcc
	global_load_dword v61, v[4:5], off nt
	v_add_co_u32_e32 v4, vcc, s1, v2
	s_mov_b32 s1, 0x3c000
	s_nop 0
	v_addc_co_u32_e32 v5, vcc, 0, v3, vcc
	global_load_dword v62, v[4:5], off nt
	v_add_co_u32_e32 v4, vcc, s1, v2
	s_mov_b32 s1, 0x3e000
	s_nop 0
	v_addc_co_u32_e32 v5, vcc, 0, v3, vcc
	v_add_co_u32_e32 v2, vcc, s1, v2
	global_load_dword v4, v[4:5], off nt
	s_nop 0
	v_addc_co_u32_e32 v3, vcc, 0, v3, vcc
	global_load_dword v2, v[2:3], off nt
	s_waitcnt vmcnt(30)
; #define LAS __attribute__((address_space(3)))
; __device__ __forceinline__ unsigned pk2(float lo, float hi) { const f32x2 v = {lo, hi}; const bf16x2_hw b = __builtin_convertvector(v, bf16x2_hw); return __builtin_bit_cast(unsigned, b); }
; __device__ __forceinline__ void gst_wt16(void* p, const u32x4 v) { asm volatile("global_store_dwordx4 %0, %1, off sc1\n\ts_nop 1" :: "v"(p), "v"(v) : "memory"); }
; __device__ __forceinline__ void transpose_item(const float* W, int K, int N, bf16_t* WT, int kb, int nb, int drow0, const float* kscale, LAS float* scr, int lane) {
;     ...
;     for (int i = 0; i < 32; ++i) scr[(2 * i + (lane >> 5)) * 33 + (lane & 31)] = w[i];
;     asm volatile("s_waitcnt lgkmcnt(0)" ::: "memory");
; #pragma unroll
;     for (int j = 0; j < 4; ++j) { const int n = (lane >> 3) + 8 * j; const LAS float* s = scr + (8 * c) * 33 + n;
;         u32x4 o; o.x = pk2(s[0 * 33] * s0[0], s[1 * 33] * s0[1]); o.y = pk2(s[2 * 33] * s0[2], s[3 * 33] * s0[3]); o.z = pk2(s[4 * 33] * s1[0], s[5 * 33] * s1[1]); o.w = pk2(s[6 * 33] * s1[2], s[7 * 33] * s1[3]);
;         gst_wt16(WT + (size_t)(drow0 + n) * K + k0 + 8 * c, o); }
;     asm volatile("s_waitcnt lgkmcnt(0)" ::: "memory");
	ds_write2_b32 v34, v0, v6 offset1:66
	s_waitcnt vmcnt(28)
	ds_write2_b32 v34, v7, v8 offset0:132 offset1:198
	v_add_u32_e32 v0, 0x400, v34
	s_waitcnt vmcnt(26)
	ds_write2_b32 v0, v9, v32 offset0:8 offset1:74
	s_waitcnt vmcnt(24)
	ds_write2_b32 v0, v33, v40 offset0:140 offset1:206
	v_add_u32_e32 v0, 0x800, v34
	s_waitcnt vmcnt(22)
	ds_write2_b32 v0, v41, v42 offset0:16 offset1:82
	s_waitcnt vmcnt(20)
	ds_write2_b32 v0, v43, v44 offset0:148 offset1:214
	v_add_u32_e32 v0, 0xc00, v34
	s_waitcnt vmcnt(18)
	ds_write2_b32 v0, v45, v46 offset0:24 offset1:90
	s_waitcnt vmcnt(16)
	ds_write2_b32 v0, v47, v48 offset0:156 offset1:222
	v_add_u32_e32 v0, 0x1000, v34
	s_waitcnt vmcnt(14)
	ds_write2_b32 v0, v49, v50 offset0:32 offset1:98
	s_waitcnt vmcnt(12)
	ds_write2_b32 v0, v51, v52 offset0:164 offset1:230
	v_add_u32_e32 v0, 0x1400, v34
	s_waitcnt vmcnt(10)
	ds_write2_b32 v0, v53, v54 offset0:40 offset1:106
	s_waitcnt vmcnt(8)
	ds_write2_b32 v0, v55, v56 offset0:172 offset1:238
	v_add_u32_e32 v0, 0x1800, v34
	s_waitcnt vmcnt(6)
	ds_write2_b32 v0, v57, v58 offset0:48 offset1:114
	s_waitcnt vmcnt(4)
	ds_write2_b32 v0, v59, v60 offset0:180 offset1:246
	v_add_u32_e32 v0, 0x1c00, v34
	s_waitcnt vmcnt(2)
	ds_write2_b32 v0, v61, v62 offset0:56 offset1:122
	s_waitcnt vmcnt(0)
	ds_write2_b32 v0, v4, v2 offset0:188 offset1:254
	s_waitcnt lgkmcnt(0)
	ds_read2_b32 v[2:3], v36 offset1:33
	ds_read2_b32 v[4:5], v36 offset0:66 offset1:99
	ds_read2_b32 v[8:9], v36 offset0:198 offset1:231
	v_or_b32_e32 v0, s0, v35
	v_lshl_add_u64 v[6:7], s[72:73], 1, v[18:19]
	s_waitcnt lgkmcnt(2)
	v_cvt_pk_bf16_f32 v2, v2, v3
	s_waitcnt lgkmcnt(1)
	v_cvt_pk_bf16_f32 v3, v4, v5
	ds_read2_b32 v[4:5], v36 offset0:132 offset1:165
	v_lshlrev_b32_e32 v0, 11, v0
	s_waitcnt lgkmcnt(0)
	v_cvt_pk_bf16_f32 v4, v4, v5
	v_cvt_pk_bf16_f32 v5, v8, v9
	v_lshl_add_u64 v[8:9], v[6:7], 0, v[0:1]
	global_store_dwordx4 v[8:9], v[2:5], off sc1 nt
	s_nop 1
	ds_read2_b32 v[2:3], v36 offset0:8 offset1:41
	ds_read2_b32 v[4:5], v36 offset0:74 offset1:107
	ds_read2_b32 v[8:9], v36 offset0:206 offset1:239
	v_or_b32_e32 v0, s0, v37
	v_lshlrev_b32_e32 v0, 11, v0
	s_waitcnt lgkmcnt(2)
	v_cvt_pk_bf16_f32 v2, v2, v3
	s_waitcnt lgkmcnt(1)
	v_cvt_pk_bf16_f32 v3, v4, v5
	ds_read2_b32 v[4:5], v36 offset0:140 offset1:173
	s_waitcnt lgkmcnt(0)
	v_cvt_pk_bf16_f32 v4, v4, v5
	v_cvt_pk_bf16_f32 v5, v8, v9
	v_lshl_add_u64 v[8:9], v[6:7], 0, v[0:1]
	global_store_dwordx4 v[8:9], v[2:5], off sc1 nt
	s_nop 1
	ds_read2_b32 v[2:3], v36 offset0:16 offset1:49
	ds_read2_b32 v[4:5], v36 offset0:82 offset1:115
	ds_read2_b32 v[8:9], v36 offset0:214 offset1:247
	v_or_b32_e32 v0, s0, v38
	v_lshlrev_b32_e32 v0, 11, v0
	s_waitcnt lgkmcnt(2)
	v_cvt_pk_bf16_f32 v2, v2, v3
	s_waitcnt lgkmcnt(1)
	v_cvt_pk_bf16_f32 v3, v4, v5
	ds_read2_b32 v[4:5], v36 offset0:148 offset1:181
	s_waitcnt lgkmcnt(0)
	v_cvt_pk_bf16_f32 v4, v4, v5
	v_cvt_pk_bf16_f32 v5, v8, v9
	v_lshl_add_u64 v[8:9], v[6:7], 0, v[0:1]
	global_store_dwordx4 v[8:9], v[2:5], off sc1 nt
	s_nop 1
	ds_read2_b32 v[2:3], v36 offset0:24 offset1:57
	ds_read2_b32 v[4:5], v36 offset0:90 offset1:123
	ds_read2_b32 v[8:9], v36 offset0:222 offset1:255
	v_or_b32_e32 v0, s0, v39
	v_lshlrev_b32_e32 v0, 11, v0
	s_waitcnt lgkmcnt(2)
	v_cvt_pk_bf16_f32 v2, v2, v3
	s_waitcnt lgkmcnt(1)
	v_cvt_pk_bf16_f32 v3, v4, v5
	ds_read2_b32 v[4:5], v36 offset0:156 offset1:189
	v_lshl_add_u64 v[6:7], v[6:7], 0, v[0:1]
	s_waitcnt lgkmcnt(0)
	v_cvt_pk_bf16_f32 v4, v4, v5
	v_cvt_pk_bf16_f32 v5, v8, v9
	global_store_dwordx4 v[6:7], v[2:5], off sc1 nt
	s_nop 1
	s_waitcnt lgkmcnt(0)

; __device__ __forceinline__ void transpose_item(const float* W, int K, int N, bf16_t* WT, int kb, int nb, int drow0, const float* kscale, LAS float* scr, int lane) {
;     const int k0 = 64 * kb, n0 = 32 * nb, c = lane & 7;
;     f32x4 s0 = {1.f, 1.f, 1.f, 1.f}, s1 = {1.f, 1.f, 1.f, 1.f};
;     if (kscale) { s0 = *(const f32x4*)(kscale + k0 + 8 * c); s1 = *(const f32x4*)(kscale + k0 + 8 * c + 4); }
;     const float* src = W + (size_t)(k0 + (lane >> 5)) * N + n0 + (lane & 31);
;     float w[32];
; #pragma unroll
;     for (int i = 0; i < 32; ++i) w[i] = __builtin_nontemporal_load(src + (size_t)(2 * i) * N);
; __device__ __forceinline__ void prep_weights(Frame& F, const Args& a, int l, int it_lo, int it_hi, int gw, int ngw) {
;     ...
;         if (r < I4) { const int kb = r / 32, nb = r % 32; transpose_item(w_so, 512, DM, W + WO_SO, kb, nb, 32 * nb, nullptr, scr, F.lane); continue; } r -= I4;
.LBB0_1418:
	s_andn2_b64 vcc, exec, s[0:1]
	s_cbranch_vccnz .LBB0_1420
	s_and_b32 s1, s23, 0x1fc0
	s_add_i32 s72, s1, 0xffffe400
	v_or_b32_e32 v0, s72, v11
	s_and_b32 s0, s21, 0x3e0
	v_lshlrev_b64 v[2:3], 12, v[0:1]
	v_lshl_add_u64 v[2:3], s[10:11], 0, v[2:3]
	s_lshl_b32 s18, s0, 2
	s_mov_b32 s19, s73
	v_lshl_add_u64 v[2:3], v[2:3], 0, s[18:19]
	v_lshlrev_b32_e32 v0, 2, v10
	v_lshl_add_u64 v[2:3], v[2:3], 0, v[0:1]
	s_movk_i32 s1, 0x2000
	v_add_co_u32_e32 v4, vcc, s1, v2
	s_movk_i32 s1, 0x4000
	s_nop 0
	v_addc_co_u32_e32 v5, vcc, 0, v3, vcc
	global_load_dword v0, v[2:3], off nt
	global_load_dword v6, v[4:5], off nt
	v_add_co_u32_e32 v4, vcc, s1, v2
	s_movk_i32 s1, 0x6000
	s_nop 0
	v_addc_co_u32_e32 v5, vcc, 0, v3, vcc
	global_load_dword v7, v[4:5], off nt
	v_add_co_u32_e32 v4, vcc, s1, v2
	s_mov_b32 s1, 0x8000
	s_nop 0
	v_addc_co_u32_e32 v5, vcc, 0, v3, vcc
	global_load_dword v8, v[4:5], off nt
	v_add_co_u32_e32 v4, vcc, s1, v2
	s_mov_b32 s1, 0xa000
	s_nop 0
	v_addc_co_u32_e32 v5, vcc, 0, v3, vcc
	global_load_dword v9, v[4:5], off nt
	v_add_co_u32_e32 v4, vcc, s1, v2
	s_mov_b32 s1, 0xc000
	s_nop 0
	v_addc_co_u32_e32 v5, vcc, 0, v3, vcc
	global_load_dword v32, v[4:5], off nt
	v_add_co_u32_e32 v4, vcc, s1, v2
	s_mov_b32 s1, 0xe000
	s_nop 0
	v_addc_co_u32_e32 v5, vcc, 0, v3, vcc
	global_load_dword v33, v[4:5], off nt
	v_add_co_u32_e32 v4, vcc, s1, v2
	s_mov_b32 s1, 0x10000
	s_nop 0
	v_addc_co_u32_e32 v5, vcc, 0, v3, vcc
	global_load_dword v40, v[4:5], off nt
	v_add_co_u32_e32 v4, vcc, s1, v2
	s_mov_b32 s1, 0x12000
	s_nop 0
	v_addc_co_u32_e32 v5, vcc, 0, v3, vcc
	global_load_dword v41, v[4:5], off nt
	v_add_co_u32_e32 v4, vcc, s1, v2
	s_mov_b32 s1, 0x14000
	s_nop 0
	v_addc_co_u32_e32 v5, vcc, 0, v3, vcc
	global_load_dword v42, v[4:5], off nt
	v_add_co_u32_e32 v4, vcc, s1, v2
	s_mov_b32 s1, 0x16000
	s_nop 0
	v_addc_co_u32_e32 v5, vcc, 0, v3, vcc
	global_load_dword v43, v[4:5], off nt
	v_add_co_u32_e32 v4, vcc, s1, v2
	s_mov_b32 s1, 0x18000
	s_nop 0
	v_addc_co_u32_e32 v5, vcc, 0, v3, vcc
	global_load_dword v44, v[4:5], off nt
	v_add_co_u32_e32 v4, vcc, s1, v2
	s_mov_b32 s1, 0x1a000
	s_nop 0
	v_addc_co_u32_e32 v5, vcc, 0, v3, vcc
	global_load_dword v45, v[4:5], off nt
	v_add_co_u32_e32 v4, vcc, s1, v2
	s_mov_b32 s1, 0x1c000
	s_nop 0
	v_addc_co_u32_e32 v5, vcc, 0, v3, vcc
	global_load_dword v46, v[4:5], off nt
	v_add_co_u32_e32 v4, vcc, s1, v2
	s_mov_b32 s1, 0x1e000
	s_nop 0
	v_addc_co_u32_e32 v5, vcc, 0, v3, vcc
	global_load_dword v47, v[4:5], off nt
	v_add_co_u32_e32 v4, vcc, s1, v2
	s_mov_b32 s1, 0x22000
	s_nop 0
	v_addc_co_u32_e32 v5, vcc, 0, v3, vcc
	global_load_dword v48, v[4:5], off nt
	v_add_co_u32_e32 v4, vcc, s79, v2
	s_nop 1
	v_addc_co_u32_e32 v5, vcc, 0, v3, vcc
	global_load_dword v49, v[4:5], off nt
	v_add_co_u32_e32 v4, vcc, s1, v2
	s_mov_b32 s1, 0x24000
	s_nop 0
	v_addc_co_u32_e32 v5, vcc, 0, v3, vcc
	global_load_dword v50, v[4:5], off nt
	v_add_co_u32_e32 v4, vcc, s1, v2
	s_mov_b32 s1, 0x26000
	s_nop 0
	v_addc_co_u32_e32 v5, vcc, 0, v3, vcc
	global_load_dword v51, v[4:5], off nt
	v_add_co_u32_e32 v4, vcc, s1, v2
	s_mov_b32 s1, 0x28000
	s_nop 0
	v_addc_co_u32_e32 v5, vcc, 0, v3, vcc
	global_load_dword v52, v[4:5], off nt
	v_add_co_u32_e32 v4, vcc, s1, v2
	s_mov_b32 s1, 0x2a000
	s_nop 0
	v_addc_co_u32_e32 v5, vcc, 0, v3, vcc
	global_load_dword v53, v[4:5], off nt
	v_add_co_u32_e32 v4, vcc, s1, v2
	s_mov_b32 s1, 0x2c000
	s_nop 0
	v_addc_co_u32_e32 v5, vcc, 0, v3, vcc
	global_load_dword v54, v[4:5], off nt
	v_add_co_u32_e32 v4, vcc, s1, v2
	s_mov_b32 s1, 0x2e000
	s_nop 0
	v_addc_co_u32_e32 v5, vcc, 0, v3, vcc
	global_load_dword v55, v[4:5], off nt
	v_add_co_u32_e32 v4, vcc, s1, v2
	s_mov_b32 s1, 0x30000
	s_nop 0
	v_addc_co_u32_e32 v5, vcc, 0, v3, vcc
	global_load_dword v56, v[4:5], off nt
	v_add_co_u32_e32 v4, vcc, s1, v2
	s_mov_b32 s1, 0x32000
	s_nop 0
	v_addc_co_u32_e32 v5, vcc, 0, v3, vcc
	global_load_dword v57, v[4:5], off nt
	v_add_co_u32_e32 v4, vcc, s1, v2
	s_mov_b32 s1, 0x34000
	s_nop 0
	v_addc_co_u32_e32 v5, vcc, 0, v3, vcc
	global_load_dword v58, v[4:5], off nt
	v_add_co_u32_e32 v4, vcc, s1, v2
	s_mov_b32 s1, 0x36000
	s_nop 0
	v_addc_co_u32_e32 v5, vcc, 0, v3, vcc
	global_load_dword v59, v[4:5], off nt
	v_add_co_u32_e32 v4, vcc, s1, v2
	s_mov_b32 s1, 0x38000
	s_nop 0
	v_addc_co_u32_e32 v5, vcc, 0, v3, vcc
	global_load_dword v60, v[4:5], off nt
	v_add_co_u32_e32 v4, vcc, s1, v2
	s_mov_b32 s1, 0x3a000
	s_nop 0
	v_addc_co_u32_e32 v5, vcc, 0, v3, vcc
	global_load_dword v61, v[4:5], off nt
	v_add_co_u32_e32 v4, vcc, s1, v2
	s_mov_b32 s1, 0x3c000
	s_nop 0
	v_addc_co_u32_e32 v5, vcc, 0, v3, vcc
	global_load_dword v62, v[4:5], off nt
	v_add_co_u32_e32 v4, vcc, s1, v2
	s_mov_b32 s1, 0x3e000
	s_nop 0
	v_addc_co_u32_e32 v5, vcc, 0, v3, vcc
	v_add_co_u32_e32 v2, vcc, s1, v2
	global_load_dword v4, v[4:5], off nt
	s_nop 0
	v_addc_co_u32_e32 v3, vcc, 0, v3, vcc
	global_load_dword v2, v[2:3], off nt
	s_waitcnt vmcnt(30)
; #define LAS __attribute__((address_space(3)))
; __device__ __forceinline__ unsigned pk2(float lo, float hi) { const f32x2 v = {lo, hi}; const bf16x2_hw b = __builtin_convertvector(v, bf16x2_hw); return __builtin_bit_cast(unsigned, b); }
; __device__ __forceinline__ void gst_wt16(void* p, const u32x4 v) { asm volatile("global_store_dwordx4 %0, %1, off sc1\n\ts_nop 1" :: "v"(p), "v"(v) : "memory"); }
; __device__ __forceinline__ void transpose_item(const float* W, int K, int N, bf16_t* WT, int kb, int nb, int drow0, const float* kscale, LAS float* scr, int lane) {
;     ...
;     for (int i = 0; i < 32; ++i) scr[(2 * i + (lane >> 5)) * 33 + (lane & 31)] = w[i];
;     asm volatile("s_waitcnt lgkmcnt(0)" ::: "memory");
; #pragma unroll
;     for (int j = 0; j < 4; ++j) { const int n = (lane >> 3) + 8 * j; const LAS float* s = scr + (8 * c) * 33 + n;
;         u32x4 o; o.x = pk2(s[0 * 33] * s0[0], s[1 * 33] * s0[1]); o.y = pk2(s[2 * 33] * s0[2], s[3 * 33] * s0[3]); o.z = pk2(s[4 * 33] * s1[0], s[5 * 33] * s1[1]); o.w = pk2(s[6 * 33] * s1[2], s[7 * 33] * s1[3]);
;         gst_wt16(WT + (size_t)(drow0 + n) * K + k0 + 8 * c, o); }
;     asm volatile("s_waitcnt lgkmcnt(0)" ::: "memory");
	ds_write2_b32 v34, v0, v6 offset1:66
	s_waitcnt vmcnt(28)
	ds_write2_b32 v34, v7, v8 offset0:132 offset1:198
	v_add_u32_e32 v0, 0x400, v34
	s_waitcnt vmcnt(26)
	ds_write2_b32 v0, v9, v32 offset0:8 offset1:74
	s_waitcnt vmcnt(24)
	ds_write2_b32 v0, v33, v40 offset0:140 offset1:206
	v_add_u32_e32 v0, 0x800, v34
	s_waitcnt vmcnt(22)
	ds_write2_b32 v0, v41, v42 offset0:16 offset1:82
	s_waitcnt vmcnt(20)
	ds_write2_b32 v0, v43, v44 offset0:148 offset1:214
	v_add_u32_e32 v0, 0xc00, v34
	s_waitcnt vmcnt(18)
	ds_write2_b32 v0, v45, v46 offset0:24 offset1:90
	s_waitcnt vmcnt(16)
	ds_write2_b32 v0, v47, v48 offset0:156 offset1:222
	v_add_u32_e32 v0, 0x1000, v34
	s_waitcnt vmcnt(14)
	ds_write2_b32 v0, v49, v50 offset0:32 offset1:98
	s_waitcnt vmcnt(12)
	ds_write2_b32 v0, v51, v52 offset0:164 offset1:230
	v_add_u32_e32 v0, 0x1400, v34
	s_waitcnt vmcnt(10)
	ds_write2_b32 v0, v53, v54 offset0:40 offset1:106
	s_waitcnt vmcnt(8)
	ds_write2_b32 v0, v55, v56 offset0:172 offset1:238
	v_add_u32_e32 v0, 0x1800, v34
	s_waitcnt vmcnt(6)
	ds_write2_b32 v0, v57, v58 offset0:48 offset1:114
	s_waitcnt vmcnt(4)
	ds_write2_b32 v0, v59, v60 offset0:180 offset1:246
	v_add_u32_e32 v0, 0x1c00, v34
	s_waitcnt vmcnt(2)
	ds_write2_b32 v0, v61, v62 offset0:56 offset1:122
	s_waitcnt vmcnt(0)
	ds_write2_b32 v0, v4, v2 offset0:188 offset1:254
	s_waitcnt lgkmcnt(0)
	ds_read2_b32 v[2:3], v36 offset1:33
	ds_read2_b32 v[4:5], v36 offset0:66 offset1:99
	ds_read2_b32 v[8:9], v36 offset0:198 offset1:231
	v_or_b32_e32 v0, s0, v35
	v_lshl_add_u64 v[6:7], s[72:73], 1, v[20:21]
	s_waitcnt lgkmcnt(2)
	v_cvt_pk_bf16_f32 v2, v2, v3
	s_waitcnt lgkmcnt(1)
	v_cvt_pk_bf16_f32 v3, v4, v5
	ds_read2_b32 v[4:5], v36 offset0:132 offset1:165
	v_lshlrev_b32_e32 v0, 10, v0
	s_waitcnt lgkmcnt(0)
	v_cvt_pk_bf16_f32 v4, v4, v5
	v_cvt_pk_bf16_f32 v5, v8, v9
	v_lshl_add_u64 v[8:9], v[6:7], 0, v[0:1]
	global_store_dwordx4 v[8:9], v[2:5], off sc1 nt
	s_nop 1
	ds_read2_b32 v[2:3], v36 offset0:8 offset1:41
	ds_read2_b32 v[4:5], v36 offset0:74 offset1:107
	ds_read2_b32 v[8:9], v36 offset0:206 offset1:239
	v_or_b32_e32 v0, s0, v37
	v_lshlrev_b32_e32 v0, 10, v0
	s_waitcnt lgkmcnt(2)
	v_cvt_pk_bf16_f32 v2, v2, v3
	s_waitcnt lgkmcnt(1)
	v_cvt_pk_bf16_f32 v3, v4, v5
	ds_read2_b32 v[4:5], v36 offset0:140 offset1:173
	s_waitcnt lgkmcnt(0)
	v_cvt_pk_bf16_f32 v4, v4, v5
	v_cvt_pk_bf16_f32 v5, v8, v9
	v_lshl_add_u64 v[8:9], v[6:7], 0, v[0:1]
	global_store_dwordx4 v[8:9], v[2:5], off sc1 nt
	s_nop 1
	ds_read2_b32 v[2:3], v36 offset0:16 offset1:49
	ds_read2_b32 v[4:5], v36 offset0:82 offset1:115
	ds_read2_b32 v[8:9], v36 offset0:214 offset1:247
	v_or_b32_e32 v0, s0, v38
	v_lshlrev_b32_e32 v0, 10, v0
	s_waitcnt lgkmcnt(2)
	v_cvt_pk_bf16_f32 v2, v2, v3
	s_waitcnt lgkmcnt(1)
	v_cvt_pk_bf16_f32 v3, v4, v5
	ds_read2_b32 v[4:5], v36 offset0:148 offset1:181
	s_waitcnt lgkmcnt(0)
	v_cvt_pk_bf16_f32 v4, v4, v5
	v_cvt_pk_bf16_f32 v5, v8, v9
	v_lshl_add_u64 v[8:9], v[6:7], 0, v[0:1]
	global_store_dwordx4 v[8:9], v[2:5], off sc1 nt
	s_nop 1
	ds_read2_b32 v[2:3], v36 offset0:24 offset1:57
	ds_read2_b32 v[4:5], v36 offset0:90 offset1:123
	ds_read2_b32 v[8:9], v36 offset0:222 offset1:255
	v_or_b32_e32 v0, s0, v39
	v_lshlrev_b32_e32 v0, 10, v0
	s_waitcnt lgkmcnt(2)
	v_cvt_pk_bf16_f32 v2, v2, v3
	s_waitcnt lgkmcnt(1)
	v_cvt_pk_bf16_f32 v3, v4, v5
	ds_read2_b32 v[4:5], v36 offset0:156 offset1:189
	v_lshl_add_u64 v[6:7], v[6:7], 0, v[0:1]
	s_waitcnt lgkmcnt(0)
	v_cvt_pk_bf16_f32 v4, v4, v5
	v_cvt_pk_bf16_f32 v5, v8, v9
	global_store_dwordx4 v[6:7], v[2:5], off sc1 nt
	s_nop 1
	s_waitcnt lgkmcnt(0)

; __device__ __forceinline__ void prep_weights(Frame& F, const Args& a, int l, int it_lo, int it_hi, int gw, int ngw) {
;     ...
;         if (r < I3) { const int kb = r / 16, nb = r % 16; transpose_item(w_gl, 512, 512, W + WO_GLU, kb, nb, 32 * nb, nullptr, scr, F.lane); continue; } r -= I3;
.LBB0_1421:
	s_andn2_b64 vcc, exec, s[0:1]
	s_cbranch_vccnz .LBB0_1423
; #define LAS __attribute__((address_space(3)))
; __device__ __forceinline__ unsigned pk2(float lo, float hi) { const f32x2 v = {lo, hi}; const bf16x2_hw b = __builtin_convertvector(v, bf16x2_hw); return __builtin_bit_cast(unsigned, b); }
; __device__ __forceinline__ void gst_wt16(void* p, const u32x4 v) { asm volatile("global_store_dwordx4 %0, %1, off sc1\n\ts_nop 1" :: "v"(p), "v"(v) : "memory"); }
; __device__ __forceinline__ void transpose_item(const float* W, int K, int N, bf16_t* WT, int kb, int nb, int drow0, const float* kscale, LAS float* scr, int lane) {
;     const int k0 = 64 * kb, n0 = 32 * nb, c = lane & 7;
;     f32x4 s0 = {1.f, 1.f, 1.f, 1.f}, s1 = {1.f, 1.f, 1.f, 1.f};
;     if (kscale) { s0 = *(const f32x4*)(kscale + k0 + 8 * c); s1 = *(const f32x4*)(kscale + k0 + 8 * c + 4); }
;     const float* src = W + (size_t)(k0 + (lane >> 5)) * N + n0 + (lane & 31);
;     float w[32];
; #pragma unroll
;     for (int i = 0; i < 32; ++i) w[i] = __builtin_nontemporal_load(src + (size_t)(2 * i) * N);
; #pragma unroll
;     for (int i = 0; i < 32; ++i) scr[(2 * i + (lane >> 5)) * 33 + (lane & 31)] = w[i];
;     asm volatile("s_waitcnt lgkmcnt(0)" ::: "memory");
; #pragma unroll
;     for (int j = 0; j < 4; ++j) { const int n = (lane >> 3) + 8 * j; const LAS float* s = scr + (8 * c) * 33 + n;
;         u32x4 o; o.x = pk2(s[0 * 33] * s0[0], s[1 * 33] * s0[1]); o.y = pk2(s[2 * 33] * s0[2], s[3 * 33] * s0[3]); o.z = pk2(s[4 * 33] * s1[0], s[5 * 33] * s1[1]); o.w = pk2(s[6 * 33] * s1[2], s[7 * 33] * s1[3]);
;         gst_wt16(WT + (size_t)(drow0 + n) * K + k0 + 8 * c, o); }
;     asm volatile("s_waitcnt lgkmcnt(0)" ::: "memory");
; __device__ __forceinline__ void prep_weights(Frame& F, const Args& a, int l, int it_lo, int it_hi, int gw, int ngw) {
;     ...
;         if (r < I3) { const int kb = r / 16, nb = r % 16; transpose_item(w_gl, 512, 512, W + WO_GLU, kb, nb, 32 * nb, nullptr, scr, F.lane); continue; } r -= I3;
	s_and_b32 s1, s24, 0x3fc0
	s_add_i32 s72, s1, 0xffffca00
	v_or_b32_e32 v0, s72, v11
	s_and_b32 s0, s21, 0x1e0
	v_lshlrev_b64 v[2:3], 11, v[0:1]
	v_lshl_add_u64 v[2:3], s[8:9], 0, v[2:3]
	s_lshl_b32 s18, s0, 2
	s_mov_b32 s19, s73
	v_lshl_add_u64 v[2:3], v[2:3], 0, s[18:19]
	v_lshlrev_b32_e32 v0, 2, v10
	v_lshl_add_u64 v[2:3], v[2:3], 0, v[0:1]
	s_movk_i32 s1, 0x2000
	v_add_co_u32_e32 v4, vcc, s1, v2
	s_movk_i32 s1, 0x4000
	s_nop 0
	v_addc_co_u32_e32 v5, vcc, 0, v3, vcc
	global_load_dword v0, v[2:3], off nt
	global_load_dword v6, v[4:5], off offset:-4096 nt
	global_load_dword v7, v[4:5], off nt
	v_add_co_u32_e32 v4, vcc, s1, v2
	s_movk_i32 s1, 0x6000
	s_nop 0
	v_addc_co_u32_e32 v5, vcc, 0, v3, vcc
	global_load_dword v8, v[4:5], off offset:-4096 nt
	global_load_dword v9, v[4:5], off nt
	v_add_co_u32_e32 v4, vcc, s1, v2
	s_mov_b32 s1, 0x8000
	s_nop 0
	v_addc_co_u32_e32 v5, vcc, 0, v3, vcc
	global_load_dword v32, v[4:5], off offset:-4096 nt
	global_load_dword v33, v[4:5], off nt
	v_add_co_u32_e32 v4, vcc, s1, v2
	s_mov_b32 s1, 0xa000
	s_nop 0
	v_addc_co_u32_e32 v5, vcc, 0, v3, vcc
	global_load_dword v40, v[4:5], off offset:-4096 nt
	global_load_dword v41, v[4:5], off nt
	v_add_co_u32_e32 v4, vcc, s1, v2
	s_mov_b32 s1, 0xc000
	s_nop 0
	v_addc_co_u32_e32 v5, vcc, 0, v3, vcc
	global_load_dword v42, v[4:5], off offset:-4096 nt
	global_load_dword v43, v[4:5], off nt
	v_add_co_u32_e32 v4, vcc, s1, v2
	s_mov_b32 s1, 0xe000
	s_nop 0
	v_addc_co_u32_e32 v5, vcc, 0, v3, vcc
	global_load_dword v44, v[4:5], off offset:-4096 nt
	global_load_dword v45, v[4:5], off nt
	v_add_co_u32_e32 v4, vcc, s1, v2
	s_mov_b32 s1, 0x10000
	s_nop 0
	v_addc_co_u32_e32 v5, vcc, 0, v3, vcc
	global_load_dword v46, v[4:5], off offset:-4096 nt
	global_load_dword v47, v[4:5], off nt
	v_add_co_u32_e32 v4, vcc, s1, v2
	s_mov_b32 s1, 0x12000
	s_nop 0
	v_addc_co_u32_e32 v5, vcc, 0, v3, vcc
	global_load_dword v48, v[4:5], off offset:-4096 nt
	global_load_dword v49, v[4:5], off nt
	v_add_co_u32_e32 v4, vcc, s1, v2
	s_mov_b32 s1, 0x14000
	s_nop 0
	v_addc_co_u32_e32 v5, vcc, 0, v3, vcc
	global_load_dword v50, v[4:5], off offset:-4096 nt
	global_load_dword v51, v[4:5], off nt
	v_add_co_u32_e32 v4, vcc, s1, v2
	s_mov_b32 s1, 0x16000
	s_nop 0
	v_addc_co_u32_e32 v5, vcc, 0, v3, vcc
	global_load_dword v52, v[4:5], off offset:-4096 nt
	global_load_dword v53, v[4:5], off nt
	v_add_co_u32_e32 v4, vcc, s1, v2
	s_mov_b32 s1, 0x18000
	s_nop 0
	v_addc_co_u32_e32 v5, vcc, 0, v3, vcc
	global_load_dword v54, v[4:5], off offset:-4096 nt
	global_load_dword v55, v[4:5], off nt
	v_add_co_u32_e32 v4, vcc, s1, v2
	s_mov_b32 s1, 0x1a000
	s_nop 0
	v_addc_co_u32_e32 v5, vcc, 0, v3, vcc
	global_load_dword v56, v[4:5], off offset:-4096 nt
	global_load_dword v57, v[4:5], off nt
	v_add_co_u32_e32 v4, vcc, s1, v2
	s_mov_b32 s1, 0x1c000
	s_nop 0
	v_addc_co_u32_e32 v5, vcc, 0, v3, vcc
	global_load_dword v58, v[4:5], off offset:-4096 nt
	global_load_dword v59, v[4:5], off nt
	v_add_co_u32_e32 v4, vcc, s1, v2
	s_mov_b32 s1, 0x1e000
	s_nop 0
	v_addc_co_u32_e32 v5, vcc, 0, v3, vcc
	global_load_dword v60, v[4:5], off offset:-4096 nt
	global_load_dword v61, v[4:5], off nt
	v_add_co_u32_e32 v4, vcc, s1, v2
	s_mov_b32 s1, 0x1f000
	s_nop 0
	v_addc_co_u32_e32 v5, vcc, 0, v3, vcc
	v_add_co_u32_e32 v2, vcc, s1, v2
	global_load_dword v62, v[4:5], off offset:-4096 nt
	s_nop 0
	global_load_dword v4, v[4:5], off nt
	v_addc_co_u32_e32 v3, vcc, 0, v3, vcc
	global_load_dword v2, v[2:3], off nt
	s_waitcnt vmcnt(30)
	ds_write2_b32 v34, v0, v6 offset1:66
	s_waitcnt vmcnt(28)
	ds_write2_b32 v34, v7, v8 offset0:132 offset1:198
	v_add_u32_e32 v0, 0x400, v34
	s_waitcnt vmcnt(26)
	ds_write2_b32 v0, v9, v32 offset0:8 offset1:74
	s_waitcnt vmcnt(24)
	ds_write2_b32 v0, v33, v40 offset0:140 offset1:206
	v_add_u32_e32 v0, 0x800, v34
	s_waitcnt vmcnt(22)
	ds_write2_b32 v0, v41, v42 offset0:16 offset1:82
	s_waitcnt vmcnt(20)
	ds_write2_b32 v0, v43, v44 offset0:148 offset1:214
	v_add_u32_e32 v0, 0xc00, v34
	s_waitcnt vmcnt(18)
	ds_write2_b32 v0, v45, v46 offset0:24 offset1:90
	s_waitcnt vmcnt(16)
	ds_write2_b32 v0, v47, v48 offset0:156 offset1:222
	v_add_u32_e32 v0, 0x1000, v34
	s_waitcnt vmcnt(14)
	ds_write2_b32 v0, v49, v50 offset0:32 offset1:98
	s_waitcnt vmcnt(12)
	ds_write2_b32 v0, v51, v52 offset0:164 offset1:230
	v_add_u32_e32 v0, 0x1400, v34
	s_waitcnt vmcnt(10)
	ds_write2_b32 v0, v53, v54 offset0:40 offset1:106
	s_waitcnt vmcnt(8)
	ds_write2_b32 v0, v55, v56 offset0:172 offset1:238
	v_add_u32_e32 v0, 0x1800, v34
	s_waitcnt vmcnt(6)
	ds_write2_b32 v0, v57, v58 offset0:48 offset1:114
	s_waitcnt vmcnt(4)
	ds_write2_b32 v0, v59, v60 offset0:180 offset1:246
	v_add_u32_e32 v0, 0x1c00, v34
	s_waitcnt vmcnt(2)
	ds_write2_b32 v0, v61, v62 offset0:56 offset1:122
	s_waitcnt vmcnt(0)
	ds_write2_b32 v0, v4, v2 offset0:188 offset1:254
	s_waitcnt lgkmcnt(0)
	ds_read2_b32 v[2:3], v36 offset1:33
	ds_read2_b32 v[4:5], v36 offset0:66 offset1:99
	ds_read2_b32 v[8:9], v36 offset0:198 offset1:231
	v_or_b32_e32 v0, s0, v35
	v_lshl_add_u64 v[6:7], s[72:73], 1, v[22:23]
	s_waitcnt lgkmcnt(2)
	v_cvt_pk_bf16_f32 v2, v2, v3
	s_waitcnt lgkmcnt(1)
	v_cvt_pk_bf16_f32 v3, v4, v5
	ds_read2_b32 v[4:5], v36 offset0:132 offset1:165
	v_lshlrev_b32_e32 v0, 10, v0
	s_waitcnt lgkmcnt(0)
	v_cvt_pk_bf16_f32 v4, v4, v5
	v_cvt_pk_bf16_f32 v5, v8, v9
	v_lshl_add_u64 v[8:9], v[6:7], 0, v[0:1]
	global_store_dwordx4 v[8:9], v[2:5], off sc1 nt
	s_nop 1
	ds_read2_b32 v[2:3], v36 offset0:8 offset1:41
	ds_read2_b32 v[4:5], v36 offset0:74 offset1:107
	ds_read2_b32 v[8:9], v36 offset0:206 offset1:239
	v_or_b32_e32 v0, s0, v37
	v_lshlrev_b32_e32 v0, 10, v0
	s_waitcnt lgkmcnt(2)
	v_cvt_pk_bf16_f32 v2, v2, v3
	s_waitcnt lgkmcnt(1)
	v_cvt_pk_bf16_f32 v3, v4, v5
	ds_read2_b32 v[4:5], v36 offset0:140 offset1:173
	s_waitcnt lgkmcnt(0)
	v_cvt_pk_bf16_f32 v4, v4, v5
	v_cvt_pk_bf16_f32 v5, v8, v9
	v_lshl_add_u64 v[8:9], v[6:7], 0, v[0:1]
	global_store_dwordx4 v[8:9], v[2:5], off sc1 nt
	s_nop 1
	ds_read2_b32 v[2:3], v36 offset0:16 offset1:49
	ds_read2_b32 v[4:5], v36 offset0:82 offset1:115
	ds_read2_b32 v[8:9], v36 offset0:214 offset1:247
	v_or_b32_e32 v0, s0, v38
	v_lshlrev_b32_e32 v0, 10, v0
	s_waitcnt lgkmcnt(2)
	v_cvt_pk_bf16_f32 v2, v2, v3
	s_waitcnt lgkmcnt(1)
	v_cvt_pk_bf16_f32 v3, v4, v5
	ds_read2_b32 v[4:5], v36 offset0:148 offset1:181
	s_waitcnt lgkmcnt(0)
	v_cvt_pk_bf16_f32 v4, v4, v5
	v_cvt_pk_bf16_f32 v5, v8, v9
	v_lshl_add_u64 v[8:9], v[6:7], 0, v[0:1]
	global_store_dwordx4 v[8:9], v[2:5], off sc1 nt
	s_nop 1
	ds_read2_b32 v[2:3], v36 offset0:24 offset1:57
	ds_read2_b32 v[4:5], v36 offset0:90 offset1:123
	ds_read2_b32 v[8:9], v36 offset0:222 offset1:255
	v_or_b32_e32 v0, s0, v39
	v_lshlrev_b32_e32 v0, 10, v0
	s_waitcnt lgkmcnt(2)
	v_cvt_pk_bf16_f32 v2, v2, v3
	s_waitcnt lgkmcnt(1)
	v_cvt_pk_bf16_f32 v3, v4, v5
	ds_read2_b32 v[4:5], v36 offset0:156 offset1:189
	v_lshl_add_u64 v[6:7], v[6:7], 0, v[0:1]
	s_waitcnt lgkmcnt(0)
	v_cvt_pk_bf16_f32 v4, v4, v5
	v_cvt_pk_bf16_f32 v5, v8, v9
	global_store_dwordx4 v[6:7], v[2:5], off sc1 nt
	s_nop 1
	s_waitcnt lgkmcnt(0)

; __device__ __forceinline__ void transpose_item(const float* W, int K, int N, bf16_t* WT, int kb, int nb, int drow0, const float* kscale, LAS float* scr, int lane) {
;     const int k0 = 64 * kb, n0 = 32 * nb, c = lane & 7;
;     f32x4 s0 = {1.f, 1.f, 1.f, 1.f}, s1 = {1.f, 1.f, 1.f, 1.f};
;     if (kscale) { s0 = *(const f32x4*)(kscale + k0 + 8 * c); s1 = *(const f32x4*)(kscale + k0 + 8 * c + 4); }
;     const float* src = W + (size_t)(k0 + (lane >> 5)) * N + n0 + (lane & 31);
;     float w[32];
; #pragma unroll
;     for (int i = 0; i < 32; ++i) w[i] = __builtin_nontemporal_load(src + (size_t)(2 * i) * N);
; __device__ __forceinline__ void prep_weights(Frame& F, const Args& a, int l, int it_lo, int it_hi, int gw, int ngw) {
;     ...
;         if (r < I2) { const int kb = r / 32, nb = r % 32; transpose_item(w_co, 512, DM, W + WO_CO, kb, nb, 32 * nb, nullptr, scr, F.lane); continue; } r -= I2;
.LBB0_1424:
	s_andn2_b64 vcc, exec, s[0:1]
	s_cbranch_vccnz .LBB0_1426
	s_and_b32 s1, s23, 0x1fc0
	s_add_i32 s72, s1, 0xffffe700
	v_or_b32_e32 v0, s72, v11
	s_and_b32 s0, s21, 0x3e0
	v_lshlrev_b64 v[2:3], 12, v[0:1]
	v_lshl_add_u64 v[2:3], s[6:7], 0, v[2:3]
	s_lshl_b32 s18, s0, 2
	s_mov_b32 s19, s73
	v_lshl_add_u64 v[2:3], v[2:3], 0, s[18:19]
	v_lshlrev_b32_e32 v0, 2, v10
	v_lshl_add_u64 v[2:3], v[2:3], 0, v[0:1]
	s_movk_i32 s1, 0x2000
	v_add_co_u32_e32 v4, vcc, s1, v2
	s_movk_i32 s1, 0x4000
	s_nop 0
	v_addc_co_u32_e32 v5, vcc, 0, v3, vcc
	global_load_dword v0, v[2:3], off nt
	global_load_dword v6, v[4:5], off nt
	v_add_co_u32_e32 v4, vcc, s1, v2
	s_movk_i32 s1, 0x6000
	s_nop 0
	v_addc_co_u32_e32 v5, vcc, 0, v3, vcc
	global_load_dword v7, v[4:5], off nt
	v_add_co_u32_e32 v4, vcc, s1, v2
	s_mov_b32 s1, 0x8000
	s_nop 0
	v_addc_co_u32_e32 v5, vcc, 0, v3, vcc
	global_load_dword v8, v[4:5], off nt
	v_add_co_u32_e32 v4, vcc, s1, v2
	s_mov_b32 s1, 0xa000
	s_nop 0
	v_addc_co_u32_e32 v5, vcc, 0, v3, vcc
	global_load_dword v9, v[4:5], off nt
	v_add_co_u32_e32 v4, vcc, s1, v2
	s_mov_b32 s1, 0xc000
	s_nop 0
	v_addc_co_u32_e32 v5, vcc, 0, v3, vcc
	global_load_dword v32, v[4:5], off nt
	v_add_co_u32_e32 v4, vcc, s1, v2
	s_mov_b32 s1, 0xe000
	s_nop 0
	v_addc_co_u32_e32 v5, vcc, 0, v3, vcc
	global_load_dword v33, v[4:5], off nt
	v_add_co_u32_e32 v4, vcc, s1, v2
	s_mov_b32 s1, 0x10000
	s_nop 0
	v_addc_co_u32_e32 v5, vcc, 0, v3, vcc
	global_load_dword v40, v[4:5], off nt
	v_add_co_u32_e32 v4, vcc, s1, v2
	s_mov_b32 s1, 0x12000
	s_nop 0
	v_addc_co_u32_e32 v5, vcc, 0, v3, vcc
	global_load_dword v41, v[4:5], off nt
	v_add_co_u32_e32 v4, vcc, s1, v2
	s_mov_b32 s1, 0x14000
	s_nop 0
	v_addc_co_u32_e32 v5, vcc, 0, v3, vcc
	global_load_dword v42, v[4:5], off nt
	v_add_co_u32_e32 v4, vcc, s1, v2
	s_mov_b32 s1, 0x16000
	s_nop 0
	v_addc_co_u32_e32 v5, vcc, 0, v3, vcc
	global_load_dword v43, v[4:5], off nt
	v_add_co_u32_e32 v4, vcc, s1, v2
	s_mov_b32 s1, 0x18000
	s_nop 0
	v_addc_co_u32_e32 v5, vcc, 0, v3, vcc
	global_load_dword v44, v[4:5], off nt
	v_add_co_u32_e32 v4, vcc, s1, v2
	s_mov_b32 s1, 0x1a000
	s_nop 0
	v_addc_co_u32_e32 v5, vcc, 0, v3, vcc
	global_load_dword v45, v[4:5], off nt
	v_add_co_u32_e32 v4, vcc, s1, v2
	s_mov_b32 s1, 0x1c000
	s_nop 0
	v_addc_co_u32_e32 v5, vcc, 0, v3, vcc
	global_load_dword v46, v[4:5], off nt
	v_add_co_u32_e32 v4, vcc, s1, v2
	s_mov_b32 s1, 0x1e000
	s_nop 0
	v_addc_co_u32_e32 v5, vcc, 0, v3, vcc
	global_load_dword v47, v[4:5], off nt
	v_add_co_u32_e32 v4, vcc, s1, v2
	s_mov_b32 s1, 0x22000
	s_nop 0
	v_addc_co_u32_e32 v5, vcc, 0, v3, vcc
	global_load_dword v48, v[4:5], off nt
	v_add_co_u32_e32 v4, vcc, s79, v2
	s_nop 1
	v_addc_co_u32_e32 v5, vcc, 0, v3, vcc
	global_load_dword v49, v[4:5], off nt
	v_add_co_u32_e32 v4, vcc, s1, v2
	s_mov_b32 s1, 0x24000
	s_nop 0
	v_addc_co_u32_e32 v5, vcc, 0, v3, vcc
	global_load_dword v50, v[4:5], off nt
	v_add_co_u32_e32 v4, vcc, s1, v2
	s_mov_b32 s1, 0x26000
	s_nop 0
	v_addc_co_u32_e32 v5, vcc, 0, v3, vcc
	global_load_dword v51, v[4:5], off nt
	v_add_co_u32_e32 v4, vcc, s1, v2
	s_mov_b32 s1, 0x28000
	s_nop 0
	v_addc_co_u32_e32 v5, vcc, 0, v3, vcc
	global_load_dword v52, v[4:5], off nt
	v_add_co_u32_e32 v4, vcc, s1, v2
	s_mov_b32 s1, 0x2a000
	s_nop 0
	v_addc_co_u32_e32 v5, vcc, 0, v3, vcc
	global_load_dword v53, v[4:5], off nt
	v_add_co_u32_e32 v4, vcc, s1, v2
	s_mov_b32 s1, 0x2c000
	s_nop 0
	v_addc_co_u32_e32 v5, vcc, 0, v3, vcc
	global_load_dword v54, v[4:5], off nt
	v_add_co_u32_e32 v4, vcc, s1, v2
	s_mov_b32 s1, 0x2e000
	s_nop 0
	v_addc_co_u32_e32 v5, vcc, 0, v3, vcc
	global_load_dword v55, v[4:5], off nt
	v_add_co_u32_e32 v4, vcc, s1, v2
	s_mov_b32 s1, 0x30000
	s_nop 0
	v_addc_co_u32_e32 v5, vcc, 0, v3, vcc
	global_load_dword v56, v[4:5], off nt
	v_add_co_u32_e32 v4, vcc, s1, v2
	s_mov_b32 s1, 0x32000
	s_nop 0
	v_addc_co_u32_e32 v5, vcc, 0, v3, vcc
	global_load_dword v57, v[4:5], off nt
	v_add_co_u32_e32 v4, vcc, s1, v2
	s_mov_b32 s1, 0x34000
	s_nop 0
	v_addc_co_u32_e32 v5, vcc, 0, v3, vcc
	global_load_dword v58, v[4:5], off nt
	v_add_co_u32_e32 v4, vcc, s1, v2
	s_mov_b32 s1, 0x36000
	s_nop 0
	v_addc_co_u32_e32 v5, vcc, 0, v3, vcc
	global_load_dword v59, v[4:5], off nt
	v_add_co_u32_e32 v4, vcc, s1, v2
	s_mov_b32 s1, 0x38000
	s_nop 0
	v_addc_co_u32_e32 v5, vcc, 0, v3, vcc
	global_load_dword v60, v[4:5], off nt
	v_add_co_u32_e32 v4, vcc, s1, v2
	s_mov_b32 s1, 0x3a000
	s_nop 0
	v_addc_co_u32_e32 v5, vcc, 0, v3, vcc
	global_load_dword v61, v[4:5], off nt
	v_add_co_u32_e32 v4, vcc, s1, v2
	s_mov_b32 s1, 0x3c000
	s_nop 0
	v_addc_co_u32_e32 v5, vcc, 0, v3, vcc
	global_load_dword v62, v[4:5], off nt
	v_add_co_u32_e32 v4, vcc, s1, v2
	s_mov_b32 s1, 0x3e000
	s_nop 0
	v_addc_co_u32_e32 v5, vcc, 0, v3, vcc
	v_add_co_u32_e32 v2, vcc, s1, v2
	global_load_dword v4, v[4:5], off nt
	s_nop 0
	v_addc_co_u32_e32 v3, vcc, 0, v3, vcc
	global_load_dword v2, v[2:3], off nt
	s_waitcnt vmcnt(30)
; #define LAS __attribute__((address_space(3)))
; __device__ __forceinline__ unsigned pk2(float lo, float hi) { const f32x2 v = {lo, hi}; const bf16x2_hw b = __builtin_convertvector(v, bf16x2_hw); return __builtin_bit_cast(unsigned, b); }
; __device__ __forceinline__ void gst_wt16(void* p, const u32x4 v) { asm volatile("global_store_dwordx4 %0, %1, off sc1\n\ts_nop 1" :: "v"(p), "v"(v) : "memory"); }
; __device__ __forceinline__ void transpose_item(const float* W, int K, int N, bf16_t* WT, int kb, int nb, int drow0, const float* kscale, LAS float* scr, int lane) {
;     ...
;     for (int i = 0; i < 32; ++i) scr[(2 * i + (lane >> 5)) * 33 + (lane & 31)] = w[i];
;     asm volatile("s_waitcnt lgkmcnt(0)" ::: "memory");
; #pragma unroll
;     for (int j = 0; j < 4; ++j) { const int n = (lane >> 3) + 8 * j; const LAS float* s = scr + (8 * c) * 33 + n;
;         u32x4 o; o.x = pk2(s[0 * 33] * s0[0], s[1 * 33] * s0[1]); o.y = pk2(s[2 * 33] * s0[2], s[3 * 33] * s0[3]); o.z = pk2(s[4 * 33] * s1[0], s[5 * 33] * s1[1]); o.w = pk2(s[6 * 33] * s1[2], s[7 * 33] * s1[3]);
;         gst_wt16(WT + (size_t)(drow0 + n) * K + k0 + 8 * c, o); }
;     asm volatile("s_waitcnt lgkmcnt(0)" ::: "memory");
	ds_write2_b32 v34, v0, v6 offset1:66
	s_waitcnt vmcnt(28)
	ds_write2_b32 v34, v7, v8 offset0:132 offset1:198
	v_add_u32_e32 v0, 0x400, v34
	s_waitcnt vmcnt(26)
	ds_write2_b32 v0, v9, v32 offset0:8 offset1:74
	s_waitcnt vmcnt(24)
	ds_write2_b32 v0, v33, v40 offset0:140 offset1:206
	v_add_u32_e32 v0, 0x800, v34
	s_waitcnt vmcnt(22)
	ds_write2_b32 v0, v41, v42 offset0:16 offset1:82
	s_waitcnt vmcnt(20)
	ds_write2_b32 v0, v43, v44 offset0:148 offset1:214
	v_add_u32_e32 v0, 0xc00, v34
	s_waitcnt vmcnt(18)
	ds_write2_b32 v0, v45, v46 offset0:24 offset1:90
	s_waitcnt vmcnt(16)
	ds_write2_b32 v0, v47, v48 offset0:156 offset1:222
	v_add_u32_e32 v0, 0x1000, v34
	s_waitcnt vmcnt(14)
	ds_write2_b32 v0, v49, v50 offset0:32 offset1:98
	s_waitcnt vmcnt(12)
	ds_write2_b32 v0, v51, v52 offset0:164 offset1:230
	v_add_u32_e32 v0, 0x1400, v34
	s_waitcnt vmcnt(10)
	ds_write2_b32 v0, v53, v54 offset0:40 offset1:106
	s_waitcnt vmcnt(8)
	ds_write2_b32 v0, v55, v56 offset0:172 offset1:238
	v_add_u32_e32 v0, 0x1800, v34
	s_waitcnt vmcnt(6)
	ds_write2_b32 v0, v57, v58 offset0:48 offset1:114
	s_waitcnt vmcnt(4)
	ds_write2_b32 v0, v59, v60 offset0:180 offset1:246
	v_add_u32_e32 v0, 0x1c00, v34
	s_waitcnt vmcnt(2)
	ds_write2_b32 v0, v61, v62 offset0:56 offset1:122
	s_waitcnt vmcnt(0)
	ds_write2_b32 v0, v4, v2 offset0:188 offset1:254
	s_waitcnt lgkmcnt(0)
	ds_read2_b32 v[2:3], v36 offset1:33
	ds_read2_b32 v[4:5], v36 offset0:66 offset1:99
	ds_read2_b32 v[8:9], v36 offset0:198 offset1:231
	v_or_b32_e32 v0, s0, v35
	v_lshl_add_u64 v[6:7], s[72:73], 1, v[24:25]
	s_waitcnt lgkmcnt(2)
	v_cvt_pk_bf16_f32 v2, v2, v3
	s_waitcnt lgkmcnt(1)
	v_cvt_pk_bf16_f32 v3, v4, v5
	ds_read2_b32 v[4:5], v36 offset0:132 offset1:165
	v_lshlrev_b32_e32 v0, 10, v0
	s_waitcnt lgkmcnt(0)
	v_cvt_pk_bf16_f32 v4, v4, v5
	v_cvt_pk_bf16_f32 v5, v8, v9
	v_lshl_add_u64 v[8:9], v[6:7], 0, v[0:1]
	global_store_dwordx4 v[8:9], v[2:5], off sc1 nt
	s_nop 1
	ds_read2_b32 v[2:3], v36 offset0:8 offset1:41
	ds_read2_b32 v[4:5], v36 offset0:74 offset1:107
	ds_read2_b32 v[8:9], v36 offset0:206 offset1:239
	v_or_b32_e32 v0, s0, v37
	v_lshlrev_b32_e32 v0, 10, v0
	s_waitcnt lgkmcnt(2)
	v_cvt_pk_bf16_f32 v2, v2, v3
	s_waitcnt lgkmcnt(1)
	v_cvt_pk_bf16_f32 v3, v4, v5
	ds_read2_b32 v[4:5], v36 offset0:140 offset1:173
	s_waitcnt lgkmcnt(0)
	v_cvt_pk_bf16_f32 v4, v4, v5
	v_cvt_pk_bf16_f32 v5, v8, v9
	v_lshl_add_u64 v[8:9], v[6:7], 0, v[0:1]
	global_store_dwordx4 v[8:9], v[2:5], off sc1 nt
	s_nop 1
	ds_read2_b32 v[2:3], v36 offset0:16 offset1:49
	ds_read2_b32 v[4:5], v36 offset0:82 offset1:115
	ds_read2_b32 v[8:9], v36 offset0:214 offset1:247
	v_or_b32_e32 v0, s0, v38
	v_lshlrev_b32_e32 v0, 10, v0
	s_waitcnt lgkmcnt(2)
	v_cvt_pk_bf16_f32 v2, v2, v3
	s_waitcnt lgkmcnt(1)
	v_cvt_pk_bf16_f32 v3, v4, v5
	ds_read2_b32 v[4:5], v36 offset0:148 offset1:181
	s_waitcnt lgkmcnt(0)
	v_cvt_pk_bf16_f32 v4, v4, v5
	v_cvt_pk_bf16_f32 v5, v8, v9
	v_lshl_add_u64 v[8:9], v[6:7], 0, v[0:1]
	global_store_dwordx4 v[8:9], v[2:5], off sc1 nt
	s_nop 1
	ds_read2_b32 v[2:3], v36 offset0:24 offset1:57
	ds_read2_b32 v[4:5], v36 offset0:90 offset1:123
	ds_read2_b32 v[8:9], v36 offset0:222 offset1:255
	v_or_b32_e32 v0, s0, v39
	v_lshlrev_b32_e32 v0, 10, v0
	s_waitcnt lgkmcnt(2)
	v_cvt_pk_bf16_f32 v2, v2, v3
	s_waitcnt lgkmcnt(1)
	v_cvt_pk_bf16_f32 v3, v4, v5
	ds_read2_b32 v[4:5], v36 offset0:156 offset1:189
	v_lshl_add_u64 v[6:7], v[6:7], 0, v[0:1]
	s_waitcnt lgkmcnt(0)
	v_cvt_pk_bf16_f32 v4, v4, v5
	v_cvt_pk_bf16_f32 v5, v8, v9
	global_store_dwordx4 v[6:7], v[2:5], off sc1 nt
	s_nop 1
	s_waitcnt lgkmcnt(0)

; __device__ __forceinline__ void transpose_item(const float* W, int K, int N, bf16_t* WT, int kb, int nb, int drow0, const float* kscale, LAS float* scr, int lane) {
;     const int k0 = 64 * kb, n0 = 32 * nb, c = lane & 7;
;     f32x4 s0 = {1.f, 1.f, 1.f, 1.f}, s1 = {1.f, 1.f, 1.f, 1.f};
;     if (kscale) { s0 = *(const f32x4*)(kscale + k0 + 8 * c); s1 = *(const f32x4*)(kscale + k0 + 8 * c + 4); }
;     const float* src = W + (size_t)(k0 + (lane >> 5)) * N + n0 + (lane & 31);
;     float w[32];
; #pragma unroll
;     for (int i = 0; i < 32; ++i) w[i] = __builtin_nontemporal_load(src + (size_t)(2 * i) * N);
; __device__ __forceinline__ void prep_weights(Frame& F, const Args& a, int l, int it_lo, int it_hi, int gw, int ngw) {
;     ...
;         if (r < I1) { const int kb = r / 32, nb = r % 32; transpose_item(w_ao, 512, DM, W + WO_AO, kb, nb, 32 * nb, nullptr, scr, F.lane); continue; } r -= I1;
.LBB0_1427:
	s_andn2_b64 vcc, exec, s[0:1]
	s_cbranch_vccnz .LBB0_1429
	s_and_b32 s1, s23, 0x1fc0
	s_add_i32 s72, s1, 0xffffe900
	v_or_b32_e32 v0, s72, v11
	s_and_b32 s0, s21, 0x3e0
	v_lshlrev_b64 v[2:3], 12, v[0:1]
	v_lshl_add_u64 v[2:3], s[4:5], 0, v[2:3]
	s_lshl_b32 s18, s0, 2
	s_mov_b32 s19, s73
	v_lshl_add_u64 v[2:3], v[2:3], 0, s[18:19]
	v_lshlrev_b32_e32 v0, 2, v10
	v_lshl_add_u64 v[2:3], v[2:3], 0, v[0:1]
	s_movk_i32 s1, 0x2000
	v_add_co_u32_e32 v4, vcc, s1, v2
	s_movk_i32 s1, 0x4000
	s_nop 0
	v_addc_co_u32_e32 v5, vcc, 0, v3, vcc
	global_load_dword v0, v[2:3], off nt
	global_load_dword v6, v[4:5], off nt
	v_add_co_u32_e32 v4, vcc, s1, v2
	s_movk_i32 s1, 0x6000
	s_nop 0
	v_addc_co_u32_e32 v5, vcc, 0, v3, vcc
	global_load_dword v7, v[4:5], off nt
	v_add_co_u32_e32 v4, vcc, s1, v2
	s_mov_b32 s1, 0x8000
	s_nop 0
	v_addc_co_u32_e32 v5, vcc, 0, v3, vcc
	global_load_dword v8, v[4:5], off nt
	v_add_co_u32_e32 v4, vcc, s1, v2
	s_mov_b32 s1, 0xa000
	s_nop 0
	v_addc_co_u32_e32 v5, vcc, 0, v3, vcc
	global_load_dword v9, v[4:5], off nt
	v_add_co_u32_e32 v4, vcc, s1, v2
	s_mov_b32 s1, 0xc000
	s_nop 0
	v_addc_co_u32_e32 v5, vcc, 0, v3, vcc
	global_load_dword v32, v[4:5], off nt
	v_add_co_u32_e32 v4, vcc, s1, v2
	s_mov_b32 s1, 0xe000
	s_nop 0
	v_addc_co_u32_e32 v5, vcc, 0, v3, vcc
	global_load_dword v33, v[4:5], off nt
	v_add_co_u32_e32 v4, vcc, s1, v2
	s_mov_b32 s1, 0x10000
	s_nop 0
	v_addc_co_u32_e32 v5, vcc, 0, v3, vcc
	global_load_dword v40, v[4:5], off nt
	v_add_co_u32_e32 v4, vcc, s1, v2
	s_mov_b32 s1, 0x12000
	s_nop 0
	v_addc_co_u32_e32 v5, vcc, 0, v3, vcc
	global_load_dword v41, v[4:5], off nt
	v_add_co_u32_e32 v4, vcc, s1, v2
	s_mov_b32 s1, 0x14000
	s_nop 0
	v_addc_co_u32_e32 v5, vcc, 0, v3, vcc
	global_load_dword v42, v[4:5], off nt
	v_add_co_u32_e32 v4, vcc, s1, v2
	s_mov_b32 s1, 0x16000
	s_nop 0
	v_addc_co_u32_e32 v5, vcc, 0, v3, vcc
	global_load_dword v43, v[4:5], off nt
	v_add_co_u32_e32 v4, vcc, s1, v2
	s_mov_b32 s1, 0x18000
	s_nop 0
	v_addc_co_u32_e32 v5, vcc, 0, v3, vcc
	global_load_dword v44, v[4:5], off nt
	v_add_co_u32_e32 v4, vcc, s1, v2
	s_mov_b32 s1, 0x1a000
	s_nop 0
	v_addc_co_u32_e32 v5, vcc, 0, v3, vcc
	global_load_dword v45, v[4:5], off nt
	v_add_co_u32_e32 v4, vcc, s1, v2
	s_mov_b32 s1, 0x1c000
	s_nop 0
	v_addc_co_u32_e32 v5, vcc, 0, v3, vcc
	global_load_dword v46, v[4:5], off nt
	v_add_co_u32_e32 v4, vcc, s1, v2
	s_mov_b32 s1, 0x1e000
	s_nop 0
	v_addc_co_u32_e32 v5, vcc, 0, v3, vcc
	global_load_dword v47, v[4:5], off nt
	v_add_co_u32_e32 v4, vcc, s1, v2
	s_mov_b32 s1, 0x22000
	s_nop 0
	v_addc_co_u32_e32 v5, vcc, 0, v3, vcc
	global_load_dword v48, v[4:5], off nt
	v_add_co_u32_e32 v4, vcc, s79, v2
	s_nop 1
	v_addc_co_u32_e32 v5, vcc, 0, v3, vcc
	global_load_dword v49, v[4:5], off nt
	v_add_co_u32_e32 v4, vcc, s1, v2
	s_mov_b32 s1, 0x24000
	s_nop 0
	v_addc_co_u32_e32 v5, vcc, 0, v3, vcc
	global_load_dword v50, v[4:5], off nt
	v_add_co_u32_e32 v4, vcc, s1, v2
	s_mov_b32 s1, 0x26000
	s_nop 0
	v_addc_co_u32_e32 v5, vcc, 0, v3, vcc
	global_load_dword v51, v[4:5], off nt
	v_add_co_u32_e32 v4, vcc, s1, v2
	s_mov_b32 s1, 0x28000
	s_nop 0
	v_addc_co_u32_e32 v5, vcc, 0, v3, vcc
	global_load_dword v52, v[4:5], off nt
	v_add_co_u32_e32 v4, vcc, s1, v2
	s_mov_b32 s1, 0x2a000
	s_nop 0
	v_addc_co_u32_e32 v5, vcc, 0, v3, vcc
	global_load_dword v53, v[4:5], off nt
	v_add_co_u32_e32 v4, vcc, s1, v2
	s_mov_b32 s1, 0x2c000
	s_nop 0
	v_addc_co_u32_e32 v5, vcc, 0, v3, vcc
	global_load_dword v54, v[4:5], off nt
	v_add_co_u32_e32 v4, vcc, s1, v2
	s_mov_b32 s1, 0x2e000
	s_nop 0
	v_addc_co_u32_e32 v5, vcc, 0, v3, vcc
	global_load_dword v55, v[4:5], off nt
	v_add_co_u32_e32 v4, vcc, s1, v2
	s_mov_b32 s1, 0x30000
	s_nop 0
	v_addc_co_u32_e32 v5, vcc, 0, v3, vcc
	global_load_dword v56, v[4:5], off nt
	v_add_co_u32_e32 v4, vcc, s1, v2
	s_mov_b32 s1, 0x32000
	s_nop 0
	v_addc_co_u32_e32 v5, vcc, 0, v3, vcc
	global_load_dword v57, v[4:5], off nt
	v_add_co_u32_e32 v4, vcc, s1, v2
	s_mov_b32 s1, 0x34000
	s_nop 0
	v_addc_co_u32_e32 v5, vcc, 0, v3, vcc
	global_load_dword v58, v[4:5], off nt
	v_add_co_u32_e32 v4, vcc, s1, v2
	s_mov_b32 s1, 0x36000
	s_nop 0
	v_addc_co_u32_e32 v5, vcc, 0, v3, vcc
	global_load_dword v59, v[4:5], off nt
	v_add_co_u32_e32 v4, vcc, s1, v2
	s_mov_b32 s1, 0x38000
	s_nop 0
	v_addc_co_u32_e32 v5, vcc, 0, v3, vcc
	global_load_dword v60, v[4:5], off nt
	v_add_co_u32_e32 v4, vcc, s1, v2
	s_mov_b32 s1, 0x3a000
	s_nop 0
	v_addc_co_u32_e32 v5, vcc, 0, v3, vcc
	global_load_dword v61, v[4:5], off nt
	v_add_co_u32_e32 v4, vcc, s1, v2
	s_mov_b32 s1, 0x3c000
	s_nop 0
	v_addc_co_u32_e32 v5, vcc, 0, v3, vcc
	global_load_dword v62, v[4:5], off nt
	v_add_co_u32_e32 v4, vcc, s1, v2
	s_mov_b32 s1, 0x3e000
	s_nop 0
	v_addc_co_u32_e32 v5, vcc, 0, v3, vcc
	v_add_co_u32_e32 v2, vcc, s1, v2
	global_load_dword v4, v[4:5], off nt
	s_nop 0
	v_addc_co_u32_e32 v3, vcc, 0, v3, vcc
	global_load_dword v2, v[2:3], off nt
	s_waitcnt vmcnt(30)
; #define LAS __attribute__((address_space(3)))
; __device__ __forceinline__ unsigned pk2(float lo, float hi) { const f32x2 v = {lo, hi}; const bf16x2_hw b = __builtin_convertvector(v, bf16x2_hw); return __builtin_bit_cast(unsigned, b); }
; __device__ __forceinline__ void gst_wt16(void* p, const u32x4 v) { asm volatile("global_store_dwordx4 %0, %1, off sc1\n\ts_nop 1" :: "v"(p), "v"(v) : "memory"); }
; __device__ __forceinline__ void transpose_item(const float* W, int K, int N, bf16_t* WT, int kb, int nb, int drow0, const float* kscale, LAS float* scr, int lane) {
;     const int k0 = 64 * kb, n0 = 32 * nb, c = lane & 7;
;     f32x4 s0 = {1.f, 1.f, 1.f, 1.f}, s1 = {1.f, 1.f, 1.f, 1.f};
;     if (kscale) { s0 = *(const f32x4*)(kscale + k0 + 8 * c); s1 = *(const f32x4*)(kscale + k0 + 8 * c + 4); }
;     const float* src = W + (size_t)(k0 + (lane >> 5)) * N + n0 + (lane & 31);
;     float w[32];
; #pragma unroll
;     for (int i = 0; i < 32; ++i) w[i] = __builtin_nontemporal_load(src + (size_t)(2 * i) * N);
; #pragma unroll
;     for (int i = 0; i < 32; ++i) scr[(2 * i + (lane >> 5)) * 33 + (lane & 31)] = w[i];
;     asm volatile("s_waitcnt lgkmcnt(0)" ::: "memory");
; #pragma unroll
;     for (int j = 0; j < 4; ++j) { const int n = (lane >> 3) + 8 * j; const LAS float* s = scr + (8 * c) * 33 + n;
;         u32x4 o; o.x = pk2(s[0 * 33] * s0[0], s[1 * 33] * s0[1]); o.y = pk2(s[2 * 33] * s0[2], s[3 * 33] * s0[3]); o.z = pk2(s[4 * 33] * s1[0], s[5 * 33] * s1[1]); o.w = pk2(s[6 * 33] * s1[2], s[7 * 33] * s1[3]);
;         gst_wt16(WT + (size_t)(drow0 + n) * K + k0 + 8 * c, o); }
;     asm volatile("s_waitcnt lgkmcnt(0)" ::: "memory");
; }
	ds_write2_b32 v34, v0, v6 offset1:66
	s_waitcnt vmcnt(28)
	ds_write2_b32 v34, v7, v8 offset0:132 offset1:198
	v_add_u32_e32 v0, 0x400, v34
	s_waitcnt vmcnt(26)
	ds_write2_b32 v0, v9, v32 offset0:8 offset1:74
	s_waitcnt vmcnt(24)
	ds_write2_b32 v0, v33, v40 offset0:140 offset1:206
	v_add_u32_e32 v0, 0x800, v34
	s_waitcnt vmcnt(22)
	ds_write2_b32 v0, v41, v42 offset0:16 offset1:82
	s_waitcnt vmcnt(20)
	ds_write2_b32 v0, v43, v44 offset0:148 offset1:214
	v_add_u32_e32 v0, 0xc00, v34
	s_waitcnt vmcnt(18)
	ds_write2_b32 v0, v45, v46 offset0:24 offset1:90
	s_waitcnt vmcnt(16)
	ds_write2_b32 v0, v47, v48 offset0:156 offset1:222
	v_add_u32_e32 v0, 0x1000, v34
	s_waitcnt vmcnt(14)
	ds_write2_b32 v0, v49, v50 offset0:32 offset1:98
	s_waitcnt vmcnt(12)
	ds_write2_b32 v0, v51, v52 offset0:164 offset1:230
	v_add_u32_e32 v0, 0x1400, v34
	s_waitcnt vmcnt(10)
	ds_write2_b32 v0, v53, v54 offset0:40 offset1:106
	s_waitcnt vmcnt(8)
	ds_write2_b32 v0, v55, v56 offset0:172 offset1:238
	v_add_u32_e32 v0, 0x1800, v34
	s_waitcnt vmcnt(6)
	ds_write2_b32 v0, v57, v58 offset0:48 offset1:114
	s_waitcnt vmcnt(4)
	ds_write2_b32 v0, v59, v60 offset0:180 offset1:246
	v_add_u32_e32 v0, 0x1c00, v34
	s_waitcnt vmcnt(2)
	ds_write2_b32 v0, v61, v62 offset0:56 offset1:122
	s_waitcnt vmcnt(0)
	ds_write2_b32 v0, v4, v2 offset0:188 offset1:254
	s_waitcnt lgkmcnt(0)
	ds_read2_b32 v[2:3], v36 offset1:33
	ds_read2_b32 v[4:5], v36 offset0:66 offset1:99
	ds_read2_b32 v[8:9], v36 offset0:198 offset1:231
	v_or_b32_e32 v0, s0, v35
	v_lshl_add_u64 v[6:7], s[72:73], 1, v[26:27]
	s_waitcnt lgkmcnt(2)
	v_cvt_pk_bf16_f32 v2, v2, v3
	s_waitcnt lgkmcnt(1)
	v_cvt_pk_bf16_f32 v3, v4, v5
	ds_read2_b32 v[4:5], v36 offset0:132 offset1:165
	v_lshlrev_b32_e32 v0, 10, v0
	s_waitcnt lgkmcnt(0)
	v_cvt_pk_bf16_f32 v4, v4, v5
	v_cvt_pk_bf16_f32 v5, v8, v9
	v_lshl_add_u64 v[8:9], v[6:7], 0, v[0:1]
	global_store_dwordx4 v[8:9], v[2:5], off sc1 nt
	s_nop 1
	ds_read2_b32 v[2:3], v36 offset0:8 offset1:41
	ds_read2_b32 v[4:5], v36 offset0:74 offset1:107
	ds_read2_b32 v[8:9], v36 offset0:206 offset1:239
	v_or_b32_e32 v0, s0, v37
	v_lshlrev_b32_e32 v0, 10, v0
	s_waitcnt lgkmcnt(2)
	v_cvt_pk_bf16_f32 v2, v2, v3
	s_waitcnt lgkmcnt(1)
	v_cvt_pk_bf16_f32 v3, v4, v5
	ds_read2_b32 v[4:5], v36 offset0:140 offset1:173
	s_waitcnt lgkmcnt(0)
	v_cvt_pk_bf16_f32 v4, v4, v5
	v_cvt_pk_bf16_f32 v5, v8, v9
	v_lshl_add_u64 v[8:9], v[6:7], 0, v[0:1]
	global_store_dwordx4 v[8:9], v[2:5], off sc1 nt
	s_nop 1
	ds_read2_b32 v[2:3], v36 offset0:16 offset1:49
	ds_read2_b32 v[4:5], v36 offset0:82 offset1:115
	ds_read2_b32 v[8:9], v36 offset0:214 offset1:247
	v_or_b32_e32 v0, s0, v38
	v_lshlrev_b32_e32 v0, 10, v0
	s_waitcnt lgkmcnt(2)
	v_cvt_pk_bf16_f32 v2, v2, v3
	s_waitcnt lgkmcnt(1)
	v_cvt_pk_bf16_f32 v3, v4, v5
	ds_read2_b32 v[4:5], v36 offset0:148 offset1:181
	s_waitcnt lgkmcnt(0)
	v_cvt_pk_bf16_f32 v4, v4, v5
	v_cvt_pk_bf16_f32 v5, v8, v9
	v_lshl_add_u64 v[8:9], v[6:7], 0, v[0:1]
	global_store_dwordx4 v[8:9], v[2:5], off sc1 nt
	s_nop 1
	ds_read2_b32 v[2:3], v36 offset0:24 offset1:57
	ds_read2_b32 v[4:5], v36 offset0:90 offset1:123
	ds_read2_b32 v[8:9], v36 offset0:222 offset1:255
	v_or_b32_e32 v0, s0, v39
	v_lshlrev_b32_e32 v0, 10, v0
	s_waitcnt lgkmcnt(2)
	v_cvt_pk_bf16_f32 v2, v2, v3
	s_waitcnt lgkmcnt(1)
	v_cvt_pk_bf16_f32 v3, v4, v5
	ds_read2_b32 v[4:5], v36 offset0:156 offset1:189
	v_lshl_add_u64 v[6:7], v[6:7], 0, v[0:1]
	s_waitcnt lgkmcnt(0)
	v_cvt_pk_bf16_f32 v4, v4, v5
	v_cvt_pk_bf16_f32 v5, v8, v9
	global_store_dwordx4 v[6:7], v[2:5], off sc1 nt
	s_nop 1
	s_waitcnt lgkmcnt(0)
